# A2 r-tile epilogue rewritten: single pass over o_f/o_b (un-normalised product kept in the accumulators, scaled by rstd after the LDS row-sum exchange), 3-deep load pipeline; f32 math, rstd via v_rsq_f
# speedup vs baseline: 1.0137x; 1.0137x over previous
;     __device__ __forceinline__ void operator()(const af4 (&acc)[2][2][4][2], const pg8::Unit& u, int wr, int wc, int fr_, int fq_) const {
;     ...
;             const int col0 = (pn - 2) * 256 + wc * 32 + 8 * fq;
;             float ssq[8];
; #pragma unroll
;             for (int b_ = 0; b_ < 4; ++b_) {
;                 const int ai = b_ >> 1, mp = b_ & 1;
;                 int RRb = row0 + ai * 128 + mp * 32; asm volatile("" : "+v"(RRb));
;                 const size_t ob = (size_t)RRb * 1024 + col0; v4u of_[2][2], ob_[2][2];
; #pragma unroll
;                 for (int mi = 0; mi < 2; ++mi)
; #pragma unroll
;                     for (int bj = 0; bj < 2; ++bj) { of_[mi][bj] = *(const v4u*)(ON + ob + mi * 16 * 1024 + bj * 128); ob_[mi][bj] = *(const v4u*)(OBp + ob + mi * 16 * 1024 + bj * 128); }
; #pragma unroll
;                 for (int mi = 0; mi < 2; ++mi) { float q = 0.f;
; #pragma unroll
;                     for (int bj = 0; bj < 2; ++bj) { const v4u a = of_[mi][bj], c = ob_[mi][bj];
;                         const float o0 = bflo(a.x) + bflo(c.x), o1 = bfhi(a.x) + bfhi(c.x), o2 = bflo(a.y) + bflo(c.y), o3 = bfhi(a.y) + bfhi(c.y), o4 = bflo(a.z) + bflo(c.z), o5 = bfhi(a.z) + bfhi(c.z), o6 = bflo(a.w) + bflo(c.w), o7 = bfhi(a.w) + bfhi(c.w);
;                         q += (o0 * o0 + o1 * o1) + (o2 * o2 + o3 * o3) + (o4 * o4 + o5 * o5) + (o6 * o6 + o7 * o7); }
;                     ssq[ai * 4 + mp * 2 + mi] = q; }
;                 asm volatile("" ::: "memory");
;             }
; #pragma unroll
;             for (int k = 0; k < 8; ++k) { float v = ssq[k];
;                 v += __int_as_float(__builtin_amdgcn_ds_bpermute((ln_ ^ 16) << 2, __float_as_int(v)));
;                 v += __int_as_float(__builtin_amdgcn_ds_bpermute((ln_ ^ 32) << 2, __float_as_int(v))); ssq[k] = v; }
;             if (fq == 0) {
; #pragma unroll
;                 for (int k = 0; k < 8; ++k) xch[((k >> 2) * 128 + wr * 64 + (k & 3) * 16 + fr) * 4 + wc] = ssq[k];
;             }
;             asm volatile("s_waitcnt lgkmcnt(0)" ::: "memory"); __builtin_amdgcn_s_barrier(); asm volatile("" ::: "memory");
;             float rs[8];
; #pragma unroll
;             for (int k = 0; k < 8; ++k) { const f32x4 p4 = *(const LAS f32x4*)(xch + ((k >> 2) * 128 + wr * 64 + (k & 3) * 16 + fr) * 4);
;                 rs[k] = 1.0f / sqrtf(((p4[0] + p4[1]) + (p4[2] + p4[3])) * (1.f / 256.f) + LN_EPS); }
.LBB0_354:
	s_andn2_b64 vcc, exec, s[6:7]
	s_cbranch_vccnz .LBB0_358
	s_lshl_b32 s10, s66, 8
	v_lshlrev_b32_e32 v136, 3, v215
	s_add_i32 s6, s51, s10
	v_mov_b32_e32 v128, v214
	v_add_u32_e32 v192, s6, v136
	v_ashrrev_i32_e32 v193, 31, v192
	v_ashrrev_i32_e32 v129, 31, v128
	v_lshlrev_b64 v[128:129], 10, v[128:129]
	v_lshl_add_u64 v[128:129], v[128:129], 0, v[192:193]
	v_lshlrev_b64 v[128:129], 1, v[128:129]
	v_lshl_add_u64 v[130:131], s[16:17], 0, v[128:129]
	v_lshl_add_u64 v[128:129], s[18:19], 0, v[128:129]
	v_mov_b32_e32 v216, v137
	v_mov_b32_e32 v217, v138
	v_lshlrev_b32_e32 v218, 2, v192
	v_mov_b32_e32 v220, v130
	v_mov_b32_e32 v221, v131
	v_mov_b32_e32 v222, v128
	v_mov_b32_e32 v223, v129
	s_load_dwordx2 s[8:9], s[84:85], 0x58
	v_add_u32_e32 v225, s87, v216
	v_lshlrev_b32_e32 v225, 4, v225
	v_add_u32_e32 v225, 0x20400, v225
	s_lshr_b32 vcc_lo, s73, 3
	v_add_u32_e32 v224, vcc_lo, v225
	v_xor_b32_e32 v226, 16, v217
	v_lshlrev_b32_e32 v226, 2, v226
	v_xor_b32_e32 v227, 32, v217
	v_lshlrev_b32_e32 v227, 2, v227
	s_waitcnt lgkmcnt(0)
	global_load_dwordx4 v[228:231], v218, s[8:9]
	global_load_dwordx4 v[232:235], v218, s[8:9] offset:16
	global_load_dwordx4 v[236:239], v218, s[8:9] offset:512
	global_load_dwordx4 v[240:243], v218, s[8:9] offset:528
	v_mov_b32_e32 v244, 0
	v_mov_b32_e32 v245, 0
	v_mov_b32_e32 v246, 0
	v_mov_b32_e32 v247, 0
	v_mov_b32_e32 v248, 0
	v_mov_b32_e32 v249, 0
	v_mov_b32_e32 v250, 0
	v_mov_b32_e32 v251, 0
	global_load_dwordx4 v[128:131], v[220:221], off
	global_load_dwordx4 v[132:135], v[220:221], off offset:256
	global_load_dwordx4 v[136:139], v[222:223], off
	global_load_dwordx4 v[140:143], v[222:223], off offset:256
	v_add_co_u32_e32 v220, vcc, 0x8000, v220
	s_nop 1
	v_addc_co_u32_e32 v221, vcc, 0, v221, vcc
	v_add_co_u32_e32 v222, vcc, 0x8000, v222
	s_nop 1
	v_addc_co_u32_e32 v223, vcc, 0, v223, vcc
	global_load_dwordx4 v[144:147], v[220:221], off
	global_load_dwordx4 v[148:151], v[220:221], off offset:256
	global_load_dwordx4 v[152:155], v[222:223], off
	global_load_dwordx4 v[156:159], v[222:223], off offset:256
	v_add_co_u32_e32 v220, vcc, 0x8000, v220
	s_nop 1
	v_addc_co_u32_e32 v221, vcc, 0, v221, vcc
	v_add_co_u32_e32 v222, vcc, 0x8000, v222
	s_nop 1
	v_addc_co_u32_e32 v223, vcc, 0, v223, vcc
	global_load_dwordx4 v[160:163], v[220:221], off
	global_load_dwordx4 v[164:167], v[220:221], off offset:256
	global_load_dwordx4 v[168:171], v[222:223], off
	global_load_dwordx4 v[172:175], v[222:223], off offset:256
	v_add_co_u32_e32 v220, vcc, 0x8000, v220
	s_nop 1
	v_addc_co_u32_e32 v221, vcc, 0, v221, vcc
	v_add_co_u32_e32 v222, vcc, 0x8000, v222
	s_nop 1
	v_addc_co_u32_e32 v223, vcc, 0, v223, vcc
	s_waitcnt vmcnt(8)
	v_lshlrev_b32_e32 v192, 16, v128
	v_and_b32_e32 v193, 0xffff0000, v128
	v_lshlrev_b32_e32 v200, 16, v136
	v_and_b32_e32 v252, 0xffff0000, v136
	v_add_f32_e32 v192, v192, v200
	v_add_f32_e32 v193, v193, v252
	v_lshlrev_b32_e32 v194, 16, v129
	v_and_b32_e32 v195, 0xffff0000, v129
	v_lshlrev_b32_e32 v200, 16, v137
	v_and_b32_e32 v252, 0xffff0000, v137
	v_add_f32_e32 v194, v194, v200
	v_add_f32_e32 v195, v195, v252
	v_lshlrev_b32_e32 v196, 16, v130
	v_and_b32_e32 v197, 0xffff0000, v130
	v_lshlrev_b32_e32 v200, 16, v138
	v_and_b32_e32 v252, 0xffff0000, v138
	v_add_f32_e32 v196, v196, v200
	v_add_f32_e32 v197, v197, v252
	v_lshlrev_b32_e32 v198, 16, v131
	v_and_b32_e32 v199, 0xffff0000, v131
	v_lshlrev_b32_e32 v200, 16, v139
	v_and_b32_e32 v252, 0xffff0000, v139
	v_add_f32_e32 v198, v198, v200
	v_add_f32_e32 v199, v199, v252
	v_mul_f32_e32 v200, v192, v192
	v_mul_f32_e32 v252, v194, v194
	v_mul_f32_e32 v253, v196, v196
	v_mul_f32_e32 v219, v198, v198
	v_fmac_f32_e32 v200, v193, v193
	v_fmac_f32_e32 v252, v195, v195
	v_fmac_f32_e32 v253, v197, v197
	v_fmac_f32_e32 v219, v199, v199
	v_add_f32_e32 v200, v200, v252
	v_add_f32_e32 v253, v253, v219
	v_add_f32_e32 v200, v200, v253
	v_add_f32_e32 v244, v244, v200
	v_mul_f32_e32 v200, 0xbfb8aa3b, v124
	v_mul_f32_e32 v252, 0xbfb8aa3b, v125
	v_mul_f32_e32 v253, 0xbfb8aa3b, v126
	v_mul_f32_e32 v219, 0xbfb8aa3b, v127
	v_exp_f32_e32 v200, v200
	v_exp_f32_e32 v252, v252
	v_exp_f32_e32 v253, v253
	v_exp_f32_e32 v219, v219
	v_add_f32_e32 v200, 1.0, v200
	v_add_f32_e32 v252, 1.0, v252
	v_add_f32_e32 v253, 1.0, v253
	v_add_f32_e32 v219, 1.0, v219
	v_rcp_f32_e32 v200, v200
	v_rcp_f32_e32 v252, v252
	v_rcp_f32_e32 v253, v253
	v_rcp_f32_e32 v219, v219
	v_mul_f32_e32 v200, v124, v200
	v_mul_f32_e32 v252, v125, v252
	v_mul_f32_e32 v253, v126, v253
	v_mul_f32_e32 v219, v127, v219
	v_mul_f32_e32 v200, v200, v228
	v_mul_f32_e32 v252, v252, v229
	v_mul_f32_e32 v253, v253, v230
	v_mul_f32_e32 v219, v219, v231
	v_mul_f32_e32 v124, v200, v192
	v_mul_f32_e32 v125, v252, v193
	v_mul_f32_e32 v126, v253, v194
	v_mul_f32_e32 v127, v219, v195
	v_mul_f32_e32 v200, 0xbfb8aa3b, v120
	v_mul_f32_e32 v252, 0xbfb8aa3b, v121
	v_mul_f32_e32 v253, 0xbfb8aa3b, v122
	v_mul_f32_e32 v219, 0xbfb8aa3b, v123
	v_exp_f32_e32 v200, v200
	v_exp_f32_e32 v252, v252
	v_exp_f32_e32 v253, v253
	v_exp_f32_e32 v219, v219
	v_add_f32_e32 v200, 1.0, v200
	v_add_f32_e32 v252, 1.0, v252
	v_add_f32_e32 v253, 1.0, v253
	v_add_f32_e32 v219, 1.0, v219
	v_rcp_f32_e32 v200, v200
	v_rcp_f32_e32 v252, v252
	v_rcp_f32_e32 v253, v253
	v_rcp_f32_e32 v219, v219
	v_mul_f32_e32 v200, v120, v200
	v_mul_f32_e32 v252, v121, v252
	v_mul_f32_e32 v253, v122, v253
	v_mul_f32_e32 v219, v123, v219
	v_mul_f32_e32 v200, v200, v232
	v_mul_f32_e32 v252, v252, v233
	v_mul_f32_e32 v253, v253, v234
	v_mul_f32_e32 v219, v219, v235
	v_mul_f32_e32 v120, v200, v196
	v_mul_f32_e32 v121, v252, v197
	v_mul_f32_e32 v122, v253, v198
	v_mul_f32_e32 v123, v219, v199
;     __device__ __forceinline__ void operator()(const af4 (&acc)[2][2][4][2], const pg8::Unit& u, int wr, int wc, int fr_, int fq_) const {
;     ...
;             const int col0 = (pn - 2) * 256 + wc * 32 + 8 * fq;
;             float ssq[8];
; #pragma unroll
;             for (int b_ = 0; b_ < 4; ++b_) {
;                 const int ai = b_ >> 1, mp = b_ & 1;
;                 int RRb = row0 + ai * 128 + mp * 32; asm volatile("" : "+v"(RRb));
;                 const size_t ob = (size_t)RRb * 1024 + col0; v4u of_[2][2], ob_[2][2];
; #pragma unroll
;                 for (int mi = 0; mi < 2; ++mi)
; #pragma unroll
;                     for (int bj = 0; bj < 2; ++bj) { of_[mi][bj] = *(const v4u*)(ON + ob + mi * 16 * 1024 + bj * 128); ob_[mi][bj] = *(const v4u*)(OBp + ob + mi * 16 * 1024 + bj * 128); }
; #pragma unroll
;                 for (int mi = 0; mi < 2; ++mi) { float q = 0.f;
; #pragma unroll
;                     for (int bj = 0; bj < 2; ++bj) { const v4u a = of_[mi][bj], c = ob_[mi][bj];
;                         const float o0 = bflo(a.x) + bflo(c.x), o1 = bfhi(a.x) + bfhi(c.x), o2 = bflo(a.y) + bflo(c.y), o3 = bfhi(a.y) + bfhi(c.y), o4 = bflo(a.z) + bflo(c.z), o5 = bfhi(a.z) + bfhi(c.z), o6 = bflo(a.w) + bflo(c.w), o7 = bfhi(a.w) + bfhi(c.w);
;                         q += (o0 * o0 + o1 * o1) + (o2 * o2 + o3 * o3) + (o4 * o4 + o5 * o5) + (o6 * o6 + o7 * o7); }
;                     ssq[ai * 4 + mp * 2 + mi] = q; }
;                 asm volatile("" ::: "memory");
;             }
; #pragma unroll
;             for (int k = 0; k < 8; ++k) { float v = ssq[k];
;                 v += __int_as_float(__builtin_amdgcn_ds_bpermute((ln_ ^ 16) << 2, __float_as_int(v)));
;                 v += __int_as_float(__builtin_amdgcn_ds_bpermute((ln_ ^ 32) << 2, __float_as_int(v))); ssq[k] = v; }
;             if (fq == 0) {
; #pragma unroll
;                 for (int k = 0; k < 8; ++k) xch[((k >> 2) * 128 + wr * 64 + (k & 3) * 16 + fr) * 4 + wc] = ssq[k];
;             }
;             asm volatile("s_waitcnt lgkmcnt(0)" ::: "memory"); __builtin_amdgcn_s_barrier(); asm volatile("" ::: "memory");
;             float rs[8];
; #pragma unroll
;             for (int k = 0; k < 8; ++k) { const f32x4 p4 = *(const LAS f32x4*)(xch + ((k >> 2) * 128 + wr * 64 + (k & 3) * 16 + fr) * 4);
;                 rs[k] = 1.0f / sqrtf(((p4[0] + p4[1]) + (p4[2] + p4[3])) * (1.f / 256.f) + LN_EPS); }
	v_lshlrev_b32_e32 v192, 16, v132
	v_and_b32_e32 v193, 0xffff0000, v132
	v_lshlrev_b32_e32 v200, 16, v140
	v_and_b32_e32 v252, 0xffff0000, v140
	v_add_f32_e32 v192, v192, v200
	v_add_f32_e32 v193, v193, v252
	v_lshlrev_b32_e32 v194, 16, v133
	v_and_b32_e32 v195, 0xffff0000, v133
	v_lshlrev_b32_e32 v200, 16, v141
	v_and_b32_e32 v252, 0xffff0000, v141
	v_add_f32_e32 v194, v194, v200
	v_add_f32_e32 v195, v195, v252
	v_lshlrev_b32_e32 v196, 16, v134
	v_and_b32_e32 v197, 0xffff0000, v134
	v_lshlrev_b32_e32 v200, 16, v142
	v_and_b32_e32 v252, 0xffff0000, v142
	v_add_f32_e32 v196, v196, v200
	v_add_f32_e32 v197, v197, v252
	v_lshlrev_b32_e32 v198, 16, v135
	v_and_b32_e32 v199, 0xffff0000, v135
	v_lshlrev_b32_e32 v200, 16, v143
	v_and_b32_e32 v252, 0xffff0000, v143
	v_add_f32_e32 v198, v198, v200
	v_add_f32_e32 v199, v199, v252
	v_mul_f32_e32 v200, v192, v192
	v_mul_f32_e32 v252, v194, v194
	v_mul_f32_e32 v253, v196, v196
	v_mul_f32_e32 v219, v198, v198
	v_fmac_f32_e32 v200, v193, v193
	v_fmac_f32_e32 v252, v195, v195
	v_fmac_f32_e32 v253, v197, v197
	v_fmac_f32_e32 v219, v199, v199
	v_add_f32_e32 v200, v200, v252
	v_add_f32_e32 v253, v253, v219
	v_add_f32_e32 v200, v200, v253
	v_add_f32_e32 v244, v244, v200
	v_mul_f32_e32 v200, 0xbfb8aa3b, v112
	v_mul_f32_e32 v252, 0xbfb8aa3b, v113
	v_mul_f32_e32 v253, 0xbfb8aa3b, v114
	v_mul_f32_e32 v219, 0xbfb8aa3b, v115
	v_exp_f32_e32 v200, v200
	v_exp_f32_e32 v252, v252
	v_exp_f32_e32 v253, v253
	v_exp_f32_e32 v219, v219
	v_add_f32_e32 v200, 1.0, v200
	v_add_f32_e32 v252, 1.0, v252
	v_add_f32_e32 v253, 1.0, v253
	v_add_f32_e32 v219, 1.0, v219
	v_rcp_f32_e32 v200, v200
	v_rcp_f32_e32 v252, v252
	v_rcp_f32_e32 v253, v253
	v_rcp_f32_e32 v219, v219
	v_mul_f32_e32 v200, v112, v200
	v_mul_f32_e32 v252, v113, v252
	v_mul_f32_e32 v253, v114, v253
	v_mul_f32_e32 v219, v115, v219
	v_mul_f32_e32 v200, v200, v236
	v_mul_f32_e32 v252, v252, v237
	v_mul_f32_e32 v253, v253, v238
	v_mul_f32_e32 v219, v219, v239
	v_mul_f32_e32 v112, v200, v192
	v_mul_f32_e32 v113, v252, v193
	v_mul_f32_e32 v114, v253, v194
	v_mul_f32_e32 v115, v219, v195
	v_mul_f32_e32 v200, 0xbfb8aa3b, v104
	v_mul_f32_e32 v252, 0xbfb8aa3b, v105
	v_mul_f32_e32 v253, 0xbfb8aa3b, v106
	v_mul_f32_e32 v219, 0xbfb8aa3b, v107
	v_exp_f32_e32 v200, v200
	v_exp_f32_e32 v252, v252
	v_exp_f32_e32 v253, v253
	v_exp_f32_e32 v219, v219
	v_add_f32_e32 v200, 1.0, v200
	v_add_f32_e32 v252, 1.0, v252
	v_add_f32_e32 v253, 1.0, v253
	v_add_f32_e32 v219, 1.0, v219
	v_rcp_f32_e32 v200, v200
	v_rcp_f32_e32 v252, v252
	v_rcp_f32_e32 v253, v253
	v_rcp_f32_e32 v219, v219
	v_mul_f32_e32 v200, v104, v200
	v_mul_f32_e32 v252, v105, v252
	v_mul_f32_e32 v253, v106, v253
	v_mul_f32_e32 v219, v107, v219
	v_mul_f32_e32 v200, v200, v240
	v_mul_f32_e32 v252, v252, v241
	v_mul_f32_e32 v253, v253, v242
	v_mul_f32_e32 v219, v219, v243
	v_mul_f32_e32 v104, v200, v196
	v_mul_f32_e32 v105, v252, v197
	v_mul_f32_e32 v106, v253, v198
	v_mul_f32_e32 v107, v219, v199
	global_load_dwordx4 v[128:131], v[220:221], off
	global_load_dwordx4 v[132:135], v[220:221], off offset:256
	global_load_dwordx4 v[136:139], v[222:223], off
	global_load_dwordx4 v[140:143], v[222:223], off offset:256
	v_add_co_u32_e32 v220, vcc, 0x28000, v220
	s_nop 1
	v_addc_co_u32_e32 v221, vcc, 0, v221, vcc
	v_add_co_u32_e32 v222, vcc, 0x28000, v222
	s_nop 1
	v_addc_co_u32_e32 v223, vcc, 0, v223, vcc
	s_waitcnt vmcnt(8)
	v_lshlrev_b32_e32 v192, 16, v144
	v_and_b32_e32 v193, 0xffff0000, v144
	v_lshlrev_b32_e32 v200, 16, v152
	v_and_b32_e32 v252, 0xffff0000, v152
	v_add_f32_e32 v192, v192, v200
	v_add_f32_e32 v193, v193, v252
	v_lshlrev_b32_e32 v194, 16, v145
	v_and_b32_e32 v195, 0xffff0000, v145
	v_lshlrev_b32_e32 v200, 16, v153
	v_and_b32_e32 v252, 0xffff0000, v153
	v_add_f32_e32 v194, v194, v200
	v_add_f32_e32 v195, v195, v252
	v_lshlrev_b32_e32 v196, 16, v146
	v_and_b32_e32 v197, 0xffff0000, v146
	v_lshlrev_b32_e32 v200, 16, v154
	v_and_b32_e32 v252, 0xffff0000, v154
	v_add_f32_e32 v196, v196, v200
	v_add_f32_e32 v197, v197, v252
	v_lshlrev_b32_e32 v198, 16, v147
	v_and_b32_e32 v199, 0xffff0000, v147
	v_lshlrev_b32_e32 v200, 16, v155
	v_and_b32_e32 v252, 0xffff0000, v155
	v_add_f32_e32 v198, v198, v200
	v_add_f32_e32 v199, v199, v252
	v_mul_f32_e32 v200, v192, v192
	v_mul_f32_e32 v252, v194, v194
	v_mul_f32_e32 v253, v196, v196
	v_mul_f32_e32 v219, v198, v198
	v_fmac_f32_e32 v200, v193, v193
	v_fmac_f32_e32 v252, v195, v195
	v_fmac_f32_e32 v253, v197, v197
	v_fmac_f32_e32 v219, v199, v199
	v_add_f32_e32 v200, v200, v252
	v_add_f32_e32 v253, v253, v219
	v_add_f32_e32 v200, v200, v253
	v_add_f32_e32 v245, v245, v200
	v_mul_f32_e32 v200, 0xbfb8aa3b, v116
	v_mul_f32_e32 v252, 0xbfb8aa3b, v117
	v_mul_f32_e32 v253, 0xbfb8aa3b, v118
	v_mul_f32_e32 v219, 0xbfb8aa3b, v119
	v_exp_f32_e32 v200, v200
	v_exp_f32_e32 v252, v252
	v_exp_f32_e32 v253, v253
	v_exp_f32_e32 v219, v219
	v_add_f32_e32 v200, 1.0, v200
	v_add_f32_e32 v252, 1.0, v252
	v_add_f32_e32 v253, 1.0, v253
	v_add_f32_e32 v219, 1.0, v219
	v_rcp_f32_e32 v200, v200
	v_rcp_f32_e32 v252, v252
	v_rcp_f32_e32 v253, v253
	v_rcp_f32_e32 v219, v219
	v_mul_f32_e32 v200, v116, v200
	v_mul_f32_e32 v252, v117, v252
	v_mul_f32_e32 v253, v118, v253
	v_mul_f32_e32 v219, v119, v219
	v_mul_f32_e32 v200, v200, v228
	v_mul_f32_e32 v252, v252, v229
	v_mul_f32_e32 v253, v253, v230
	v_mul_f32_e32 v219, v219, v231
	v_mul_f32_e32 v116, v200, v192
	v_mul_f32_e32 v117, v252, v193
	v_mul_f32_e32 v118, v253, v194
	v_mul_f32_e32 v119, v219, v195
	v_mul_f32_e32 v200, 0xbfb8aa3b, v108
	v_mul_f32_e32 v252, 0xbfb8aa3b, v109
	v_mul_f32_e32 v253, 0xbfb8aa3b, v110
	v_mul_f32_e32 v219, 0xbfb8aa3b, v111
	v_exp_f32_e32 v200, v200
;     __device__ __forceinline__ void operator()(const af4 (&acc)[2][2][4][2], const pg8::Unit& u, int wr, int wc, int fr_, int fq_) const {
;     ...
;             const int col0 = (pn - 2) * 256 + wc * 32 + 8 * fq;
;             float ssq[8];
; #pragma unroll
;             for (int b_ = 0; b_ < 4; ++b_) {
;                 const int ai = b_ >> 1, mp = b_ & 1;
;                 int RRb = row0 + ai * 128 + mp * 32; asm volatile("" : "+v"(RRb));
;                 const size_t ob = (size_t)RRb * 1024 + col0; v4u of_[2][2], ob_[2][2];
; #pragma unroll
;                 for (int mi = 0; mi < 2; ++mi)
; #pragma unroll
;                     for (int bj = 0; bj < 2; ++bj) { of_[mi][bj] = *(const v4u*)(ON + ob + mi * 16 * 1024 + bj * 128); ob_[mi][bj] = *(const v4u*)(OBp + ob + mi * 16 * 1024 + bj * 128); }
; #pragma unroll
;                 for (int mi = 0; mi < 2; ++mi) { float q = 0.f;
; #pragma unroll
;                     for (int bj = 0; bj < 2; ++bj) { const v4u a = of_[mi][bj], c = ob_[mi][bj];
;                         const float o0 = bflo(a.x) + bflo(c.x), o1 = bfhi(a.x) + bfhi(c.x), o2 = bflo(a.y) + bflo(c.y), o3 = bfhi(a.y) + bfhi(c.y), o4 = bflo(a.z) + bflo(c.z), o5 = bfhi(a.z) + bfhi(c.z), o6 = bflo(a.w) + bflo(c.w), o7 = bfhi(a.w) + bfhi(c.w);
;                         q += (o0 * o0 + o1 * o1) + (o2 * o2 + o3 * o3) + (o4 * o4 + o5 * o5) + (o6 * o6 + o7 * o7); }
;                     ssq[ai * 4 + mp * 2 + mi] = q; }
;                 asm volatile("" ::: "memory");
;             }
; #pragma unroll
;             for (int k = 0; k < 8; ++k) { float v = ssq[k];
;                 v += __int_as_float(__builtin_amdgcn_ds_bpermute((ln_ ^ 16) << 2, __float_as_int(v)));
;                 v += __int_as_float(__builtin_amdgcn_ds_bpermute((ln_ ^ 32) << 2, __float_as_int(v))); ssq[k] = v; }
;             if (fq == 0) {
; #pragma unroll
;                 for (int k = 0; k < 8; ++k) xch[((k >> 2) * 128 + wr * 64 + (k & 3) * 16 + fr) * 4 + wc] = ssq[k];
;             }
;             asm volatile("s_waitcnt lgkmcnt(0)" ::: "memory"); __builtin_amdgcn_s_barrier(); asm volatile("" ::: "memory");
;             float rs[8];
; #pragma unroll
;             for (int k = 0; k < 8; ++k) { const f32x4 p4 = *(const LAS f32x4*)(xch + ((k >> 2) * 128 + wr * 64 + (k & 3) * 16 + fr) * 4);
;                 rs[k] = 1.0f / sqrtf(((p4[0] + p4[1]) + (p4[2] + p4[3])) * (1.f / 256.f) + LN_EPS); }
	v_exp_f32_e32 v252, v252
	v_exp_f32_e32 v253, v253
	v_exp_f32_e32 v219, v219
	v_add_f32_e32 v200, 1.0, v200
	v_add_f32_e32 v252, 1.0, v252
	v_add_f32_e32 v253, 1.0, v253
	v_add_f32_e32 v219, 1.0, v219
	v_rcp_f32_e32 v200, v200
	v_rcp_f32_e32 v252, v252
	v_rcp_f32_e32 v253, v253
	v_rcp_f32_e32 v219, v219
	v_mul_f32_e32 v200, v108, v200
	v_mul_f32_e32 v252, v109, v252
	v_mul_f32_e32 v253, v110, v253
	v_mul_f32_e32 v219, v111, v219
	v_mul_f32_e32 v200, v200, v232
	v_mul_f32_e32 v252, v252, v233
	v_mul_f32_e32 v253, v253, v234
	v_mul_f32_e32 v219, v219, v235
	v_mul_f32_e32 v108, v200, v196
	v_mul_f32_e32 v109, v252, v197
	v_mul_f32_e32 v110, v253, v198
	v_mul_f32_e32 v111, v219, v199
	v_lshlrev_b32_e32 v192, 16, v148
	v_and_b32_e32 v193, 0xffff0000, v148
	v_lshlrev_b32_e32 v200, 16, v156
	v_and_b32_e32 v252, 0xffff0000, v156
	v_add_f32_e32 v192, v192, v200
	v_add_f32_e32 v193, v193, v252
	v_lshlrev_b32_e32 v194, 16, v149
	v_and_b32_e32 v195, 0xffff0000, v149
	v_lshlrev_b32_e32 v200, 16, v157
	v_and_b32_e32 v252, 0xffff0000, v157
	v_add_f32_e32 v194, v194, v200
	v_add_f32_e32 v195, v195, v252
	v_lshlrev_b32_e32 v196, 16, v150
	v_and_b32_e32 v197, 0xffff0000, v150
	v_lshlrev_b32_e32 v200, 16, v158
	v_and_b32_e32 v252, 0xffff0000, v158
	v_add_f32_e32 v196, v196, v200
	v_add_f32_e32 v197, v197, v252
	v_lshlrev_b32_e32 v198, 16, v151
	v_and_b32_e32 v199, 0xffff0000, v151
	v_lshlrev_b32_e32 v200, 16, v159
	v_and_b32_e32 v252, 0xffff0000, v159
	v_add_f32_e32 v198, v198, v200
	v_add_f32_e32 v199, v199, v252
	v_mul_f32_e32 v200, v192, v192
	v_mul_f32_e32 v252, v194, v194
	v_mul_f32_e32 v253, v196, v196
	v_mul_f32_e32 v219, v198, v198
	v_fmac_f32_e32 v200, v193, v193
	v_fmac_f32_e32 v252, v195, v195
	v_fmac_f32_e32 v253, v197, v197
	v_fmac_f32_e32 v219, v199, v199
	v_add_f32_e32 v200, v200, v252
	v_add_f32_e32 v253, v253, v219
	v_add_f32_e32 v200, v200, v253
	v_add_f32_e32 v245, v245, v200
	v_mul_f32_e32 v200, 0xbfb8aa3b, v96
	v_mul_f32_e32 v252, 0xbfb8aa3b, v97
	v_mul_f32_e32 v253, 0xbfb8aa3b, v98
	v_mul_f32_e32 v219, 0xbfb8aa3b, v99
	v_exp_f32_e32 v200, v200
	v_exp_f32_e32 v252, v252
	v_exp_f32_e32 v253, v253
	v_exp_f32_e32 v219, v219
	v_add_f32_e32 v200, 1.0, v200
	v_add_f32_e32 v252, 1.0, v252
	v_add_f32_e32 v253, 1.0, v253
	v_add_f32_e32 v219, 1.0, v219
	v_rcp_f32_e32 v200, v200
	v_rcp_f32_e32 v252, v252
	v_rcp_f32_e32 v253, v253
	v_rcp_f32_e32 v219, v219
	v_mul_f32_e32 v200, v96, v200
	v_mul_f32_e32 v252, v97, v252
	v_mul_f32_e32 v253, v98, v253
	v_mul_f32_e32 v219, v99, v219
	v_mul_f32_e32 v200, v200, v236
	v_mul_f32_e32 v252, v252, v237
	v_mul_f32_e32 v253, v253, v238
	v_mul_f32_e32 v219, v219, v239
	v_mul_f32_e32 v96, v200, v192
	v_mul_f32_e32 v97, v252, v193
	v_mul_f32_e32 v98, v253, v194
	v_mul_f32_e32 v99, v219, v195
	v_mul_f32_e32 v200, 0xbfb8aa3b, v88
	v_mul_f32_e32 v252, 0xbfb8aa3b, v89
	v_mul_f32_e32 v253, 0xbfb8aa3b, v90
	v_mul_f32_e32 v219, 0xbfb8aa3b, v91
	v_exp_f32_e32 v200, v200
	v_exp_f32_e32 v252, v252
	v_exp_f32_e32 v253, v253
	v_exp_f32_e32 v219, v219
	v_add_f32_e32 v200, 1.0, v200
	v_add_f32_e32 v252, 1.0, v252
	v_add_f32_e32 v253, 1.0, v253
	v_add_f32_e32 v219, 1.0, v219
	v_rcp_f32_e32 v200, v200
	v_rcp_f32_e32 v252, v252
	v_rcp_f32_e32 v253, v253
	v_rcp_f32_e32 v219, v219
	v_mul_f32_e32 v200, v88, v200
	v_mul_f32_e32 v252, v89, v252
	v_mul_f32_e32 v253, v90, v253
	v_mul_f32_e32 v219, v91, v219
	v_mul_f32_e32 v200, v200, v240
	v_mul_f32_e32 v252, v252, v241
	v_mul_f32_e32 v253, v253, v242
	v_mul_f32_e32 v219, v219, v243
	v_mul_f32_e32 v88, v200, v196
	v_mul_f32_e32 v89, v252, v197
	v_mul_f32_e32 v90, v253, v198
	v_mul_f32_e32 v91, v219, v199
	global_load_dwordx4 v[144:147], v[220:221], off
	global_load_dwordx4 v[148:151], v[220:221], off offset:256
	global_load_dwordx4 v[152:155], v[222:223], off
	global_load_dwordx4 v[156:159], v[222:223], off offset:256
	v_add_co_u32_e32 v220, vcc, 0x8000, v220
	s_nop 1
	v_addc_co_u32_e32 v221, vcc, 0, v221, vcc
	v_add_co_u32_e32 v222, vcc, 0x8000, v222
	s_nop 1
	v_addc_co_u32_e32 v223, vcc, 0, v223, vcc
	s_waitcnt vmcnt(8)
	v_lshlrev_b32_e32 v192, 16, v160
	v_and_b32_e32 v193, 0xffff0000, v160
	v_lshlrev_b32_e32 v200, 16, v168
	v_and_b32_e32 v252, 0xffff0000, v168
	v_add_f32_e32 v192, v192, v200
	v_add_f32_e32 v193, v193, v252
	v_lshlrev_b32_e32 v194, 16, v161
	v_and_b32_e32 v195, 0xffff0000, v161
	v_lshlrev_b32_e32 v200, 16, v169
	v_and_b32_e32 v252, 0xffff0000, v169
	v_add_f32_e32 v194, v194, v200
	v_add_f32_e32 v195, v195, v252
	v_lshlrev_b32_e32 v196, 16, v162
	v_and_b32_e32 v197, 0xffff0000, v162
	v_lshlrev_b32_e32 v200, 16, v170
	v_and_b32_e32 v252, 0xffff0000, v170
	v_add_f32_e32 v196, v196, v200
	v_add_f32_e32 v197, v197, v252
	v_lshlrev_b32_e32 v198, 16, v163
	v_and_b32_e32 v199, 0xffff0000, v163
	v_lshlrev_b32_e32 v200, 16, v171
	v_and_b32_e32 v252, 0xffff0000, v171
	v_add_f32_e32 v198, v198, v200
	v_add_f32_e32 v199, v199, v252
	v_mul_f32_e32 v200, v192, v192
	v_mul_f32_e32 v252, v194, v194
	v_mul_f32_e32 v253, v196, v196
	v_mul_f32_e32 v219, v198, v198
	v_fmac_f32_e32 v200, v193, v193
	v_fmac_f32_e32 v252, v195, v195
	v_fmac_f32_e32 v253, v197, v197
	v_fmac_f32_e32 v219, v199, v199
	v_add_f32_e32 v200, v200, v252
	v_add_f32_e32 v253, v253, v219
	v_add_f32_e32 v200, v200, v253
	v_add_f32_e32 v246, v246, v200
	v_mul_f32_e32 v200, 0xbfb8aa3b, v100
	v_mul_f32_e32 v252, 0xbfb8aa3b, v101
	v_mul_f32_e32 v253, 0xbfb8aa3b, v102
	v_mul_f32_e32 v219, 0xbfb8aa3b, v103
	v_exp_f32_e32 v200, v200
	v_exp_f32_e32 v252, v252
	v_exp_f32_e32 v253, v253
	v_exp_f32_e32 v219, v219
	v_add_f32_e32 v200, 1.0, v200
	v_add_f32_e32 v252, 1.0, v252
	v_add_f32_e32 v253, 1.0, v253
	v_add_f32_e32 v219, 1.0, v219
;     __device__ __forceinline__ void operator()(const af4 (&acc)[2][2][4][2], const pg8::Unit& u, int wr, int wc, int fr_, int fq_) const {
;     ...
;             const int col0 = (pn - 2) * 256 + wc * 32 + 8 * fq;
;             float ssq[8];
; #pragma unroll
;             for (int b_ = 0; b_ < 4; ++b_) {
;                 const int ai = b_ >> 1, mp = b_ & 1;
;                 int RRb = row0 + ai * 128 + mp * 32; asm volatile("" : "+v"(RRb));
;                 const size_t ob = (size_t)RRb * 1024 + col0; v4u of_[2][2], ob_[2][2];
; #pragma unroll
;                 for (int mi = 0; mi < 2; ++mi)
; #pragma unroll
;                     for (int bj = 0; bj < 2; ++bj) { of_[mi][bj] = *(const v4u*)(ON + ob + mi * 16 * 1024 + bj * 128); ob_[mi][bj] = *(const v4u*)(OBp + ob + mi * 16 * 1024 + bj * 128); }
; #pragma unroll
;                 for (int mi = 0; mi < 2; ++mi) { float q = 0.f;
; #pragma unroll
;                     for (int bj = 0; bj < 2; ++bj) { const v4u a = of_[mi][bj], c = ob_[mi][bj];
;                         const float o0 = bflo(a.x) + bflo(c.x), o1 = bfhi(a.x) + bfhi(c.x), o2 = bflo(a.y) + bflo(c.y), o3 = bfhi(a.y) + bfhi(c.y), o4 = bflo(a.z) + bflo(c.z), o5 = bfhi(a.z) + bfhi(c.z), o6 = bflo(a.w) + bflo(c.w), o7 = bfhi(a.w) + bfhi(c.w);
;                         q += (o0 * o0 + o1 * o1) + (o2 * o2 + o3 * o3) + (o4 * o4 + o5 * o5) + (o6 * o6 + o7 * o7); }
;                     ssq[ai * 4 + mp * 2 + mi] = q; }
;                 asm volatile("" ::: "memory");
;             }
; #pragma unroll
;             for (int k = 0; k < 8; ++k) { float v = ssq[k];
;                 v += __int_as_float(__builtin_amdgcn_ds_bpermute((ln_ ^ 16) << 2, __float_as_int(v)));
;                 v += __int_as_float(__builtin_amdgcn_ds_bpermute((ln_ ^ 32) << 2, __float_as_int(v))); ssq[k] = v; }
;             if (fq == 0) {
; #pragma unroll
;                 for (int k = 0; k < 8; ++k) xch[((k >> 2) * 128 + wr * 64 + (k & 3) * 16 + fr) * 4 + wc] = ssq[k];
;             }
;             asm volatile("s_waitcnt lgkmcnt(0)" ::: "memory"); __builtin_amdgcn_s_barrier(); asm volatile("" ::: "memory");
;             float rs[8];
; #pragma unroll
;             for (int k = 0; k < 8; ++k) { const f32x4 p4 = *(const LAS f32x4*)(xch + ((k >> 2) * 128 + wr * 64 + (k & 3) * 16 + fr) * 4);
;                 rs[k] = 1.0f / sqrtf(((p4[0] + p4[1]) + (p4[2] + p4[3])) * (1.f / 256.f) + LN_EPS); }
	v_rcp_f32_e32 v200, v200
	v_rcp_f32_e32 v252, v252
	v_rcp_f32_e32 v253, v253
	v_rcp_f32_e32 v219, v219
	v_mul_f32_e32 v200, v100, v200
	v_mul_f32_e32 v252, v101, v252
	v_mul_f32_e32 v253, v102, v253
	v_mul_f32_e32 v219, v103, v219
	v_mul_f32_e32 v200, v200, v228
	v_mul_f32_e32 v252, v252, v229
	v_mul_f32_e32 v253, v253, v230
	v_mul_f32_e32 v219, v219, v231
	v_mul_f32_e32 v100, v200, v192
	v_mul_f32_e32 v101, v252, v193
	v_mul_f32_e32 v102, v253, v194
	v_mul_f32_e32 v103, v219, v195
	v_mul_f32_e32 v200, 0xbfb8aa3b, v92
	v_mul_f32_e32 v252, 0xbfb8aa3b, v93
	v_mul_f32_e32 v253, 0xbfb8aa3b, v94
	v_mul_f32_e32 v219, 0xbfb8aa3b, v95
	v_exp_f32_e32 v200, v200
	v_exp_f32_e32 v252, v252
	v_exp_f32_e32 v253, v253
	v_exp_f32_e32 v219, v219
	v_add_f32_e32 v200, 1.0, v200
	v_add_f32_e32 v252, 1.0, v252
	v_add_f32_e32 v253, 1.0, v253
	v_add_f32_e32 v219, 1.0, v219
	v_rcp_f32_e32 v200, v200
	v_rcp_f32_e32 v252, v252
	v_rcp_f32_e32 v253, v253
	v_rcp_f32_e32 v219, v219
	v_mul_f32_e32 v200, v92, v200
	v_mul_f32_e32 v252, v93, v252
	v_mul_f32_e32 v253, v94, v253
	v_mul_f32_e32 v219, v95, v219
	v_mul_f32_e32 v200, v200, v232
	v_mul_f32_e32 v252, v252, v233
	v_mul_f32_e32 v253, v253, v234
	v_mul_f32_e32 v219, v219, v235
	v_mul_f32_e32 v92, v200, v196
	v_mul_f32_e32 v93, v252, v197
	v_mul_f32_e32 v94, v253, v198
	v_mul_f32_e32 v95, v219, v199
	v_lshlrev_b32_e32 v192, 16, v164
	v_and_b32_e32 v193, 0xffff0000, v164
	v_lshlrev_b32_e32 v200, 16, v172
	v_and_b32_e32 v252, 0xffff0000, v172
	v_add_f32_e32 v192, v192, v200
	v_add_f32_e32 v193, v193, v252
	v_lshlrev_b32_e32 v194, 16, v165
	v_and_b32_e32 v195, 0xffff0000, v165
	v_lshlrev_b32_e32 v200, 16, v173
	v_and_b32_e32 v252, 0xffff0000, v173
	v_add_f32_e32 v194, v194, v200
	v_add_f32_e32 v195, v195, v252
	v_lshlrev_b32_e32 v196, 16, v166
	v_and_b32_e32 v197, 0xffff0000, v166
	v_lshlrev_b32_e32 v200, 16, v174
	v_and_b32_e32 v252, 0xffff0000, v174
	v_add_f32_e32 v196, v196, v200
	v_add_f32_e32 v197, v197, v252
	v_lshlrev_b32_e32 v198, 16, v167
	v_and_b32_e32 v199, 0xffff0000, v167
	v_lshlrev_b32_e32 v200, 16, v175
	v_and_b32_e32 v252, 0xffff0000, v175
	v_add_f32_e32 v198, v198, v200
	v_add_f32_e32 v199, v199, v252
	v_mul_f32_e32 v200, v192, v192
	v_mul_f32_e32 v252, v194, v194
	v_mul_f32_e32 v253, v196, v196
	v_mul_f32_e32 v219, v198, v198
	v_fmac_f32_e32 v200, v193, v193
	v_fmac_f32_e32 v252, v195, v195
	v_fmac_f32_e32 v253, v197, v197
	v_fmac_f32_e32 v219, v199, v199
	v_add_f32_e32 v200, v200, v252
	v_add_f32_e32 v253, v253, v219
	v_add_f32_e32 v200, v200, v253
	v_add_f32_e32 v246, v246, v200
	v_mul_f32_e32 v200, 0xbfb8aa3b, v80
	v_mul_f32_e32 v252, 0xbfb8aa3b, v81
	v_mul_f32_e32 v253, 0xbfb8aa3b, v82
	v_mul_f32_e32 v219, 0xbfb8aa3b, v83
	v_exp_f32_e32 v200, v200
	v_exp_f32_e32 v252, v252
	v_exp_f32_e32 v253, v253
	v_exp_f32_e32 v219, v219
	v_add_f32_e32 v200, 1.0, v200
	v_add_f32_e32 v252, 1.0, v252
	v_add_f32_e32 v253, 1.0, v253
	v_add_f32_e32 v219, 1.0, v219
	v_rcp_f32_e32 v200, v200
	v_rcp_f32_e32 v252, v252
	v_rcp_f32_e32 v253, v253
	v_rcp_f32_e32 v219, v219
	v_mul_f32_e32 v200, v80, v200
	v_mul_f32_e32 v252, v81, v252
	v_mul_f32_e32 v253, v82, v253
	v_mul_f32_e32 v219, v83, v219
	v_mul_f32_e32 v200, v200, v236
	v_mul_f32_e32 v252, v252, v237
	v_mul_f32_e32 v253, v253, v238
	v_mul_f32_e32 v219, v219, v239
	v_mul_f32_e32 v80, v200, v192
	v_mul_f32_e32 v81, v252, v193
	v_mul_f32_e32 v82, v253, v194
	v_mul_f32_e32 v83, v219, v195
	v_mul_f32_e32 v200, 0xbfb8aa3b, v72
	v_mul_f32_e32 v252, 0xbfb8aa3b, v73
	v_mul_f32_e32 v253, 0xbfb8aa3b, v74
	v_mul_f32_e32 v219, 0xbfb8aa3b, v75
	v_exp_f32_e32 v200, v200
	v_exp_f32_e32 v252, v252
	v_exp_f32_e32 v253, v253
	v_exp_f32_e32 v219, v219
	v_add_f32_e32 v200, 1.0, v200
	v_add_f32_e32 v252, 1.0, v252
	v_add_f32_e32 v253, 1.0, v253
	v_add_f32_e32 v219, 1.0, v219
	v_rcp_f32_e32 v200, v200
	v_rcp_f32_e32 v252, v252
	v_rcp_f32_e32 v253, v253
	v_rcp_f32_e32 v219, v219
	v_mul_f32_e32 v200, v72, v200
	v_mul_f32_e32 v252, v73, v252
	v_mul_f32_e32 v253, v74, v253
	v_mul_f32_e32 v219, v75, v219
	v_mul_f32_e32 v200, v200, v240
	v_mul_f32_e32 v252, v252, v241
	v_mul_f32_e32 v253, v253, v242
	v_mul_f32_e32 v219, v219, v243
	v_mul_f32_e32 v72, v200, v196
	v_mul_f32_e32 v73, v252, v197
	v_mul_f32_e32 v74, v253, v198
	v_mul_f32_e32 v75, v219, v199
	global_load_dwordx4 v[160:163], v[220:221], off
	global_load_dwordx4 v[164:167], v[220:221], off offset:256
	global_load_dwordx4 v[168:171], v[222:223], off
	global_load_dwordx4 v[172:175], v[222:223], off offset:256
	v_add_co_u32_e32 v220, vcc, 0x8000, v220
	s_nop 1
	v_addc_co_u32_e32 v221, vcc, 0, v221, vcc
	v_add_co_u32_e32 v222, vcc, 0x8000, v222
	s_nop 1
	v_addc_co_u32_e32 v223, vcc, 0, v223, vcc
	s_waitcnt vmcnt(8)
;     __device__ __forceinline__ void operator()(const af4 (&acc)[2][2][4][2], const pg8::Unit& u, int wr, int wc, int fr_, int fq_) const {
;     ...
;             const int col0 = (pn - 2) * 256 + wc * 32 + 8 * fq;
;             float ssq[8];
; #pragma unroll
;             for (int b_ = 0; b_ < 4; ++b_) {
;                 const int ai = b_ >> 1, mp = b_ & 1;
;                 int RRb = row0 + ai * 128 + mp * 32; asm volatile("" : "+v"(RRb));
;                 const size_t ob = (size_t)RRb * 1024 + col0; v4u of_[2][2], ob_[2][2];
; #pragma unroll
;                 for (int mi = 0; mi < 2; ++mi)
; #pragma unroll
;                     for (int bj = 0; bj < 2; ++bj) { of_[mi][bj] = *(const v4u*)(ON + ob + mi * 16 * 1024 + bj * 128); ob_[mi][bj] = *(const v4u*)(OBp + ob + mi * 16 * 1024 + bj * 128); }
; #pragma unroll
;                 for (int mi = 0; mi < 2; ++mi) { float q = 0.f;
; #pragma unroll
;                     for (int bj = 0; bj < 2; ++bj) { const v4u a = of_[mi][bj], c = ob_[mi][bj];
;                         const float o0 = bflo(a.x) + bflo(c.x), o1 = bfhi(a.x) + bfhi(c.x), o2 = bflo(a.y) + bflo(c.y), o3 = bfhi(a.y) + bfhi(c.y), o4 = bflo(a.z) + bflo(c.z), o5 = bfhi(a.z) + bfhi(c.z), o6 = bflo(a.w) + bflo(c.w), o7 = bfhi(a.w) + bfhi(c.w);
;                         q += (o0 * o0 + o1 * o1) + (o2 * o2 + o3 * o3) + (o4 * o4 + o5 * o5) + (o6 * o6 + o7 * o7); }
;                     ssq[ai * 4 + mp * 2 + mi] = q; }
;                 asm volatile("" ::: "memory");
;             }
; #pragma unroll
;             for (int k = 0; k < 8; ++k) { float v = ssq[k];
;                 v += __int_as_float(__builtin_amdgcn_ds_bpermute((ln_ ^ 16) << 2, __float_as_int(v)));
;                 v += __int_as_float(__builtin_amdgcn_ds_bpermute((ln_ ^ 32) << 2, __float_as_int(v))); ssq[k] = v; }
;             if (fq == 0) {
; #pragma unroll
;                 for (int k = 0; k < 8; ++k) xch[((k >> 2) * 128 + wr * 64 + (k & 3) * 16 + fr) * 4 + wc] = ssq[k];
;             }
;             asm volatile("s_waitcnt lgkmcnt(0)" ::: "memory"); __builtin_amdgcn_s_barrier(); asm volatile("" ::: "memory");
;             float rs[8];
; #pragma unroll
;             for (int k = 0; k < 8; ++k) { const f32x4 p4 = *(const LAS f32x4*)(xch + ((k >> 2) * 128 + wr * 64 + (k & 3) * 16 + fr) * 4);
;                 rs[k] = 1.0f / sqrtf(((p4[0] + p4[1]) + (p4[2] + p4[3])) * (1.f / 256.f) + LN_EPS); }
	v_lshlrev_b32_e32 v192, 16, v128
	v_and_b32_e32 v193, 0xffff0000, v128
	v_lshlrev_b32_e32 v200, 16, v136
	v_and_b32_e32 v252, 0xffff0000, v136
	v_add_f32_e32 v192, v192, v200
	v_add_f32_e32 v193, v193, v252
	v_lshlrev_b32_e32 v194, 16, v129
	v_and_b32_e32 v195, 0xffff0000, v129
	v_lshlrev_b32_e32 v200, 16, v137
	v_and_b32_e32 v252, 0xffff0000, v137
	v_add_f32_e32 v194, v194, v200
	v_add_f32_e32 v195, v195, v252
	v_lshlrev_b32_e32 v196, 16, v130
	v_and_b32_e32 v197, 0xffff0000, v130
	v_lshlrev_b32_e32 v200, 16, v138
	v_and_b32_e32 v252, 0xffff0000, v138
	v_add_f32_e32 v196, v196, v200
	v_add_f32_e32 v197, v197, v252
	v_lshlrev_b32_e32 v198, 16, v131
	v_and_b32_e32 v199, 0xffff0000, v131
	v_lshlrev_b32_e32 v200, 16, v139
	v_and_b32_e32 v252, 0xffff0000, v139
	v_add_f32_e32 v198, v198, v200
	v_add_f32_e32 v199, v199, v252
	v_mul_f32_e32 v200, v192, v192
	v_mul_f32_e32 v252, v194, v194
	v_mul_f32_e32 v253, v196, v196
	v_mul_f32_e32 v219, v198, v198
	v_fmac_f32_e32 v200, v193, v193
	v_fmac_f32_e32 v252, v195, v195
	v_fmac_f32_e32 v253, v197, v197
	v_fmac_f32_e32 v219, v199, v199
	v_add_f32_e32 v200, v200, v252
	v_add_f32_e32 v253, v253, v219
	v_add_f32_e32 v200, v200, v253
	v_add_f32_e32 v247, v247, v200
	v_mul_f32_e32 v200, 0xbfb8aa3b, v84
	v_mul_f32_e32 v252, 0xbfb8aa3b, v85
	v_mul_f32_e32 v253, 0xbfb8aa3b, v86
	v_mul_f32_e32 v219, 0xbfb8aa3b, v87
	v_exp_f32_e32 v200, v200
	v_exp_f32_e32 v252, v252
	v_exp_f32_e32 v253, v253
	v_exp_f32_e32 v219, v219
	v_add_f32_e32 v200, 1.0, v200
	v_add_f32_e32 v252, 1.0, v252
	v_add_f32_e32 v253, 1.0, v253
	v_add_f32_e32 v219, 1.0, v219
	v_rcp_f32_e32 v200, v200
	v_rcp_f32_e32 v252, v252
	v_rcp_f32_e32 v253, v253
	v_rcp_f32_e32 v219, v219
	v_mul_f32_e32 v200, v84, v200
	v_mul_f32_e32 v252, v85, v252
	v_mul_f32_e32 v253, v86, v253
	v_mul_f32_e32 v219, v87, v219
	v_mul_f32_e32 v200, v200, v228
	v_mul_f32_e32 v252, v252, v229
	v_mul_f32_e32 v253, v253, v230
	v_mul_f32_e32 v219, v219, v231
	v_mul_f32_e32 v84, v200, v192
	v_mul_f32_e32 v85, v252, v193
	v_mul_f32_e32 v86, v253, v194
	v_mul_f32_e32 v87, v219, v195
	v_mul_f32_e32 v200, 0xbfb8aa3b, v76
	v_mul_f32_e32 v252, 0xbfb8aa3b, v77
	v_mul_f32_e32 v253, 0xbfb8aa3b, v78
	v_mul_f32_e32 v219, 0xbfb8aa3b, v79
	v_exp_f32_e32 v200, v200
	v_exp_f32_e32 v252, v252
	v_exp_f32_e32 v253, v253
	v_exp_f32_e32 v219, v219
	v_add_f32_e32 v200, 1.0, v200
	v_add_f32_e32 v252, 1.0, v252
	v_add_f32_e32 v253, 1.0, v253
	v_add_f32_e32 v219, 1.0, v219
	v_rcp_f32_e32 v200, v200
	v_rcp_f32_e32 v252, v252
	v_rcp_f32_e32 v253, v253
	v_rcp_f32_e32 v219, v219
	v_mul_f32_e32 v200, v76, v200
	v_mul_f32_e32 v252, v77, v252
	v_mul_f32_e32 v253, v78, v253
	v_mul_f32_e32 v219, v79, v219
	v_mul_f32_e32 v200, v200, v232
	v_mul_f32_e32 v252, v252, v233
	v_mul_f32_e32 v253, v253, v234
	v_mul_f32_e32 v219, v219, v235
	v_mul_f32_e32 v76, v200, v196
	v_mul_f32_e32 v77, v252, v197
	v_mul_f32_e32 v78, v253, v198
	v_mul_f32_e32 v79, v219, v199
	v_lshlrev_b32_e32 v192, 16, v132
	v_and_b32_e32 v193, 0xffff0000, v132
	v_lshlrev_b32_e32 v200, 16, v140
	v_and_b32_e32 v252, 0xffff0000, v140
	v_add_f32_e32 v192, v192, v200
	v_add_f32_e32 v193, v193, v252
	v_lshlrev_b32_e32 v194, 16, v133
	v_and_b32_e32 v195, 0xffff0000, v133
	v_lshlrev_b32_e32 v200, 16, v141
	v_and_b32_e32 v252, 0xffff0000, v141
	v_add_f32_e32 v194, v194, v200
	v_add_f32_e32 v195, v195, v252
	v_lshlrev_b32_e32 v196, 16, v134
	v_and_b32_e32 v197, 0xffff0000, v134
	v_lshlrev_b32_e32 v200, 16, v142
	v_and_b32_e32 v252, 0xffff0000, v142
	v_add_f32_e32 v196, v196, v200
	v_add_f32_e32 v197, v197, v252
	v_lshlrev_b32_e32 v198, 16, v135
	v_and_b32_e32 v199, 0xffff0000, v135
	v_lshlrev_b32_e32 v200, 16, v143
	v_and_b32_e32 v252, 0xffff0000, v143
	v_add_f32_e32 v198, v198, v200
	v_add_f32_e32 v199, v199, v252
	v_mul_f32_e32 v200, v192, v192
	v_mul_f32_e32 v252, v194, v194
	v_mul_f32_e32 v253, v196, v196
	v_mul_f32_e32 v219, v198, v198
	v_fmac_f32_e32 v200, v193, v193
	v_fmac_f32_e32 v252, v195, v195
	v_fmac_f32_e32 v253, v197, v197
	v_fmac_f32_e32 v219, v199, v199
	v_add_f32_e32 v200, v200, v252
	v_add_f32_e32 v253, v253, v219
	v_add_f32_e32 v200, v200, v253
	v_add_f32_e32 v247, v247, v200
	v_mul_f32_e32 v200, 0xbfb8aa3b, v68
	v_mul_f32_e32 v252, 0xbfb8aa3b, v69
	v_mul_f32_e32 v253, 0xbfb8aa3b, v70
	v_mul_f32_e32 v219, 0xbfb8aa3b, v71
	v_exp_f32_e32 v200, v200
	v_exp_f32_e32 v252, v252
	v_exp_f32_e32 v253, v253
	v_exp_f32_e32 v219, v219
	v_add_f32_e32 v200, 1.0, v200
	v_add_f32_e32 v252, 1.0, v252
	v_add_f32_e32 v253, 1.0, v253
	v_add_f32_e32 v219, 1.0, v219
	v_rcp_f32_e32 v200, v200
	v_rcp_f32_e32 v252, v252
	v_rcp_f32_e32 v253, v253
	v_rcp_f32_e32 v219, v219
	v_mul_f32_e32 v200, v68, v200
	v_mul_f32_e32 v252, v69, v252
	v_mul_f32_e32 v253, v70, v253
	v_mul_f32_e32 v219, v71, v219
	v_mul_f32_e32 v200, v200, v236
	v_mul_f32_e32 v252, v252, v237
	v_mul_f32_e32 v253, v253, v238
	v_mul_f32_e32 v219, v219, v239
	v_mul_f32_e32 v68, v200, v192
	v_mul_f32_e32 v69, v252, v193
	v_mul_f32_e32 v70, v253, v194
	v_mul_f32_e32 v71, v219, v195
	v_mul_f32_e32 v200, 0xbfb8aa3b, v64
	v_mul_f32_e32 v252, 0xbfb8aa3b, v65
	v_mul_f32_e32 v253, 0xbfb8aa3b, v66
	v_mul_f32_e32 v219, 0xbfb8aa3b, v67
	v_exp_f32_e32 v200, v200
	v_exp_f32_e32 v252, v252
	v_exp_f32_e32 v253, v253
	v_exp_f32_e32 v219, v219
	v_add_f32_e32 v200, 1.0, v200
	v_add_f32_e32 v252, 1.0, v252
	v_add_f32_e32 v253, 1.0, v253
	v_add_f32_e32 v219, 1.0, v219
	v_rcp_f32_e32 v200, v200
	v_rcp_f32_e32 v252, v252
	v_rcp_f32_e32 v253, v253
	v_rcp_f32_e32 v219, v219
	v_mul_f32_e32 v200, v64, v200
	v_mul_f32_e32 v252, v65, v252
	v_mul_f32_e32 v253, v66, v253
	v_mul_f32_e32 v219, v67, v219
	v_mul_f32_e32 v200, v200, v240
	v_mul_f32_e32 v252, v252, v241
	v_mul_f32_e32 v253, v253, v242
	v_mul_f32_e32 v219, v219, v243
	v_mul_f32_e32 v64, v200, v196
	v_mul_f32_e32 v65, v252, v197
	v_mul_f32_e32 v66, v253, v198
	v_mul_f32_e32 v67, v219, v199
	global_load_dwordx4 v[128:131], v[220:221], off
	global_load_dwordx4 v[132:135], v[220:221], off offset:256
	global_load_dwordx4 v[136:139], v[222:223], off
	global_load_dwordx4 v[140:143], v[222:223], off offset:256
	v_add_co_u32_e32 v220, vcc, 0x8000, v220
	s_nop 1
	v_addc_co_u32_e32 v221, vcc, 0, v221, vcc
	v_add_co_u32_e32 v222, vcc, 0x8000, v222
	s_nop 1
	v_addc_co_u32_e32 v223, vcc, 0, v223, vcc
	s_waitcnt vmcnt(8)
;     __device__ __forceinline__ void operator()(const af4 (&acc)[2][2][4][2], const pg8::Unit& u, int wr, int wc, int fr_, int fq_) const {
;     ...
;             const int col0 = (pn - 2) * 256 + wc * 32 + 8 * fq;
;             float ssq[8];
; #pragma unroll
;             for (int b_ = 0; b_ < 4; ++b_) {
;                 const int ai = b_ >> 1, mp = b_ & 1;
;                 int RRb = row0 + ai * 128 + mp * 32; asm volatile("" : "+v"(RRb));
;                 const size_t ob = (size_t)RRb * 1024 + col0; v4u of_[2][2], ob_[2][2];
; #pragma unroll
;                 for (int mi = 0; mi < 2; ++mi)
; #pragma unroll
;                     for (int bj = 0; bj < 2; ++bj) { of_[mi][bj] = *(const v4u*)(ON + ob + mi * 16 * 1024 + bj * 128); ob_[mi][bj] = *(const v4u*)(OBp + ob + mi * 16 * 1024 + bj * 128); }
; #pragma unroll
;                 for (int mi = 0; mi < 2; ++mi) { float q = 0.f;
; #pragma unroll
;                     for (int bj = 0; bj < 2; ++bj) { const v4u a = of_[mi][bj], c = ob_[mi][bj];
;                         const float o0 = bflo(a.x) + bflo(c.x), o1 = bfhi(a.x) + bfhi(c.x), o2 = bflo(a.y) + bflo(c.y), o3 = bfhi(a.y) + bfhi(c.y), o4 = bflo(a.z) + bflo(c.z), o5 = bfhi(a.z) + bfhi(c.z), o6 = bflo(a.w) + bflo(c.w), o7 = bfhi(a.w) + bfhi(c.w);
;                         q += (o0 * o0 + o1 * o1) + (o2 * o2 + o3 * o3) + (o4 * o4 + o5 * o5) + (o6 * o6 + o7 * o7); }
;                     ssq[ai * 4 + mp * 2 + mi] = q; }
;                 asm volatile("" ::: "memory");
;             }
; #pragma unroll
;             for (int k = 0; k < 8; ++k) { float v = ssq[k];
;                 v += __int_as_float(__builtin_amdgcn_ds_bpermute((ln_ ^ 16) << 2, __float_as_int(v)));
;                 v += __int_as_float(__builtin_amdgcn_ds_bpermute((ln_ ^ 32) << 2, __float_as_int(v))); ssq[k] = v; }
;             if (fq == 0) {
; #pragma unroll
;                 for (int k = 0; k < 8; ++k) xch[((k >> 2) * 128 + wr * 64 + (k & 3) * 16 + fr) * 4 + wc] = ssq[k];
;             }
;             asm volatile("s_waitcnt lgkmcnt(0)" ::: "memory"); __builtin_amdgcn_s_barrier(); asm volatile("" ::: "memory");
;             float rs[8];
; #pragma unroll
;             for (int k = 0; k < 8; ++k) { const f32x4 p4 = *(const LAS f32x4*)(xch + ((k >> 2) * 128 + wr * 64 + (k & 3) * 16 + fr) * 4);
;                 rs[k] = 1.0f / sqrtf(((p4[0] + p4[1]) + (p4[2] + p4[3])) * (1.f / 256.f) + LN_EPS); }
	v_lshlrev_b32_e32 v192, 16, v144
	v_and_b32_e32 v193, 0xffff0000, v144
	v_lshlrev_b32_e32 v200, 16, v152
	v_and_b32_e32 v252, 0xffff0000, v152
	v_add_f32_e32 v192, v192, v200
	v_add_f32_e32 v193, v193, v252
	v_lshlrev_b32_e32 v194, 16, v145
	v_and_b32_e32 v195, 0xffff0000, v145
	v_lshlrev_b32_e32 v200, 16, v153
	v_and_b32_e32 v252, 0xffff0000, v153
	v_add_f32_e32 v194, v194, v200
	v_add_f32_e32 v195, v195, v252
	v_lshlrev_b32_e32 v196, 16, v146
	v_and_b32_e32 v197, 0xffff0000, v146
	v_lshlrev_b32_e32 v200, 16, v154
	v_and_b32_e32 v252, 0xffff0000, v154
	v_add_f32_e32 v196, v196, v200
	v_add_f32_e32 v197, v197, v252
	v_lshlrev_b32_e32 v198, 16, v147
	v_and_b32_e32 v199, 0xffff0000, v147
	v_lshlrev_b32_e32 v200, 16, v155
	v_and_b32_e32 v252, 0xffff0000, v155
	v_add_f32_e32 v198, v198, v200
	v_add_f32_e32 v199, v199, v252
	v_mul_f32_e32 v200, v192, v192
	v_mul_f32_e32 v252, v194, v194
	v_mul_f32_e32 v253, v196, v196
	v_mul_f32_e32 v219, v198, v198
	v_fmac_f32_e32 v200, v193, v193
	v_fmac_f32_e32 v252, v195, v195
	v_fmac_f32_e32 v253, v197, v197
	v_fmac_f32_e32 v219, v199, v199
	v_add_f32_e32 v200, v200, v252
	v_add_f32_e32 v253, v253, v219
	v_add_f32_e32 v200, v200, v253
	v_add_f32_e32 v248, v248, v200
	v_mul_f32_e32 v200, 0xbfb8aa3b, v60
	v_mul_f32_e32 v252, 0xbfb8aa3b, v61
	v_mul_f32_e32 v253, 0xbfb8aa3b, v62
	v_mul_f32_e32 v219, 0xbfb8aa3b, v63
	v_exp_f32_e32 v200, v200
	v_exp_f32_e32 v252, v252
	v_exp_f32_e32 v253, v253
	v_exp_f32_e32 v219, v219
	v_add_f32_e32 v200, 1.0, v200
	v_add_f32_e32 v252, 1.0, v252
	v_add_f32_e32 v253, 1.0, v253
	v_add_f32_e32 v219, 1.0, v219
	v_rcp_f32_e32 v200, v200
	v_rcp_f32_e32 v252, v252
	v_rcp_f32_e32 v253, v253
	v_rcp_f32_e32 v219, v219
	v_mul_f32_e32 v200, v60, v200
	v_mul_f32_e32 v252, v61, v252
	v_mul_f32_e32 v253, v62, v253
	v_mul_f32_e32 v219, v63, v219
	v_mul_f32_e32 v200, v200, v228
	v_mul_f32_e32 v252, v252, v229
	v_mul_f32_e32 v253, v253, v230
	v_mul_f32_e32 v219, v219, v231
	v_mul_f32_e32 v60, v200, v192
	v_mul_f32_e32 v61, v252, v193
	v_mul_f32_e32 v62, v253, v194
	v_mul_f32_e32 v63, v219, v195
	v_mul_f32_e32 v200, 0xbfb8aa3b, v56
	v_mul_f32_e32 v252, 0xbfb8aa3b, v57
	v_mul_f32_e32 v253, 0xbfb8aa3b, v58
	v_mul_f32_e32 v219, 0xbfb8aa3b, v59
	v_exp_f32_e32 v200, v200
	v_exp_f32_e32 v252, v252
	v_exp_f32_e32 v253, v253
	v_exp_f32_e32 v219, v219
	v_add_f32_e32 v200, 1.0, v200
	v_add_f32_e32 v252, 1.0, v252
	v_add_f32_e32 v253, 1.0, v253
	v_add_f32_e32 v219, 1.0, v219
	v_rcp_f32_e32 v200, v200
	v_rcp_f32_e32 v252, v252
	v_rcp_f32_e32 v253, v253
	v_rcp_f32_e32 v219, v219
	v_mul_f32_e32 v200, v56, v200
	v_mul_f32_e32 v252, v57, v252
	v_mul_f32_e32 v253, v58, v253
	v_mul_f32_e32 v219, v59, v219
	v_mul_f32_e32 v200, v200, v232
	v_mul_f32_e32 v252, v252, v233
	v_mul_f32_e32 v253, v253, v234
	v_mul_f32_e32 v219, v219, v235
	v_mul_f32_e32 v56, v200, v196
	v_mul_f32_e32 v57, v252, v197
	v_mul_f32_e32 v58, v253, v198
	v_mul_f32_e32 v59, v219, v199
	v_lshlrev_b32_e32 v192, 16, v148
	v_and_b32_e32 v193, 0xffff0000, v148
	v_lshlrev_b32_e32 v200, 16, v156
	v_and_b32_e32 v252, 0xffff0000, v156
	v_add_f32_e32 v192, v192, v200
	v_add_f32_e32 v193, v193, v252
	v_lshlrev_b32_e32 v194, 16, v149
	v_and_b32_e32 v195, 0xffff0000, v149
	v_lshlrev_b32_e32 v200, 16, v157
	v_and_b32_e32 v252, 0xffff0000, v157
	v_add_f32_e32 v194, v194, v200
	v_add_f32_e32 v195, v195, v252
	v_lshlrev_b32_e32 v196, 16, v150
	v_and_b32_e32 v197, 0xffff0000, v150
	v_lshlrev_b32_e32 v200, 16, v158
	v_and_b32_e32 v252, 0xffff0000, v158
	v_add_f32_e32 v196, v196, v200
	v_add_f32_e32 v197, v197, v252
	v_lshlrev_b32_e32 v198, 16, v151
	v_and_b32_e32 v199, 0xffff0000, v151
	v_lshlrev_b32_e32 v200, 16, v159
	v_and_b32_e32 v252, 0xffff0000, v159
	v_add_f32_e32 v198, v198, v200
	v_add_f32_e32 v199, v199, v252
	v_mul_f32_e32 v200, v192, v192
	v_mul_f32_e32 v252, v194, v194
	v_mul_f32_e32 v253, v196, v196
	v_mul_f32_e32 v219, v198, v198
	v_fmac_f32_e32 v200, v193, v193
	v_fmac_f32_e32 v252, v195, v195
	v_fmac_f32_e32 v253, v197, v197
	v_fmac_f32_e32 v219, v199, v199
	v_add_f32_e32 v200, v200, v252
	v_add_f32_e32 v253, v253, v219
	v_add_f32_e32 v200, v200, v253
	v_add_f32_e32 v248, v248, v200
	v_mul_f32_e32 v200, 0xbfb8aa3b, v48
	v_mul_f32_e32 v252, 0xbfb8aa3b, v49
	v_mul_f32_e32 v253, 0xbfb8aa3b, v50
	v_mul_f32_e32 v219, 0xbfb8aa3b, v51
	v_exp_f32_e32 v200, v200
	v_exp_f32_e32 v252, v252
	v_exp_f32_e32 v253, v253
	v_exp_f32_e32 v219, v219
	v_add_f32_e32 v200, 1.0, v200
	v_add_f32_e32 v252, 1.0, v252
	v_add_f32_e32 v253, 1.0, v253
	v_add_f32_e32 v219, 1.0, v219
	v_rcp_f32_e32 v200, v200
	v_rcp_f32_e32 v252, v252
	v_rcp_f32_e32 v253, v253
	v_rcp_f32_e32 v219, v219
	v_mul_f32_e32 v200, v48, v200
	v_mul_f32_e32 v252, v49, v252
	v_mul_f32_e32 v253, v50, v253
	v_mul_f32_e32 v219, v51, v219
	v_mul_f32_e32 v200, v200, v236
	v_mul_f32_e32 v252, v252, v237
	v_mul_f32_e32 v253, v253, v238
	v_mul_f32_e32 v219, v219, v239
	v_mul_f32_e32 v48, v200, v192
	v_mul_f32_e32 v49, v252, v193
	v_mul_f32_e32 v50, v253, v194
	v_mul_f32_e32 v51, v219, v195
	v_mul_f32_e32 v200, 0xbfb8aa3b, v40
	v_mul_f32_e32 v252, 0xbfb8aa3b, v41
	v_mul_f32_e32 v253, 0xbfb8aa3b, v42
	v_mul_f32_e32 v219, 0xbfb8aa3b, v43
	v_exp_f32_e32 v200, v200
	v_exp_f32_e32 v252, v252
	v_exp_f32_e32 v253, v253
	v_exp_f32_e32 v219, v219
	v_add_f32_e32 v200, 1.0, v200
	v_add_f32_e32 v252, 1.0, v252
	v_add_f32_e32 v253, 1.0, v253
	v_add_f32_e32 v219, 1.0, v219
	v_rcp_f32_e32 v200, v200
	v_rcp_f32_e32 v252, v252
	v_rcp_f32_e32 v253, v253
	v_rcp_f32_e32 v219, v219
	v_mul_f32_e32 v200, v40, v200
	v_mul_f32_e32 v252, v41, v252
	v_mul_f32_e32 v253, v42, v253
	v_mul_f32_e32 v219, v43, v219
	v_mul_f32_e32 v200, v200, v240
	v_mul_f32_e32 v252, v252, v241
	v_mul_f32_e32 v253, v253, v242
	v_mul_f32_e32 v219, v219, v243
	v_mul_f32_e32 v40, v200, v196
	v_mul_f32_e32 v41, v252, v197
	v_mul_f32_e32 v42, v253, v198
	v_mul_f32_e32 v43, v219, v199
	global_load_dwordx4 v[144:147], v[220:221], off
	global_load_dwordx4 v[148:151], v[220:221], off offset:256
	global_load_dwordx4 v[152:155], v[222:223], off
	global_load_dwordx4 v[156:159], v[222:223], off offset:256
	s_waitcnt vmcnt(8)
;     __device__ __forceinline__ void operator()(const af4 (&acc)[2][2][4][2], const pg8::Unit& u, int wr, int wc, int fr_, int fq_) const {
;     ...
;             const int col0 = (pn - 2) * 256 + wc * 32 + 8 * fq;
;             float ssq[8];
; #pragma unroll
;             for (int b_ = 0; b_ < 4; ++b_) {
;                 const int ai = b_ >> 1, mp = b_ & 1;
;                 int RRb = row0 + ai * 128 + mp * 32; asm volatile("" : "+v"(RRb));
;                 const size_t ob = (size_t)RRb * 1024 + col0; v4u of_[2][2], ob_[2][2];
; #pragma unroll
;                 for (int mi = 0; mi < 2; ++mi)
; #pragma unroll
;                     for (int bj = 0; bj < 2; ++bj) { of_[mi][bj] = *(const v4u*)(ON + ob + mi * 16 * 1024 + bj * 128); ob_[mi][bj] = *(const v4u*)(OBp + ob + mi * 16 * 1024 + bj * 128); }
; #pragma unroll
;                 for (int mi = 0; mi < 2; ++mi) { float q = 0.f;
; #pragma unroll
;                     for (int bj = 0; bj < 2; ++bj) { const v4u a = of_[mi][bj], c = ob_[mi][bj];
;                         const float o0 = bflo(a.x) + bflo(c.x), o1 = bfhi(a.x) + bfhi(c.x), o2 = bflo(a.y) + bflo(c.y), o3 = bfhi(a.y) + bfhi(c.y), o4 = bflo(a.z) + bflo(c.z), o5 = bfhi(a.z) + bfhi(c.z), o6 = bflo(a.w) + bflo(c.w), o7 = bfhi(a.w) + bfhi(c.w);
;                         q += (o0 * o0 + o1 * o1) + (o2 * o2 + o3 * o3) + (o4 * o4 + o5 * o5) + (o6 * o6 + o7 * o7); }
;                     ssq[ai * 4 + mp * 2 + mi] = q; }
;                 asm volatile("" ::: "memory");
;             }
; #pragma unroll
;             for (int k = 0; k < 8; ++k) { float v = ssq[k];
;                 v += __int_as_float(__builtin_amdgcn_ds_bpermute((ln_ ^ 16) << 2, __float_as_int(v)));
;                 v += __int_as_float(__builtin_amdgcn_ds_bpermute((ln_ ^ 32) << 2, __float_as_int(v))); ssq[k] = v; }
;             if (fq == 0) {
; #pragma unroll
;                 for (int k = 0; k < 8; ++k) xch[((k >> 2) * 128 + wr * 64 + (k & 3) * 16 + fr) * 4 + wc] = ssq[k];
;             }
;             asm volatile("s_waitcnt lgkmcnt(0)" ::: "memory"); __builtin_amdgcn_s_barrier(); asm volatile("" ::: "memory");
;             float rs[8];
; #pragma unroll
;             for (int k = 0; k < 8; ++k) { const f32x4 p4 = *(const LAS f32x4*)(xch + ((k >> 2) * 128 + wr * 64 + (k & 3) * 16 + fr) * 4);
;                 rs[k] = 1.0f / sqrtf(((p4[0] + p4[1]) + (p4[2] + p4[3])) * (1.f / 256.f) + LN_EPS); }
	v_lshlrev_b32_e32 v192, 16, v160
	v_and_b32_e32 v193, 0xffff0000, v160
	v_lshlrev_b32_e32 v200, 16, v168
	v_and_b32_e32 v252, 0xffff0000, v168
	v_add_f32_e32 v192, v192, v200
	v_add_f32_e32 v193, v193, v252
	v_lshlrev_b32_e32 v194, 16, v161
	v_and_b32_e32 v195, 0xffff0000, v161
	v_lshlrev_b32_e32 v200, 16, v169
	v_and_b32_e32 v252, 0xffff0000, v169
	v_add_f32_e32 v194, v194, v200
	v_add_f32_e32 v195, v195, v252
	v_lshlrev_b32_e32 v196, 16, v162
	v_and_b32_e32 v197, 0xffff0000, v162
	v_lshlrev_b32_e32 v200, 16, v170
	v_and_b32_e32 v252, 0xffff0000, v170
	v_add_f32_e32 v196, v196, v200
	v_add_f32_e32 v197, v197, v252
	v_lshlrev_b32_e32 v198, 16, v163
	v_and_b32_e32 v199, 0xffff0000, v163
	v_lshlrev_b32_e32 v200, 16, v171
	v_and_b32_e32 v252, 0xffff0000, v171
	v_add_f32_e32 v198, v198, v200
	v_add_f32_e32 v199, v199, v252
	v_mul_f32_e32 v200, v192, v192
	v_mul_f32_e32 v252, v194, v194
	v_mul_f32_e32 v253, v196, v196
	v_mul_f32_e32 v219, v198, v198
	v_fmac_f32_e32 v200, v193, v193
	v_fmac_f32_e32 v252, v195, v195
	v_fmac_f32_e32 v253, v197, v197
	v_fmac_f32_e32 v219, v199, v199
	v_add_f32_e32 v200, v200, v252
	v_add_f32_e32 v253, v253, v219
	v_add_f32_e32 v200, v200, v253
	v_add_f32_e32 v249, v249, v200
	v_mul_f32_e32 v200, 0xbfb8aa3b, v52
	v_mul_f32_e32 v252, 0xbfb8aa3b, v53
	v_mul_f32_e32 v253, 0xbfb8aa3b, v54
	v_mul_f32_e32 v219, 0xbfb8aa3b, v55
	v_exp_f32_e32 v200, v200
	v_exp_f32_e32 v252, v252
	v_exp_f32_e32 v253, v253
	v_exp_f32_e32 v219, v219
	v_add_f32_e32 v200, 1.0, v200
	v_add_f32_e32 v252, 1.0, v252
	v_add_f32_e32 v253, 1.0, v253
	v_add_f32_e32 v219, 1.0, v219
	v_rcp_f32_e32 v200, v200
	v_rcp_f32_e32 v252, v252
	v_rcp_f32_e32 v253, v253
	v_rcp_f32_e32 v219, v219
	v_mul_f32_e32 v200, v52, v200
	v_mul_f32_e32 v252, v53, v252
	v_mul_f32_e32 v253, v54, v253
	v_mul_f32_e32 v219, v55, v219
	v_mul_f32_e32 v200, v200, v228
	v_mul_f32_e32 v252, v252, v229
	v_mul_f32_e32 v253, v253, v230
	v_mul_f32_e32 v219, v219, v231
	v_mul_f32_e32 v52, v200, v192
	v_mul_f32_e32 v53, v252, v193
	v_mul_f32_e32 v54, v253, v194
	v_mul_f32_e32 v55, v219, v195
	v_mul_f32_e32 v200, 0xbfb8aa3b, v44
	v_mul_f32_e32 v252, 0xbfb8aa3b, v45
	v_mul_f32_e32 v253, 0xbfb8aa3b, v46
	v_mul_f32_e32 v219, 0xbfb8aa3b, v47
	v_exp_f32_e32 v200, v200
	v_exp_f32_e32 v252, v252
	v_exp_f32_e32 v253, v253
	v_exp_f32_e32 v219, v219
	v_add_f32_e32 v200, 1.0, v200
	v_add_f32_e32 v252, 1.0, v252
	v_add_f32_e32 v253, 1.0, v253
	v_add_f32_e32 v219, 1.0, v219
	v_rcp_f32_e32 v200, v200
	v_rcp_f32_e32 v252, v252
	v_rcp_f32_e32 v253, v253
	v_rcp_f32_e32 v219, v219
	v_mul_f32_e32 v200, v44, v200
	v_mul_f32_e32 v252, v45, v252
	v_mul_f32_e32 v253, v46, v253
	v_mul_f32_e32 v219, v47, v219
	v_mul_f32_e32 v200, v200, v232
	v_mul_f32_e32 v252, v252, v233
	v_mul_f32_e32 v253, v253, v234
	v_mul_f32_e32 v219, v219, v235
	v_mul_f32_e32 v44, v200, v196
	v_mul_f32_e32 v45, v252, v197
	v_mul_f32_e32 v46, v253, v198
	v_mul_f32_e32 v47, v219, v199
	v_lshlrev_b32_e32 v192, 16, v164
	v_and_b32_e32 v193, 0xffff0000, v164
	v_lshlrev_b32_e32 v200, 16, v172
	v_and_b32_e32 v252, 0xffff0000, v172
	v_add_f32_e32 v192, v192, v200
	v_add_f32_e32 v193, v193, v252
	v_lshlrev_b32_e32 v194, 16, v165
	v_and_b32_e32 v195, 0xffff0000, v165
	v_lshlrev_b32_e32 v200, 16, v173
	v_and_b32_e32 v252, 0xffff0000, v173
	v_add_f32_e32 v194, v194, v200
	v_add_f32_e32 v195, v195, v252
	v_lshlrev_b32_e32 v196, 16, v166
	v_and_b32_e32 v197, 0xffff0000, v166
	v_lshlrev_b32_e32 v200, 16, v174
	v_and_b32_e32 v252, 0xffff0000, v174
	v_add_f32_e32 v196, v196, v200
	v_add_f32_e32 v197, v197, v252
	v_lshlrev_b32_e32 v198, 16, v167
	v_and_b32_e32 v199, 0xffff0000, v167
	v_lshlrev_b32_e32 v200, 16, v175
	v_and_b32_e32 v252, 0xffff0000, v175
	v_add_f32_e32 v198, v198, v200
	v_add_f32_e32 v199, v199, v252
	v_mul_f32_e32 v200, v192, v192
	v_mul_f32_e32 v252, v194, v194
	v_mul_f32_e32 v253, v196, v196
	v_mul_f32_e32 v219, v198, v198
	v_fmac_f32_e32 v200, v193, v193
	v_fmac_f32_e32 v252, v195, v195
	v_fmac_f32_e32 v253, v197, v197
	v_fmac_f32_e32 v219, v199, v199
	v_add_f32_e32 v200, v200, v252
	v_add_f32_e32 v253, v253, v219
	v_add_f32_e32 v200, v200, v253
	v_add_f32_e32 v249, v249, v200
	v_mul_f32_e32 v200, 0xbfb8aa3b, v32
	v_mul_f32_e32 v252, 0xbfb8aa3b, v33
	v_mul_f32_e32 v253, 0xbfb8aa3b, v34
	v_mul_f32_e32 v219, 0xbfb8aa3b, v35
	v_exp_f32_e32 v200, v200
	v_exp_f32_e32 v252, v252
	v_exp_f32_e32 v253, v253
	v_exp_f32_e32 v219, v219
	v_add_f32_e32 v200, 1.0, v200
	v_add_f32_e32 v252, 1.0, v252
	v_add_f32_e32 v253, 1.0, v253
	v_add_f32_e32 v219, 1.0, v219
	v_rcp_f32_e32 v200, v200
	v_rcp_f32_e32 v252, v252
	v_rcp_f32_e32 v253, v253
	v_rcp_f32_e32 v219, v219
	v_mul_f32_e32 v200, v32, v200
	v_mul_f32_e32 v252, v33, v252
	v_mul_f32_e32 v253, v34, v253
	v_mul_f32_e32 v219, v35, v219
	v_mul_f32_e32 v200, v200, v236
	v_mul_f32_e32 v252, v252, v237
	v_mul_f32_e32 v253, v253, v238
	v_mul_f32_e32 v219, v219, v239
	v_mul_f32_e32 v32, v200, v192
	v_mul_f32_e32 v33, v252, v193
	v_mul_f32_e32 v34, v253, v194
	v_mul_f32_e32 v35, v219, v195
	v_mul_f32_e32 v200, 0xbfb8aa3b, v24
	v_mul_f32_e32 v252, 0xbfb8aa3b, v25
	v_mul_f32_e32 v253, 0xbfb8aa3b, v26
	v_mul_f32_e32 v219, 0xbfb8aa3b, v27
	v_exp_f32_e32 v200, v200
	v_exp_f32_e32 v252, v252
	v_exp_f32_e32 v253, v253
	v_exp_f32_e32 v219, v219
	v_add_f32_e32 v200, 1.0, v200
	v_add_f32_e32 v252, 1.0, v252
	v_add_f32_e32 v253, 1.0, v253
	v_add_f32_e32 v219, 1.0, v219
	v_rcp_f32_e32 v200, v200
	v_rcp_f32_e32 v252, v252
	v_rcp_f32_e32 v253, v253
	v_rcp_f32_e32 v219, v219
	v_mul_f32_e32 v200, v24, v200
	v_mul_f32_e32 v252, v25, v252
	v_mul_f32_e32 v253, v26, v253
	v_mul_f32_e32 v219, v27, v219
	v_mul_f32_e32 v200, v200, v240
	v_mul_f32_e32 v252, v252, v241
	v_mul_f32_e32 v253, v253, v242
	v_mul_f32_e32 v219, v219, v243
	v_mul_f32_e32 v24, v200, v196
	v_mul_f32_e32 v25, v252, v197
	v_mul_f32_e32 v26, v253, v198
	v_mul_f32_e32 v27, v219, v199
	s_waitcnt vmcnt(4)
;     __device__ __forceinline__ void operator()(const af4 (&acc)[2][2][4][2], const pg8::Unit& u, int wr, int wc, int fr_, int fq_) const {
;     ...
;             const int col0 = (pn - 2) * 256 + wc * 32 + 8 * fq;
;             float ssq[8];
; #pragma unroll
;             for (int b_ = 0; b_ < 4; ++b_) {
;                 const int ai = b_ >> 1, mp = b_ & 1;
;                 int RRb = row0 + ai * 128 + mp * 32; asm volatile("" : "+v"(RRb));
;                 const size_t ob = (size_t)RRb * 1024 + col0; v4u of_[2][2], ob_[2][2];
; #pragma unroll
;                 for (int mi = 0; mi < 2; ++mi)
; #pragma unroll
;                     for (int bj = 0; bj < 2; ++bj) { of_[mi][bj] = *(const v4u*)(ON + ob + mi * 16 * 1024 + bj * 128); ob_[mi][bj] = *(const v4u*)(OBp + ob + mi * 16 * 1024 + bj * 128); }
; #pragma unroll
;                 for (int mi = 0; mi < 2; ++mi) { float q = 0.f;
; #pragma unroll
;                     for (int bj = 0; bj < 2; ++bj) { const v4u a = of_[mi][bj], c = ob_[mi][bj];
;                         const float o0 = bflo(a.x) + bflo(c.x), o1 = bfhi(a.x) + bfhi(c.x), o2 = bflo(a.y) + bflo(c.y), o3 = bfhi(a.y) + bfhi(c.y), o4 = bflo(a.z) + bflo(c.z), o5 = bfhi(a.z) + bfhi(c.z), o6 = bflo(a.w) + bflo(c.w), o7 = bfhi(a.w) + bfhi(c.w);
;                         q += (o0 * o0 + o1 * o1) + (o2 * o2 + o3 * o3) + (o4 * o4 + o5 * o5) + (o6 * o6 + o7 * o7); }
;                     ssq[ai * 4 + mp * 2 + mi] = q; }
;                 asm volatile("" ::: "memory");
;             }
; #pragma unroll
;             for (int k = 0; k < 8; ++k) { float v = ssq[k];
;                 v += __int_as_float(__builtin_amdgcn_ds_bpermute((ln_ ^ 16) << 2, __float_as_int(v)));
;                 v += __int_as_float(__builtin_amdgcn_ds_bpermute((ln_ ^ 32) << 2, __float_as_int(v))); ssq[k] = v; }
;             if (fq == 0) {
; #pragma unroll
;                 for (int k = 0; k < 8; ++k) xch[((k >> 2) * 128 + wr * 64 + (k & 3) * 16 + fr) * 4 + wc] = ssq[k];
;             }
;             asm volatile("s_waitcnt lgkmcnt(0)" ::: "memory"); __builtin_amdgcn_s_barrier(); asm volatile("" ::: "memory");
;             float rs[8];
; #pragma unroll
;             for (int k = 0; k < 8; ++k) { const f32x4 p4 = *(const LAS f32x4*)(xch + ((k >> 2) * 128 + wr * 64 + (k & 3) * 16 + fr) * 4);
;                 rs[k] = 1.0f / sqrtf(((p4[0] + p4[1]) + (p4[2] + p4[3])) * (1.f / 256.f) + LN_EPS); }
	v_lshlrev_b32_e32 v192, 16, v128
	v_and_b32_e32 v193, 0xffff0000, v128
	v_lshlrev_b32_e32 v200, 16, v136
	v_and_b32_e32 v252, 0xffff0000, v136
	v_add_f32_e32 v192, v192, v200
	v_add_f32_e32 v193, v193, v252
	v_lshlrev_b32_e32 v194, 16, v129
	v_and_b32_e32 v195, 0xffff0000, v129
	v_lshlrev_b32_e32 v200, 16, v137
	v_and_b32_e32 v252, 0xffff0000, v137
	v_add_f32_e32 v194, v194, v200
	v_add_f32_e32 v195, v195, v252
	v_lshlrev_b32_e32 v196, 16, v130
	v_and_b32_e32 v197, 0xffff0000, v130
	v_lshlrev_b32_e32 v200, 16, v138
	v_and_b32_e32 v252, 0xffff0000, v138
	v_add_f32_e32 v196, v196, v200
	v_add_f32_e32 v197, v197, v252
	v_lshlrev_b32_e32 v198, 16, v131
	v_and_b32_e32 v199, 0xffff0000, v131
	v_lshlrev_b32_e32 v200, 16, v139
	v_and_b32_e32 v252, 0xffff0000, v139
	v_add_f32_e32 v198, v198, v200
	v_add_f32_e32 v199, v199, v252
	v_mul_f32_e32 v200, v192, v192
	v_mul_f32_e32 v252, v194, v194
	v_mul_f32_e32 v253, v196, v196
	v_mul_f32_e32 v219, v198, v198
	v_fmac_f32_e32 v200, v193, v193
	v_fmac_f32_e32 v252, v195, v195
	v_fmac_f32_e32 v253, v197, v197
	v_fmac_f32_e32 v219, v199, v199
	v_add_f32_e32 v200, v200, v252
	v_add_f32_e32 v253, v253, v219
	v_add_f32_e32 v200, v200, v253
	v_add_f32_e32 v250, v250, v200
	v_mul_f32_e32 v200, 0xbfb8aa3b, v36
	v_mul_f32_e32 v252, 0xbfb8aa3b, v37
	v_mul_f32_e32 v253, 0xbfb8aa3b, v38
	v_mul_f32_e32 v219, 0xbfb8aa3b, v39
	v_exp_f32_e32 v200, v200
	v_exp_f32_e32 v252, v252
	v_exp_f32_e32 v253, v253
	v_exp_f32_e32 v219, v219
	v_add_f32_e32 v200, 1.0, v200
	v_add_f32_e32 v252, 1.0, v252
	v_add_f32_e32 v253, 1.0, v253
	v_add_f32_e32 v219, 1.0, v219
	v_rcp_f32_e32 v200, v200
	v_rcp_f32_e32 v252, v252
	v_rcp_f32_e32 v253, v253
	v_rcp_f32_e32 v219, v219
	v_mul_f32_e32 v200, v36, v200
	v_mul_f32_e32 v252, v37, v252
	v_mul_f32_e32 v253, v38, v253
	v_mul_f32_e32 v219, v39, v219
	v_mul_f32_e32 v200, v200, v228
	v_mul_f32_e32 v252, v252, v229
	v_mul_f32_e32 v253, v253, v230
	v_mul_f32_e32 v219, v219, v231
	v_mul_f32_e32 v36, v200, v192
	v_mul_f32_e32 v37, v252, v193
	v_mul_f32_e32 v38, v253, v194
	v_mul_f32_e32 v39, v219, v195
	v_mul_f32_e32 v200, 0xbfb8aa3b, v28
	v_mul_f32_e32 v252, 0xbfb8aa3b, v29
	v_mul_f32_e32 v253, 0xbfb8aa3b, v30
	v_mul_f32_e32 v219, 0xbfb8aa3b, v31
	v_exp_f32_e32 v200, v200
	v_exp_f32_e32 v252, v252
	v_exp_f32_e32 v253, v253
	v_exp_f32_e32 v219, v219
	v_add_f32_e32 v200, 1.0, v200
	v_add_f32_e32 v252, 1.0, v252
	v_add_f32_e32 v253, 1.0, v253
	v_add_f32_e32 v219, 1.0, v219
	v_rcp_f32_e32 v200, v200
	v_rcp_f32_e32 v252, v252
	v_rcp_f32_e32 v253, v253
	v_rcp_f32_e32 v219, v219
	v_mul_f32_e32 v200, v28, v200
	v_mul_f32_e32 v252, v29, v252
	v_mul_f32_e32 v253, v30, v253
	v_mul_f32_e32 v219, v31, v219
	v_mul_f32_e32 v200, v200, v232
	v_mul_f32_e32 v252, v252, v233
	v_mul_f32_e32 v253, v253, v234
	v_mul_f32_e32 v219, v219, v235
	v_mul_f32_e32 v28, v200, v196
	v_mul_f32_e32 v29, v252, v197
	v_mul_f32_e32 v30, v253, v198
	v_mul_f32_e32 v31, v219, v199
	v_lshlrev_b32_e32 v192, 16, v132
	v_and_b32_e32 v193, 0xffff0000, v132
	v_lshlrev_b32_e32 v200, 16, v140
	v_and_b32_e32 v252, 0xffff0000, v140
	v_add_f32_e32 v192, v192, v200
	v_add_f32_e32 v193, v193, v252
	v_lshlrev_b32_e32 v194, 16, v133
	v_and_b32_e32 v195, 0xffff0000, v133
	v_lshlrev_b32_e32 v200, 16, v141
	v_and_b32_e32 v252, 0xffff0000, v141
	v_add_f32_e32 v194, v194, v200
	v_add_f32_e32 v195, v195, v252
	v_lshlrev_b32_e32 v196, 16, v134
	v_and_b32_e32 v197, 0xffff0000, v134
	v_lshlrev_b32_e32 v200, 16, v142
	v_and_b32_e32 v252, 0xffff0000, v142
	v_add_f32_e32 v196, v196, v200
	v_add_f32_e32 v197, v197, v252
	v_lshlrev_b32_e32 v198, 16, v135
	v_and_b32_e32 v199, 0xffff0000, v135
	v_lshlrev_b32_e32 v200, 16, v143
	v_and_b32_e32 v252, 0xffff0000, v143
	v_add_f32_e32 v198, v198, v200
	v_add_f32_e32 v199, v199, v252
	v_mul_f32_e32 v200, v192, v192
	v_mul_f32_e32 v252, v194, v194
	v_mul_f32_e32 v253, v196, v196
	v_mul_f32_e32 v219, v198, v198
	v_fmac_f32_e32 v200, v193, v193
	v_fmac_f32_e32 v252, v195, v195
	v_fmac_f32_e32 v253, v197, v197
	v_fmac_f32_e32 v219, v199, v199
	v_add_f32_e32 v200, v200, v252
	v_add_f32_e32 v253, v253, v219
	v_add_f32_e32 v200, v200, v253
	v_add_f32_e32 v250, v250, v200
	v_mul_f32_e32 v200, 0xbfb8aa3b, v16
	v_mul_f32_e32 v252, 0xbfb8aa3b, v17
	v_mul_f32_e32 v253, 0xbfb8aa3b, v18
	v_mul_f32_e32 v219, 0xbfb8aa3b, v19
	v_exp_f32_e32 v200, v200
	v_exp_f32_e32 v252, v252
	v_exp_f32_e32 v253, v253
	v_exp_f32_e32 v219, v219
	v_add_f32_e32 v200, 1.0, v200
	v_add_f32_e32 v252, 1.0, v252
	v_add_f32_e32 v253, 1.0, v253
	v_add_f32_e32 v219, 1.0, v219
	v_rcp_f32_e32 v200, v200
	v_rcp_f32_e32 v252, v252
	v_rcp_f32_e32 v253, v253
	v_rcp_f32_e32 v219, v219
	v_mul_f32_e32 v200, v16, v200
	v_mul_f32_e32 v252, v17, v252
	v_mul_f32_e32 v253, v18, v253
	v_mul_f32_e32 v219, v19, v219
	v_mul_f32_e32 v200, v200, v236
	v_mul_f32_e32 v252, v252, v237
	v_mul_f32_e32 v253, v253, v238
	v_mul_f32_e32 v219, v219, v239
	v_mul_f32_e32 v16, v200, v192
	v_mul_f32_e32 v17, v252, v193
	v_mul_f32_e32 v18, v253, v194
	v_mul_f32_e32 v19, v219, v195
	v_mul_f32_e32 v200, 0xbfb8aa3b, v8
	v_mul_f32_e32 v252, 0xbfb8aa3b, v9
	v_mul_f32_e32 v253, 0xbfb8aa3b, v10
	v_mul_f32_e32 v219, 0xbfb8aa3b, v11
	v_exp_f32_e32 v200, v200
	v_exp_f32_e32 v252, v252
	v_exp_f32_e32 v253, v253
	v_exp_f32_e32 v219, v219
	v_add_f32_e32 v200, 1.0, v200
	v_add_f32_e32 v252, 1.0, v252
	v_add_f32_e32 v253, 1.0, v253
	v_add_f32_e32 v219, 1.0, v219
	v_rcp_f32_e32 v200, v200
	v_rcp_f32_e32 v252, v252
	v_rcp_f32_e32 v253, v253
	v_rcp_f32_e32 v219, v219
	v_mul_f32_e32 v200, v8, v200
	v_mul_f32_e32 v252, v9, v252
	v_mul_f32_e32 v253, v10, v253
	v_mul_f32_e32 v219, v11, v219
	v_mul_f32_e32 v200, v200, v240
	v_mul_f32_e32 v252, v252, v241
	v_mul_f32_e32 v253, v253, v242
	v_mul_f32_e32 v219, v219, v243
	v_mul_f32_e32 v8, v200, v196
	v_mul_f32_e32 v9, v252, v197
	v_mul_f32_e32 v10, v253, v198
	v_mul_f32_e32 v11, v219, v199
	s_waitcnt vmcnt(0)
;     __device__ __forceinline__ void operator()(const af4 (&acc)[2][2][4][2], const pg8::Unit& u, int wr, int wc, int fr_, int fq_) const {
;     ...
;             const int col0 = (pn - 2) * 256 + wc * 32 + 8 * fq;
;             float ssq[8];
; #pragma unroll
;             for (int b_ = 0; b_ < 4; ++b_) {
;                 const int ai = b_ >> 1, mp = b_ & 1;
;                 int RRb = row0 + ai * 128 + mp * 32; asm volatile("" : "+v"(RRb));
;                 const size_t ob = (size_t)RRb * 1024 + col0; v4u of_[2][2], ob_[2][2];
; #pragma unroll
;                 for (int mi = 0; mi < 2; ++mi)
; #pragma unroll
;                     for (int bj = 0; bj < 2; ++bj) { of_[mi][bj] = *(const v4u*)(ON + ob + mi * 16 * 1024 + bj * 128); ob_[mi][bj] = *(const v4u*)(OBp + ob + mi * 16 * 1024 + bj * 128); }
; #pragma unroll
;                 for (int mi = 0; mi < 2; ++mi) { float q = 0.f;
; #pragma unroll
;                     for (int bj = 0; bj < 2; ++bj) { const v4u a = of_[mi][bj], c = ob_[mi][bj];
;                         const float o0 = bflo(a.x) + bflo(c.x), o1 = bfhi(a.x) + bfhi(c.x), o2 = bflo(a.y) + bflo(c.y), o3 = bfhi(a.y) + bfhi(c.y), o4 = bflo(a.z) + bflo(c.z), o5 = bfhi(a.z) + bfhi(c.z), o6 = bflo(a.w) + bflo(c.w), o7 = bfhi(a.w) + bfhi(c.w);
;                         q += (o0 * o0 + o1 * o1) + (o2 * o2 + o3 * o3) + (o4 * o4 + o5 * o5) + (o6 * o6 + o7 * o7); }
;                     ssq[ai * 4 + mp * 2 + mi] = q; }
;                 asm volatile("" ::: "memory");
;             }
; #pragma unroll
;             for (int k = 0; k < 8; ++k) { float v = ssq[k];
;                 v += __int_as_float(__builtin_amdgcn_ds_bpermute((ln_ ^ 16) << 2, __float_as_int(v)));
;                 v += __int_as_float(__builtin_amdgcn_ds_bpermute((ln_ ^ 32) << 2, __float_as_int(v))); ssq[k] = v; }
;             if (fq == 0) {
; #pragma unroll
;                 for (int k = 0; k < 8; ++k) xch[((k >> 2) * 128 + wr * 64 + (k & 3) * 16 + fr) * 4 + wc] = ssq[k];
;             }
;             asm volatile("s_waitcnt lgkmcnt(0)" ::: "memory"); __builtin_amdgcn_s_barrier(); asm volatile("" ::: "memory");
;             float rs[8];
; #pragma unroll
;             for (int k = 0; k < 8; ++k) { const f32x4 p4 = *(const LAS f32x4*)(xch + ((k >> 2) * 128 + wr * 64 + (k & 3) * 16 + fr) * 4);
;                 rs[k] = 1.0f / sqrtf(((p4[0] + p4[1]) + (p4[2] + p4[3])) * (1.f / 256.f) + LN_EPS); }
	v_lshlrev_b32_e32 v192, 16, v144
	v_and_b32_e32 v193, 0xffff0000, v144
	v_lshlrev_b32_e32 v200, 16, v152
	v_and_b32_e32 v252, 0xffff0000, v152
	v_add_f32_e32 v192, v192, v200
	v_add_f32_e32 v193, v193, v252
	v_lshlrev_b32_e32 v194, 16, v145
	v_and_b32_e32 v195, 0xffff0000, v145
	v_lshlrev_b32_e32 v200, 16, v153
	v_and_b32_e32 v252, 0xffff0000, v153
	v_add_f32_e32 v194, v194, v200
	v_add_f32_e32 v195, v195, v252
	v_lshlrev_b32_e32 v196, 16, v146
	v_and_b32_e32 v197, 0xffff0000, v146
	v_lshlrev_b32_e32 v200, 16, v154
	v_and_b32_e32 v252, 0xffff0000, v154
	v_add_f32_e32 v196, v196, v200
	v_add_f32_e32 v197, v197, v252
	v_lshlrev_b32_e32 v198, 16, v147
	v_and_b32_e32 v199, 0xffff0000, v147
	v_lshlrev_b32_e32 v200, 16, v155
	v_and_b32_e32 v252, 0xffff0000, v155
	v_add_f32_e32 v198, v198, v200
	v_add_f32_e32 v199, v199, v252
	v_mul_f32_e32 v200, v192, v192
	v_mul_f32_e32 v252, v194, v194
	v_mul_f32_e32 v253, v196, v196
	v_mul_f32_e32 v219, v198, v198
	v_fmac_f32_e32 v200, v193, v193
	v_fmac_f32_e32 v252, v195, v195
	v_fmac_f32_e32 v253, v197, v197
	v_fmac_f32_e32 v219, v199, v199
	v_add_f32_e32 v200, v200, v252
	v_add_f32_e32 v253, v253, v219
	v_add_f32_e32 v200, v200, v253
	v_add_f32_e32 v251, v251, v200
	v_mul_f32_e32 v200, 0xbfb8aa3b, v20
	v_mul_f32_e32 v252, 0xbfb8aa3b, v21
	v_mul_f32_e32 v253, 0xbfb8aa3b, v22
	v_mul_f32_e32 v219, 0xbfb8aa3b, v23
	v_exp_f32_e32 v200, v200
	v_exp_f32_e32 v252, v252
	v_exp_f32_e32 v253, v253
	v_exp_f32_e32 v219, v219
	v_add_f32_e32 v200, 1.0, v200
	v_add_f32_e32 v252, 1.0, v252
	v_add_f32_e32 v253, 1.0, v253
	v_add_f32_e32 v219, 1.0, v219
	v_rcp_f32_e32 v200, v200
	v_rcp_f32_e32 v252, v252
	v_rcp_f32_e32 v253, v253
	v_rcp_f32_e32 v219, v219
	v_mul_f32_e32 v200, v20, v200
	v_mul_f32_e32 v252, v21, v252
	v_mul_f32_e32 v253, v22, v253
	v_mul_f32_e32 v219, v23, v219
	v_mul_f32_e32 v200, v200, v228
	v_mul_f32_e32 v252, v252, v229
	v_mul_f32_e32 v253, v253, v230
	v_mul_f32_e32 v219, v219, v231
	v_mul_f32_e32 v20, v200, v192
	v_mul_f32_e32 v21, v252, v193
	v_mul_f32_e32 v22, v253, v194
	v_mul_f32_e32 v23, v219, v195
	v_mul_f32_e32 v200, 0xbfb8aa3b, v12
	v_mul_f32_e32 v252, 0xbfb8aa3b, v13
	v_mul_f32_e32 v253, 0xbfb8aa3b, v14
	v_mul_f32_e32 v219, 0xbfb8aa3b, v15
	v_exp_f32_e32 v200, v200
	v_exp_f32_e32 v252, v252
	v_exp_f32_e32 v253, v253
	v_exp_f32_e32 v219, v219
	v_add_f32_e32 v200, 1.0, v200
	v_add_f32_e32 v252, 1.0, v252
	v_add_f32_e32 v253, 1.0, v253
	v_add_f32_e32 v219, 1.0, v219
	v_rcp_f32_e32 v200, v200
	v_rcp_f32_e32 v252, v252
	v_rcp_f32_e32 v253, v253
	v_rcp_f32_e32 v219, v219
	v_mul_f32_e32 v200, v12, v200
	v_mul_f32_e32 v252, v13, v252
	v_mul_f32_e32 v253, v14, v253
	v_mul_f32_e32 v219, v15, v219
	v_mul_f32_e32 v200, v200, v232
	v_mul_f32_e32 v252, v252, v233
	v_mul_f32_e32 v253, v253, v234
	v_mul_f32_e32 v219, v219, v235
	v_mul_f32_e32 v12, v200, v196
	v_mul_f32_e32 v13, v252, v197
	v_mul_f32_e32 v14, v253, v198
	v_mul_f32_e32 v15, v219, v199
	v_lshlrev_b32_e32 v192, 16, v148
	v_and_b32_e32 v193, 0xffff0000, v148
	v_lshlrev_b32_e32 v200, 16, v156
	v_and_b32_e32 v252, 0xffff0000, v156
	v_add_f32_e32 v192, v192, v200
	v_add_f32_e32 v193, v193, v252
	v_lshlrev_b32_e32 v194, 16, v149
	v_and_b32_e32 v195, 0xffff0000, v149
	v_lshlrev_b32_e32 v200, 16, v157
	v_and_b32_e32 v252, 0xffff0000, v157
	v_add_f32_e32 v194, v194, v200
	v_add_f32_e32 v195, v195, v252
	v_lshlrev_b32_e32 v196, 16, v150
	v_and_b32_e32 v197, 0xffff0000, v150
	v_lshlrev_b32_e32 v200, 16, v158
	v_and_b32_e32 v252, 0xffff0000, v158
	v_add_f32_e32 v196, v196, v200
	v_add_f32_e32 v197, v197, v252
	v_lshlrev_b32_e32 v198, 16, v151
	v_and_b32_e32 v199, 0xffff0000, v151
	v_lshlrev_b32_e32 v200, 16, v159
	v_and_b32_e32 v252, 0xffff0000, v159
	v_add_f32_e32 v198, v198, v200
	v_add_f32_e32 v199, v199, v252
	v_mul_f32_e32 v200, v192, v192
	v_mul_f32_e32 v252, v194, v194
	v_mul_f32_e32 v253, v196, v196
	v_mul_f32_e32 v219, v198, v198
	v_fmac_f32_e32 v200, v193, v193
	v_fmac_f32_e32 v252, v195, v195
	v_fmac_f32_e32 v253, v197, v197
	v_fmac_f32_e32 v219, v199, v199
	v_add_f32_e32 v200, v200, v252
	v_add_f32_e32 v253, v253, v219
	v_add_f32_e32 v200, v200, v253
	v_add_f32_e32 v251, v251, v200
	v_mul_f32_e32 v200, 0xbfb8aa3b, v4
	v_mul_f32_e32 v252, 0xbfb8aa3b, v5
	v_mul_f32_e32 v253, 0xbfb8aa3b, v6
	v_mul_f32_e32 v219, 0xbfb8aa3b, v7
	v_exp_f32_e32 v200, v200
	v_exp_f32_e32 v252, v252
	v_exp_f32_e32 v253, v253
	v_exp_f32_e32 v219, v219
	v_add_f32_e32 v200, 1.0, v200
	v_add_f32_e32 v252, 1.0, v252
	v_add_f32_e32 v253, 1.0, v253
	v_add_f32_e32 v219, 1.0, v219
	v_rcp_f32_e32 v200, v200
	v_rcp_f32_e32 v252, v252
	v_rcp_f32_e32 v253, v253
	v_rcp_f32_e32 v219, v219
	v_mul_f32_e32 v200, v4, v200
	v_mul_f32_e32 v252, v5, v252
	v_mul_f32_e32 v253, v6, v253
	v_mul_f32_e32 v219, v7, v219
	v_mul_f32_e32 v200, v200, v236
	v_mul_f32_e32 v252, v252, v237
	v_mul_f32_e32 v253, v253, v238
	v_mul_f32_e32 v219, v219, v239
	v_mul_f32_e32 v4, v200, v192
	v_mul_f32_e32 v5, v252, v193
	v_mul_f32_e32 v6, v253, v194
	v_mul_f32_e32 v7, v219, v195
	v_mul_f32_e32 v200, 0xbfb8aa3b, v0
	v_mul_f32_e32 v252, 0xbfb8aa3b, v1
	v_mul_f32_e32 v253, 0xbfb8aa3b, v2
	v_mul_f32_e32 v219, 0xbfb8aa3b, v3
	v_exp_f32_e32 v200, v200
	v_exp_f32_e32 v252, v252
	v_exp_f32_e32 v253, v253
	v_exp_f32_e32 v219, v219
	v_add_f32_e32 v200, 1.0, v200
	v_add_f32_e32 v252, 1.0, v252
	v_add_f32_e32 v253, 1.0, v253
	v_add_f32_e32 v219, 1.0, v219
	v_rcp_f32_e32 v200, v200
	v_rcp_f32_e32 v252, v252
	v_rcp_f32_e32 v253, v253
	v_rcp_f32_e32 v219, v219
	v_mul_f32_e32 v200, v0, v200
	v_mul_f32_e32 v252, v1, v252
	v_mul_f32_e32 v253, v2, v253
	v_mul_f32_e32 v219, v3, v219
	v_mul_f32_e32 v200, v200, v240
	v_mul_f32_e32 v252, v252, v241
	v_mul_f32_e32 v253, v253, v242
	v_mul_f32_e32 v219, v219, v243
	v_mul_f32_e32 v0, v200, v196
	v_mul_f32_e32 v1, v252, v197
	v_mul_f32_e32 v2, v253, v198
	v_mul_f32_e32 v3, v219, v199
	ds_bpermute_b32 v200, v226, v244
	ds_bpermute_b32 v252, v226, v245
	ds_bpermute_b32 v253, v226, v246
	ds_bpermute_b32 v219, v226, v247
	s_waitcnt lgkmcnt(0)
; #define LAS __attribute__((address_space(3)))
; __device__ __forceinline__ unsigned cvtpk(float lo, float hi) { f32x2 v = {lo, hi}; bf16x2_t b = __builtin_convertvector(v, bf16x2_t); return __builtin_bit_cast(unsigned, b); }
; __device__ __forceinline__ float bflo(unsigned u) { return __uint_as_float(u << 16); }
;     __device__ __forceinline__ void operator()(const af4 (&acc)[2][2][4][2], const pg8::Unit& u, int wr, int wc, int fr_, int fq_) const {
;     ...
; #pragma unroll
;             for (int k = 0; k < 8; ++k) { float v = ssq[k];
;                 v += __int_as_float(__builtin_amdgcn_ds_bpermute((ln_ ^ 16) << 2, __float_as_int(v)));
;                 v += __int_as_float(__builtin_amdgcn_ds_bpermute((ln_ ^ 32) << 2, __float_as_int(v))); ssq[k] = v; }
;             if (fq == 0) {
; #pragma unroll
;                 for (int k = 0; k < 8; ++k) xch[((k >> 2) * 128 + wr * 64 + (k & 3) * 16 + fr) * 4 + wc] = ssq[k];
;             }
;             asm volatile("s_waitcnt lgkmcnt(0)" ::: "memory"); __builtin_amdgcn_s_barrier(); asm volatile("" ::: "memory");
;             float rs[8];
; #pragma unroll
;             for (int k = 0; k < 8; ++k) { const f32x4 p4 = *(const LAS f32x4*)(xch + ((k >> 2) * 128 + wr * 64 + (k & 3) * 16 + fr) * 4);
;                 rs[k] = 1.0f / sqrtf(((p4[0] + p4[1]) + (p4[2] + p4[3])) * (1.f / 256.f) + LN_EPS); }
;     ...
;                 for (int mi = 0; mi < 2; ++mi) { const float rstd = rs[ai * 4 + mp * 2 + mi];
; #pragma unroll
;                     for (int bj = 0; bj < 2; ++bj) { af4 v0 = acc[ai][bj][mp * 2 + mi][0], v1 = acc[ai][bj][mp * 2 + mi][1]; asm volatile("" : "+v"(v0), "+v"(v1)); const v4u a = of_[mi][bj], c = ob_[mi][bj];
; #pragma unroll
;                         for (int e = 0; e < 4; ++e) { v0[e] = v0[e] * sigmoidf_(v0[e]) * (rstd * nwv[bj][0][e]); v1[e] = v1[e] * sigmoidf_(v1[e]) * (rstd * nwv[bj][1][e]); }
;                         v4u w; w.x = cvtpk(v0[0] * (bflo(a.x) + bflo(c.x)), v0[1] * (bfhi(a.x) + bfhi(c.x))); w.y = cvtpk(v0[2] * (bflo(a.y) + bflo(c.y)), v0[3] * (bfhi(a.y) + bfhi(c.y)));
;                         w.z = cvtpk(v1[0] * (bflo(a.z) + bflo(c.z)), v1[1] * (bfhi(a.z) + bfhi(c.z))); w.w = cvtpk(v1[2] * (bflo(a.w) + bflo(c.w)), v1[3] * (bfhi(a.w) + bfhi(c.w)));
;                         *(v4u*)(ON + ob + mi * 16 * 1024 + bj * 128) = w; } }
	v_add_f32_e32 v244, v244, v200
	v_add_f32_e32 v245, v245, v252
	v_add_f32_e32 v246, v246, v253
	v_add_f32_e32 v247, v247, v219
	ds_bpermute_b32 v200, v226, v248
	ds_bpermute_b32 v252, v226, v249
	ds_bpermute_b32 v253, v226, v250
	ds_bpermute_b32 v219, v226, v251
	s_waitcnt lgkmcnt(0)
	v_add_f32_e32 v248, v248, v200
	v_add_f32_e32 v249, v249, v252
	v_add_f32_e32 v250, v250, v253
	v_add_f32_e32 v251, v251, v219
	ds_bpermute_b32 v200, v227, v244
	ds_bpermute_b32 v252, v227, v245
	ds_bpermute_b32 v253, v227, v246
	ds_bpermute_b32 v219, v227, v247
	s_waitcnt lgkmcnt(0)
	v_add_f32_e32 v244, v244, v200
	v_add_f32_e32 v245, v245, v252
	v_add_f32_e32 v246, v246, v253
	v_add_f32_e32 v247, v247, v219
	ds_bpermute_b32 v200, v227, v248
	ds_bpermute_b32 v252, v227, v249
	ds_bpermute_b32 v253, v227, v250
	ds_bpermute_b32 v219, v227, v251
	s_waitcnt lgkmcnt(0)
	v_add_f32_e32 v248, v248, v200
	v_add_f32_e32 v249, v249, v252
	v_add_f32_e32 v250, v250, v253
	v_add_f32_e32 v251, v251, v219
	ds_write_b32 v224, v244 offset:0
	ds_write_b32 v224, v245 offset:256
	ds_write_b32 v224, v246 offset:512
	ds_write_b32 v224, v247 offset:768
	ds_write_b32 v224, v248 offset:2048
	ds_write_b32 v224, v249 offset:2304
	ds_write_b32 v224, v250 offset:2560
	ds_write_b32 v224, v251 offset:2816
	s_waitcnt lgkmcnt(0)
	s_barrier
	ds_read_b128 v[128:131], v225 offset:0
	ds_read_b128 v[132:135], v225 offset:256
	ds_read_b128 v[136:139], v225 offset:512
	ds_read_b128 v[140:143], v225 offset:768
	ds_read_b128 v[144:147], v225 offset:2048
	ds_read_b128 v[148:151], v225 offset:2304
	ds_read_b128 v[152:155], v225 offset:2560
	ds_read_b128 v[156:159], v225 offset:2816
	s_waitcnt lgkmcnt(0)
	v_add_f32_e32 v128, v128, v129
	v_add_f32_e32 v130, v130, v131
	v_add_f32_e32 v128, v128, v130
	v_mul_f32_e32 v128, 0x3b800000, v128
	v_add_f32_e32 v128, 0x358637bd, v128
	v_add_f32_e32 v132, v132, v133
	v_add_f32_e32 v134, v134, v135
	v_add_f32_e32 v132, v132, v134
	v_mul_f32_e32 v132, 0x3b800000, v132
	v_add_f32_e32 v132, 0x358637bd, v132
	v_add_f32_e32 v136, v136, v137
	v_add_f32_e32 v138, v138, v139
	v_add_f32_e32 v136, v136, v138
	v_mul_f32_e32 v136, 0x3b800000, v136
	v_add_f32_e32 v136, 0x358637bd, v136
	v_add_f32_e32 v140, v140, v141
	v_add_f32_e32 v142, v142, v143
	v_add_f32_e32 v140, v140, v142
	v_mul_f32_e32 v140, 0x3b800000, v140
	v_add_f32_e32 v140, 0x358637bd, v140
	v_add_f32_e32 v144, v144, v145
	v_add_f32_e32 v146, v146, v147
	v_add_f32_e32 v144, v144, v146
	v_mul_f32_e32 v144, 0x3b800000, v144
	v_add_f32_e32 v144, 0x358637bd, v144
	v_add_f32_e32 v148, v148, v149
	v_add_f32_e32 v150, v150, v151
	v_add_f32_e32 v148, v148, v150
	v_mul_f32_e32 v148, 0x3b800000, v148
	v_add_f32_e32 v148, 0x358637bd, v148
	v_add_f32_e32 v152, v152, v153
	v_add_f32_e32 v154, v154, v155
	v_add_f32_e32 v152, v152, v154
	v_mul_f32_e32 v152, 0x3b800000, v152
	v_add_f32_e32 v152, 0x358637bd, v152
	v_add_f32_e32 v156, v156, v157
	v_add_f32_e32 v158, v158, v159
	v_add_f32_e32 v156, v156, v158
	v_mul_f32_e32 v156, 0x3b800000, v156
	v_add_f32_e32 v156, 0x358637bd, v156
	v_rsq_f32_e32 v244, v128
	v_rsq_f32_e32 v245, v132
	v_rsq_f32_e32 v246, v136
	v_rsq_f32_e32 v247, v140
	v_rsq_f32_e32 v248, v144
	v_rsq_f32_e32 v249, v148
	v_rsq_f32_e32 v250, v152
	v_rsq_f32_e32 v251, v156
	v_subrev_co_u32_e32 v220, vcc, 0x58000, v220
	s_nop 1
	v_subbrev_co_u32_e32 v221, vcc, 0, v221, vcc
	v_mul_f32_e32 v124, v124, v244
	v_mul_f32_e32 v125, v125, v244
	v_mul_f32_e32 v126, v126, v244
	v_mul_f32_e32 v127, v127, v244
	v_mul_f32_e32 v120, v120, v244
	v_mul_f32_e32 v121, v121, v244
	v_mul_f32_e32 v122, v122, v244
	v_mul_f32_e32 v123, v123, v244
	v_cvt_pk_bf16_f32 v160, v124, v125
	v_cvt_pk_bf16_f32 v161, v126, v127
	v_cvt_pk_bf16_f32 v162, v120, v121
	v_cvt_pk_bf16_f32 v163, v122, v123
	global_store_dwordx4 v[220:221], v[160:163], off
	v_mul_f32_e32 v112, v112, v244
	v_mul_f32_e32 v113, v113, v244
	v_mul_f32_e32 v114, v114, v244
	v_mul_f32_e32 v115, v115, v244
	v_mul_f32_e32 v104, v104, v244
	v_mul_f32_e32 v105, v105, v244
	v_mul_f32_e32 v106, v106, v244
	v_mul_f32_e32 v107, v107, v244
	v_cvt_pk_bf16_f32 v164, v112, v113
	v_cvt_pk_bf16_f32 v165, v114, v115
	v_cvt_pk_bf16_f32 v166, v104, v105
	v_cvt_pk_bf16_f32 v167, v106, v107
	global_store_dwordx4 v[220:221], v[164:167], off offset:256
	s_nop 0
	v_add_co_u32_e32 v220, vcc, 0x8000, v220
	s_nop 1
	v_addc_co_u32_e32 v221, vcc, 0, v221, vcc
	v_mul_f32_e32 v116, v116, v245
	v_mul_f32_e32 v117, v117, v245
	v_mul_f32_e32 v118, v118, v245
	v_mul_f32_e32 v119, v119, v245
	v_mul_f32_e32 v108, v108, v245
	v_mul_f32_e32 v109, v109, v245
	v_mul_f32_e32 v110, v110, v245
	v_mul_f32_e32 v111, v111, v245
	v_cvt_pk_bf16_f32 v160, v116, v117
	v_cvt_pk_bf16_f32 v161, v118, v119
	v_cvt_pk_bf16_f32 v162, v108, v109
	v_cvt_pk_bf16_f32 v163, v110, v111
	global_store_dwordx4 v[220:221], v[160:163], off
	v_mul_f32_e32 v96, v96, v245
	v_mul_f32_e32 v97, v97, v245
	v_mul_f32_e32 v98, v98, v245
	v_mul_f32_e32 v99, v99, v245
	v_mul_f32_e32 v88, v88, v245
	v_mul_f32_e32 v89, v89, v245
	v_mul_f32_e32 v90, v90, v245
	v_mul_f32_e32 v91, v91, v245
	v_cvt_pk_bf16_f32 v164, v96, v97
	v_cvt_pk_bf16_f32 v165, v98, v99
	v_cvt_pk_bf16_f32 v166, v88, v89
	v_cvt_pk_bf16_f32 v167, v90, v91
	global_store_dwordx4 v[220:221], v[164:167], off offset:256
	s_nop 0
	v_add_co_u32_e32 v220, vcc, 0x8000, v220
	s_nop 1
	v_addc_co_u32_e32 v221, vcc, 0, v221, vcc
	v_mul_f32_e32 v100, v100, v246
	v_mul_f32_e32 v101, v101, v246
	v_mul_f32_e32 v102, v102, v246
	v_mul_f32_e32 v103, v103, v246
	v_mul_f32_e32 v92, v92, v246
; __device__ __forceinline__ unsigned cvtpk(float lo, float hi) { f32x2 v = {lo, hi}; bf16x2_t b = __builtin_convertvector(v, bf16x2_t); return __builtin_bit_cast(unsigned, b); }
; __device__ __forceinline__ float bflo(unsigned u) { return __uint_as_float(u << 16); }
; __device__ __forceinline__ float bfhi(unsigned u) { return __uint_as_float(u & 0xffff0000u); }
; __device__ __forceinline__ float sigmoidf_(float x) { return __builtin_amdgcn_rcpf(1.0f + __expf(-x)); }
;     __device__ __forceinline__ void operator()(const af4 (&acc)[2][2][4][2], const pg8::Unit& u, int wr, int wc, int fr_, int fq_) const {
;     ...
;                 for (int mi = 0; mi < 2; ++mi) { const float rstd = rs[ai * 4 + mp * 2 + mi];
; #pragma unroll
;                     for (int bj = 0; bj < 2; ++bj) { af4 v0 = acc[ai][bj][mp * 2 + mi][0], v1 = acc[ai][bj][mp * 2 + mi][1]; asm volatile("" : "+v"(v0), "+v"(v1)); const v4u a = of_[mi][bj], c = ob_[mi][bj];
; #pragma unroll
;                         for (int e = 0; e < 4; ++e) { v0[e] = v0[e] * sigmoidf_(v0[e]) * (rstd * nwv[bj][0][e]); v1[e] = v1[e] * sigmoidf_(v1[e]) * (rstd * nwv[bj][1][e]); }
;                         v4u w; w.x = cvtpk(v0[0] * (bflo(a.x) + bflo(c.x)), v0[1] * (bfhi(a.x) + bfhi(c.x))); w.y = cvtpk(v0[2] * (bflo(a.y) + bflo(c.y)), v0[3] * (bfhi(a.y) + bfhi(c.y)));
;                         w.z = cvtpk(v1[0] * (bflo(a.z) + bflo(c.z)), v1[1] * (bfhi(a.z) + bfhi(c.z))); w.w = cvtpk(v1[2] * (bflo(a.w) + bflo(c.w)), v1[3] * (bfhi(a.w) + bfhi(c.w)));
;                         *(v4u*)(ON + ob + mi * 16 * 1024 + bj * 128) = w; } }
	v_mul_f32_e32 v93, v93, v246
	v_mul_f32_e32 v94, v94, v246
	v_mul_f32_e32 v95, v95, v246
	v_cvt_pk_bf16_f32 v160, v100, v101
	v_cvt_pk_bf16_f32 v161, v102, v103
	v_cvt_pk_bf16_f32 v162, v92, v93
	v_cvt_pk_bf16_f32 v163, v94, v95
	global_store_dwordx4 v[220:221], v[160:163], off
	v_mul_f32_e32 v80, v80, v246
	v_mul_f32_e32 v81, v81, v246
	v_mul_f32_e32 v82, v82, v246
	v_mul_f32_e32 v83, v83, v246
	v_mul_f32_e32 v72, v72, v246
	v_mul_f32_e32 v73, v73, v246
	v_mul_f32_e32 v74, v74, v246
	v_mul_f32_e32 v75, v75, v246
	v_cvt_pk_bf16_f32 v164, v80, v81
	v_cvt_pk_bf16_f32 v165, v82, v83
	v_cvt_pk_bf16_f32 v166, v72, v73
	v_cvt_pk_bf16_f32 v167, v74, v75
	global_store_dwordx4 v[220:221], v[164:167], off offset:256
	s_nop 0
	v_add_co_u32_e32 v220, vcc, 0x8000, v220
	s_nop 1
	v_addc_co_u32_e32 v221, vcc, 0, v221, vcc
	v_mul_f32_e32 v84, v84, v247
	v_mul_f32_e32 v85, v85, v247
	v_mul_f32_e32 v86, v86, v247
	v_mul_f32_e32 v87, v87, v247
	v_mul_f32_e32 v76, v76, v247
	v_mul_f32_e32 v77, v77, v247
	v_mul_f32_e32 v78, v78, v247
	v_mul_f32_e32 v79, v79, v247
	v_cvt_pk_bf16_f32 v160, v84, v85
	v_cvt_pk_bf16_f32 v161, v86, v87
	v_cvt_pk_bf16_f32 v162, v76, v77
	v_cvt_pk_bf16_f32 v163, v78, v79
	global_store_dwordx4 v[220:221], v[160:163], off
	v_mul_f32_e32 v68, v68, v247
	v_mul_f32_e32 v69, v69, v247
	v_mul_f32_e32 v70, v70, v247
	v_mul_f32_e32 v71, v71, v247
	v_mul_f32_e32 v64, v64, v247
	v_mul_f32_e32 v65, v65, v247
	v_mul_f32_e32 v66, v66, v247
	v_mul_f32_e32 v67, v67, v247
	v_cvt_pk_bf16_f32 v164, v68, v69
	v_cvt_pk_bf16_f32 v165, v70, v71
	v_cvt_pk_bf16_f32 v166, v64, v65
	v_cvt_pk_bf16_f32 v167, v66, v67
	global_store_dwordx4 v[220:221], v[164:167], off offset:256
	s_nop 0
	v_add_co_u32_e32 v220, vcc, 0x28000, v220
	s_nop 1
	v_addc_co_u32_e32 v221, vcc, 0, v221, vcc
	v_mul_f32_e32 v60, v60, v248
	v_mul_f32_e32 v61, v61, v248
	v_mul_f32_e32 v62, v62, v248
	v_mul_f32_e32 v63, v63, v248
	v_mul_f32_e32 v56, v56, v248
	v_mul_f32_e32 v57, v57, v248
	v_mul_f32_e32 v58, v58, v248
	v_mul_f32_e32 v59, v59, v248
	v_cvt_pk_bf16_f32 v160, v60, v61
	v_cvt_pk_bf16_f32 v161, v62, v63
	v_cvt_pk_bf16_f32 v162, v56, v57
	v_cvt_pk_bf16_f32 v163, v58, v59
	global_store_dwordx4 v[220:221], v[160:163], off
	v_mul_f32_e32 v48, v48, v248
	v_mul_f32_e32 v49, v49, v248
	v_mul_f32_e32 v50, v50, v248
	v_mul_f32_e32 v51, v51, v248
	v_mul_f32_e32 v40, v40, v248
	v_mul_f32_e32 v41, v41, v248
	v_mul_f32_e32 v42, v42, v248
	v_mul_f32_e32 v43, v43, v248
	v_cvt_pk_bf16_f32 v164, v48, v49
	v_cvt_pk_bf16_f32 v165, v50, v51
	v_cvt_pk_bf16_f32 v166, v40, v41
	v_cvt_pk_bf16_f32 v167, v42, v43
	global_store_dwordx4 v[220:221], v[164:167], off offset:256
	s_nop 0
	v_add_co_u32_e32 v220, vcc, 0x8000, v220
	s_nop 1
	v_addc_co_u32_e32 v221, vcc, 0, v221, vcc
	v_mul_f32_e32 v52, v52, v249
	v_mul_f32_e32 v53, v53, v249
	v_mul_f32_e32 v54, v54, v249
	v_mul_f32_e32 v55, v55, v249
	v_mul_f32_e32 v44, v44, v249
	v_mul_f32_e32 v45, v45, v249
	v_mul_f32_e32 v46, v46, v249
	v_mul_f32_e32 v47, v47, v249
	v_cvt_pk_bf16_f32 v160, v52, v53
	v_cvt_pk_bf16_f32 v161, v54, v55
	v_cvt_pk_bf16_f32 v162, v44, v45
	v_cvt_pk_bf16_f32 v163, v46, v47
	global_store_dwordx4 v[220:221], v[160:163], off
	v_mul_f32_e32 v32, v32, v249
	v_mul_f32_e32 v33, v33, v249
	v_mul_f32_e32 v34, v34, v249
	v_mul_f32_e32 v35, v35, v249
	v_mul_f32_e32 v24, v24, v249
	v_mul_f32_e32 v25, v25, v249
	v_mul_f32_e32 v26, v26, v249
	v_mul_f32_e32 v27, v27, v249
	v_cvt_pk_bf16_f32 v164, v32, v33
	v_cvt_pk_bf16_f32 v165, v34, v35
	v_cvt_pk_bf16_f32 v166, v24, v25
	v_cvt_pk_bf16_f32 v167, v26, v27
	global_store_dwordx4 v[220:221], v[164:167], off offset:256
	s_nop 0
	v_add_co_u32_e32 v220, vcc, 0x8000, v220
	s_nop 1
	v_addc_co_u32_e32 v221, vcc, 0, v221, vcc
	v_mul_f32_e32 v36, v36, v250
	v_mul_f32_e32 v37, v37, v250
	v_mul_f32_e32 v38, v38, v250
	v_mul_f32_e32 v39, v39, v250
	v_mul_f32_e32 v28, v28, v250
	v_mul_f32_e32 v29, v29, v250
	v_mul_f32_e32 v30, v30, v250
	v_mul_f32_e32 v31, v31, v250
	v_cvt_pk_bf16_f32 v160, v36, v37
	v_cvt_pk_bf16_f32 v161, v38, v39
	v_cvt_pk_bf16_f32 v162, v28, v29
	v_cvt_pk_bf16_f32 v163, v30, v31
	global_store_dwordx4 v[220:221], v[160:163], off
	v_mul_f32_e32 v16, v16, v250
	v_mul_f32_e32 v17, v17, v250
	v_mul_f32_e32 v18, v18, v250
	v_mul_f32_e32 v19, v19, v250
	v_mul_f32_e32 v8, v8, v250
	v_mul_f32_e32 v9, v9, v250
	v_mul_f32_e32 v10, v10, v250
	v_mul_f32_e32 v11, v11, v250
	v_cvt_pk_bf16_f32 v164, v16, v17
	v_cvt_pk_bf16_f32 v165, v18, v19
	v_cvt_pk_bf16_f32 v166, v8, v9
	v_cvt_pk_bf16_f32 v167, v10, v11
	global_store_dwordx4 v[220:221], v[164:167], off offset:256
	s_nop 0
	v_add_co_u32_e32 v220, vcc, 0x8000, v220
	s_nop 1
	v_addc_co_u32_e32 v221, vcc, 0, v221, vcc
	v_mul_f32_e32 v20, v20, v251
	v_mul_f32_e32 v21, v21, v251
	v_mul_f32_e32 v22, v22, v251
	v_mul_f32_e32 v23, v23, v251
	v_mul_f32_e32 v12, v12, v251
	v_mul_f32_e32 v13, v13, v251
	v_mul_f32_e32 v14, v14, v251
	v_mul_f32_e32 v15, v15, v251
	v_cvt_pk_bf16_f32 v160, v20, v21
	v_cvt_pk_bf16_f32 v161, v22, v23
	v_cvt_pk_bf16_f32 v162, v12, v13
	v_cvt_pk_bf16_f32 v163, v14, v15
	global_store_dwordx4 v[220:221], v[160:163], off
	v_mul_f32_e32 v4, v4, v251
	v_mul_f32_e32 v5, v5, v251
	v_mul_f32_e32 v6, v6, v251
	v_mul_f32_e32 v7, v7, v251
	v_mul_f32_e32 v0, v0, v251
	v_mul_f32_e32 v1, v1, v251
	v_mul_f32_e32 v2, v2, v251
	v_mul_f32_e32 v3, v3, v251
	v_cvt_pk_bf16_f32 v164, v4, v5
	v_cvt_pk_bf16_f32 v165, v6, v7
	v_cvt_pk_bf16_f32 v166, v0, v1
	v_cvt_pk_bf16_f32 v167, v2, v3
	global_store_dwordx4 v[220:221], v[164:167], off offset:256

;     __device__ __forceinline__ void operator()(const af4 (&acc)[2][2][4][2], const pg8::Unit& u, int wr, int wc, int fr_, int fq_) const {
;     ...
;             const int col0 = (pn - 2) * 256 + wc * 32 + 8 * fq;
;             float ssq[8];
; #pragma unroll
;             for (int b_ = 0; b_ < 4; ++b_) {
;                 const int ai = b_ >> 1, mp = b_ & 1;
;                 int RRb = row0 + ai * 128 + mp * 32; asm volatile("" : "+v"(RRb));
;                 const size_t ob = (size_t)RRb * 1024 + col0; v4u of_[2][2], ob_[2][2];
; #pragma unroll
;                 for (int mi = 0; mi < 2; ++mi)
; #pragma unroll
;                     for (int bj = 0; bj < 2; ++bj) { of_[mi][bj] = *(const v4u*)(ON + ob + mi * 16 * 1024 + bj * 128); ob_[mi][bj] = *(const v4u*)(OBp + ob + mi * 16 * 1024 + bj * 128); }
; #pragma unroll
;                 for (int mi = 0; mi < 2; ++mi) { float q = 0.f;
; #pragma unroll
;                     for (int bj = 0; bj < 2; ++bj) { const v4u a = of_[mi][bj], c = ob_[mi][bj];
;                         const float o0 = bflo(a.x) + bflo(c.x), o1 = bfhi(a.x) + bfhi(c.x), o2 = bflo(a.y) + bflo(c.y), o3 = bfhi(a.y) + bfhi(c.y), o4 = bflo(a.z) + bflo(c.z), o5 = bfhi(a.z) + bfhi(c.z), o6 = bflo(a.w) + bflo(c.w), o7 = bfhi(a.w) + bfhi(c.w);
;                         q += (o0 * o0 + o1 * o1) + (o2 * o2 + o3 * o3) + (o4 * o4 + o5 * o5) + (o6 * o6 + o7 * o7); }
;                     ssq[ai * 4 + mp * 2 + mi] = q; }
;     ...
;             f32x4 nwv[2][2];
; #pragma unroll
;             for (int bj = 0; bj < 2; ++bj) { nwv[bj][0] = *(const f32x4*)(nw + col0 + bj * 128); nwv[bj][1] = *(const f32x4*)(nw + col0 + bj * 128 + 4); }
; #pragma unroll
;             for (int b_ = 0; b_ < 4; ++b_) {
;                 const int ai = b_ >> 1, mp = b_ & 1;
;                 int RRb = row0 + ai * 128 + mp * 32; asm volatile("" : "+v"(RRb));
;                 const size_t ob = (size_t)RRb * 1024 + col0; v4u of_[2][2], ob_[2][2];
; #pragma unroll
;                 for (int mi = 0; mi < 2; ++mi)
; #pragma unroll
;                     for (int bj = 0; bj < 2; ++bj) { of_[mi][bj] = *(const v4u*)(ON + ob + mi * 16 * 1024 + bj * 128); ob_[mi][bj] = *(const v4u*)(OBp + ob + mi * 16 * 1024 + bj * 128); }
; #pragma unroll
;                 for (int mi = 0; mi < 2; ++mi) { const float rstd = rs[ai * 4 + mp * 2 + mi];
; #pragma unroll
.LBB0_1132:
	s_andn2_b64 vcc, exec, s[8:9]
	s_cbranch_vccnz .LBB0_1136
	s_lshl_b32 s4, s68, 8
	v_lshlrev_b32_e32 v136, 3, v215
	s_add_i32 s8, s53, s4
	v_mov_b32_e32 v128, v214
	v_add_u32_e32 v192, s8, v136
	v_ashrrev_i32_e32 v193, 31, v192
	v_ashrrev_i32_e32 v129, 31, v128
	v_lshlrev_b64 v[128:129], 10, v[128:129]
	v_lshl_add_u64 v[128:129], v[128:129], 0, v[192:193]
	v_lshlrev_b64 v[128:129], 1, v[128:129]
	v_lshl_add_u64 v[130:131], s[22:23], 0, v[128:129]
	v_lshl_add_u64 v[128:129], s[24:25], 0, v[128:129]
	v_mov_b32_e32 v216, v137
	v_mov_b32_e32 v217, v138
	v_lshlrev_b32_e32 v218, 2, v192
	v_mov_b32_e32 v220, v130
	v_mov_b32_e32 v221, v131
	v_mov_b32_e32 v222, v128
	v_mov_b32_e32 v223, v129
	s_load_dwordx2 s[8:9], s[84:85], 0x58
	v_add_u32_e32 v225, s87, v216
	v_lshlrev_b32_e32 v225, 4, v225
	v_add_u32_e32 v225, 0x20400, v225
	s_lshr_b32 vcc_lo, s73, 3
	v_add_u32_e32 v224, vcc_lo, v225
	v_xor_b32_e32 v226, 16, v217
	v_lshlrev_b32_e32 v226, 2, v226
	v_xor_b32_e32 v227, 32, v217
	v_lshlrev_b32_e32 v227, 2, v227
	s_waitcnt lgkmcnt(0)
	s_add_u32 s8, s8, 0x1000
	s_addc_u32 s9, s9, 0
	global_load_dwordx4 v[228:231], v218, s[8:9]
	global_load_dwordx4 v[232:235], v218, s[8:9] offset:16
	global_load_dwordx4 v[236:239], v218, s[8:9] offset:512
	global_load_dwordx4 v[240:243], v218, s[8:9] offset:528
	v_mov_b32_e32 v244, 0
	v_mov_b32_e32 v245, 0
	v_mov_b32_e32 v246, 0
	v_mov_b32_e32 v247, 0
	v_mov_b32_e32 v248, 0
	v_mov_b32_e32 v249, 0
	v_mov_b32_e32 v250, 0
	v_mov_b32_e32 v251, 0
	global_load_dwordx4 v[128:131], v[220:221], off
	global_load_dwordx4 v[132:135], v[220:221], off offset:256
	global_load_dwordx4 v[136:139], v[222:223], off
	global_load_dwordx4 v[140:143], v[222:223], off offset:256
	v_add_co_u32_e32 v220, vcc, 0x8000, v220
	s_nop 1
	v_addc_co_u32_e32 v221, vcc, 0, v221, vcc
	v_add_co_u32_e32 v222, vcc, 0x8000, v222
	s_nop 1
	v_addc_co_u32_e32 v223, vcc, 0, v223, vcc
	global_load_dwordx4 v[144:147], v[220:221], off
	global_load_dwordx4 v[148:151], v[220:221], off offset:256
	global_load_dwordx4 v[152:155], v[222:223], off
	global_load_dwordx4 v[156:159], v[222:223], off offset:256
	v_add_co_u32_e32 v220, vcc, 0x8000, v220
	s_nop 1
	v_addc_co_u32_e32 v221, vcc, 0, v221, vcc
	v_add_co_u32_e32 v222, vcc, 0x8000, v222
	s_nop 1
	v_addc_co_u32_e32 v223, vcc, 0, v223, vcc
	global_load_dwordx4 v[160:163], v[220:221], off
	global_load_dwordx4 v[164:167], v[220:221], off offset:256
	global_load_dwordx4 v[168:171], v[222:223], off
	global_load_dwordx4 v[172:175], v[222:223], off offset:256
	v_add_co_u32_e32 v220, vcc, 0x8000, v220
	s_nop 1
	v_addc_co_u32_e32 v221, vcc, 0, v221, vcc
	v_add_co_u32_e32 v222, vcc, 0x8000, v222
	s_nop 1
	v_addc_co_u32_e32 v223, vcc, 0, v223, vcc
	s_waitcnt vmcnt(8)
	v_lshlrev_b32_e32 v192, 16, v128
	v_and_b32_e32 v193, 0xffff0000, v128
	v_lshlrev_b32_e32 v200, 16, v136
	v_and_b32_e32 v252, 0xffff0000, v136
	v_add_f32_e32 v192, v192, v200
	v_add_f32_e32 v193, v193, v252
	v_lshlrev_b32_e32 v194, 16, v129
	v_and_b32_e32 v195, 0xffff0000, v129
	v_lshlrev_b32_e32 v200, 16, v137
	v_and_b32_e32 v252, 0xffff0000, v137
	v_add_f32_e32 v194, v194, v200
	v_add_f32_e32 v195, v195, v252
	v_lshlrev_b32_e32 v196, 16, v130
	v_and_b32_e32 v197, 0xffff0000, v130
	v_lshlrev_b32_e32 v200, 16, v138
	v_and_b32_e32 v252, 0xffff0000, v138
	v_add_f32_e32 v196, v196, v200
	v_add_f32_e32 v197, v197, v252
	v_lshlrev_b32_e32 v198, 16, v131
	v_and_b32_e32 v199, 0xffff0000, v131
	v_lshlrev_b32_e32 v200, 16, v139
	v_and_b32_e32 v252, 0xffff0000, v139
	v_add_f32_e32 v198, v198, v200
	v_add_f32_e32 v199, v199, v252
	v_mul_f32_e32 v200, v192, v192
	v_mul_f32_e32 v252, v194, v194
	v_mul_f32_e32 v253, v196, v196
	v_mul_f32_e32 v219, v198, v198
	v_fmac_f32_e32 v200, v193, v193
	v_fmac_f32_e32 v252, v195, v195
	v_fmac_f32_e32 v253, v197, v197
	v_fmac_f32_e32 v219, v199, v199
	v_add_f32_e32 v200, v200, v252
	v_add_f32_e32 v253, v253, v219
	v_add_f32_e32 v200, v200, v253
	v_add_f32_e32 v244, v244, v200
	v_mul_f32_e32 v200, 0xbfb8aa3b, v124
	v_mul_f32_e32 v252, 0xbfb8aa3b, v125
	v_mul_f32_e32 v253, 0xbfb8aa3b, v126
	v_mul_f32_e32 v219, 0xbfb8aa3b, v127
	v_exp_f32_e32 v200, v200
	v_exp_f32_e32 v252, v252
	v_exp_f32_e32 v253, v253
	v_exp_f32_e32 v219, v219
	v_add_f32_e32 v200, 1.0, v200
	v_add_f32_e32 v252, 1.0, v252
	v_add_f32_e32 v253, 1.0, v253
	v_add_f32_e32 v219, 1.0, v219
	v_rcp_f32_e32 v200, v200
	v_rcp_f32_e32 v252, v252
	v_rcp_f32_e32 v253, v253
	v_rcp_f32_e32 v219, v219
	v_mul_f32_e32 v200, v124, v200
	v_mul_f32_e32 v252, v125, v252
	v_mul_f32_e32 v253, v126, v253
	v_mul_f32_e32 v219, v127, v219
	v_mul_f32_e32 v200, v200, v228
	v_mul_f32_e32 v252, v252, v229
	v_mul_f32_e32 v253, v253, v230
	v_mul_f32_e32 v219, v219, v231
	v_mul_f32_e32 v124, v200, v192
	v_mul_f32_e32 v125, v252, v193
	v_mul_f32_e32 v126, v253, v194
	v_mul_f32_e32 v127, v219, v195
	v_mul_f32_e32 v200, 0xbfb8aa3b, v120
	v_mul_f32_e32 v252, 0xbfb8aa3b, v121
	v_mul_f32_e32 v253, 0xbfb8aa3b, v122
	v_mul_f32_e32 v219, 0xbfb8aa3b, v123
	v_exp_f32_e32 v200, v200
	v_exp_f32_e32 v252, v252
	v_exp_f32_e32 v253, v253
	v_exp_f32_e32 v219, v219
	v_add_f32_e32 v200, 1.0, v200
	v_add_f32_e32 v252, 1.0, v252
	v_add_f32_e32 v253, 1.0, v253
	v_add_f32_e32 v219, 1.0, v219
	v_rcp_f32_e32 v200, v200
	v_rcp_f32_e32 v252, v252
	v_rcp_f32_e32 v253, v253
	v_rcp_f32_e32 v219, v219
	v_mul_f32_e32 v200, v120, v200
	v_mul_f32_e32 v252, v121, v252
	v_mul_f32_e32 v253, v122, v253
	v_mul_f32_e32 v219, v123, v219
	v_mul_f32_e32 v200, v200, v232
	v_mul_f32_e32 v252, v252, v233
	v_mul_f32_e32 v253, v253, v234
	v_mul_f32_e32 v219, v219, v235
	v_mul_f32_e32 v120, v200, v196
	v_mul_f32_e32 v121, v252, v197
; __device__ __forceinline__ unsigned cvtpk(float lo, float hi) { f32x2 v = {lo, hi}; bf16x2_t b = __builtin_convertvector(v, bf16x2_t); return __builtin_bit_cast(unsigned, b); }
;     __device__ __forceinline__ void operator()(const af4 (&acc)[2][2][4][2], const pg8::Unit& u, int wr, int wc, int fr_, int fq_) const {
;     ...
;             for (int b_ = 0; b_ < 4; ++b_) {
;                 const int ai = b_ >> 1, mp = b_ & 1;
;                 int RRb = row0 + ai * 128 + mp * 32; asm volatile("" : "+v"(RRb));
;                 const size_t ob = (size_t)RRb * 1024 + col0; v4u of_[2][2], ob_[2][2];
; #pragma unroll
;                 for (int mi = 0; mi < 2; ++mi)
; #pragma unroll
;                     for (int bj = 0; bj < 2; ++bj) { of_[mi][bj] = *(const v4u*)(ON + ob + mi * 16 * 1024 + bj * 128); ob_[mi][bj] = *(const v4u*)(OBp + ob + mi * 16 * 1024 + bj * 128); }
; #pragma unroll
;                 for (int mi = 0; mi < 2; ++mi) { float q = 0.f;
; #pragma unroll
;                     for (int bj = 0; bj < 2; ++bj) { const v4u a = of_[mi][bj], c = ob_[mi][bj];
;                         const float o0 = bflo(a.x) + bflo(c.x), o1 = bfhi(a.x) + bfhi(c.x), o2 = bflo(a.y) + bflo(c.y), o3 = bfhi(a.y) + bfhi(c.y), o4 = bflo(a.z) + bflo(c.z), o5 = bfhi(a.z) + bfhi(c.z), o6 = bflo(a.w) + bflo(c.w), o7 = bfhi(a.w) + bfhi(c.w);
;                         q += (o0 * o0 + o1 * o1) + (o2 * o2 + o3 * o3) + (o4 * o4 + o5 * o5) + (o6 * o6 + o7 * o7); }
;                     ssq[ai * 4 + mp * 2 + mi] = q; }
;     ...
;                 for (int mi = 0; mi < 2; ++mi) { const float rstd = rs[ai * 4 + mp * 2 + mi];
; #pragma unroll
;                     for (int bj = 0; bj < 2; ++bj) { af4 v0 = acc[ai][bj][mp * 2 + mi][0], v1 = acc[ai][bj][mp * 2 + mi][1]; asm volatile("" : "+v"(v0), "+v"(v1)); const v4u a = of_[mi][bj], c = ob_[mi][bj];
; #pragma unroll
;                         for (int e = 0; e < 4; ++e) { v0[e] = v0[e] * sigmoidf_(v0[e]) * (rstd * nwv[bj][0][e]); v1[e] = v1[e] * sigmoidf_(v1[e]) * (rstd * nwv[bj][1][e]); }
;                         v4u w; w.x = cvtpk(v0[0] * (bflo(a.x) + bflo(c.x)), v0[1] * (bfhi(a.x) + bfhi(c.x))); w.y = cvtpk(v0[2] * (bflo(a.y) + bflo(c.y)), v0[3] * (bfhi(a.y) + bfhi(c.y)));
;                         w.z = cvtpk(v1[0] * (bflo(a.z) + bflo(c.z)), v1[1] * (bfhi(a.z) + bfhi(c.z))); w.w = cvtpk(v1[2] * (bflo(a.w) + bflo(c.w)), v1[3] * (bfhi(a.w) + bfhi(c.w)));
	v_mul_f32_e32 v122, v253, v198
	v_mul_f32_e32 v123, v219, v199
	v_lshlrev_b32_e32 v192, 16, v132
	v_and_b32_e32 v193, 0xffff0000, v132
	v_lshlrev_b32_e32 v200, 16, v140
	v_and_b32_e32 v252, 0xffff0000, v140
	v_add_f32_e32 v192, v192, v200
	v_add_f32_e32 v193, v193, v252
	v_lshlrev_b32_e32 v194, 16, v133
	v_and_b32_e32 v195, 0xffff0000, v133
	v_lshlrev_b32_e32 v200, 16, v141
	v_and_b32_e32 v252, 0xffff0000, v141
	v_add_f32_e32 v194, v194, v200
	v_add_f32_e32 v195, v195, v252
	v_lshlrev_b32_e32 v196, 16, v134
	v_and_b32_e32 v197, 0xffff0000, v134
	v_lshlrev_b32_e32 v200, 16, v142
	v_and_b32_e32 v252, 0xffff0000, v142
	v_add_f32_e32 v196, v196, v200
	v_add_f32_e32 v197, v197, v252
	v_lshlrev_b32_e32 v198, 16, v135
	v_and_b32_e32 v199, 0xffff0000, v135
	v_lshlrev_b32_e32 v200, 16, v143
	v_and_b32_e32 v252, 0xffff0000, v143
	v_add_f32_e32 v198, v198, v200
	v_add_f32_e32 v199, v199, v252
	v_mul_f32_e32 v200, v192, v192
	v_mul_f32_e32 v252, v194, v194
	v_mul_f32_e32 v253, v196, v196
	v_mul_f32_e32 v219, v198, v198
	v_fmac_f32_e32 v200, v193, v193
	v_fmac_f32_e32 v252, v195, v195
	v_fmac_f32_e32 v253, v197, v197
	v_fmac_f32_e32 v219, v199, v199
	v_add_f32_e32 v200, v200, v252
	v_add_f32_e32 v253, v253, v219
	v_add_f32_e32 v200, v200, v253
	v_add_f32_e32 v244, v244, v200
	v_mul_f32_e32 v200, 0xbfb8aa3b, v112
	v_mul_f32_e32 v252, 0xbfb8aa3b, v113
	v_mul_f32_e32 v253, 0xbfb8aa3b, v114
	v_mul_f32_e32 v219, 0xbfb8aa3b, v115
	v_exp_f32_e32 v200, v200
	v_exp_f32_e32 v252, v252
	v_exp_f32_e32 v253, v253
	v_exp_f32_e32 v219, v219
	v_add_f32_e32 v200, 1.0, v200
	v_add_f32_e32 v252, 1.0, v252
	v_add_f32_e32 v253, 1.0, v253
	v_add_f32_e32 v219, 1.0, v219
	v_rcp_f32_e32 v200, v200
	v_rcp_f32_e32 v252, v252
	v_rcp_f32_e32 v253, v253
	v_rcp_f32_e32 v219, v219
	v_mul_f32_e32 v200, v112, v200
	v_mul_f32_e32 v252, v113, v252
	v_mul_f32_e32 v253, v114, v253
	v_mul_f32_e32 v219, v115, v219
	v_mul_f32_e32 v200, v200, v236
	v_mul_f32_e32 v252, v252, v237
	v_mul_f32_e32 v253, v253, v238
	v_mul_f32_e32 v219, v219, v239
	v_mul_f32_e32 v112, v200, v192
	v_mul_f32_e32 v113, v252, v193
	v_mul_f32_e32 v114, v253, v194
	v_mul_f32_e32 v115, v219, v195
	v_mul_f32_e32 v200, 0xbfb8aa3b, v104
	v_mul_f32_e32 v252, 0xbfb8aa3b, v105
	v_mul_f32_e32 v253, 0xbfb8aa3b, v106
	v_mul_f32_e32 v219, 0xbfb8aa3b, v107
	v_exp_f32_e32 v200, v200
	v_exp_f32_e32 v252, v252
	v_exp_f32_e32 v253, v253
	v_exp_f32_e32 v219, v219
	v_add_f32_e32 v200, 1.0, v200
	v_add_f32_e32 v252, 1.0, v252
	v_add_f32_e32 v253, 1.0, v253
	v_add_f32_e32 v219, 1.0, v219
	v_rcp_f32_e32 v200, v200
	v_rcp_f32_e32 v252, v252
	v_rcp_f32_e32 v253, v253
	v_rcp_f32_e32 v219, v219
	v_mul_f32_e32 v200, v104, v200
	v_mul_f32_e32 v252, v105, v252
	v_mul_f32_e32 v253, v106, v253
	v_mul_f32_e32 v219, v107, v219
	v_mul_f32_e32 v200, v200, v240
	v_mul_f32_e32 v252, v252, v241
	v_mul_f32_e32 v253, v253, v242
	v_mul_f32_e32 v219, v219, v243
	v_mul_f32_e32 v104, v200, v196
	v_mul_f32_e32 v105, v252, v197
	v_mul_f32_e32 v106, v253, v198
	v_mul_f32_e32 v107, v219, v199
	global_load_dwordx4 v[128:131], v[220:221], off
	global_load_dwordx4 v[132:135], v[220:221], off offset:256
	global_load_dwordx4 v[136:139], v[222:223], off
	global_load_dwordx4 v[140:143], v[222:223], off offset:256
	v_add_co_u32_e32 v220, vcc, 0x28000, v220
	s_nop 1
	v_addc_co_u32_e32 v221, vcc, 0, v221, vcc
	v_add_co_u32_e32 v222, vcc, 0x28000, v222
	s_nop 1
	v_addc_co_u32_e32 v223, vcc, 0, v223, vcc
	s_waitcnt vmcnt(8)
	v_lshlrev_b32_e32 v192, 16, v144
	v_and_b32_e32 v193, 0xffff0000, v144
	v_lshlrev_b32_e32 v200, 16, v152
	v_and_b32_e32 v252, 0xffff0000, v152
	v_add_f32_e32 v192, v192, v200
	v_add_f32_e32 v193, v193, v252
	v_lshlrev_b32_e32 v194, 16, v145
	v_and_b32_e32 v195, 0xffff0000, v145
	v_lshlrev_b32_e32 v200, 16, v153
	v_and_b32_e32 v252, 0xffff0000, v153
	v_add_f32_e32 v194, v194, v200
	v_add_f32_e32 v195, v195, v252
	v_lshlrev_b32_e32 v196, 16, v146
	v_and_b32_e32 v197, 0xffff0000, v146
	v_lshlrev_b32_e32 v200, 16, v154
	v_and_b32_e32 v252, 0xffff0000, v154
	v_add_f32_e32 v196, v196, v200
	v_add_f32_e32 v197, v197, v252
	v_lshlrev_b32_e32 v198, 16, v147
	v_and_b32_e32 v199, 0xffff0000, v147
	v_lshlrev_b32_e32 v200, 16, v155
	v_and_b32_e32 v252, 0xffff0000, v155
	v_add_f32_e32 v198, v198, v200
	v_add_f32_e32 v199, v199, v252
	v_mul_f32_e32 v200, v192, v192
	v_mul_f32_e32 v252, v194, v194
	v_mul_f32_e32 v253, v196, v196
	v_mul_f32_e32 v219, v198, v198
	v_fmac_f32_e32 v200, v193, v193
	v_fmac_f32_e32 v252, v195, v195
	v_fmac_f32_e32 v253, v197, v197
	v_fmac_f32_e32 v219, v199, v199
	v_add_f32_e32 v200, v200, v252
	v_add_f32_e32 v253, v253, v219
	v_add_f32_e32 v200, v200, v253
	v_add_f32_e32 v245, v245, v200
	v_mul_f32_e32 v200, 0xbfb8aa3b, v116
	v_mul_f32_e32 v252, 0xbfb8aa3b, v117
	v_mul_f32_e32 v253, 0xbfb8aa3b, v118
	v_mul_f32_e32 v219, 0xbfb8aa3b, v119
	v_exp_f32_e32 v200, v200
	v_exp_f32_e32 v252, v252
	v_exp_f32_e32 v253, v253
	v_exp_f32_e32 v219, v219
	v_add_f32_e32 v200, 1.0, v200
	v_add_f32_e32 v252, 1.0, v252
	v_add_f32_e32 v253, 1.0, v253
	v_add_f32_e32 v219, 1.0, v219
	v_rcp_f32_e32 v200, v200
	v_rcp_f32_e32 v252, v252
	v_rcp_f32_e32 v253, v253
	v_rcp_f32_e32 v219, v219
	v_mul_f32_e32 v200, v116, v200
	v_mul_f32_e32 v252, v117, v252
	v_mul_f32_e32 v253, v118, v253
	v_mul_f32_e32 v219, v119, v219
	v_mul_f32_e32 v200, v200, v228
	v_mul_f32_e32 v252, v252, v229
	v_mul_f32_e32 v253, v253, v230
	v_mul_f32_e32 v219, v219, v231
	v_mul_f32_e32 v116, v200, v192
	v_mul_f32_e32 v117, v252, v193
	v_mul_f32_e32 v118, v253, v194
	v_mul_f32_e32 v119, v219, v195
	v_mul_f32_e32 v200, 0xbfb8aa3b, v108
	v_mul_f32_e32 v252, 0xbfb8aa3b, v109
	v_mul_f32_e32 v253, 0xbfb8aa3b, v110
; __device__ __forceinline__ unsigned cvtpk(float lo, float hi) { f32x2 v = {lo, hi}; bf16x2_t b = __builtin_convertvector(v, bf16x2_t); return __builtin_bit_cast(unsigned, b); }
;     __device__ __forceinline__ void operator()(const af4 (&acc)[2][2][4][2], const pg8::Unit& u, int wr, int wc, int fr_, int fq_) const {
;     ...
;             for (int b_ = 0; b_ < 4; ++b_) {
;                 const int ai = b_ >> 1, mp = b_ & 1;
;                 int RRb = row0 + ai * 128 + mp * 32; asm volatile("" : "+v"(RRb));
;                 const size_t ob = (size_t)RRb * 1024 + col0; v4u of_[2][2], ob_[2][2];
; #pragma unroll
;                 for (int mi = 0; mi < 2; ++mi)
; #pragma unroll
;                     for (int bj = 0; bj < 2; ++bj) { of_[mi][bj] = *(const v4u*)(ON + ob + mi * 16 * 1024 + bj * 128); ob_[mi][bj] = *(const v4u*)(OBp + ob + mi * 16 * 1024 + bj * 128); }
; #pragma unroll
;                 for (int mi = 0; mi < 2; ++mi) { float q = 0.f;
; #pragma unroll
;                     for (int bj = 0; bj < 2; ++bj) { const v4u a = of_[mi][bj], c = ob_[mi][bj];
;                         const float o0 = bflo(a.x) + bflo(c.x), o1 = bfhi(a.x) + bfhi(c.x), o2 = bflo(a.y) + bflo(c.y), o3 = bfhi(a.y) + bfhi(c.y), o4 = bflo(a.z) + bflo(c.z), o5 = bfhi(a.z) + bfhi(c.z), o6 = bflo(a.w) + bflo(c.w), o7 = bfhi(a.w) + bfhi(c.w);
;                         q += (o0 * o0 + o1 * o1) + (o2 * o2 + o3 * o3) + (o4 * o4 + o5 * o5) + (o6 * o6 + o7 * o7); }
;                     ssq[ai * 4 + mp * 2 + mi] = q; }
;     ...
;                 for (int mi = 0; mi < 2; ++mi) { const float rstd = rs[ai * 4 + mp * 2 + mi];
; #pragma unroll
;                     for (int bj = 0; bj < 2; ++bj) { af4 v0 = acc[ai][bj][mp * 2 + mi][0], v1 = acc[ai][bj][mp * 2 + mi][1]; asm volatile("" : "+v"(v0), "+v"(v1)); const v4u a = of_[mi][bj], c = ob_[mi][bj];
; #pragma unroll
;                         for (int e = 0; e < 4; ++e) { v0[e] = v0[e] * sigmoidf_(v0[e]) * (rstd * nwv[bj][0][e]); v1[e] = v1[e] * sigmoidf_(v1[e]) * (rstd * nwv[bj][1][e]); }
;                         v4u w; w.x = cvtpk(v0[0] * (bflo(a.x) + bflo(c.x)), v0[1] * (bfhi(a.x) + bfhi(c.x))); w.y = cvtpk(v0[2] * (bflo(a.y) + bflo(c.y)), v0[3] * (bfhi(a.y) + bfhi(c.y)));
;                         w.z = cvtpk(v1[0] * (bflo(a.z) + bflo(c.z)), v1[1] * (bfhi(a.z) + bfhi(c.z))); w.w = cvtpk(v1[2] * (bflo(a.w) + bflo(c.w)), v1[3] * (bfhi(a.w) + bfhi(c.w)));
	v_mul_f32_e32 v219, 0xbfb8aa3b, v111
	v_exp_f32_e32 v200, v200
	v_exp_f32_e32 v252, v252
	v_exp_f32_e32 v253, v253
	v_exp_f32_e32 v219, v219
	v_add_f32_e32 v200, 1.0, v200
	v_add_f32_e32 v252, 1.0, v252
	v_add_f32_e32 v253, 1.0, v253
	v_add_f32_e32 v219, 1.0, v219
	v_rcp_f32_e32 v200, v200
	v_rcp_f32_e32 v252, v252
	v_rcp_f32_e32 v253, v253
	v_rcp_f32_e32 v219, v219
	v_mul_f32_e32 v200, v108, v200
	v_mul_f32_e32 v252, v109, v252
	v_mul_f32_e32 v253, v110, v253
	v_mul_f32_e32 v219, v111, v219
	v_mul_f32_e32 v200, v200, v232
	v_mul_f32_e32 v252, v252, v233
	v_mul_f32_e32 v253, v253, v234
	v_mul_f32_e32 v219, v219, v235
	v_mul_f32_e32 v108, v200, v196
	v_mul_f32_e32 v109, v252, v197
	v_mul_f32_e32 v110, v253, v198
	v_mul_f32_e32 v111, v219, v199
	v_lshlrev_b32_e32 v192, 16, v148
	v_and_b32_e32 v193, 0xffff0000, v148
	v_lshlrev_b32_e32 v200, 16, v156
	v_and_b32_e32 v252, 0xffff0000, v156
	v_add_f32_e32 v192, v192, v200
	v_add_f32_e32 v193, v193, v252
	v_lshlrev_b32_e32 v194, 16, v149
	v_and_b32_e32 v195, 0xffff0000, v149
	v_lshlrev_b32_e32 v200, 16, v157
	v_and_b32_e32 v252, 0xffff0000, v157
	v_add_f32_e32 v194, v194, v200
	v_add_f32_e32 v195, v195, v252
	v_lshlrev_b32_e32 v196, 16, v150
	v_and_b32_e32 v197, 0xffff0000, v150
	v_lshlrev_b32_e32 v200, 16, v158
	v_and_b32_e32 v252, 0xffff0000, v158
	v_add_f32_e32 v196, v196, v200
	v_add_f32_e32 v197, v197, v252
	v_lshlrev_b32_e32 v198, 16, v151
	v_and_b32_e32 v199, 0xffff0000, v151
	v_lshlrev_b32_e32 v200, 16, v159
	v_and_b32_e32 v252, 0xffff0000, v159
	v_add_f32_e32 v198, v198, v200
	v_add_f32_e32 v199, v199, v252
	v_mul_f32_e32 v200, v192, v192
	v_mul_f32_e32 v252, v194, v194
	v_mul_f32_e32 v253, v196, v196
	v_mul_f32_e32 v219, v198, v198
	v_fmac_f32_e32 v200, v193, v193
	v_fmac_f32_e32 v252, v195, v195
	v_fmac_f32_e32 v253, v197, v197
	v_fmac_f32_e32 v219, v199, v199
	v_add_f32_e32 v200, v200, v252
	v_add_f32_e32 v253, v253, v219
	v_add_f32_e32 v200, v200, v253
	v_add_f32_e32 v245, v245, v200
	v_mul_f32_e32 v200, 0xbfb8aa3b, v96
	v_mul_f32_e32 v252, 0xbfb8aa3b, v97
	v_mul_f32_e32 v253, 0xbfb8aa3b, v98
	v_mul_f32_e32 v219, 0xbfb8aa3b, v99
	v_exp_f32_e32 v200, v200
	v_exp_f32_e32 v252, v252
	v_exp_f32_e32 v253, v253
	v_exp_f32_e32 v219, v219
	v_add_f32_e32 v200, 1.0, v200
	v_add_f32_e32 v252, 1.0, v252
	v_add_f32_e32 v253, 1.0, v253
	v_add_f32_e32 v219, 1.0, v219
	v_rcp_f32_e32 v200, v200
	v_rcp_f32_e32 v252, v252
	v_rcp_f32_e32 v253, v253
	v_rcp_f32_e32 v219, v219
	v_mul_f32_e32 v200, v96, v200
	v_mul_f32_e32 v252, v97, v252
	v_mul_f32_e32 v253, v98, v253
	v_mul_f32_e32 v219, v99, v219
	v_mul_f32_e32 v200, v200, v236
	v_mul_f32_e32 v252, v252, v237
	v_mul_f32_e32 v253, v253, v238
	v_mul_f32_e32 v219, v219, v239
	v_mul_f32_e32 v96, v200, v192
	v_mul_f32_e32 v97, v252, v193
	v_mul_f32_e32 v98, v253, v194
	v_mul_f32_e32 v99, v219, v195
	v_mul_f32_e32 v200, 0xbfb8aa3b, v88
	v_mul_f32_e32 v252, 0xbfb8aa3b, v89
	v_mul_f32_e32 v253, 0xbfb8aa3b, v90
	v_mul_f32_e32 v219, 0xbfb8aa3b, v91
	v_exp_f32_e32 v200, v200
	v_exp_f32_e32 v252, v252
	v_exp_f32_e32 v253, v253
	v_exp_f32_e32 v219, v219
	v_add_f32_e32 v200, 1.0, v200
	v_add_f32_e32 v252, 1.0, v252
	v_add_f32_e32 v253, 1.0, v253
	v_add_f32_e32 v219, 1.0, v219
	v_rcp_f32_e32 v200, v200
	v_rcp_f32_e32 v252, v252
	v_rcp_f32_e32 v253, v253
	v_rcp_f32_e32 v219, v219
	v_mul_f32_e32 v200, v88, v200
	v_mul_f32_e32 v252, v89, v252
	v_mul_f32_e32 v253, v90, v253
	v_mul_f32_e32 v219, v91, v219
	v_mul_f32_e32 v200, v200, v240
	v_mul_f32_e32 v252, v252, v241
	v_mul_f32_e32 v253, v253, v242
	v_mul_f32_e32 v219, v219, v243
	v_mul_f32_e32 v88, v200, v196
	v_mul_f32_e32 v89, v252, v197
	v_mul_f32_e32 v90, v253, v198
	v_mul_f32_e32 v91, v219, v199
	global_load_dwordx4 v[144:147], v[220:221], off
	global_load_dwordx4 v[148:151], v[220:221], off offset:256
	global_load_dwordx4 v[152:155], v[222:223], off
	global_load_dwordx4 v[156:159], v[222:223], off offset:256
	v_add_co_u32_e32 v220, vcc, 0x8000, v220
	s_nop 1
	v_addc_co_u32_e32 v221, vcc, 0, v221, vcc
	v_add_co_u32_e32 v222, vcc, 0x8000, v222
	s_nop 1
	v_addc_co_u32_e32 v223, vcc, 0, v223, vcc
	s_waitcnt vmcnt(8)
	v_lshlrev_b32_e32 v192, 16, v160
	v_and_b32_e32 v193, 0xffff0000, v160
	v_lshlrev_b32_e32 v200, 16, v168
	v_and_b32_e32 v252, 0xffff0000, v168
	v_add_f32_e32 v192, v192, v200
	v_add_f32_e32 v193, v193, v252
	v_lshlrev_b32_e32 v194, 16, v161
	v_and_b32_e32 v195, 0xffff0000, v161
	v_lshlrev_b32_e32 v200, 16, v169
	v_and_b32_e32 v252, 0xffff0000, v169
	v_add_f32_e32 v194, v194, v200
	v_add_f32_e32 v195, v195, v252
	v_lshlrev_b32_e32 v196, 16, v162
	v_and_b32_e32 v197, 0xffff0000, v162
	v_lshlrev_b32_e32 v200, 16, v170
	v_and_b32_e32 v252, 0xffff0000, v170
	v_add_f32_e32 v196, v196, v200
	v_add_f32_e32 v197, v197, v252
	v_lshlrev_b32_e32 v198, 16, v163
	v_and_b32_e32 v199, 0xffff0000, v163
	v_lshlrev_b32_e32 v200, 16, v171
	v_and_b32_e32 v252, 0xffff0000, v171
	v_add_f32_e32 v198, v198, v200
	v_add_f32_e32 v199, v199, v252
	v_mul_f32_e32 v200, v192, v192
	v_mul_f32_e32 v252, v194, v194
	v_mul_f32_e32 v253, v196, v196
	v_mul_f32_e32 v219, v198, v198
	v_fmac_f32_e32 v200, v193, v193
	v_fmac_f32_e32 v252, v195, v195
	v_fmac_f32_e32 v253, v197, v197
	v_fmac_f32_e32 v219, v199, v199
	v_add_f32_e32 v200, v200, v252
	v_add_f32_e32 v253, v253, v219
	v_add_f32_e32 v200, v200, v253
	v_add_f32_e32 v246, v246, v200
	v_mul_f32_e32 v200, 0xbfb8aa3b, v100
	v_mul_f32_e32 v252, 0xbfb8aa3b, v101
	v_mul_f32_e32 v253, 0xbfb8aa3b, v102
	v_mul_f32_e32 v219, 0xbfb8aa3b, v103
	v_exp_f32_e32 v200, v200
	v_exp_f32_e32 v252, v252
	v_exp_f32_e32 v253, v253
	v_exp_f32_e32 v219, v219
	v_add_f32_e32 v200, 1.0, v200
	v_add_f32_e32 v252, 1.0, v252
; __device__ __forceinline__ unsigned cvtpk(float lo, float hi) { f32x2 v = {lo, hi}; bf16x2_t b = __builtin_convertvector(v, bf16x2_t); return __builtin_bit_cast(unsigned, b); }
;     __device__ __forceinline__ void operator()(const af4 (&acc)[2][2][4][2], const pg8::Unit& u, int wr, int wc, int fr_, int fq_) const {
;     ...
;             for (int b_ = 0; b_ < 4; ++b_) {
;                 const int ai = b_ >> 1, mp = b_ & 1;
;                 int RRb = row0 + ai * 128 + mp * 32; asm volatile("" : "+v"(RRb));
;                 const size_t ob = (size_t)RRb * 1024 + col0; v4u of_[2][2], ob_[2][2];
; #pragma unroll
;                 for (int mi = 0; mi < 2; ++mi)
; #pragma unroll
;                     for (int bj = 0; bj < 2; ++bj) { of_[mi][bj] = *(const v4u*)(ON + ob + mi * 16 * 1024 + bj * 128); ob_[mi][bj] = *(const v4u*)(OBp + ob + mi * 16 * 1024 + bj * 128); }
; #pragma unroll
;                 for (int mi = 0; mi < 2; ++mi) { float q = 0.f;
; #pragma unroll
;                     for (int bj = 0; bj < 2; ++bj) { const v4u a = of_[mi][bj], c = ob_[mi][bj];
;                         const float o0 = bflo(a.x) + bflo(c.x), o1 = bfhi(a.x) + bfhi(c.x), o2 = bflo(a.y) + bflo(c.y), o3 = bfhi(a.y) + bfhi(c.y), o4 = bflo(a.z) + bflo(c.z), o5 = bfhi(a.z) + bfhi(c.z), o6 = bflo(a.w) + bflo(c.w), o7 = bfhi(a.w) + bfhi(c.w);
;                         q += (o0 * o0 + o1 * o1) + (o2 * o2 + o3 * o3) + (o4 * o4 + o5 * o5) + (o6 * o6 + o7 * o7); }
;                     ssq[ai * 4 + mp * 2 + mi] = q; }
;     ...
;                 for (int mi = 0; mi < 2; ++mi) { const float rstd = rs[ai * 4 + mp * 2 + mi];
; #pragma unroll
;                     for (int bj = 0; bj < 2; ++bj) { af4 v0 = acc[ai][bj][mp * 2 + mi][0], v1 = acc[ai][bj][mp * 2 + mi][1]; asm volatile("" : "+v"(v0), "+v"(v1)); const v4u a = of_[mi][bj], c = ob_[mi][bj];
; #pragma unroll
;                         for (int e = 0; e < 4; ++e) { v0[e] = v0[e] * sigmoidf_(v0[e]) * (rstd * nwv[bj][0][e]); v1[e] = v1[e] * sigmoidf_(v1[e]) * (rstd * nwv[bj][1][e]); }
;                         v4u w; w.x = cvtpk(v0[0] * (bflo(a.x) + bflo(c.x)), v0[1] * (bfhi(a.x) + bfhi(c.x))); w.y = cvtpk(v0[2] * (bflo(a.y) + bflo(c.y)), v0[3] * (bfhi(a.y) + bfhi(c.y)));
;                         w.z = cvtpk(v1[0] * (bflo(a.z) + bflo(c.z)), v1[1] * (bfhi(a.z) + bfhi(c.z))); w.w = cvtpk(v1[2] * (bflo(a.w) + bflo(c.w)), v1[3] * (bfhi(a.w) + bfhi(c.w)));
	v_add_f32_e32 v253, 1.0, v253
	v_add_f32_e32 v219, 1.0, v219
	v_rcp_f32_e32 v200, v200
	v_rcp_f32_e32 v252, v252
	v_rcp_f32_e32 v253, v253
	v_rcp_f32_e32 v219, v219
	v_mul_f32_e32 v200, v100, v200
	v_mul_f32_e32 v252, v101, v252
	v_mul_f32_e32 v253, v102, v253
	v_mul_f32_e32 v219, v103, v219
	v_mul_f32_e32 v200, v200, v228
	v_mul_f32_e32 v252, v252, v229
	v_mul_f32_e32 v253, v253, v230
	v_mul_f32_e32 v219, v219, v231
	v_mul_f32_e32 v100, v200, v192
	v_mul_f32_e32 v101, v252, v193
	v_mul_f32_e32 v102, v253, v194
	v_mul_f32_e32 v103, v219, v195
	v_mul_f32_e32 v200, 0xbfb8aa3b, v92
	v_mul_f32_e32 v252, 0xbfb8aa3b, v93
	v_mul_f32_e32 v253, 0xbfb8aa3b, v94
	v_mul_f32_e32 v219, 0xbfb8aa3b, v95
	v_exp_f32_e32 v200, v200
	v_exp_f32_e32 v252, v252
	v_exp_f32_e32 v253, v253
	v_exp_f32_e32 v219, v219
	v_add_f32_e32 v200, 1.0, v200
	v_add_f32_e32 v252, 1.0, v252
	v_add_f32_e32 v253, 1.0, v253
	v_add_f32_e32 v219, 1.0, v219
	v_rcp_f32_e32 v200, v200
	v_rcp_f32_e32 v252, v252
	v_rcp_f32_e32 v253, v253
	v_rcp_f32_e32 v219, v219
	v_mul_f32_e32 v200, v92, v200
	v_mul_f32_e32 v252, v93, v252
	v_mul_f32_e32 v253, v94, v253
	v_mul_f32_e32 v219, v95, v219
	v_mul_f32_e32 v200, v200, v232
	v_mul_f32_e32 v252, v252, v233
	v_mul_f32_e32 v253, v253, v234
	v_mul_f32_e32 v219, v219, v235
	v_mul_f32_e32 v92, v200, v196
	v_mul_f32_e32 v93, v252, v197
	v_mul_f32_e32 v94, v253, v198
	v_mul_f32_e32 v95, v219, v199
	v_lshlrev_b32_e32 v192, 16, v164
	v_and_b32_e32 v193, 0xffff0000, v164
	v_lshlrev_b32_e32 v200, 16, v172
	v_and_b32_e32 v252, 0xffff0000, v172
	v_add_f32_e32 v192, v192, v200
	v_add_f32_e32 v193, v193, v252
	v_lshlrev_b32_e32 v194, 16, v165
	v_and_b32_e32 v195, 0xffff0000, v165
	v_lshlrev_b32_e32 v200, 16, v173
	v_and_b32_e32 v252, 0xffff0000, v173
	v_add_f32_e32 v194, v194, v200
	v_add_f32_e32 v195, v195, v252
	v_lshlrev_b32_e32 v196, 16, v166
	v_and_b32_e32 v197, 0xffff0000, v166
	v_lshlrev_b32_e32 v200, 16, v174
	v_and_b32_e32 v252, 0xffff0000, v174
	v_add_f32_e32 v196, v196, v200
	v_add_f32_e32 v197, v197, v252
	v_lshlrev_b32_e32 v198, 16, v167
	v_and_b32_e32 v199, 0xffff0000, v167
	v_lshlrev_b32_e32 v200, 16, v175
	v_and_b32_e32 v252, 0xffff0000, v175
	v_add_f32_e32 v198, v198, v200
	v_add_f32_e32 v199, v199, v252
	v_mul_f32_e32 v200, v192, v192
	v_mul_f32_e32 v252, v194, v194
	v_mul_f32_e32 v253, v196, v196
	v_mul_f32_e32 v219, v198, v198
	v_fmac_f32_e32 v200, v193, v193
	v_fmac_f32_e32 v252, v195, v195
	v_fmac_f32_e32 v253, v197, v197
	v_fmac_f32_e32 v219, v199, v199
	v_add_f32_e32 v200, v200, v252
	v_add_f32_e32 v253, v253, v219
	v_add_f32_e32 v200, v200, v253
	v_add_f32_e32 v246, v246, v200
	v_mul_f32_e32 v200, 0xbfb8aa3b, v80
	v_mul_f32_e32 v252, 0xbfb8aa3b, v81
	v_mul_f32_e32 v253, 0xbfb8aa3b, v82
	v_mul_f32_e32 v219, 0xbfb8aa3b, v83
	v_exp_f32_e32 v200, v200
	v_exp_f32_e32 v252, v252
	v_exp_f32_e32 v253, v253
	v_exp_f32_e32 v219, v219
	v_add_f32_e32 v200, 1.0, v200
	v_add_f32_e32 v252, 1.0, v252
	v_add_f32_e32 v253, 1.0, v253
	v_add_f32_e32 v219, 1.0, v219
	v_rcp_f32_e32 v200, v200
	v_rcp_f32_e32 v252, v252
	v_rcp_f32_e32 v253, v253
	v_rcp_f32_e32 v219, v219
	v_mul_f32_e32 v200, v80, v200
	v_mul_f32_e32 v252, v81, v252
	v_mul_f32_e32 v253, v82, v253
	v_mul_f32_e32 v219, v83, v219
	v_mul_f32_e32 v200, v200, v236
	v_mul_f32_e32 v252, v252, v237
	v_mul_f32_e32 v253, v253, v238
	v_mul_f32_e32 v219, v219, v239
	v_mul_f32_e32 v80, v200, v192
	v_mul_f32_e32 v81, v252, v193
	v_mul_f32_e32 v82, v253, v194
	v_mul_f32_e32 v83, v219, v195
	v_mul_f32_e32 v200, 0xbfb8aa3b, v72
	v_mul_f32_e32 v252, 0xbfb8aa3b, v73
	v_mul_f32_e32 v253, 0xbfb8aa3b, v74
	v_mul_f32_e32 v219, 0xbfb8aa3b, v75
	v_exp_f32_e32 v200, v200
	v_exp_f32_e32 v252, v252
	v_exp_f32_e32 v253, v253
	v_exp_f32_e32 v219, v219
	v_add_f32_e32 v200, 1.0, v200
	v_add_f32_e32 v252, 1.0, v252
	v_add_f32_e32 v253, 1.0, v253
	v_add_f32_e32 v219, 1.0, v219
	v_rcp_f32_e32 v200, v200
	v_rcp_f32_e32 v252, v252
	v_rcp_f32_e32 v253, v253
	v_rcp_f32_e32 v219, v219
	v_mul_f32_e32 v200, v72, v200
	v_mul_f32_e32 v252, v73, v252
	v_mul_f32_e32 v253, v74, v253
	v_mul_f32_e32 v219, v75, v219
	v_mul_f32_e32 v200, v200, v240
	v_mul_f32_e32 v252, v252, v241
	v_mul_f32_e32 v253, v253, v242
	v_mul_f32_e32 v219, v219, v243
	v_mul_f32_e32 v72, v200, v196
	v_mul_f32_e32 v73, v252, v197
	v_mul_f32_e32 v74, v253, v198
	v_mul_f32_e32 v75, v219, v199
	global_load_dwordx4 v[160:163], v[220:221], off
	global_load_dwordx4 v[164:167], v[220:221], off offset:256
	global_load_dwordx4 v[168:171], v[222:223], off
	global_load_dwordx4 v[172:175], v[222:223], off offset:256
	v_add_co_u32_e32 v220, vcc, 0x8000, v220
	s_nop 1
	v_addc_co_u32_e32 v221, vcc, 0, v221, vcc
	v_add_co_u32_e32 v222, vcc, 0x8000, v222
	s_nop 1
	v_addc_co_u32_e32 v223, vcc, 0, v223, vcc
	s_waitcnt vmcnt(8)
; __device__ __forceinline__ unsigned cvtpk(float lo, float hi) { f32x2 v = {lo, hi}; bf16x2_t b = __builtin_convertvector(v, bf16x2_t); return __builtin_bit_cast(unsigned, b); }
;     __device__ __forceinline__ void operator()(const af4 (&acc)[2][2][4][2], const pg8::Unit& u, int wr, int wc, int fr_, int fq_) const {
;     ...
;             for (int b_ = 0; b_ < 4; ++b_) {
;                 const int ai = b_ >> 1, mp = b_ & 1;
;                 int RRb = row0 + ai * 128 + mp * 32; asm volatile("" : "+v"(RRb));
;                 const size_t ob = (size_t)RRb * 1024 + col0; v4u of_[2][2], ob_[2][2];
; #pragma unroll
;                 for (int mi = 0; mi < 2; ++mi)
; #pragma unroll
;                     for (int bj = 0; bj < 2; ++bj) { of_[mi][bj] = *(const v4u*)(ON + ob + mi * 16 * 1024 + bj * 128); ob_[mi][bj] = *(const v4u*)(OBp + ob + mi * 16 * 1024 + bj * 128); }
; #pragma unroll
;                 for (int mi = 0; mi < 2; ++mi) { float q = 0.f;
; #pragma unroll
;                     for (int bj = 0; bj < 2; ++bj) { const v4u a = of_[mi][bj], c = ob_[mi][bj];
;                         const float o0 = bflo(a.x) + bflo(c.x), o1 = bfhi(a.x) + bfhi(c.x), o2 = bflo(a.y) + bflo(c.y), o3 = bfhi(a.y) + bfhi(c.y), o4 = bflo(a.z) + bflo(c.z), o5 = bfhi(a.z) + bfhi(c.z), o6 = bflo(a.w) + bflo(c.w), o7 = bfhi(a.w) + bfhi(c.w);
;                         q += (o0 * o0 + o1 * o1) + (o2 * o2 + o3 * o3) + (o4 * o4 + o5 * o5) + (o6 * o6 + o7 * o7); }
;                     ssq[ai * 4 + mp * 2 + mi] = q; }
;     ...
;                 for (int mi = 0; mi < 2; ++mi) { const float rstd = rs[ai * 4 + mp * 2 + mi];
; #pragma unroll
;                     for (int bj = 0; bj < 2; ++bj) { af4 v0 = acc[ai][bj][mp * 2 + mi][0], v1 = acc[ai][bj][mp * 2 + mi][1]; asm volatile("" : "+v"(v0), "+v"(v1)); const v4u a = of_[mi][bj], c = ob_[mi][bj];
; #pragma unroll
;                         for (int e = 0; e < 4; ++e) { v0[e] = v0[e] * sigmoidf_(v0[e]) * (rstd * nwv[bj][0][e]); v1[e] = v1[e] * sigmoidf_(v1[e]) * (rstd * nwv[bj][1][e]); }
;                         v4u w; w.x = cvtpk(v0[0] * (bflo(a.x) + bflo(c.x)), v0[1] * (bfhi(a.x) + bfhi(c.x))); w.y = cvtpk(v0[2] * (bflo(a.y) + bflo(c.y)), v0[3] * (bfhi(a.y) + bfhi(c.y)));
;                         w.z = cvtpk(v1[0] * (bflo(a.z) + bflo(c.z)), v1[1] * (bfhi(a.z) + bfhi(c.z))); w.w = cvtpk(v1[2] * (bflo(a.w) + bflo(c.w)), v1[3] * (bfhi(a.w) + bfhi(c.w)));
	v_lshlrev_b32_e32 v192, 16, v128
	v_and_b32_e32 v193, 0xffff0000, v128
	v_lshlrev_b32_e32 v200, 16, v136
	v_and_b32_e32 v252, 0xffff0000, v136
	v_add_f32_e32 v192, v192, v200
	v_add_f32_e32 v193, v193, v252
	v_lshlrev_b32_e32 v194, 16, v129
	v_and_b32_e32 v195, 0xffff0000, v129
	v_lshlrev_b32_e32 v200, 16, v137
	v_and_b32_e32 v252, 0xffff0000, v137
	v_add_f32_e32 v194, v194, v200
	v_add_f32_e32 v195, v195, v252
	v_lshlrev_b32_e32 v196, 16, v130
	v_and_b32_e32 v197, 0xffff0000, v130
	v_lshlrev_b32_e32 v200, 16, v138
	v_and_b32_e32 v252, 0xffff0000, v138
	v_add_f32_e32 v196, v196, v200
	v_add_f32_e32 v197, v197, v252
	v_lshlrev_b32_e32 v198, 16, v131
	v_and_b32_e32 v199, 0xffff0000, v131
	v_lshlrev_b32_e32 v200, 16, v139
	v_and_b32_e32 v252, 0xffff0000, v139
	v_add_f32_e32 v198, v198, v200
	v_add_f32_e32 v199, v199, v252
	v_mul_f32_e32 v200, v192, v192
	v_mul_f32_e32 v252, v194, v194
	v_mul_f32_e32 v253, v196, v196
	v_mul_f32_e32 v219, v198, v198
	v_fmac_f32_e32 v200, v193, v193
	v_fmac_f32_e32 v252, v195, v195
	v_fmac_f32_e32 v253, v197, v197
	v_fmac_f32_e32 v219, v199, v199
	v_add_f32_e32 v200, v200, v252
	v_add_f32_e32 v253, v253, v219
	v_add_f32_e32 v200, v200, v253
	v_add_f32_e32 v247, v247, v200
	v_mul_f32_e32 v200, 0xbfb8aa3b, v84
	v_mul_f32_e32 v252, 0xbfb8aa3b, v85
	v_mul_f32_e32 v253, 0xbfb8aa3b, v86
	v_mul_f32_e32 v219, 0xbfb8aa3b, v87
	v_exp_f32_e32 v200, v200
	v_exp_f32_e32 v252, v252
	v_exp_f32_e32 v253, v253
	v_exp_f32_e32 v219, v219
	v_add_f32_e32 v200, 1.0, v200
	v_add_f32_e32 v252, 1.0, v252
	v_add_f32_e32 v253, 1.0, v253
	v_add_f32_e32 v219, 1.0, v219
	v_rcp_f32_e32 v200, v200
	v_rcp_f32_e32 v252, v252
	v_rcp_f32_e32 v253, v253
	v_rcp_f32_e32 v219, v219
	v_mul_f32_e32 v200, v84, v200
	v_mul_f32_e32 v252, v85, v252
	v_mul_f32_e32 v253, v86, v253
	v_mul_f32_e32 v219, v87, v219
	v_mul_f32_e32 v200, v200, v228
	v_mul_f32_e32 v252, v252, v229
	v_mul_f32_e32 v253, v253, v230
	v_mul_f32_e32 v219, v219, v231
	v_mul_f32_e32 v84, v200, v192
	v_mul_f32_e32 v85, v252, v193
	v_mul_f32_e32 v86, v253, v194
	v_mul_f32_e32 v87, v219, v195
	v_mul_f32_e32 v200, 0xbfb8aa3b, v76
	v_mul_f32_e32 v252, 0xbfb8aa3b, v77
	v_mul_f32_e32 v253, 0xbfb8aa3b, v78
	v_mul_f32_e32 v219, 0xbfb8aa3b, v79
	v_exp_f32_e32 v200, v200
	v_exp_f32_e32 v252, v252
	v_exp_f32_e32 v253, v253
	v_exp_f32_e32 v219, v219
	v_add_f32_e32 v200, 1.0, v200
	v_add_f32_e32 v252, 1.0, v252
	v_add_f32_e32 v253, 1.0, v253
	v_add_f32_e32 v219, 1.0, v219
	v_rcp_f32_e32 v200, v200
	v_rcp_f32_e32 v252, v252
	v_rcp_f32_e32 v253, v253
	v_rcp_f32_e32 v219, v219
	v_mul_f32_e32 v200, v76, v200
	v_mul_f32_e32 v252, v77, v252
	v_mul_f32_e32 v253, v78, v253
	v_mul_f32_e32 v219, v79, v219
	v_mul_f32_e32 v200, v200, v232
	v_mul_f32_e32 v252, v252, v233
	v_mul_f32_e32 v253, v253, v234
	v_mul_f32_e32 v219, v219, v235
	v_mul_f32_e32 v76, v200, v196
	v_mul_f32_e32 v77, v252, v197
	v_mul_f32_e32 v78, v253, v198
	v_mul_f32_e32 v79, v219, v199
	v_lshlrev_b32_e32 v192, 16, v132
	v_and_b32_e32 v193, 0xffff0000, v132
	v_lshlrev_b32_e32 v200, 16, v140
	v_and_b32_e32 v252, 0xffff0000, v140
	v_add_f32_e32 v192, v192, v200
	v_add_f32_e32 v193, v193, v252
	v_lshlrev_b32_e32 v194, 16, v133
	v_and_b32_e32 v195, 0xffff0000, v133
	v_lshlrev_b32_e32 v200, 16, v141
	v_and_b32_e32 v252, 0xffff0000, v141
	v_add_f32_e32 v194, v194, v200
	v_add_f32_e32 v195, v195, v252
	v_lshlrev_b32_e32 v196, 16, v134
	v_and_b32_e32 v197, 0xffff0000, v134
	v_lshlrev_b32_e32 v200, 16, v142
	v_and_b32_e32 v252, 0xffff0000, v142
	v_add_f32_e32 v196, v196, v200
	v_add_f32_e32 v197, v197, v252
	v_lshlrev_b32_e32 v198, 16, v135
	v_and_b32_e32 v199, 0xffff0000, v135
	v_lshlrev_b32_e32 v200, 16, v143
	v_and_b32_e32 v252, 0xffff0000, v143
	v_add_f32_e32 v198, v198, v200
	v_add_f32_e32 v199, v199, v252
	v_mul_f32_e32 v200, v192, v192
	v_mul_f32_e32 v252, v194, v194
	v_mul_f32_e32 v253, v196, v196
	v_mul_f32_e32 v219, v198, v198
	v_fmac_f32_e32 v200, v193, v193
	v_fmac_f32_e32 v252, v195, v195
	v_fmac_f32_e32 v253, v197, v197
	v_fmac_f32_e32 v219, v199, v199
	v_add_f32_e32 v200, v200, v252
	v_add_f32_e32 v253, v253, v219
	v_add_f32_e32 v200, v200, v253
	v_add_f32_e32 v247, v247, v200
	v_mul_f32_e32 v200, 0xbfb8aa3b, v68
	v_mul_f32_e32 v252, 0xbfb8aa3b, v69
	v_mul_f32_e32 v253, 0xbfb8aa3b, v70
	v_mul_f32_e32 v219, 0xbfb8aa3b, v71
	v_exp_f32_e32 v200, v200
	v_exp_f32_e32 v252, v252
	v_exp_f32_e32 v253, v253
	v_exp_f32_e32 v219, v219
	v_add_f32_e32 v200, 1.0, v200
	v_add_f32_e32 v252, 1.0, v252
	v_add_f32_e32 v253, 1.0, v253
	v_add_f32_e32 v219, 1.0, v219
	v_rcp_f32_e32 v200, v200
	v_rcp_f32_e32 v252, v252
	v_rcp_f32_e32 v253, v253
	v_rcp_f32_e32 v219, v219
	v_mul_f32_e32 v200, v68, v200
	v_mul_f32_e32 v252, v69, v252
	v_mul_f32_e32 v253, v70, v253
	v_mul_f32_e32 v219, v71, v219
	v_mul_f32_e32 v200, v200, v236
	v_mul_f32_e32 v252, v252, v237
	v_mul_f32_e32 v253, v253, v238
	v_mul_f32_e32 v219, v219, v239
	v_mul_f32_e32 v68, v200, v192
	v_mul_f32_e32 v69, v252, v193
	v_mul_f32_e32 v70, v253, v194
	v_mul_f32_e32 v71, v219, v195
	v_mul_f32_e32 v200, 0xbfb8aa3b, v64
	v_mul_f32_e32 v252, 0xbfb8aa3b, v65
	v_mul_f32_e32 v253, 0xbfb8aa3b, v66
	v_mul_f32_e32 v219, 0xbfb8aa3b, v67
	v_exp_f32_e32 v200, v200
	v_exp_f32_e32 v252, v252
	v_exp_f32_e32 v253, v253
	v_exp_f32_e32 v219, v219
	v_add_f32_e32 v200, 1.0, v200
	v_add_f32_e32 v252, 1.0, v252
	v_add_f32_e32 v253, 1.0, v253
	v_add_f32_e32 v219, 1.0, v219
	v_rcp_f32_e32 v200, v200
	v_rcp_f32_e32 v252, v252
	v_rcp_f32_e32 v253, v253
	v_rcp_f32_e32 v219, v219
	v_mul_f32_e32 v200, v64, v200
	v_mul_f32_e32 v252, v65, v252
	v_mul_f32_e32 v253, v66, v253
	v_mul_f32_e32 v219, v67, v219
	v_mul_f32_e32 v200, v200, v240
	v_mul_f32_e32 v252, v252, v241
	v_mul_f32_e32 v253, v253, v242
	v_mul_f32_e32 v219, v219, v243
	v_mul_f32_e32 v64, v200, v196
	v_mul_f32_e32 v65, v252, v197
	v_mul_f32_e32 v66, v253, v198
	v_mul_f32_e32 v67, v219, v199
	global_load_dwordx4 v[128:131], v[220:221], off
	global_load_dwordx4 v[132:135], v[220:221], off offset:256
	global_load_dwordx4 v[136:139], v[222:223], off
	global_load_dwordx4 v[140:143], v[222:223], off offset:256
	v_add_co_u32_e32 v220, vcc, 0x8000, v220
	s_nop 1
	v_addc_co_u32_e32 v221, vcc, 0, v221, vcc
	v_add_co_u32_e32 v222, vcc, 0x8000, v222
	s_nop 1
	v_addc_co_u32_e32 v223, vcc, 0, v223, vcc
	s_waitcnt vmcnt(8)
; __device__ __forceinline__ unsigned cvtpk(float lo, float hi) { f32x2 v = {lo, hi}; bf16x2_t b = __builtin_convertvector(v, bf16x2_t); return __builtin_bit_cast(unsigned, b); }
;     __device__ __forceinline__ void operator()(const af4 (&acc)[2][2][4][2], const pg8::Unit& u, int wr, int wc, int fr_, int fq_) const {
;     ...
;             for (int b_ = 0; b_ < 4; ++b_) {
;                 const int ai = b_ >> 1, mp = b_ & 1;
;                 int RRb = row0 + ai * 128 + mp * 32; asm volatile("" : "+v"(RRb));
;                 const size_t ob = (size_t)RRb * 1024 + col0; v4u of_[2][2], ob_[2][2];
; #pragma unroll
;                 for (int mi = 0; mi < 2; ++mi)
; #pragma unroll
;                     for (int bj = 0; bj < 2; ++bj) { of_[mi][bj] = *(const v4u*)(ON + ob + mi * 16 * 1024 + bj * 128); ob_[mi][bj] = *(const v4u*)(OBp + ob + mi * 16 * 1024 + bj * 128); }
; #pragma unroll
;                 for (int mi = 0; mi < 2; ++mi) { float q = 0.f;
; #pragma unroll
;                     for (int bj = 0; bj < 2; ++bj) { const v4u a = of_[mi][bj], c = ob_[mi][bj];
;                         const float o0 = bflo(a.x) + bflo(c.x), o1 = bfhi(a.x) + bfhi(c.x), o2 = bflo(a.y) + bflo(c.y), o3 = bfhi(a.y) + bfhi(c.y), o4 = bflo(a.z) + bflo(c.z), o5 = bfhi(a.z) + bfhi(c.z), o6 = bflo(a.w) + bflo(c.w), o7 = bfhi(a.w) + bfhi(c.w);
;                         q += (o0 * o0 + o1 * o1) + (o2 * o2 + o3 * o3) + (o4 * o4 + o5 * o5) + (o6 * o6 + o7 * o7); }
;                     ssq[ai * 4 + mp * 2 + mi] = q; }
;     ...
;                 for (int mi = 0; mi < 2; ++mi) { const float rstd = rs[ai * 4 + mp * 2 + mi];
; #pragma unroll
;                     for (int bj = 0; bj < 2; ++bj) { af4 v0 = acc[ai][bj][mp * 2 + mi][0], v1 = acc[ai][bj][mp * 2 + mi][1]; asm volatile("" : "+v"(v0), "+v"(v1)); const v4u a = of_[mi][bj], c = ob_[mi][bj];
; #pragma unroll
;                         for (int e = 0; e < 4; ++e) { v0[e] = v0[e] * sigmoidf_(v0[e]) * (rstd * nwv[bj][0][e]); v1[e] = v1[e] * sigmoidf_(v1[e]) * (rstd * nwv[bj][1][e]); }
;                         v4u w; w.x = cvtpk(v0[0] * (bflo(a.x) + bflo(c.x)), v0[1] * (bfhi(a.x) + bfhi(c.x))); w.y = cvtpk(v0[2] * (bflo(a.y) + bflo(c.y)), v0[3] * (bfhi(a.y) + bfhi(c.y)));
;                         w.z = cvtpk(v1[0] * (bflo(a.z) + bflo(c.z)), v1[1] * (bfhi(a.z) + bfhi(c.z))); w.w = cvtpk(v1[2] * (bflo(a.w) + bflo(c.w)), v1[3] * (bfhi(a.w) + bfhi(c.w)));
	v_lshlrev_b32_e32 v192, 16, v144
	v_and_b32_e32 v193, 0xffff0000, v144
	v_lshlrev_b32_e32 v200, 16, v152
	v_and_b32_e32 v252, 0xffff0000, v152
	v_add_f32_e32 v192, v192, v200
	v_add_f32_e32 v193, v193, v252
	v_lshlrev_b32_e32 v194, 16, v145
	v_and_b32_e32 v195, 0xffff0000, v145
	v_lshlrev_b32_e32 v200, 16, v153
	v_and_b32_e32 v252, 0xffff0000, v153
	v_add_f32_e32 v194, v194, v200
	v_add_f32_e32 v195, v195, v252
	v_lshlrev_b32_e32 v196, 16, v146
	v_and_b32_e32 v197, 0xffff0000, v146
	v_lshlrev_b32_e32 v200, 16, v154
	v_and_b32_e32 v252, 0xffff0000, v154
	v_add_f32_e32 v196, v196, v200
	v_add_f32_e32 v197, v197, v252
	v_lshlrev_b32_e32 v198, 16, v147
	v_and_b32_e32 v199, 0xffff0000, v147
	v_lshlrev_b32_e32 v200, 16, v155
	v_and_b32_e32 v252, 0xffff0000, v155
	v_add_f32_e32 v198, v198, v200
	v_add_f32_e32 v199, v199, v252
	v_mul_f32_e32 v200, v192, v192
	v_mul_f32_e32 v252, v194, v194
	v_mul_f32_e32 v253, v196, v196
	v_mul_f32_e32 v219, v198, v198
	v_fmac_f32_e32 v200, v193, v193
	v_fmac_f32_e32 v252, v195, v195
	v_fmac_f32_e32 v253, v197, v197
	v_fmac_f32_e32 v219, v199, v199
	v_add_f32_e32 v200, v200, v252
	v_add_f32_e32 v253, v253, v219
	v_add_f32_e32 v200, v200, v253
	v_add_f32_e32 v248, v248, v200
	v_mul_f32_e32 v200, 0xbfb8aa3b, v60
	v_mul_f32_e32 v252, 0xbfb8aa3b, v61
	v_mul_f32_e32 v253, 0xbfb8aa3b, v62
	v_mul_f32_e32 v219, 0xbfb8aa3b, v63
	v_exp_f32_e32 v200, v200
	v_exp_f32_e32 v252, v252
	v_exp_f32_e32 v253, v253
	v_exp_f32_e32 v219, v219
	v_add_f32_e32 v200, 1.0, v200
	v_add_f32_e32 v252, 1.0, v252
	v_add_f32_e32 v253, 1.0, v253
	v_add_f32_e32 v219, 1.0, v219
	v_rcp_f32_e32 v200, v200
	v_rcp_f32_e32 v252, v252
	v_rcp_f32_e32 v253, v253
	v_rcp_f32_e32 v219, v219
	v_mul_f32_e32 v200, v60, v200
	v_mul_f32_e32 v252, v61, v252
	v_mul_f32_e32 v253, v62, v253
	v_mul_f32_e32 v219, v63, v219
	v_mul_f32_e32 v200, v200, v228
	v_mul_f32_e32 v252, v252, v229
	v_mul_f32_e32 v253, v253, v230
	v_mul_f32_e32 v219, v219, v231
	v_mul_f32_e32 v60, v200, v192
	v_mul_f32_e32 v61, v252, v193
	v_mul_f32_e32 v62, v253, v194
	v_mul_f32_e32 v63, v219, v195
	v_mul_f32_e32 v200, 0xbfb8aa3b, v56
	v_mul_f32_e32 v252, 0xbfb8aa3b, v57
	v_mul_f32_e32 v253, 0xbfb8aa3b, v58
	v_mul_f32_e32 v219, 0xbfb8aa3b, v59
	v_exp_f32_e32 v200, v200
	v_exp_f32_e32 v252, v252
	v_exp_f32_e32 v253, v253
	v_exp_f32_e32 v219, v219
	v_add_f32_e32 v200, 1.0, v200
	v_add_f32_e32 v252, 1.0, v252
	v_add_f32_e32 v253, 1.0, v253
	v_add_f32_e32 v219, 1.0, v219
	v_rcp_f32_e32 v200, v200
	v_rcp_f32_e32 v252, v252
	v_rcp_f32_e32 v253, v253
	v_rcp_f32_e32 v219, v219
	v_mul_f32_e32 v200, v56, v200
	v_mul_f32_e32 v252, v57, v252
	v_mul_f32_e32 v253, v58, v253
	v_mul_f32_e32 v219, v59, v219
	v_mul_f32_e32 v200, v200, v232
	v_mul_f32_e32 v252, v252, v233
	v_mul_f32_e32 v253, v253, v234
	v_mul_f32_e32 v219, v219, v235
	v_mul_f32_e32 v56, v200, v196
	v_mul_f32_e32 v57, v252, v197
	v_mul_f32_e32 v58, v253, v198
	v_mul_f32_e32 v59, v219, v199
	v_lshlrev_b32_e32 v192, 16, v148
	v_and_b32_e32 v193, 0xffff0000, v148
	v_lshlrev_b32_e32 v200, 16, v156
	v_and_b32_e32 v252, 0xffff0000, v156
	v_add_f32_e32 v192, v192, v200
	v_add_f32_e32 v193, v193, v252
	v_lshlrev_b32_e32 v194, 16, v149
	v_and_b32_e32 v195, 0xffff0000, v149
	v_lshlrev_b32_e32 v200, 16, v157
	v_and_b32_e32 v252, 0xffff0000, v157
	v_add_f32_e32 v194, v194, v200
	v_add_f32_e32 v195, v195, v252
	v_lshlrev_b32_e32 v196, 16, v150
	v_and_b32_e32 v197, 0xffff0000, v150
	v_lshlrev_b32_e32 v200, 16, v158
	v_and_b32_e32 v252, 0xffff0000, v158
	v_add_f32_e32 v196, v196, v200
	v_add_f32_e32 v197, v197, v252
	v_lshlrev_b32_e32 v198, 16, v151
	v_and_b32_e32 v199, 0xffff0000, v151
	v_lshlrev_b32_e32 v200, 16, v159
	v_and_b32_e32 v252, 0xffff0000, v159
	v_add_f32_e32 v198, v198, v200
	v_add_f32_e32 v199, v199, v252
	v_mul_f32_e32 v200, v192, v192
	v_mul_f32_e32 v252, v194, v194
	v_mul_f32_e32 v253, v196, v196
	v_mul_f32_e32 v219, v198, v198
	v_fmac_f32_e32 v200, v193, v193
	v_fmac_f32_e32 v252, v195, v195
	v_fmac_f32_e32 v253, v197, v197
	v_fmac_f32_e32 v219, v199, v199
	v_add_f32_e32 v200, v200, v252
	v_add_f32_e32 v253, v253, v219
	v_add_f32_e32 v200, v200, v253
	v_add_f32_e32 v248, v248, v200
	v_mul_f32_e32 v200, 0xbfb8aa3b, v48
	v_mul_f32_e32 v252, 0xbfb8aa3b, v49
	v_mul_f32_e32 v253, 0xbfb8aa3b, v50
	v_mul_f32_e32 v219, 0xbfb8aa3b, v51
	v_exp_f32_e32 v200, v200
	v_exp_f32_e32 v252, v252
	v_exp_f32_e32 v253, v253
	v_exp_f32_e32 v219, v219
	v_add_f32_e32 v200, 1.0, v200
	v_add_f32_e32 v252, 1.0, v252
	v_add_f32_e32 v253, 1.0, v253
	v_add_f32_e32 v219, 1.0, v219
	v_rcp_f32_e32 v200, v200
	v_rcp_f32_e32 v252, v252
	v_rcp_f32_e32 v253, v253
	v_rcp_f32_e32 v219, v219
	v_mul_f32_e32 v200, v48, v200
	v_mul_f32_e32 v252, v49, v252
	v_mul_f32_e32 v253, v50, v253
	v_mul_f32_e32 v219, v51, v219
	v_mul_f32_e32 v200, v200, v236
	v_mul_f32_e32 v252, v252, v237
	v_mul_f32_e32 v253, v253, v238
	v_mul_f32_e32 v219, v219, v239
	v_mul_f32_e32 v48, v200, v192
	v_mul_f32_e32 v49, v252, v193
	v_mul_f32_e32 v50, v253, v194
	v_mul_f32_e32 v51, v219, v195
	v_mul_f32_e32 v200, 0xbfb8aa3b, v40
	v_mul_f32_e32 v252, 0xbfb8aa3b, v41
	v_mul_f32_e32 v253, 0xbfb8aa3b, v42
	v_mul_f32_e32 v219, 0xbfb8aa3b, v43
	v_exp_f32_e32 v200, v200
	v_exp_f32_e32 v252, v252
	v_exp_f32_e32 v253, v253
	v_exp_f32_e32 v219, v219
	v_add_f32_e32 v200, 1.0, v200
	v_add_f32_e32 v252, 1.0, v252
	v_add_f32_e32 v253, 1.0, v253
	v_add_f32_e32 v219, 1.0, v219
	v_rcp_f32_e32 v200, v200
	v_rcp_f32_e32 v252, v252
	v_rcp_f32_e32 v253, v253
	v_rcp_f32_e32 v219, v219
	v_mul_f32_e32 v200, v40, v200
	v_mul_f32_e32 v252, v41, v252
	v_mul_f32_e32 v253, v42, v253
	v_mul_f32_e32 v219, v43, v219
	v_mul_f32_e32 v200, v200, v240
	v_mul_f32_e32 v252, v252, v241
	v_mul_f32_e32 v253, v253, v242
	v_mul_f32_e32 v219, v219, v243
	v_mul_f32_e32 v40, v200, v196
	v_mul_f32_e32 v41, v252, v197
	v_mul_f32_e32 v42, v253, v198
	v_mul_f32_e32 v43, v219, v199
	global_load_dwordx4 v[144:147], v[220:221], off
	global_load_dwordx4 v[148:151], v[220:221], off offset:256
	global_load_dwordx4 v[152:155], v[222:223], off
	global_load_dwordx4 v[156:159], v[222:223], off offset:256
	s_waitcnt vmcnt(8)
; __device__ __forceinline__ unsigned cvtpk(float lo, float hi) { f32x2 v = {lo, hi}; bf16x2_t b = __builtin_convertvector(v, bf16x2_t); return __builtin_bit_cast(unsigned, b); }
;     __device__ __forceinline__ void operator()(const af4 (&acc)[2][2][4][2], const pg8::Unit& u, int wr, int wc, int fr_, int fq_) const {
;     ...
;             for (int b_ = 0; b_ < 4; ++b_) {
;                 const int ai = b_ >> 1, mp = b_ & 1;
;                 int RRb = row0 + ai * 128 + mp * 32; asm volatile("" : "+v"(RRb));
;                 const size_t ob = (size_t)RRb * 1024 + col0; v4u of_[2][2], ob_[2][2];
; #pragma unroll
;                 for (int mi = 0; mi < 2; ++mi)
; #pragma unroll
;                     for (int bj = 0; bj < 2; ++bj) { of_[mi][bj] = *(const v4u*)(ON + ob + mi * 16 * 1024 + bj * 128); ob_[mi][bj] = *(const v4u*)(OBp + ob + mi * 16 * 1024 + bj * 128); }
; #pragma unroll
;                 for (int mi = 0; mi < 2; ++mi) { float q = 0.f;
; #pragma unroll
;                     for (int bj = 0; bj < 2; ++bj) { const v4u a = of_[mi][bj], c = ob_[mi][bj];
;                         const float o0 = bflo(a.x) + bflo(c.x), o1 = bfhi(a.x) + bfhi(c.x), o2 = bflo(a.y) + bflo(c.y), o3 = bfhi(a.y) + bfhi(c.y), o4 = bflo(a.z) + bflo(c.z), o5 = bfhi(a.z) + bfhi(c.z), o6 = bflo(a.w) + bflo(c.w), o7 = bfhi(a.w) + bfhi(c.w);
;                         q += (o0 * o0 + o1 * o1) + (o2 * o2 + o3 * o3) + (o4 * o4 + o5 * o5) + (o6 * o6 + o7 * o7); }
;                     ssq[ai * 4 + mp * 2 + mi] = q; }
;     ...
;                 for (int mi = 0; mi < 2; ++mi) { const float rstd = rs[ai * 4 + mp * 2 + mi];
; #pragma unroll
;                     for (int bj = 0; bj < 2; ++bj) { af4 v0 = acc[ai][bj][mp * 2 + mi][0], v1 = acc[ai][bj][mp * 2 + mi][1]; asm volatile("" : "+v"(v0), "+v"(v1)); const v4u a = of_[mi][bj], c = ob_[mi][bj];
; #pragma unroll
;                         for (int e = 0; e < 4; ++e) { v0[e] = v0[e] * sigmoidf_(v0[e]) * (rstd * nwv[bj][0][e]); v1[e] = v1[e] * sigmoidf_(v1[e]) * (rstd * nwv[bj][1][e]); }
;                         v4u w; w.x = cvtpk(v0[0] * (bflo(a.x) + bflo(c.x)), v0[1] * (bfhi(a.x) + bfhi(c.x))); w.y = cvtpk(v0[2] * (bflo(a.y) + bflo(c.y)), v0[3] * (bfhi(a.y) + bfhi(c.y)));
;                         w.z = cvtpk(v1[0] * (bflo(a.z) + bflo(c.z)), v1[1] * (bfhi(a.z) + bfhi(c.z))); w.w = cvtpk(v1[2] * (bflo(a.w) + bflo(c.w)), v1[3] * (bfhi(a.w) + bfhi(c.w)));
	v_lshlrev_b32_e32 v192, 16, v160
	v_and_b32_e32 v193, 0xffff0000, v160
	v_lshlrev_b32_e32 v200, 16, v168
	v_and_b32_e32 v252, 0xffff0000, v168
	v_add_f32_e32 v192, v192, v200
	v_add_f32_e32 v193, v193, v252
	v_lshlrev_b32_e32 v194, 16, v161
	v_and_b32_e32 v195, 0xffff0000, v161
	v_lshlrev_b32_e32 v200, 16, v169
	v_and_b32_e32 v252, 0xffff0000, v169
	v_add_f32_e32 v194, v194, v200
	v_add_f32_e32 v195, v195, v252
	v_lshlrev_b32_e32 v196, 16, v162
	v_and_b32_e32 v197, 0xffff0000, v162
	v_lshlrev_b32_e32 v200, 16, v170
	v_and_b32_e32 v252, 0xffff0000, v170
	v_add_f32_e32 v196, v196, v200
	v_add_f32_e32 v197, v197, v252
	v_lshlrev_b32_e32 v198, 16, v163
	v_and_b32_e32 v199, 0xffff0000, v163
	v_lshlrev_b32_e32 v200, 16, v171
	v_and_b32_e32 v252, 0xffff0000, v171
	v_add_f32_e32 v198, v198, v200
	v_add_f32_e32 v199, v199, v252
	v_mul_f32_e32 v200, v192, v192
	v_mul_f32_e32 v252, v194, v194
	v_mul_f32_e32 v253, v196, v196
	v_mul_f32_e32 v219, v198, v198
	v_fmac_f32_e32 v200, v193, v193
	v_fmac_f32_e32 v252, v195, v195
	v_fmac_f32_e32 v253, v197, v197
	v_fmac_f32_e32 v219, v199, v199
	v_add_f32_e32 v200, v200, v252
	v_add_f32_e32 v253, v253, v219
	v_add_f32_e32 v200, v200, v253
	v_add_f32_e32 v249, v249, v200
	v_mul_f32_e32 v200, 0xbfb8aa3b, v52
	v_mul_f32_e32 v252, 0xbfb8aa3b, v53
	v_mul_f32_e32 v253, 0xbfb8aa3b, v54
	v_mul_f32_e32 v219, 0xbfb8aa3b, v55
	v_exp_f32_e32 v200, v200
	v_exp_f32_e32 v252, v252
	v_exp_f32_e32 v253, v253
	v_exp_f32_e32 v219, v219
	v_add_f32_e32 v200, 1.0, v200
	v_add_f32_e32 v252, 1.0, v252
	v_add_f32_e32 v253, 1.0, v253
	v_add_f32_e32 v219, 1.0, v219
	v_rcp_f32_e32 v200, v200
	v_rcp_f32_e32 v252, v252
	v_rcp_f32_e32 v253, v253
	v_rcp_f32_e32 v219, v219
	v_mul_f32_e32 v200, v52, v200
	v_mul_f32_e32 v252, v53, v252
	v_mul_f32_e32 v253, v54, v253
	v_mul_f32_e32 v219, v55, v219
	v_mul_f32_e32 v200, v200, v228
	v_mul_f32_e32 v252, v252, v229
	v_mul_f32_e32 v253, v253, v230
	v_mul_f32_e32 v219, v219, v231
	v_mul_f32_e32 v52, v200, v192
	v_mul_f32_e32 v53, v252, v193
	v_mul_f32_e32 v54, v253, v194
	v_mul_f32_e32 v55, v219, v195
	v_mul_f32_e32 v200, 0xbfb8aa3b, v44
	v_mul_f32_e32 v252, 0xbfb8aa3b, v45
	v_mul_f32_e32 v253, 0xbfb8aa3b, v46
	v_mul_f32_e32 v219, 0xbfb8aa3b, v47
	v_exp_f32_e32 v200, v200
	v_exp_f32_e32 v252, v252
	v_exp_f32_e32 v253, v253
	v_exp_f32_e32 v219, v219
	v_add_f32_e32 v200, 1.0, v200
	v_add_f32_e32 v252, 1.0, v252
	v_add_f32_e32 v253, 1.0, v253
	v_add_f32_e32 v219, 1.0, v219
	v_rcp_f32_e32 v200, v200
	v_rcp_f32_e32 v252, v252
	v_rcp_f32_e32 v253, v253
	v_rcp_f32_e32 v219, v219
	v_mul_f32_e32 v200, v44, v200
	v_mul_f32_e32 v252, v45, v252
	v_mul_f32_e32 v253, v46, v253
	v_mul_f32_e32 v219, v47, v219
	v_mul_f32_e32 v200, v200, v232
	v_mul_f32_e32 v252, v252, v233
	v_mul_f32_e32 v253, v253, v234
	v_mul_f32_e32 v219, v219, v235
	v_mul_f32_e32 v44, v200, v196
	v_mul_f32_e32 v45, v252, v197
	v_mul_f32_e32 v46, v253, v198
	v_mul_f32_e32 v47, v219, v199
	v_lshlrev_b32_e32 v192, 16, v164
	v_and_b32_e32 v193, 0xffff0000, v164
	v_lshlrev_b32_e32 v200, 16, v172
	v_and_b32_e32 v252, 0xffff0000, v172
	v_add_f32_e32 v192, v192, v200
	v_add_f32_e32 v193, v193, v252
	v_lshlrev_b32_e32 v194, 16, v165
	v_and_b32_e32 v195, 0xffff0000, v165
	v_lshlrev_b32_e32 v200, 16, v173
	v_and_b32_e32 v252, 0xffff0000, v173
	v_add_f32_e32 v194, v194, v200
	v_add_f32_e32 v195, v195, v252
	v_lshlrev_b32_e32 v196, 16, v166
	v_and_b32_e32 v197, 0xffff0000, v166
	v_lshlrev_b32_e32 v200, 16, v174
	v_and_b32_e32 v252, 0xffff0000, v174
	v_add_f32_e32 v196, v196, v200
	v_add_f32_e32 v197, v197, v252
	v_lshlrev_b32_e32 v198, 16, v167
	v_and_b32_e32 v199, 0xffff0000, v167
	v_lshlrev_b32_e32 v200, 16, v175
	v_and_b32_e32 v252, 0xffff0000, v175
	v_add_f32_e32 v198, v198, v200
	v_add_f32_e32 v199, v199, v252
	v_mul_f32_e32 v200, v192, v192
	v_mul_f32_e32 v252, v194, v194
	v_mul_f32_e32 v253, v196, v196
	v_mul_f32_e32 v219, v198, v198
	v_fmac_f32_e32 v200, v193, v193
	v_fmac_f32_e32 v252, v195, v195
	v_fmac_f32_e32 v253, v197, v197
	v_fmac_f32_e32 v219, v199, v199
	v_add_f32_e32 v200, v200, v252
	v_add_f32_e32 v253, v253, v219
	v_add_f32_e32 v200, v200, v253
	v_add_f32_e32 v249, v249, v200
	v_mul_f32_e32 v200, 0xbfb8aa3b, v32
	v_mul_f32_e32 v252, 0xbfb8aa3b, v33
	v_mul_f32_e32 v253, 0xbfb8aa3b, v34
	v_mul_f32_e32 v219, 0xbfb8aa3b, v35
	v_exp_f32_e32 v200, v200
	v_exp_f32_e32 v252, v252
	v_exp_f32_e32 v253, v253
	v_exp_f32_e32 v219, v219
	v_add_f32_e32 v200, 1.0, v200
	v_add_f32_e32 v252, 1.0, v252
	v_add_f32_e32 v253, 1.0, v253
	v_add_f32_e32 v219, 1.0, v219
	v_rcp_f32_e32 v200, v200
	v_rcp_f32_e32 v252, v252
	v_rcp_f32_e32 v253, v253
	v_rcp_f32_e32 v219, v219
	v_mul_f32_e32 v200, v32, v200
	v_mul_f32_e32 v252, v33, v252
	v_mul_f32_e32 v253, v34, v253
	v_mul_f32_e32 v219, v35, v219
	v_mul_f32_e32 v200, v200, v236
	v_mul_f32_e32 v252, v252, v237
	v_mul_f32_e32 v253, v253, v238
	v_mul_f32_e32 v219, v219, v239
	v_mul_f32_e32 v32, v200, v192
	v_mul_f32_e32 v33, v252, v193
	v_mul_f32_e32 v34, v253, v194
	v_mul_f32_e32 v35, v219, v195
	v_mul_f32_e32 v200, 0xbfb8aa3b, v24
	v_mul_f32_e32 v252, 0xbfb8aa3b, v25
	v_mul_f32_e32 v253, 0xbfb8aa3b, v26
	v_mul_f32_e32 v219, 0xbfb8aa3b, v27
	v_exp_f32_e32 v200, v200
	v_exp_f32_e32 v252, v252
	v_exp_f32_e32 v253, v253
	v_exp_f32_e32 v219, v219
	v_add_f32_e32 v200, 1.0, v200
	v_add_f32_e32 v252, 1.0, v252
	v_add_f32_e32 v253, 1.0, v253
	v_add_f32_e32 v219, 1.0, v219
	v_rcp_f32_e32 v200, v200
	v_rcp_f32_e32 v252, v252
	v_rcp_f32_e32 v253, v253
	v_rcp_f32_e32 v219, v219
	v_mul_f32_e32 v200, v24, v200
	v_mul_f32_e32 v252, v25, v252
	v_mul_f32_e32 v253, v26, v253
	v_mul_f32_e32 v219, v27, v219
	v_mul_f32_e32 v200, v200, v240
	v_mul_f32_e32 v252, v252, v241
	v_mul_f32_e32 v253, v253, v242
	v_mul_f32_e32 v219, v219, v243
	v_mul_f32_e32 v24, v200, v196
	v_mul_f32_e32 v25, v252, v197
	v_mul_f32_e32 v26, v253, v198
	v_mul_f32_e32 v27, v219, v199
	s_waitcnt vmcnt(4)
; __device__ __forceinline__ unsigned cvtpk(float lo, float hi) { f32x2 v = {lo, hi}; bf16x2_t b = __builtin_convertvector(v, bf16x2_t); return __builtin_bit_cast(unsigned, b); }
;     __device__ __forceinline__ void operator()(const af4 (&acc)[2][2][4][2], const pg8::Unit& u, int wr, int wc, int fr_, int fq_) const {
;     ...
;             for (int b_ = 0; b_ < 4; ++b_) {
;                 const int ai = b_ >> 1, mp = b_ & 1;
;                 int RRb = row0 + ai * 128 + mp * 32; asm volatile("" : "+v"(RRb));
;                 const size_t ob = (size_t)RRb * 1024 + col0; v4u of_[2][2], ob_[2][2];
; #pragma unroll
;                 for (int mi = 0; mi < 2; ++mi)
; #pragma unroll
;                     for (int bj = 0; bj < 2; ++bj) { of_[mi][bj] = *(const v4u*)(ON + ob + mi * 16 * 1024 + bj * 128); ob_[mi][bj] = *(const v4u*)(OBp + ob + mi * 16 * 1024 + bj * 128); }
; #pragma unroll
;                 for (int mi = 0; mi < 2; ++mi) { float q = 0.f;
; #pragma unroll
;                     for (int bj = 0; bj < 2; ++bj) { const v4u a = of_[mi][bj], c = ob_[mi][bj];
;                         const float o0 = bflo(a.x) + bflo(c.x), o1 = bfhi(a.x) + bfhi(c.x), o2 = bflo(a.y) + bflo(c.y), o3 = bfhi(a.y) + bfhi(c.y), o4 = bflo(a.z) + bflo(c.z), o5 = bfhi(a.z) + bfhi(c.z), o6 = bflo(a.w) + bflo(c.w), o7 = bfhi(a.w) + bfhi(c.w);
;                         q += (o0 * o0 + o1 * o1) + (o2 * o2 + o3 * o3) + (o4 * o4 + o5 * o5) + (o6 * o6 + o7 * o7); }
;                     ssq[ai * 4 + mp * 2 + mi] = q; }
;     ...
;                 for (int mi = 0; mi < 2; ++mi) { const float rstd = rs[ai * 4 + mp * 2 + mi];
; #pragma unroll
;                     for (int bj = 0; bj < 2; ++bj) { af4 v0 = acc[ai][bj][mp * 2 + mi][0], v1 = acc[ai][bj][mp * 2 + mi][1]; asm volatile("" : "+v"(v0), "+v"(v1)); const v4u a = of_[mi][bj], c = ob_[mi][bj];
; #pragma unroll
;                         for (int e = 0; e < 4; ++e) { v0[e] = v0[e] * sigmoidf_(v0[e]) * (rstd * nwv[bj][0][e]); v1[e] = v1[e] * sigmoidf_(v1[e]) * (rstd * nwv[bj][1][e]); }
;                         v4u w; w.x = cvtpk(v0[0] * (bflo(a.x) + bflo(c.x)), v0[1] * (bfhi(a.x) + bfhi(c.x))); w.y = cvtpk(v0[2] * (bflo(a.y) + bflo(c.y)), v0[3] * (bfhi(a.y) + bfhi(c.y)));
;                         w.z = cvtpk(v1[0] * (bflo(a.z) + bflo(c.z)), v1[1] * (bfhi(a.z) + bfhi(c.z))); w.w = cvtpk(v1[2] * (bflo(a.w) + bflo(c.w)), v1[3] * (bfhi(a.w) + bfhi(c.w)));
	v_lshlrev_b32_e32 v192, 16, v128
	v_and_b32_e32 v193, 0xffff0000, v128
	v_lshlrev_b32_e32 v200, 16, v136
	v_and_b32_e32 v252, 0xffff0000, v136
	v_add_f32_e32 v192, v192, v200
	v_add_f32_e32 v193, v193, v252
	v_lshlrev_b32_e32 v194, 16, v129
	v_and_b32_e32 v195, 0xffff0000, v129
	v_lshlrev_b32_e32 v200, 16, v137
	v_and_b32_e32 v252, 0xffff0000, v137
	v_add_f32_e32 v194, v194, v200
	v_add_f32_e32 v195, v195, v252
	v_lshlrev_b32_e32 v196, 16, v130
	v_and_b32_e32 v197, 0xffff0000, v130
	v_lshlrev_b32_e32 v200, 16, v138
	v_and_b32_e32 v252, 0xffff0000, v138
	v_add_f32_e32 v196, v196, v200
	v_add_f32_e32 v197, v197, v252
	v_lshlrev_b32_e32 v198, 16, v131
	v_and_b32_e32 v199, 0xffff0000, v131
	v_lshlrev_b32_e32 v200, 16, v139
	v_and_b32_e32 v252, 0xffff0000, v139
	v_add_f32_e32 v198, v198, v200
	v_add_f32_e32 v199, v199, v252
	v_mul_f32_e32 v200, v192, v192
	v_mul_f32_e32 v252, v194, v194
	v_mul_f32_e32 v253, v196, v196
	v_mul_f32_e32 v219, v198, v198
	v_fmac_f32_e32 v200, v193, v193
	v_fmac_f32_e32 v252, v195, v195
	v_fmac_f32_e32 v253, v197, v197
	v_fmac_f32_e32 v219, v199, v199
	v_add_f32_e32 v200, v200, v252
	v_add_f32_e32 v253, v253, v219
	v_add_f32_e32 v200, v200, v253
	v_add_f32_e32 v250, v250, v200
	v_mul_f32_e32 v200, 0xbfb8aa3b, v36
	v_mul_f32_e32 v252, 0xbfb8aa3b, v37
	v_mul_f32_e32 v253, 0xbfb8aa3b, v38
	v_mul_f32_e32 v219, 0xbfb8aa3b, v39
	v_exp_f32_e32 v200, v200
	v_exp_f32_e32 v252, v252
	v_exp_f32_e32 v253, v253
	v_exp_f32_e32 v219, v219
	v_add_f32_e32 v200, 1.0, v200
	v_add_f32_e32 v252, 1.0, v252
	v_add_f32_e32 v253, 1.0, v253
	v_add_f32_e32 v219, 1.0, v219
	v_rcp_f32_e32 v200, v200
	v_rcp_f32_e32 v252, v252
	v_rcp_f32_e32 v253, v253
	v_rcp_f32_e32 v219, v219
	v_mul_f32_e32 v200, v36, v200
	v_mul_f32_e32 v252, v37, v252
	v_mul_f32_e32 v253, v38, v253
	v_mul_f32_e32 v219, v39, v219
	v_mul_f32_e32 v200, v200, v228
	v_mul_f32_e32 v252, v252, v229
	v_mul_f32_e32 v253, v253, v230
	v_mul_f32_e32 v219, v219, v231
	v_mul_f32_e32 v36, v200, v192
	v_mul_f32_e32 v37, v252, v193
	v_mul_f32_e32 v38, v253, v194
	v_mul_f32_e32 v39, v219, v195
	v_mul_f32_e32 v200, 0xbfb8aa3b, v28
	v_mul_f32_e32 v252, 0xbfb8aa3b, v29
	v_mul_f32_e32 v253, 0xbfb8aa3b, v30
	v_mul_f32_e32 v219, 0xbfb8aa3b, v31
	v_exp_f32_e32 v200, v200
	v_exp_f32_e32 v252, v252
	v_exp_f32_e32 v253, v253
	v_exp_f32_e32 v219, v219
	v_add_f32_e32 v200, 1.0, v200
	v_add_f32_e32 v252, 1.0, v252
	v_add_f32_e32 v253, 1.0, v253
	v_add_f32_e32 v219, 1.0, v219
	v_rcp_f32_e32 v200, v200
	v_rcp_f32_e32 v252, v252
	v_rcp_f32_e32 v253, v253
	v_rcp_f32_e32 v219, v219
	v_mul_f32_e32 v200, v28, v200
	v_mul_f32_e32 v252, v29, v252
	v_mul_f32_e32 v253, v30, v253
	v_mul_f32_e32 v219, v31, v219
	v_mul_f32_e32 v200, v200, v232
	v_mul_f32_e32 v252, v252, v233
	v_mul_f32_e32 v253, v253, v234
	v_mul_f32_e32 v219, v219, v235
	v_mul_f32_e32 v28, v200, v196
	v_mul_f32_e32 v29, v252, v197
	v_mul_f32_e32 v30, v253, v198
	v_mul_f32_e32 v31, v219, v199
	v_lshlrev_b32_e32 v192, 16, v132
	v_and_b32_e32 v193, 0xffff0000, v132
	v_lshlrev_b32_e32 v200, 16, v140
	v_and_b32_e32 v252, 0xffff0000, v140
	v_add_f32_e32 v192, v192, v200
	v_add_f32_e32 v193, v193, v252
	v_lshlrev_b32_e32 v194, 16, v133
	v_and_b32_e32 v195, 0xffff0000, v133
	v_lshlrev_b32_e32 v200, 16, v141
	v_and_b32_e32 v252, 0xffff0000, v141
	v_add_f32_e32 v194, v194, v200
	v_add_f32_e32 v195, v195, v252
	v_lshlrev_b32_e32 v196, 16, v134
	v_and_b32_e32 v197, 0xffff0000, v134
	v_lshlrev_b32_e32 v200, 16, v142
	v_and_b32_e32 v252, 0xffff0000, v142
	v_add_f32_e32 v196, v196, v200
	v_add_f32_e32 v197, v197, v252
	v_lshlrev_b32_e32 v198, 16, v135
	v_and_b32_e32 v199, 0xffff0000, v135
	v_lshlrev_b32_e32 v200, 16, v143
	v_and_b32_e32 v252, 0xffff0000, v143
	v_add_f32_e32 v198, v198, v200
	v_add_f32_e32 v199, v199, v252
	v_mul_f32_e32 v200, v192, v192
	v_mul_f32_e32 v252, v194, v194
	v_mul_f32_e32 v253, v196, v196
	v_mul_f32_e32 v219, v198, v198
	v_fmac_f32_e32 v200, v193, v193
	v_fmac_f32_e32 v252, v195, v195
	v_fmac_f32_e32 v253, v197, v197
	v_fmac_f32_e32 v219, v199, v199
	v_add_f32_e32 v200, v200, v252
	v_add_f32_e32 v253, v253, v219
	v_add_f32_e32 v200, v200, v253
	v_add_f32_e32 v250, v250, v200
	v_mul_f32_e32 v200, 0xbfb8aa3b, v16
	v_mul_f32_e32 v252, 0xbfb8aa3b, v17
	v_mul_f32_e32 v253, 0xbfb8aa3b, v18
	v_mul_f32_e32 v219, 0xbfb8aa3b, v19
	v_exp_f32_e32 v200, v200
	v_exp_f32_e32 v252, v252
	v_exp_f32_e32 v253, v253
	v_exp_f32_e32 v219, v219
	v_add_f32_e32 v200, 1.0, v200
	v_add_f32_e32 v252, 1.0, v252
	v_add_f32_e32 v253, 1.0, v253
	v_add_f32_e32 v219, 1.0, v219
	v_rcp_f32_e32 v200, v200
	v_rcp_f32_e32 v252, v252
	v_rcp_f32_e32 v253, v253
	v_rcp_f32_e32 v219, v219
	v_mul_f32_e32 v200, v16, v200
	v_mul_f32_e32 v252, v17, v252
	v_mul_f32_e32 v253, v18, v253
	v_mul_f32_e32 v219, v19, v219
	v_mul_f32_e32 v200, v200, v236
	v_mul_f32_e32 v252, v252, v237
	v_mul_f32_e32 v253, v253, v238
	v_mul_f32_e32 v219, v219, v239
	v_mul_f32_e32 v16, v200, v192
	v_mul_f32_e32 v17, v252, v193
	v_mul_f32_e32 v18, v253, v194
	v_mul_f32_e32 v19, v219, v195
	v_mul_f32_e32 v200, 0xbfb8aa3b, v8
	v_mul_f32_e32 v252, 0xbfb8aa3b, v9
	v_mul_f32_e32 v253, 0xbfb8aa3b, v10
	v_mul_f32_e32 v219, 0xbfb8aa3b, v11
	v_exp_f32_e32 v200, v200
	v_exp_f32_e32 v252, v252
	v_exp_f32_e32 v253, v253
	v_exp_f32_e32 v219, v219
	v_add_f32_e32 v200, 1.0, v200
	v_add_f32_e32 v252, 1.0, v252
	v_add_f32_e32 v253, 1.0, v253
	v_add_f32_e32 v219, 1.0, v219
	v_rcp_f32_e32 v200, v200
	v_rcp_f32_e32 v252, v252
	v_rcp_f32_e32 v253, v253
	v_rcp_f32_e32 v219, v219
	v_mul_f32_e32 v200, v8, v200
	v_mul_f32_e32 v252, v9, v252
	v_mul_f32_e32 v253, v10, v253
	v_mul_f32_e32 v219, v11, v219
	v_mul_f32_e32 v200, v200, v240
	v_mul_f32_e32 v252, v252, v241
	v_mul_f32_e32 v253, v253, v242
	v_mul_f32_e32 v219, v219, v243
	v_mul_f32_e32 v8, v200, v196
	v_mul_f32_e32 v9, v252, v197
	v_mul_f32_e32 v10, v253, v198
	v_mul_f32_e32 v11, v219, v199
	s_waitcnt vmcnt(0)
; __device__ __forceinline__ unsigned cvtpk(float lo, float hi) { f32x2 v = {lo, hi}; bf16x2_t b = __builtin_convertvector(v, bf16x2_t); return __builtin_bit_cast(unsigned, b); }
; __device__ __forceinline__ float bflo(unsigned u) { return __uint_as_float(u << 16); }
; __device__ __forceinline__ float bfhi(unsigned u) { return __uint_as_float(u & 0xffff0000u); }
;     __device__ __forceinline__ void operator()(const af4 (&acc)[2][2][4][2], const pg8::Unit& u, int wr, int wc, int fr_, int fq_) const {
;     ...
;                 for (int mi = 0; mi < 2; ++mi) { float q = 0.f;
; #pragma unroll
;                     for (int bj = 0; bj < 2; ++bj) { const v4u a = of_[mi][bj], c = ob_[mi][bj];
;                         const float o0 = bflo(a.x) + bflo(c.x), o1 = bfhi(a.x) + bfhi(c.x), o2 = bflo(a.y) + bflo(c.y), o3 = bfhi(a.y) + bfhi(c.y), o4 = bflo(a.z) + bflo(c.z), o5 = bfhi(a.z) + bfhi(c.z), o6 = bflo(a.w) + bflo(c.w), o7 = bfhi(a.w) + bfhi(c.w);
;                         q += (o0 * o0 + o1 * o1) + (o2 * o2 + o3 * o3) + (o4 * o4 + o5 * o5) + (o6 * o6 + o7 * o7); }
;                     ssq[ai * 4 + mp * 2 + mi] = q; }
;                 asm volatile("" ::: "memory");
;             }
; #pragma unroll
;             for (int k = 0; k < 8; ++k) { float v = ssq[k];
;                 v += __int_as_float(__builtin_amdgcn_ds_bpermute((ln_ ^ 16) << 2, __float_as_int(v)));
;                 v += __int_as_float(__builtin_amdgcn_ds_bpermute((ln_ ^ 32) << 2, __float_as_int(v))); ssq[k] = v; }
;     ...
;                 for (int mi = 0; mi < 2; ++mi) { const float rstd = rs[ai * 4 + mp * 2 + mi];
; #pragma unroll
;                     for (int bj = 0; bj < 2; ++bj) { af4 v0 = acc[ai][bj][mp * 2 + mi][0], v1 = acc[ai][bj][mp * 2 + mi][1]; asm volatile("" : "+v"(v0), "+v"(v1)); const v4u a = of_[mi][bj], c = ob_[mi][bj];
; #pragma unroll
;                         for (int e = 0; e < 4; ++e) { v0[e] = v0[e] * sigmoidf_(v0[e]) * (rstd * nwv[bj][0][e]); v1[e] = v1[e] * sigmoidf_(v1[e]) * (rstd * nwv[bj][1][e]); }
;                         v4u w; w.x = cvtpk(v0[0] * (bflo(a.x) + bflo(c.x)), v0[1] * (bfhi(a.x) + bfhi(c.x))); w.y = cvtpk(v0[2] * (bflo(a.y) + bflo(c.y)), v0[3] * (bfhi(a.y) + bfhi(c.y)));
;                         w.z = cvtpk(v1[0] * (bflo(a.z) + bflo(c.z)), v1[1] * (bfhi(a.z) + bfhi(c.z))); w.w = cvtpk(v1[2] * (bflo(a.w) + bflo(c.w)), v1[3] * (bfhi(a.w) + bfhi(c.w)));
	v_lshlrev_b32_e32 v192, 16, v144
	v_and_b32_e32 v193, 0xffff0000, v144
	v_lshlrev_b32_e32 v200, 16, v152
	v_and_b32_e32 v252, 0xffff0000, v152
	v_add_f32_e32 v192, v192, v200
	v_add_f32_e32 v193, v193, v252
	v_lshlrev_b32_e32 v194, 16, v145
	v_and_b32_e32 v195, 0xffff0000, v145
	v_lshlrev_b32_e32 v200, 16, v153
	v_and_b32_e32 v252, 0xffff0000, v153
	v_add_f32_e32 v194, v194, v200
	v_add_f32_e32 v195, v195, v252
	v_lshlrev_b32_e32 v196, 16, v146
	v_and_b32_e32 v197, 0xffff0000, v146
	v_lshlrev_b32_e32 v200, 16, v154
	v_and_b32_e32 v252, 0xffff0000, v154
	v_add_f32_e32 v196, v196, v200
	v_add_f32_e32 v197, v197, v252
	v_lshlrev_b32_e32 v198, 16, v147
	v_and_b32_e32 v199, 0xffff0000, v147
	v_lshlrev_b32_e32 v200, 16, v155
	v_and_b32_e32 v252, 0xffff0000, v155
	v_add_f32_e32 v198, v198, v200
	v_add_f32_e32 v199, v199, v252
	v_mul_f32_e32 v200, v192, v192
	v_mul_f32_e32 v252, v194, v194
	v_mul_f32_e32 v253, v196, v196
	v_mul_f32_e32 v219, v198, v198
	v_fmac_f32_e32 v200, v193, v193
	v_fmac_f32_e32 v252, v195, v195
	v_fmac_f32_e32 v253, v197, v197
	v_fmac_f32_e32 v219, v199, v199
	v_add_f32_e32 v200, v200, v252
	v_add_f32_e32 v253, v253, v219
	v_add_f32_e32 v200, v200, v253
	v_add_f32_e32 v251, v251, v200
	v_mul_f32_e32 v200, 0xbfb8aa3b, v20
	v_mul_f32_e32 v252, 0xbfb8aa3b, v21
	v_mul_f32_e32 v253, 0xbfb8aa3b, v22
	v_mul_f32_e32 v219, 0xbfb8aa3b, v23
	v_exp_f32_e32 v200, v200
	v_exp_f32_e32 v252, v252
	v_exp_f32_e32 v253, v253
	v_exp_f32_e32 v219, v219
	v_add_f32_e32 v200, 1.0, v200
	v_add_f32_e32 v252, 1.0, v252
	v_add_f32_e32 v253, 1.0, v253
	v_add_f32_e32 v219, 1.0, v219
	v_rcp_f32_e32 v200, v200
	v_rcp_f32_e32 v252, v252
	v_rcp_f32_e32 v253, v253
	v_rcp_f32_e32 v219, v219
	v_mul_f32_e32 v200, v20, v200
	v_mul_f32_e32 v252, v21, v252
	v_mul_f32_e32 v253, v22, v253
	v_mul_f32_e32 v219, v23, v219
	v_mul_f32_e32 v200, v200, v228
	v_mul_f32_e32 v252, v252, v229
	v_mul_f32_e32 v253, v253, v230
	v_mul_f32_e32 v219, v219, v231
	v_mul_f32_e32 v20, v200, v192
	v_mul_f32_e32 v21, v252, v193
	v_mul_f32_e32 v22, v253, v194
	v_mul_f32_e32 v23, v219, v195
	v_mul_f32_e32 v200, 0xbfb8aa3b, v12
	v_mul_f32_e32 v252, 0xbfb8aa3b, v13
	v_mul_f32_e32 v253, 0xbfb8aa3b, v14
	v_mul_f32_e32 v219, 0xbfb8aa3b, v15
	v_exp_f32_e32 v200, v200
	v_exp_f32_e32 v252, v252
	v_exp_f32_e32 v253, v253
	v_exp_f32_e32 v219, v219
	v_add_f32_e32 v200, 1.0, v200
	v_add_f32_e32 v252, 1.0, v252
	v_add_f32_e32 v253, 1.0, v253
	v_add_f32_e32 v219, 1.0, v219
	v_rcp_f32_e32 v200, v200
	v_rcp_f32_e32 v252, v252
	v_rcp_f32_e32 v253, v253
	v_rcp_f32_e32 v219, v219
	v_mul_f32_e32 v200, v12, v200
	v_mul_f32_e32 v252, v13, v252
	v_mul_f32_e32 v253, v14, v253
	v_mul_f32_e32 v219, v15, v219
	v_mul_f32_e32 v200, v200, v232
	v_mul_f32_e32 v252, v252, v233
	v_mul_f32_e32 v253, v253, v234
	v_mul_f32_e32 v219, v219, v235
	v_mul_f32_e32 v12, v200, v196
	v_mul_f32_e32 v13, v252, v197
	v_mul_f32_e32 v14, v253, v198
	v_mul_f32_e32 v15, v219, v199
	v_lshlrev_b32_e32 v192, 16, v148
	v_and_b32_e32 v193, 0xffff0000, v148
	v_lshlrev_b32_e32 v200, 16, v156
	v_and_b32_e32 v252, 0xffff0000, v156
	v_add_f32_e32 v192, v192, v200
	v_add_f32_e32 v193, v193, v252
	v_lshlrev_b32_e32 v194, 16, v149
	v_and_b32_e32 v195, 0xffff0000, v149
	v_lshlrev_b32_e32 v200, 16, v157
	v_and_b32_e32 v252, 0xffff0000, v157
	v_add_f32_e32 v194, v194, v200
	v_add_f32_e32 v195, v195, v252
	v_lshlrev_b32_e32 v196, 16, v150
	v_and_b32_e32 v197, 0xffff0000, v150
	v_lshlrev_b32_e32 v200, 16, v158
	v_and_b32_e32 v252, 0xffff0000, v158
	v_add_f32_e32 v196, v196, v200
	v_add_f32_e32 v197, v197, v252
	v_lshlrev_b32_e32 v198, 16, v151
	v_and_b32_e32 v199, 0xffff0000, v151
	v_lshlrev_b32_e32 v200, 16, v159
	v_and_b32_e32 v252, 0xffff0000, v159
	v_add_f32_e32 v198, v198, v200
	v_add_f32_e32 v199, v199, v252
	v_mul_f32_e32 v200, v192, v192
	v_mul_f32_e32 v252, v194, v194
	v_mul_f32_e32 v253, v196, v196
	v_mul_f32_e32 v219, v198, v198
	v_fmac_f32_e32 v200, v193, v193
	v_fmac_f32_e32 v252, v195, v195
	v_fmac_f32_e32 v253, v197, v197
	v_fmac_f32_e32 v219, v199, v199
	v_add_f32_e32 v200, v200, v252
	v_add_f32_e32 v253, v253, v219
	v_add_f32_e32 v200, v200, v253
	v_add_f32_e32 v251, v251, v200
	v_mul_f32_e32 v200, 0xbfb8aa3b, v4
	v_mul_f32_e32 v252, 0xbfb8aa3b, v5
	v_mul_f32_e32 v253, 0xbfb8aa3b, v6
	v_mul_f32_e32 v219, 0xbfb8aa3b, v7
	v_exp_f32_e32 v200, v200
	v_exp_f32_e32 v252, v252
	v_exp_f32_e32 v253, v253
	v_exp_f32_e32 v219, v219
	v_add_f32_e32 v200, 1.0, v200
	v_add_f32_e32 v252, 1.0, v252
	v_add_f32_e32 v253, 1.0, v253
	v_add_f32_e32 v219, 1.0, v219
	v_rcp_f32_e32 v200, v200
	v_rcp_f32_e32 v252, v252
	v_rcp_f32_e32 v253, v253
	v_rcp_f32_e32 v219, v219
	v_mul_f32_e32 v200, v4, v200
	v_mul_f32_e32 v252, v5, v252
	v_mul_f32_e32 v253, v6, v253
	v_mul_f32_e32 v219, v7, v219
	v_mul_f32_e32 v200, v200, v236
	v_mul_f32_e32 v252, v252, v237
	v_mul_f32_e32 v253, v253, v238
	v_mul_f32_e32 v219, v219, v239
	v_mul_f32_e32 v4, v200, v192
	v_mul_f32_e32 v5, v252, v193
	v_mul_f32_e32 v6, v253, v194
	v_mul_f32_e32 v7, v219, v195
	v_mul_f32_e32 v200, 0xbfb8aa3b, v0
	v_mul_f32_e32 v252, 0xbfb8aa3b, v1
	v_mul_f32_e32 v253, 0xbfb8aa3b, v2
	v_mul_f32_e32 v219, 0xbfb8aa3b, v3
	v_exp_f32_e32 v200, v200
	v_exp_f32_e32 v252, v252
	v_exp_f32_e32 v253, v253
	v_exp_f32_e32 v219, v219
	v_add_f32_e32 v200, 1.0, v200
	v_add_f32_e32 v252, 1.0, v252
	v_add_f32_e32 v253, 1.0, v253
	v_add_f32_e32 v219, 1.0, v219
	v_rcp_f32_e32 v200, v200
	v_rcp_f32_e32 v252, v252
	v_rcp_f32_e32 v253, v253
	v_rcp_f32_e32 v219, v219
	v_mul_f32_e32 v200, v0, v200
	v_mul_f32_e32 v252, v1, v252
	v_mul_f32_e32 v253, v2, v253
	v_mul_f32_e32 v219, v3, v219
	v_mul_f32_e32 v200, v200, v240
	v_mul_f32_e32 v252, v252, v241
	v_mul_f32_e32 v253, v253, v242
	v_mul_f32_e32 v219, v219, v243
	v_mul_f32_e32 v0, v200, v196
	v_mul_f32_e32 v1, v252, v197
	v_mul_f32_e32 v2, v253, v198
	v_mul_f32_e32 v3, v219, v199
	ds_bpermute_b32 v200, v226, v244
	ds_bpermute_b32 v252, v226, v245
	ds_bpermute_b32 v253, v226, v246
	ds_bpermute_b32 v219, v226, v247
	s_waitcnt lgkmcnt(0)
; #define LAS __attribute__((address_space(3)))
; __device__ __forceinline__ unsigned cvtpk(float lo, float hi) { f32x2 v = {lo, hi}; bf16x2_t b = __builtin_convertvector(v, bf16x2_t); return __builtin_bit_cast(unsigned, b); }
; __device__ __forceinline__ float bflo(unsigned u) { return __uint_as_float(u << 16); }
;     __device__ __forceinline__ void operator()(const af4 (&acc)[2][2][4][2], const pg8::Unit& u, int wr, int wc, int fr_, int fq_) const {
;     ...
; #pragma unroll
;             for (int k = 0; k < 8; ++k) { float v = ssq[k];
;                 v += __int_as_float(__builtin_amdgcn_ds_bpermute((ln_ ^ 16) << 2, __float_as_int(v)));
;                 v += __int_as_float(__builtin_amdgcn_ds_bpermute((ln_ ^ 32) << 2, __float_as_int(v))); ssq[k] = v; }
;             if (fq == 0) {
; #pragma unroll
;                 for (int k = 0; k < 8; ++k) xch[((k >> 2) * 128 + wr * 64 + (k & 3) * 16 + fr) * 4 + wc] = ssq[k];
;             }
;             asm volatile("s_waitcnt lgkmcnt(0)" ::: "memory"); __builtin_amdgcn_s_barrier(); asm volatile("" ::: "memory");
;             float rs[8];
; #pragma unroll
;             for (int k = 0; k < 8; ++k) { const f32x4 p4 = *(const LAS f32x4*)(xch + ((k >> 2) * 128 + wr * 64 + (k & 3) * 16 + fr) * 4);
;                 rs[k] = 1.0f / sqrtf(((p4[0] + p4[1]) + (p4[2] + p4[3])) * (1.f / 256.f) + LN_EPS); }
;     ...
;                 for (int mi = 0; mi < 2; ++mi) { const float rstd = rs[ai * 4 + mp * 2 + mi];
; #pragma unroll
;                     for (int bj = 0; bj < 2; ++bj) { af4 v0 = acc[ai][bj][mp * 2 + mi][0], v1 = acc[ai][bj][mp * 2 + mi][1]; asm volatile("" : "+v"(v0), "+v"(v1)); const v4u a = of_[mi][bj], c = ob_[mi][bj];
; #pragma unroll
;                         for (int e = 0; e < 4; ++e) { v0[e] = v0[e] * sigmoidf_(v0[e]) * (rstd * nwv[bj][0][e]); v1[e] = v1[e] * sigmoidf_(v1[e]) * (rstd * nwv[bj][1][e]); }
;                         v4u w; w.x = cvtpk(v0[0] * (bflo(a.x) + bflo(c.x)), v0[1] * (bfhi(a.x) + bfhi(c.x))); w.y = cvtpk(v0[2] * (bflo(a.y) + bflo(c.y)), v0[3] * (bfhi(a.y) + bfhi(c.y)));
;                         w.z = cvtpk(v1[0] * (bflo(a.z) + bflo(c.z)), v1[1] * (bfhi(a.z) + bfhi(c.z))); w.w = cvtpk(v1[2] * (bflo(a.w) + bflo(c.w)), v1[3] * (bfhi(a.w) + bfhi(c.w)));
;                         *(v4u*)(ON + ob + mi * 16 * 1024 + bj * 128) = w; } }
	v_add_f32_e32 v244, v244, v200
	v_add_f32_e32 v245, v245, v252
	v_add_f32_e32 v246, v246, v253
	v_add_f32_e32 v247, v247, v219
	ds_bpermute_b32 v200, v226, v248
	ds_bpermute_b32 v252, v226, v249
	ds_bpermute_b32 v253, v226, v250
	ds_bpermute_b32 v219, v226, v251
	s_waitcnt lgkmcnt(0)
	v_add_f32_e32 v248, v248, v200
	v_add_f32_e32 v249, v249, v252
	v_add_f32_e32 v250, v250, v253
	v_add_f32_e32 v251, v251, v219
	ds_bpermute_b32 v200, v227, v244
	ds_bpermute_b32 v252, v227, v245
	ds_bpermute_b32 v253, v227, v246
	ds_bpermute_b32 v219, v227, v247
	s_waitcnt lgkmcnt(0)
	v_add_f32_e32 v244, v244, v200
	v_add_f32_e32 v245, v245, v252
	v_add_f32_e32 v246, v246, v253
	v_add_f32_e32 v247, v247, v219
	ds_bpermute_b32 v200, v227, v248
	ds_bpermute_b32 v252, v227, v249
	ds_bpermute_b32 v253, v227, v250
	ds_bpermute_b32 v219, v227, v251
	s_waitcnt lgkmcnt(0)
	v_add_f32_e32 v248, v248, v200
	v_add_f32_e32 v249, v249, v252
	v_add_f32_e32 v250, v250, v253
	v_add_f32_e32 v251, v251, v219
	ds_write_b32 v224, v244 offset:0
	ds_write_b32 v224, v245 offset:256
	ds_write_b32 v224, v246 offset:512
	ds_write_b32 v224, v247 offset:768
	ds_write_b32 v224, v248 offset:2048
	ds_write_b32 v224, v249 offset:2304
	ds_write_b32 v224, v250 offset:2560
	ds_write_b32 v224, v251 offset:2816
	s_waitcnt lgkmcnt(0)
	s_barrier
	ds_read_b128 v[128:131], v225 offset:0
	ds_read_b128 v[132:135], v225 offset:256
	ds_read_b128 v[136:139], v225 offset:512
	ds_read_b128 v[140:143], v225 offset:768
	ds_read_b128 v[144:147], v225 offset:2048
	ds_read_b128 v[148:151], v225 offset:2304
	ds_read_b128 v[152:155], v225 offset:2560
	ds_read_b128 v[156:159], v225 offset:2816
	s_waitcnt lgkmcnt(0)
	v_add_f32_e32 v128, v128, v129
	v_add_f32_e32 v130, v130, v131
	v_add_f32_e32 v128, v128, v130
	v_mul_f32_e32 v128, 0x3b800000, v128
	v_add_f32_e32 v128, 0x358637bd, v128
	v_add_f32_e32 v132, v132, v133
	v_add_f32_e32 v134, v134, v135
	v_add_f32_e32 v132, v132, v134
	v_mul_f32_e32 v132, 0x3b800000, v132
	v_add_f32_e32 v132, 0x358637bd, v132
	v_add_f32_e32 v136, v136, v137
	v_add_f32_e32 v138, v138, v139
	v_add_f32_e32 v136, v136, v138
	v_mul_f32_e32 v136, 0x3b800000, v136
	v_add_f32_e32 v136, 0x358637bd, v136
	v_add_f32_e32 v140, v140, v141
	v_add_f32_e32 v142, v142, v143
	v_add_f32_e32 v140, v140, v142
	v_mul_f32_e32 v140, 0x3b800000, v140
	v_add_f32_e32 v140, 0x358637bd, v140
	v_add_f32_e32 v144, v144, v145
	v_add_f32_e32 v146, v146, v147
	v_add_f32_e32 v144, v144, v146
	v_mul_f32_e32 v144, 0x3b800000, v144
	v_add_f32_e32 v144, 0x358637bd, v144
	v_add_f32_e32 v148, v148, v149
	v_add_f32_e32 v150, v150, v151
	v_add_f32_e32 v148, v148, v150
	v_mul_f32_e32 v148, 0x3b800000, v148
	v_add_f32_e32 v148, 0x358637bd, v148
	v_add_f32_e32 v152, v152, v153
	v_add_f32_e32 v154, v154, v155
	v_add_f32_e32 v152, v152, v154
	v_mul_f32_e32 v152, 0x3b800000, v152
	v_add_f32_e32 v152, 0x358637bd, v152
	v_add_f32_e32 v156, v156, v157
	v_add_f32_e32 v158, v158, v159
	v_add_f32_e32 v156, v156, v158
	v_mul_f32_e32 v156, 0x3b800000, v156
	v_add_f32_e32 v156, 0x358637bd, v156
	v_rsq_f32_e32 v244, v128
	v_rsq_f32_e32 v245, v132
	v_rsq_f32_e32 v246, v136
	v_rsq_f32_e32 v247, v140
	v_rsq_f32_e32 v248, v144
	v_rsq_f32_e32 v249, v148
	v_rsq_f32_e32 v250, v152
	v_rsq_f32_e32 v251, v156
	v_subrev_co_u32_e32 v220, vcc, 0x58000, v220
	s_nop 1
	v_subbrev_co_u32_e32 v221, vcc, 0, v221, vcc
	v_mul_f32_e32 v124, v124, v244
	v_mul_f32_e32 v125, v125, v244
	v_mul_f32_e32 v126, v126, v244
	v_mul_f32_e32 v127, v127, v244
	v_mul_f32_e32 v120, v120, v244
	v_mul_f32_e32 v121, v121, v244
	v_mul_f32_e32 v122, v122, v244
	v_mul_f32_e32 v123, v123, v244
	v_cvt_pk_bf16_f32 v160, v124, v125
	v_cvt_pk_bf16_f32 v161, v126, v127
	v_cvt_pk_bf16_f32 v162, v120, v121
	v_cvt_pk_bf16_f32 v163, v122, v123
	global_store_dwordx4 v[220:221], v[160:163], off
	v_mul_f32_e32 v112, v112, v244
	v_mul_f32_e32 v113, v113, v244
	v_mul_f32_e32 v114, v114, v244
	v_mul_f32_e32 v115, v115, v244
	v_mul_f32_e32 v104, v104, v244
	v_mul_f32_e32 v105, v105, v244
	v_mul_f32_e32 v106, v106, v244
	v_mul_f32_e32 v107, v107, v244
	v_cvt_pk_bf16_f32 v164, v112, v113
	v_cvt_pk_bf16_f32 v165, v114, v115
	v_cvt_pk_bf16_f32 v166, v104, v105
	v_cvt_pk_bf16_f32 v167, v106, v107
	global_store_dwordx4 v[220:221], v[164:167], off offset:256
	s_nop 0
	v_add_co_u32_e32 v220, vcc, 0x8000, v220
	s_nop 1
	v_addc_co_u32_e32 v221, vcc, 0, v221, vcc
	v_mul_f32_e32 v116, v116, v245
	v_mul_f32_e32 v117, v117, v245
	v_mul_f32_e32 v118, v118, v245
	v_mul_f32_e32 v119, v119, v245
	v_mul_f32_e32 v108, v108, v245
	v_mul_f32_e32 v109, v109, v245
	v_mul_f32_e32 v110, v110, v245
	v_mul_f32_e32 v111, v111, v245
	v_cvt_pk_bf16_f32 v160, v116, v117
	v_cvt_pk_bf16_f32 v161, v118, v119
	v_cvt_pk_bf16_f32 v162, v108, v109
	v_cvt_pk_bf16_f32 v163, v110, v111
	global_store_dwordx4 v[220:221], v[160:163], off
	v_mul_f32_e32 v96, v96, v245
	v_mul_f32_e32 v97, v97, v245
	v_mul_f32_e32 v98, v98, v245
	v_mul_f32_e32 v99, v99, v245
	v_mul_f32_e32 v88, v88, v245
	v_mul_f32_e32 v89, v89, v245
	v_mul_f32_e32 v90, v90, v245
	v_mul_f32_e32 v91, v91, v245
	v_cvt_pk_bf16_f32 v164, v96, v97
	v_cvt_pk_bf16_f32 v165, v98, v99
	v_cvt_pk_bf16_f32 v166, v88, v89
	v_cvt_pk_bf16_f32 v167, v90, v91
	global_store_dwordx4 v[220:221], v[164:167], off offset:256
	s_nop 0
	v_add_co_u32_e32 v220, vcc, 0x8000, v220
	s_nop 1
	v_addc_co_u32_e32 v221, vcc, 0, v221, vcc
	v_mul_f32_e32 v100, v100, v246
	v_mul_f32_e32 v101, v101, v246
	v_mul_f32_e32 v102, v102, v246
	v_mul_f32_e32 v103, v103, v246
	v_mul_f32_e32 v92, v92, v246
; __device__ __forceinline__ unsigned cvtpk(float lo, float hi) { f32x2 v = {lo, hi}; bf16x2_t b = __builtin_convertvector(v, bf16x2_t); return __builtin_bit_cast(unsigned, b); }
; __device__ __forceinline__ float bflo(unsigned u) { return __uint_as_float(u << 16); }
; __device__ __forceinline__ float bfhi(unsigned u) { return __uint_as_float(u & 0xffff0000u); }
; __device__ __forceinline__ float sigmoidf_(float x) { return __builtin_amdgcn_rcpf(1.0f + __expf(-x)); }
;     __device__ __forceinline__ void operator()(const af4 (&acc)[2][2][4][2], const pg8::Unit& u, int wr, int wc, int fr_, int fq_) const {
;     ...
;                 for (int mi = 0; mi < 2; ++mi) { const float rstd = rs[ai * 4 + mp * 2 + mi];
; #pragma unroll
;                     for (int bj = 0; bj < 2; ++bj) { af4 v0 = acc[ai][bj][mp * 2 + mi][0], v1 = acc[ai][bj][mp * 2 + mi][1]; asm volatile("" : "+v"(v0), "+v"(v1)); const v4u a = of_[mi][bj], c = ob_[mi][bj];
; #pragma unroll
;                         for (int e = 0; e < 4; ++e) { v0[e] = v0[e] * sigmoidf_(v0[e]) * (rstd * nwv[bj][0][e]); v1[e] = v1[e] * sigmoidf_(v1[e]) * (rstd * nwv[bj][1][e]); }
;                         v4u w; w.x = cvtpk(v0[0] * (bflo(a.x) + bflo(c.x)), v0[1] * (bfhi(a.x) + bfhi(c.x))); w.y = cvtpk(v0[2] * (bflo(a.y) + bflo(c.y)), v0[3] * (bfhi(a.y) + bfhi(c.y)));
;                         w.z = cvtpk(v1[0] * (bflo(a.z) + bflo(c.z)), v1[1] * (bfhi(a.z) + bfhi(c.z))); w.w = cvtpk(v1[2] * (bflo(a.w) + bflo(c.w)), v1[3] * (bfhi(a.w) + bfhi(c.w)));
;                         *(v4u*)(ON + ob + mi * 16 * 1024 + bj * 128) = w; } }
	v_mul_f32_e32 v93, v93, v246
	v_mul_f32_e32 v94, v94, v246
	v_mul_f32_e32 v95, v95, v246
	v_cvt_pk_bf16_f32 v160, v100, v101
	v_cvt_pk_bf16_f32 v161, v102, v103
	v_cvt_pk_bf16_f32 v162, v92, v93
	v_cvt_pk_bf16_f32 v163, v94, v95
	global_store_dwordx4 v[220:221], v[160:163], off
	v_mul_f32_e32 v80, v80, v246
	v_mul_f32_e32 v81, v81, v246
	v_mul_f32_e32 v82, v82, v246
	v_mul_f32_e32 v83, v83, v246
	v_mul_f32_e32 v72, v72, v246
	v_mul_f32_e32 v73, v73, v246
	v_mul_f32_e32 v74, v74, v246
	v_mul_f32_e32 v75, v75, v246
	v_cvt_pk_bf16_f32 v164, v80, v81
	v_cvt_pk_bf16_f32 v165, v82, v83
	v_cvt_pk_bf16_f32 v166, v72, v73
	v_cvt_pk_bf16_f32 v167, v74, v75
	global_store_dwordx4 v[220:221], v[164:167], off offset:256
	s_nop 0
	v_add_co_u32_e32 v220, vcc, 0x8000, v220
	s_nop 1
	v_addc_co_u32_e32 v221, vcc, 0, v221, vcc
	v_mul_f32_e32 v84, v84, v247
	v_mul_f32_e32 v85, v85, v247
	v_mul_f32_e32 v86, v86, v247
	v_mul_f32_e32 v87, v87, v247
	v_mul_f32_e32 v76, v76, v247
	v_mul_f32_e32 v77, v77, v247
	v_mul_f32_e32 v78, v78, v247
	v_mul_f32_e32 v79, v79, v247
	v_cvt_pk_bf16_f32 v160, v84, v85
	v_cvt_pk_bf16_f32 v161, v86, v87
	v_cvt_pk_bf16_f32 v162, v76, v77
	v_cvt_pk_bf16_f32 v163, v78, v79
	global_store_dwordx4 v[220:221], v[160:163], off
	v_mul_f32_e32 v68, v68, v247
	v_mul_f32_e32 v69, v69, v247
	v_mul_f32_e32 v70, v70, v247
	v_mul_f32_e32 v71, v71, v247
	v_mul_f32_e32 v64, v64, v247
	v_mul_f32_e32 v65, v65, v247
	v_mul_f32_e32 v66, v66, v247
	v_mul_f32_e32 v67, v67, v247
	v_cvt_pk_bf16_f32 v164, v68, v69
	v_cvt_pk_bf16_f32 v165, v70, v71
	v_cvt_pk_bf16_f32 v166, v64, v65
	v_cvt_pk_bf16_f32 v167, v66, v67
	global_store_dwordx4 v[220:221], v[164:167], off offset:256
	s_nop 0
	v_add_co_u32_e32 v220, vcc, 0x28000, v220
	s_nop 1
	v_addc_co_u32_e32 v221, vcc, 0, v221, vcc
	v_mul_f32_e32 v60, v60, v248
	v_mul_f32_e32 v61, v61, v248
	v_mul_f32_e32 v62, v62, v248
	v_mul_f32_e32 v63, v63, v248
	v_mul_f32_e32 v56, v56, v248
	v_mul_f32_e32 v57, v57, v248
	v_mul_f32_e32 v58, v58, v248
	v_mul_f32_e32 v59, v59, v248
	v_cvt_pk_bf16_f32 v160, v60, v61
	v_cvt_pk_bf16_f32 v161, v62, v63
	v_cvt_pk_bf16_f32 v162, v56, v57
	v_cvt_pk_bf16_f32 v163, v58, v59
	global_store_dwordx4 v[220:221], v[160:163], off
	v_mul_f32_e32 v48, v48, v248
	v_mul_f32_e32 v49, v49, v248
	v_mul_f32_e32 v50, v50, v248
	v_mul_f32_e32 v51, v51, v248
	v_mul_f32_e32 v40, v40, v248
	v_mul_f32_e32 v41, v41, v248
	v_mul_f32_e32 v42, v42, v248
	v_mul_f32_e32 v43, v43, v248
	v_cvt_pk_bf16_f32 v164, v48, v49
	v_cvt_pk_bf16_f32 v165, v50, v51
	v_cvt_pk_bf16_f32 v166, v40, v41
	v_cvt_pk_bf16_f32 v167, v42, v43
	global_store_dwordx4 v[220:221], v[164:167], off offset:256
	s_nop 0
	v_add_co_u32_e32 v220, vcc, 0x8000, v220
	s_nop 1
	v_addc_co_u32_e32 v221, vcc, 0, v221, vcc
	v_mul_f32_e32 v52, v52, v249
	v_mul_f32_e32 v53, v53, v249
	v_mul_f32_e32 v54, v54, v249
	v_mul_f32_e32 v55, v55, v249
	v_mul_f32_e32 v44, v44, v249
	v_mul_f32_e32 v45, v45, v249
	v_mul_f32_e32 v46, v46, v249
	v_mul_f32_e32 v47, v47, v249
	v_cvt_pk_bf16_f32 v160, v52, v53
	v_cvt_pk_bf16_f32 v161, v54, v55
	v_cvt_pk_bf16_f32 v162, v44, v45
	v_cvt_pk_bf16_f32 v163, v46, v47
	global_store_dwordx4 v[220:221], v[160:163], off
	v_mul_f32_e32 v32, v32, v249
	v_mul_f32_e32 v33, v33, v249
	v_mul_f32_e32 v34, v34, v249
	v_mul_f32_e32 v35, v35, v249
	v_mul_f32_e32 v24, v24, v249
	v_mul_f32_e32 v25, v25, v249
	v_mul_f32_e32 v26, v26, v249
	v_mul_f32_e32 v27, v27, v249
	v_cvt_pk_bf16_f32 v164, v32, v33
	v_cvt_pk_bf16_f32 v165, v34, v35
	v_cvt_pk_bf16_f32 v166, v24, v25
	v_cvt_pk_bf16_f32 v167, v26, v27
	global_store_dwordx4 v[220:221], v[164:167], off offset:256
	s_nop 0
	v_add_co_u32_e32 v220, vcc, 0x8000, v220
	s_nop 1
	v_addc_co_u32_e32 v221, vcc, 0, v221, vcc
	v_mul_f32_e32 v36, v36, v250
	v_mul_f32_e32 v37, v37, v250
	v_mul_f32_e32 v38, v38, v250
	v_mul_f32_e32 v39, v39, v250
	v_mul_f32_e32 v28, v28, v250
	v_mul_f32_e32 v29, v29, v250
	v_mul_f32_e32 v30, v30, v250
	v_mul_f32_e32 v31, v31, v250
	v_cvt_pk_bf16_f32 v160, v36, v37
	v_cvt_pk_bf16_f32 v161, v38, v39
	v_cvt_pk_bf16_f32 v162, v28, v29
	v_cvt_pk_bf16_f32 v163, v30, v31
	global_store_dwordx4 v[220:221], v[160:163], off
	v_mul_f32_e32 v16, v16, v250
	v_mul_f32_e32 v17, v17, v250
	v_mul_f32_e32 v18, v18, v250
	v_mul_f32_e32 v19, v19, v250
	v_mul_f32_e32 v8, v8, v250
	v_mul_f32_e32 v9, v9, v250
	v_mul_f32_e32 v10, v10, v250
	v_mul_f32_e32 v11, v11, v250
	v_cvt_pk_bf16_f32 v164, v16, v17
	v_cvt_pk_bf16_f32 v165, v18, v19
	v_cvt_pk_bf16_f32 v166, v8, v9
	v_cvt_pk_bf16_f32 v167, v10, v11
	global_store_dwordx4 v[220:221], v[164:167], off offset:256
	s_nop 0
	v_add_co_u32_e32 v220, vcc, 0x8000, v220
	s_nop 1
	v_addc_co_u32_e32 v221, vcc, 0, v221, vcc
	v_mul_f32_e32 v20, v20, v251
	v_mul_f32_e32 v21, v21, v251
	v_mul_f32_e32 v22, v22, v251
	v_mul_f32_e32 v23, v23, v251
	v_mul_f32_e32 v12, v12, v251
	v_mul_f32_e32 v13, v13, v251
	v_mul_f32_e32 v14, v14, v251
	v_mul_f32_e32 v15, v15, v251
	v_cvt_pk_bf16_f32 v160, v20, v21
	v_cvt_pk_bf16_f32 v161, v22, v23
	v_cvt_pk_bf16_f32 v162, v12, v13
	v_cvt_pk_bf16_f32 v163, v14, v15
	global_store_dwordx4 v[220:221], v[160:163], off
	v_mul_f32_e32 v4, v4, v251
	v_mul_f32_e32 v5, v5, v251
	v_mul_f32_e32 v6, v6, v251
	v_mul_f32_e32 v7, v7, v251
	v_mul_f32_e32 v0, v0, v251
	v_mul_f32_e32 v1, v1, v251
	v_mul_f32_e32 v2, v2, v251
	v_mul_f32_e32 v3, v3, v251
	v_cvt_pk_bf16_f32 v164, v4, v5
	v_cvt_pk_bf16_f32 v165, v6, v7
	v_cvt_pk_bf16_f32 v166, v0, v1
	v_cvt_pk_bf16_f32 v167, v2, v3
	global_store_dwordx4 v[220:221], v[164:167], off offset:256

;     __device__ __forceinline__ void operator()(const af4 (&acc)[2][2][4][2], const pg8::Unit& u, int wr, int wc, int fr_, int fq_) const {
;     ...
;             const int col0 = (pn - 2) * 256 + wc * 32 + 8 * fq;
;             float ssq[8];
; #pragma unroll
;             for (int b_ = 0; b_ < 4; ++b_) {
;                 const int ai = b_ >> 1, mp = b_ & 1;
;                 int RRb = row0 + ai * 128 + mp * 32; asm volatile("" : "+v"(RRb));
;                 const size_t ob = (size_t)RRb * 1024 + col0; v4u of_[2][2], ob_[2][2];
; #pragma unroll
;                 for (int mi = 0; mi < 2; ++mi)
; #pragma unroll
;                     for (int bj = 0; bj < 2; ++bj) { of_[mi][bj] = *(const v4u*)(ON + ob + mi * 16 * 1024 + bj * 128); ob_[mi][bj] = *(const v4u*)(OBp + ob + mi * 16 * 1024 + bj * 128); }
; #pragma unroll
;                 for (int mi = 0; mi < 2; ++mi) { float q = 0.f;
; #pragma unroll
;                     for (int bj = 0; bj < 2; ++bj) { const v4u a = of_[mi][bj], c = ob_[mi][bj];
;                         const float o0 = bflo(a.x) + bflo(c.x), o1 = bfhi(a.x) + bfhi(c.x), o2 = bflo(a.y) + bflo(c.y), o3 = bfhi(a.y) + bfhi(c.y), o4 = bflo(a.z) + bflo(c.z), o5 = bfhi(a.z) + bfhi(c.z), o6 = bflo(a.w) + bflo(c.w), o7 = bfhi(a.w) + bfhi(c.w);
;                         q += (o0 * o0 + o1 * o1) + (o2 * o2 + o3 * o3) + (o4 * o4 + o5 * o5) + (o6 * o6 + o7 * o7); }
;                     ssq[ai * 4 + mp * 2 + mi] = q; }
;     ...
;             f32x4 nwv[2][2];
; #pragma unroll
;             for (int bj = 0; bj < 2; ++bj) { nwv[bj][0] = *(const f32x4*)(nw + col0 + bj * 128); nwv[bj][1] = *(const f32x4*)(nw + col0 + bj * 128 + 4); }
; #pragma unroll
;             for (int b_ = 0; b_ < 4; ++b_) {
;                 const int ai = b_ >> 1, mp = b_ & 1;
;                 int RRb = row0 + ai * 128 + mp * 32; asm volatile("" : "+v"(RRb));
;                 const size_t ob = (size_t)RRb * 1024 + col0; v4u of_[2][2], ob_[2][2];
; #pragma unroll
;                 for (int mi = 0; mi < 2; ++mi)
; #pragma unroll
;                     for (int bj = 0; bj < 2; ++bj) { of_[mi][bj] = *(const v4u*)(ON + ob + mi * 16 * 1024 + bj * 128); ob_[mi][bj] = *(const v4u*)(OBp + ob + mi * 16 * 1024 + bj * 128); }
; #pragma unroll
;                 for (int mi = 0; mi < 2; ++mi) { const float rstd = rs[ai * 4 + mp * 2 + mi];
; #pragma unroll
.LBB0_1892:
	s_andn2_b64 vcc, exec, s[8:9]
	s_cbranch_vccnz .LBB0_1896
	s_lshl_b32 s8, s66, 8
	s_add_i32 s8, s52, s8
	v_mov_b32_e32 v128, v214
	v_lshl_add_u32 v192, v215, 3, s8
	v_ashrrev_i32_e32 v193, 31, v192
	v_ashrrev_i32_e32 v129, 31, v128
	v_lshlrev_b64 v[128:129], 10, v[128:129]
	v_lshl_add_u64 v[128:129], v[128:129], 0, v[192:193]
	v_lshlrev_b64 v[128:129], 1, v[128:129]
	v_lshl_add_u64 v[130:131], s[6:7], 0, v[128:129]
	v_lshl_add_u64 v[128:129], s[20:21], 0, v[128:129]
	v_mov_b32_e32 v216, v136
	v_mov_b32_e32 v217, v137
	v_lshlrev_b32_e32 v218, 2, v192
	v_mov_b32_e32 v220, v130
	v_mov_b32_e32 v221, v131
	v_mov_b32_e32 v222, v128
	v_mov_b32_e32 v223, v129
	s_load_dwordx2 s[8:9], s[84:85], 0x58
	v_add_u32_e32 v225, s87, v216
	v_lshlrev_b32_e32 v225, 4, v225
	v_add_u32_e32 v225, 0x20400, v225
	s_lshr_b32 vcc_lo, s73, 3
	v_add_u32_e32 v224, vcc_lo, v225
	v_xor_b32_e32 v226, 16, v217
	v_lshlrev_b32_e32 v226, 2, v226
	v_xor_b32_e32 v227, 32, v217
	v_lshlrev_b32_e32 v227, 2, v227
	s_waitcnt lgkmcnt(0)
	s_add_u32 s8, s8, 0x2000
	s_addc_u32 s9, s9, 0
	global_load_dwordx4 v[228:231], v218, s[8:9]
	global_load_dwordx4 v[232:235], v218, s[8:9] offset:16
	global_load_dwordx4 v[236:239], v218, s[8:9] offset:512
	global_load_dwordx4 v[240:243], v218, s[8:9] offset:528
	v_mov_b32_e32 v244, 0
	v_mov_b32_e32 v245, 0
	v_mov_b32_e32 v246, 0
	v_mov_b32_e32 v247, 0
	v_mov_b32_e32 v248, 0
	v_mov_b32_e32 v249, 0
	v_mov_b32_e32 v250, 0
	v_mov_b32_e32 v251, 0
	global_load_dwordx4 v[128:131], v[220:221], off
	global_load_dwordx4 v[132:135], v[220:221], off offset:256
	global_load_dwordx4 v[136:139], v[222:223], off
	global_load_dwordx4 v[140:143], v[222:223], off offset:256
	v_add_co_u32_e32 v220, vcc, 0x8000, v220
	s_nop 1
	v_addc_co_u32_e32 v221, vcc, 0, v221, vcc
	v_add_co_u32_e32 v222, vcc, 0x8000, v222
	s_nop 1
	v_addc_co_u32_e32 v223, vcc, 0, v223, vcc
	global_load_dwordx4 v[144:147], v[220:221], off
	global_load_dwordx4 v[148:151], v[220:221], off offset:256
	global_load_dwordx4 v[152:155], v[222:223], off
	global_load_dwordx4 v[156:159], v[222:223], off offset:256
	v_add_co_u32_e32 v220, vcc, 0x8000, v220
	s_nop 1
	v_addc_co_u32_e32 v221, vcc, 0, v221, vcc
	v_add_co_u32_e32 v222, vcc, 0x8000, v222
	s_nop 1
	v_addc_co_u32_e32 v223, vcc, 0, v223, vcc
	global_load_dwordx4 v[160:163], v[220:221], off
	global_load_dwordx4 v[164:167], v[220:221], off offset:256
	global_load_dwordx4 v[168:171], v[222:223], off
	global_load_dwordx4 v[172:175], v[222:223], off offset:256
	v_add_co_u32_e32 v220, vcc, 0x8000, v220
	s_nop 1
	v_addc_co_u32_e32 v221, vcc, 0, v221, vcc
	v_add_co_u32_e32 v222, vcc, 0x8000, v222
	s_nop 1
	v_addc_co_u32_e32 v223, vcc, 0, v223, vcc
	s_waitcnt vmcnt(8)
	v_lshlrev_b32_e32 v192, 16, v128
	v_and_b32_e32 v193, 0xffff0000, v128
	v_lshlrev_b32_e32 v200, 16, v136
	v_and_b32_e32 v252, 0xffff0000, v136
	v_add_f32_e32 v192, v192, v200
	v_add_f32_e32 v193, v193, v252
	v_lshlrev_b32_e32 v194, 16, v129
	v_and_b32_e32 v195, 0xffff0000, v129
	v_lshlrev_b32_e32 v200, 16, v137
	v_and_b32_e32 v252, 0xffff0000, v137
	v_add_f32_e32 v194, v194, v200
	v_add_f32_e32 v195, v195, v252
	v_lshlrev_b32_e32 v196, 16, v130
	v_and_b32_e32 v197, 0xffff0000, v130
	v_lshlrev_b32_e32 v200, 16, v138
	v_and_b32_e32 v252, 0xffff0000, v138
	v_add_f32_e32 v196, v196, v200
	v_add_f32_e32 v197, v197, v252
	v_lshlrev_b32_e32 v198, 16, v131
	v_and_b32_e32 v199, 0xffff0000, v131
	v_lshlrev_b32_e32 v200, 16, v139
	v_and_b32_e32 v252, 0xffff0000, v139
	v_add_f32_e32 v198, v198, v200
	v_add_f32_e32 v199, v199, v252
	v_mul_f32_e32 v200, v192, v192
	v_mul_f32_e32 v252, v194, v194
	v_mul_f32_e32 v253, v196, v196
	v_mul_f32_e32 v219, v198, v198
	v_fmac_f32_e32 v200, v193, v193
	v_fmac_f32_e32 v252, v195, v195
	v_fmac_f32_e32 v253, v197, v197
	v_fmac_f32_e32 v219, v199, v199
	v_add_f32_e32 v200, v200, v252
	v_add_f32_e32 v253, v253, v219
	v_add_f32_e32 v200, v200, v253
	v_add_f32_e32 v244, v244, v200
	v_mul_f32_e32 v200, 0xbfb8aa3b, v124
	v_mul_f32_e32 v252, 0xbfb8aa3b, v125
	v_mul_f32_e32 v253, 0xbfb8aa3b, v126
	v_mul_f32_e32 v219, 0xbfb8aa3b, v127
	v_exp_f32_e32 v200, v200
	v_exp_f32_e32 v252, v252
	v_exp_f32_e32 v253, v253
	v_exp_f32_e32 v219, v219
	v_add_f32_e32 v200, 1.0, v200
	v_add_f32_e32 v252, 1.0, v252
	v_add_f32_e32 v253, 1.0, v253
	v_add_f32_e32 v219, 1.0, v219
	v_rcp_f32_e32 v200, v200
	v_rcp_f32_e32 v252, v252
	v_rcp_f32_e32 v253, v253
	v_rcp_f32_e32 v219, v219
	v_mul_f32_e32 v200, v124, v200
	v_mul_f32_e32 v252, v125, v252
	v_mul_f32_e32 v253, v126, v253
	v_mul_f32_e32 v219, v127, v219
	v_mul_f32_e32 v200, v200, v228
	v_mul_f32_e32 v252, v252, v229
	v_mul_f32_e32 v253, v253, v230
	v_mul_f32_e32 v219, v219, v231
	v_mul_f32_e32 v124, v200, v192
	v_mul_f32_e32 v125, v252, v193
	v_mul_f32_e32 v126, v253, v194
	v_mul_f32_e32 v127, v219, v195
	v_mul_f32_e32 v200, 0xbfb8aa3b, v120
	v_mul_f32_e32 v252, 0xbfb8aa3b, v121
	v_mul_f32_e32 v253, 0xbfb8aa3b, v122
	v_mul_f32_e32 v219, 0xbfb8aa3b, v123
	v_exp_f32_e32 v200, v200
	v_exp_f32_e32 v252, v252
	v_exp_f32_e32 v253, v253
	v_exp_f32_e32 v219, v219
	v_add_f32_e32 v200, 1.0, v200
	v_add_f32_e32 v252, 1.0, v252
	v_add_f32_e32 v253, 1.0, v253
	v_add_f32_e32 v219, 1.0, v219
	v_rcp_f32_e32 v200, v200
	v_rcp_f32_e32 v252, v252
	v_rcp_f32_e32 v253, v253
	v_rcp_f32_e32 v219, v219
	v_mul_f32_e32 v200, v120, v200
	v_mul_f32_e32 v252, v121, v252
	v_mul_f32_e32 v253, v122, v253
	v_mul_f32_e32 v219, v123, v219
	v_mul_f32_e32 v200, v200, v232
	v_mul_f32_e32 v252, v252, v233
	v_mul_f32_e32 v253, v253, v234
	v_mul_f32_e32 v219, v219, v235
	v_mul_f32_e32 v120, v200, v196
	v_mul_f32_e32 v121, v252, v197
	v_mul_f32_e32 v122, v253, v198
; __device__ __forceinline__ unsigned cvtpk(float lo, float hi) { f32x2 v = {lo, hi}; bf16x2_t b = __builtin_convertvector(v, bf16x2_t); return __builtin_bit_cast(unsigned, b); }
;     __device__ __forceinline__ void operator()(const af4 (&acc)[2][2][4][2], const pg8::Unit& u, int wr, int wc, int fr_, int fq_) const {
;     ...
;             for (int b_ = 0; b_ < 4; ++b_) {
;                 const int ai = b_ >> 1, mp = b_ & 1;
;                 int RRb = row0 + ai * 128 + mp * 32; asm volatile("" : "+v"(RRb));
;                 const size_t ob = (size_t)RRb * 1024 + col0; v4u of_[2][2], ob_[2][2];
; #pragma unroll
;                 for (int mi = 0; mi < 2; ++mi)
; #pragma unroll
;                     for (int bj = 0; bj < 2; ++bj) { of_[mi][bj] = *(const v4u*)(ON + ob + mi * 16 * 1024 + bj * 128); ob_[mi][bj] = *(const v4u*)(OBp + ob + mi * 16 * 1024 + bj * 128); }
; #pragma unroll
;                 for (int mi = 0; mi < 2; ++mi) { float q = 0.f;
; #pragma unroll
;                     for (int bj = 0; bj < 2; ++bj) { const v4u a = of_[mi][bj], c = ob_[mi][bj];
;                         const float o0 = bflo(a.x) + bflo(c.x), o1 = bfhi(a.x) + bfhi(c.x), o2 = bflo(a.y) + bflo(c.y), o3 = bfhi(a.y) + bfhi(c.y), o4 = bflo(a.z) + bflo(c.z), o5 = bfhi(a.z) + bfhi(c.z), o6 = bflo(a.w) + bflo(c.w), o7 = bfhi(a.w) + bfhi(c.w);
;                         q += (o0 * o0 + o1 * o1) + (o2 * o2 + o3 * o3) + (o4 * o4 + o5 * o5) + (o6 * o6 + o7 * o7); }
;                     ssq[ai * 4 + mp * 2 + mi] = q; }
;     ...
;                 for (int mi = 0; mi < 2; ++mi) { const float rstd = rs[ai * 4 + mp * 2 + mi];
; #pragma unroll
;                     for (int bj = 0; bj < 2; ++bj) { af4 v0 = acc[ai][bj][mp * 2 + mi][0], v1 = acc[ai][bj][mp * 2 + mi][1]; asm volatile("" : "+v"(v0), "+v"(v1)); const v4u a = of_[mi][bj], c = ob_[mi][bj];
; #pragma unroll
;                         for (int e = 0; e < 4; ++e) { v0[e] = v0[e] * sigmoidf_(v0[e]) * (rstd * nwv[bj][0][e]); v1[e] = v1[e] * sigmoidf_(v1[e]) * (rstd * nwv[bj][1][e]); }
;                         v4u w; w.x = cvtpk(v0[0] * (bflo(a.x) + bflo(c.x)), v0[1] * (bfhi(a.x) + bfhi(c.x))); w.y = cvtpk(v0[2] * (bflo(a.y) + bflo(c.y)), v0[3] * (bfhi(a.y) + bfhi(c.y)));
;                         w.z = cvtpk(v1[0] * (bflo(a.z) + bflo(c.z)), v1[1] * (bfhi(a.z) + bfhi(c.z))); w.w = cvtpk(v1[2] * (bflo(a.w) + bflo(c.w)), v1[3] * (bfhi(a.w) + bfhi(c.w)));
	v_mul_f32_e32 v123, v219, v199
	v_lshlrev_b32_e32 v192, 16, v132
	v_and_b32_e32 v193, 0xffff0000, v132
	v_lshlrev_b32_e32 v200, 16, v140
	v_and_b32_e32 v252, 0xffff0000, v140
	v_add_f32_e32 v192, v192, v200
	v_add_f32_e32 v193, v193, v252
	v_lshlrev_b32_e32 v194, 16, v133
	v_and_b32_e32 v195, 0xffff0000, v133
	v_lshlrev_b32_e32 v200, 16, v141
	v_and_b32_e32 v252, 0xffff0000, v141
	v_add_f32_e32 v194, v194, v200
	v_add_f32_e32 v195, v195, v252
	v_lshlrev_b32_e32 v196, 16, v134
	v_and_b32_e32 v197, 0xffff0000, v134
	v_lshlrev_b32_e32 v200, 16, v142
	v_and_b32_e32 v252, 0xffff0000, v142
	v_add_f32_e32 v196, v196, v200
	v_add_f32_e32 v197, v197, v252
	v_lshlrev_b32_e32 v198, 16, v135
	v_and_b32_e32 v199, 0xffff0000, v135
	v_lshlrev_b32_e32 v200, 16, v143
	v_and_b32_e32 v252, 0xffff0000, v143
	v_add_f32_e32 v198, v198, v200
	v_add_f32_e32 v199, v199, v252
	v_mul_f32_e32 v200, v192, v192
	v_mul_f32_e32 v252, v194, v194
	v_mul_f32_e32 v253, v196, v196
	v_mul_f32_e32 v219, v198, v198
	v_fmac_f32_e32 v200, v193, v193
	v_fmac_f32_e32 v252, v195, v195
	v_fmac_f32_e32 v253, v197, v197
	v_fmac_f32_e32 v219, v199, v199
	v_add_f32_e32 v200, v200, v252
	v_add_f32_e32 v253, v253, v219
	v_add_f32_e32 v200, v200, v253
	v_add_f32_e32 v244, v244, v200
	v_mul_f32_e32 v200, 0xbfb8aa3b, v112
	v_mul_f32_e32 v252, 0xbfb8aa3b, v113
	v_mul_f32_e32 v253, 0xbfb8aa3b, v114
	v_mul_f32_e32 v219, 0xbfb8aa3b, v115
	v_exp_f32_e32 v200, v200
	v_exp_f32_e32 v252, v252
	v_exp_f32_e32 v253, v253
	v_exp_f32_e32 v219, v219
	v_add_f32_e32 v200, 1.0, v200
	v_add_f32_e32 v252, 1.0, v252
	v_add_f32_e32 v253, 1.0, v253
	v_add_f32_e32 v219, 1.0, v219
	v_rcp_f32_e32 v200, v200
	v_rcp_f32_e32 v252, v252
	v_rcp_f32_e32 v253, v253
	v_rcp_f32_e32 v219, v219
	v_mul_f32_e32 v200, v112, v200
	v_mul_f32_e32 v252, v113, v252
	v_mul_f32_e32 v253, v114, v253
	v_mul_f32_e32 v219, v115, v219
	v_mul_f32_e32 v200, v200, v236
	v_mul_f32_e32 v252, v252, v237
	v_mul_f32_e32 v253, v253, v238
	v_mul_f32_e32 v219, v219, v239
	v_mul_f32_e32 v112, v200, v192
	v_mul_f32_e32 v113, v252, v193
	v_mul_f32_e32 v114, v253, v194
	v_mul_f32_e32 v115, v219, v195
	v_mul_f32_e32 v200, 0xbfb8aa3b, v104
	v_mul_f32_e32 v252, 0xbfb8aa3b, v105
	v_mul_f32_e32 v253, 0xbfb8aa3b, v106
	v_mul_f32_e32 v219, 0xbfb8aa3b, v107
	v_exp_f32_e32 v200, v200
	v_exp_f32_e32 v252, v252
	v_exp_f32_e32 v253, v253
	v_exp_f32_e32 v219, v219
	v_add_f32_e32 v200, 1.0, v200
	v_add_f32_e32 v252, 1.0, v252
	v_add_f32_e32 v253, 1.0, v253
	v_add_f32_e32 v219, 1.0, v219
	v_rcp_f32_e32 v200, v200
	v_rcp_f32_e32 v252, v252
	v_rcp_f32_e32 v253, v253
	v_rcp_f32_e32 v219, v219
	v_mul_f32_e32 v200, v104, v200
	v_mul_f32_e32 v252, v105, v252
	v_mul_f32_e32 v253, v106, v253
	v_mul_f32_e32 v219, v107, v219
	v_mul_f32_e32 v200, v200, v240
	v_mul_f32_e32 v252, v252, v241
	v_mul_f32_e32 v253, v253, v242
	v_mul_f32_e32 v219, v219, v243
	v_mul_f32_e32 v104, v200, v196
	v_mul_f32_e32 v105, v252, v197
	v_mul_f32_e32 v106, v253, v198
	v_mul_f32_e32 v107, v219, v199
	global_load_dwordx4 v[128:131], v[220:221], off
	global_load_dwordx4 v[132:135], v[220:221], off offset:256
	global_load_dwordx4 v[136:139], v[222:223], off
	global_load_dwordx4 v[140:143], v[222:223], off offset:256
	v_add_co_u32_e32 v220, vcc, 0x28000, v220
	s_nop 1
	v_addc_co_u32_e32 v221, vcc, 0, v221, vcc
	v_add_co_u32_e32 v222, vcc, 0x28000, v222
	s_nop 1
	v_addc_co_u32_e32 v223, vcc, 0, v223, vcc
	s_waitcnt vmcnt(8)
	v_lshlrev_b32_e32 v192, 16, v144
	v_and_b32_e32 v193, 0xffff0000, v144
	v_lshlrev_b32_e32 v200, 16, v152
	v_and_b32_e32 v252, 0xffff0000, v152
	v_add_f32_e32 v192, v192, v200
	v_add_f32_e32 v193, v193, v252
	v_lshlrev_b32_e32 v194, 16, v145
	v_and_b32_e32 v195, 0xffff0000, v145
	v_lshlrev_b32_e32 v200, 16, v153
	v_and_b32_e32 v252, 0xffff0000, v153
	v_add_f32_e32 v194, v194, v200
	v_add_f32_e32 v195, v195, v252
	v_lshlrev_b32_e32 v196, 16, v146
	v_and_b32_e32 v197, 0xffff0000, v146
	v_lshlrev_b32_e32 v200, 16, v154
	v_and_b32_e32 v252, 0xffff0000, v154
	v_add_f32_e32 v196, v196, v200
	v_add_f32_e32 v197, v197, v252
	v_lshlrev_b32_e32 v198, 16, v147
	v_and_b32_e32 v199, 0xffff0000, v147
	v_lshlrev_b32_e32 v200, 16, v155
	v_and_b32_e32 v252, 0xffff0000, v155
	v_add_f32_e32 v198, v198, v200
	v_add_f32_e32 v199, v199, v252
	v_mul_f32_e32 v200, v192, v192
	v_mul_f32_e32 v252, v194, v194
	v_mul_f32_e32 v253, v196, v196
	v_mul_f32_e32 v219, v198, v198
	v_fmac_f32_e32 v200, v193, v193
	v_fmac_f32_e32 v252, v195, v195
	v_fmac_f32_e32 v253, v197, v197
	v_fmac_f32_e32 v219, v199, v199
	v_add_f32_e32 v200, v200, v252
	v_add_f32_e32 v253, v253, v219
	v_add_f32_e32 v200, v200, v253
	v_add_f32_e32 v245, v245, v200
	v_mul_f32_e32 v200, 0xbfb8aa3b, v116
	v_mul_f32_e32 v252, 0xbfb8aa3b, v117
	v_mul_f32_e32 v253, 0xbfb8aa3b, v118
	v_mul_f32_e32 v219, 0xbfb8aa3b, v119
	v_exp_f32_e32 v200, v200
	v_exp_f32_e32 v252, v252
	v_exp_f32_e32 v253, v253
	v_exp_f32_e32 v219, v219
	v_add_f32_e32 v200, 1.0, v200
	v_add_f32_e32 v252, 1.0, v252
	v_add_f32_e32 v253, 1.0, v253
	v_add_f32_e32 v219, 1.0, v219
	v_rcp_f32_e32 v200, v200
	v_rcp_f32_e32 v252, v252
	v_rcp_f32_e32 v253, v253
	v_rcp_f32_e32 v219, v219
	v_mul_f32_e32 v200, v116, v200
	v_mul_f32_e32 v252, v117, v252
	v_mul_f32_e32 v253, v118, v253
	v_mul_f32_e32 v219, v119, v219
	v_mul_f32_e32 v200, v200, v228
	v_mul_f32_e32 v252, v252, v229
	v_mul_f32_e32 v253, v253, v230
	v_mul_f32_e32 v219, v219, v231
	v_mul_f32_e32 v116, v200, v192
	v_mul_f32_e32 v117, v252, v193
	v_mul_f32_e32 v118, v253, v194
	v_mul_f32_e32 v119, v219, v195
	v_mul_f32_e32 v200, 0xbfb8aa3b, v108
	v_mul_f32_e32 v252, 0xbfb8aa3b, v109
	v_mul_f32_e32 v253, 0xbfb8aa3b, v110
	v_mul_f32_e32 v219, 0xbfb8aa3b, v111
; __device__ __forceinline__ unsigned cvtpk(float lo, float hi) { f32x2 v = {lo, hi}; bf16x2_t b = __builtin_convertvector(v, bf16x2_t); return __builtin_bit_cast(unsigned, b); }
;     __device__ __forceinline__ void operator()(const af4 (&acc)[2][2][4][2], const pg8::Unit& u, int wr, int wc, int fr_, int fq_) const {
;     ...
;             for (int b_ = 0; b_ < 4; ++b_) {
;                 const int ai = b_ >> 1, mp = b_ & 1;
;                 int RRb = row0 + ai * 128 + mp * 32; asm volatile("" : "+v"(RRb));
;                 const size_t ob = (size_t)RRb * 1024 + col0; v4u of_[2][2], ob_[2][2];
; #pragma unroll
;                 for (int mi = 0; mi < 2; ++mi)
; #pragma unroll
;                     for (int bj = 0; bj < 2; ++bj) { of_[mi][bj] = *(const v4u*)(ON + ob + mi * 16 * 1024 + bj * 128); ob_[mi][bj] = *(const v4u*)(OBp + ob + mi * 16 * 1024 + bj * 128); }
; #pragma unroll
;                 for (int mi = 0; mi < 2; ++mi) { float q = 0.f;
; #pragma unroll
;                     for (int bj = 0; bj < 2; ++bj) { const v4u a = of_[mi][bj], c = ob_[mi][bj];
;                         const float o0 = bflo(a.x) + bflo(c.x), o1 = bfhi(a.x) + bfhi(c.x), o2 = bflo(a.y) + bflo(c.y), o3 = bfhi(a.y) + bfhi(c.y), o4 = bflo(a.z) + bflo(c.z), o5 = bfhi(a.z) + bfhi(c.z), o6 = bflo(a.w) + bflo(c.w), o7 = bfhi(a.w) + bfhi(c.w);
;                         q += (o0 * o0 + o1 * o1) + (o2 * o2 + o3 * o3) + (o4 * o4 + o5 * o5) + (o6 * o6 + o7 * o7); }
;                     ssq[ai * 4 + mp * 2 + mi] = q; }
;     ...
;                 for (int mi = 0; mi < 2; ++mi) { const float rstd = rs[ai * 4 + mp * 2 + mi];
; #pragma unroll
;                     for (int bj = 0; bj < 2; ++bj) { af4 v0 = acc[ai][bj][mp * 2 + mi][0], v1 = acc[ai][bj][mp * 2 + mi][1]; asm volatile("" : "+v"(v0), "+v"(v1)); const v4u a = of_[mi][bj], c = ob_[mi][bj];
; #pragma unroll
;                         for (int e = 0; e < 4; ++e) { v0[e] = v0[e] * sigmoidf_(v0[e]) * (rstd * nwv[bj][0][e]); v1[e] = v1[e] * sigmoidf_(v1[e]) * (rstd * nwv[bj][1][e]); }
;                         v4u w; w.x = cvtpk(v0[0] * (bflo(a.x) + bflo(c.x)), v0[1] * (bfhi(a.x) + bfhi(c.x))); w.y = cvtpk(v0[2] * (bflo(a.y) + bflo(c.y)), v0[3] * (bfhi(a.y) + bfhi(c.y)));
;                         w.z = cvtpk(v1[0] * (bflo(a.z) + bflo(c.z)), v1[1] * (bfhi(a.z) + bfhi(c.z))); w.w = cvtpk(v1[2] * (bflo(a.w) + bflo(c.w)), v1[3] * (bfhi(a.w) + bfhi(c.w)));
	v_exp_f32_e32 v200, v200
	v_exp_f32_e32 v252, v252
	v_exp_f32_e32 v253, v253
	v_exp_f32_e32 v219, v219
	v_add_f32_e32 v200, 1.0, v200
	v_add_f32_e32 v252, 1.0, v252
	v_add_f32_e32 v253, 1.0, v253
	v_add_f32_e32 v219, 1.0, v219
	v_rcp_f32_e32 v200, v200
	v_rcp_f32_e32 v252, v252
	v_rcp_f32_e32 v253, v253
	v_rcp_f32_e32 v219, v219
	v_mul_f32_e32 v200, v108, v200
	v_mul_f32_e32 v252, v109, v252
	v_mul_f32_e32 v253, v110, v253
	v_mul_f32_e32 v219, v111, v219
	v_mul_f32_e32 v200, v200, v232
	v_mul_f32_e32 v252, v252, v233
	v_mul_f32_e32 v253, v253, v234
	v_mul_f32_e32 v219, v219, v235
	v_mul_f32_e32 v108, v200, v196
	v_mul_f32_e32 v109, v252, v197
	v_mul_f32_e32 v110, v253, v198
	v_mul_f32_e32 v111, v219, v199
	v_lshlrev_b32_e32 v192, 16, v148
	v_and_b32_e32 v193, 0xffff0000, v148
	v_lshlrev_b32_e32 v200, 16, v156
	v_and_b32_e32 v252, 0xffff0000, v156
	v_add_f32_e32 v192, v192, v200
	v_add_f32_e32 v193, v193, v252
	v_lshlrev_b32_e32 v194, 16, v149
	v_and_b32_e32 v195, 0xffff0000, v149
	v_lshlrev_b32_e32 v200, 16, v157
	v_and_b32_e32 v252, 0xffff0000, v157
	v_add_f32_e32 v194, v194, v200
	v_add_f32_e32 v195, v195, v252
	v_lshlrev_b32_e32 v196, 16, v150
	v_and_b32_e32 v197, 0xffff0000, v150
	v_lshlrev_b32_e32 v200, 16, v158
	v_and_b32_e32 v252, 0xffff0000, v158
	v_add_f32_e32 v196, v196, v200
	v_add_f32_e32 v197, v197, v252
	v_lshlrev_b32_e32 v198, 16, v151
	v_and_b32_e32 v199, 0xffff0000, v151
	v_lshlrev_b32_e32 v200, 16, v159
	v_and_b32_e32 v252, 0xffff0000, v159
	v_add_f32_e32 v198, v198, v200
	v_add_f32_e32 v199, v199, v252
	v_mul_f32_e32 v200, v192, v192
	v_mul_f32_e32 v252, v194, v194
	v_mul_f32_e32 v253, v196, v196
	v_mul_f32_e32 v219, v198, v198
	v_fmac_f32_e32 v200, v193, v193
	v_fmac_f32_e32 v252, v195, v195
	v_fmac_f32_e32 v253, v197, v197
	v_fmac_f32_e32 v219, v199, v199
	v_add_f32_e32 v200, v200, v252
	v_add_f32_e32 v253, v253, v219
	v_add_f32_e32 v200, v200, v253
	v_add_f32_e32 v245, v245, v200
	v_mul_f32_e32 v200, 0xbfb8aa3b, v96
	v_mul_f32_e32 v252, 0xbfb8aa3b, v97
	v_mul_f32_e32 v253, 0xbfb8aa3b, v98
	v_mul_f32_e32 v219, 0xbfb8aa3b, v99
	v_exp_f32_e32 v200, v200
	v_exp_f32_e32 v252, v252
	v_exp_f32_e32 v253, v253
	v_exp_f32_e32 v219, v219
	v_add_f32_e32 v200, 1.0, v200
	v_add_f32_e32 v252, 1.0, v252
	v_add_f32_e32 v253, 1.0, v253
	v_add_f32_e32 v219, 1.0, v219
	v_rcp_f32_e32 v200, v200
	v_rcp_f32_e32 v252, v252
	v_rcp_f32_e32 v253, v253
	v_rcp_f32_e32 v219, v219
	v_mul_f32_e32 v200, v96, v200
	v_mul_f32_e32 v252, v97, v252
	v_mul_f32_e32 v253, v98, v253
	v_mul_f32_e32 v219, v99, v219
	v_mul_f32_e32 v200, v200, v236
	v_mul_f32_e32 v252, v252, v237
	v_mul_f32_e32 v253, v253, v238
	v_mul_f32_e32 v219, v219, v239
	v_mul_f32_e32 v96, v200, v192
	v_mul_f32_e32 v97, v252, v193
	v_mul_f32_e32 v98, v253, v194
	v_mul_f32_e32 v99, v219, v195
	v_mul_f32_e32 v200, 0xbfb8aa3b, v88
	v_mul_f32_e32 v252, 0xbfb8aa3b, v89
	v_mul_f32_e32 v253, 0xbfb8aa3b, v90
	v_mul_f32_e32 v219, 0xbfb8aa3b, v91
	v_exp_f32_e32 v200, v200
	v_exp_f32_e32 v252, v252
	v_exp_f32_e32 v253, v253
	v_exp_f32_e32 v219, v219
	v_add_f32_e32 v200, 1.0, v200
	v_add_f32_e32 v252, 1.0, v252
	v_add_f32_e32 v253, 1.0, v253
	v_add_f32_e32 v219, 1.0, v219
	v_rcp_f32_e32 v200, v200
	v_rcp_f32_e32 v252, v252
	v_rcp_f32_e32 v253, v253
	v_rcp_f32_e32 v219, v219
	v_mul_f32_e32 v200, v88, v200
	v_mul_f32_e32 v252, v89, v252
	v_mul_f32_e32 v253, v90, v253
	v_mul_f32_e32 v219, v91, v219
	v_mul_f32_e32 v200, v200, v240
	v_mul_f32_e32 v252, v252, v241
	v_mul_f32_e32 v253, v253, v242
	v_mul_f32_e32 v219, v219, v243
	v_mul_f32_e32 v88, v200, v196
	v_mul_f32_e32 v89, v252, v197
	v_mul_f32_e32 v90, v253, v198
	v_mul_f32_e32 v91, v219, v199
	global_load_dwordx4 v[144:147], v[220:221], off
	global_load_dwordx4 v[148:151], v[220:221], off offset:256
	global_load_dwordx4 v[152:155], v[222:223], off
	global_load_dwordx4 v[156:159], v[222:223], off offset:256
	v_add_co_u32_e32 v220, vcc, 0x8000, v220
	s_nop 1
	v_addc_co_u32_e32 v221, vcc, 0, v221, vcc
	v_add_co_u32_e32 v222, vcc, 0x8000, v222
	s_nop 1
	v_addc_co_u32_e32 v223, vcc, 0, v223, vcc
	s_waitcnt vmcnt(8)
	v_lshlrev_b32_e32 v192, 16, v160
	v_and_b32_e32 v193, 0xffff0000, v160
	v_lshlrev_b32_e32 v200, 16, v168
	v_and_b32_e32 v252, 0xffff0000, v168
	v_add_f32_e32 v192, v192, v200
	v_add_f32_e32 v193, v193, v252
	v_lshlrev_b32_e32 v194, 16, v161
	v_and_b32_e32 v195, 0xffff0000, v161
	v_lshlrev_b32_e32 v200, 16, v169
	v_and_b32_e32 v252, 0xffff0000, v169
	v_add_f32_e32 v194, v194, v200
	v_add_f32_e32 v195, v195, v252
	v_lshlrev_b32_e32 v196, 16, v162
	v_and_b32_e32 v197, 0xffff0000, v162
	v_lshlrev_b32_e32 v200, 16, v170
	v_and_b32_e32 v252, 0xffff0000, v170
	v_add_f32_e32 v196, v196, v200
	v_add_f32_e32 v197, v197, v252
	v_lshlrev_b32_e32 v198, 16, v163
	v_and_b32_e32 v199, 0xffff0000, v163
	v_lshlrev_b32_e32 v200, 16, v171
	v_and_b32_e32 v252, 0xffff0000, v171
	v_add_f32_e32 v198, v198, v200
	v_add_f32_e32 v199, v199, v252
	v_mul_f32_e32 v200, v192, v192
	v_mul_f32_e32 v252, v194, v194
	v_mul_f32_e32 v253, v196, v196
	v_mul_f32_e32 v219, v198, v198
	v_fmac_f32_e32 v200, v193, v193
	v_fmac_f32_e32 v252, v195, v195
	v_fmac_f32_e32 v253, v197, v197
	v_fmac_f32_e32 v219, v199, v199
	v_add_f32_e32 v200, v200, v252
	v_add_f32_e32 v253, v253, v219
	v_add_f32_e32 v200, v200, v253
	v_add_f32_e32 v246, v246, v200
	v_mul_f32_e32 v200, 0xbfb8aa3b, v100
	v_mul_f32_e32 v252, 0xbfb8aa3b, v101
	v_mul_f32_e32 v253, 0xbfb8aa3b, v102
	v_mul_f32_e32 v219, 0xbfb8aa3b, v103
	v_exp_f32_e32 v200, v200
	v_exp_f32_e32 v252, v252
	v_exp_f32_e32 v253, v253
	v_exp_f32_e32 v219, v219
	v_add_f32_e32 v200, 1.0, v200
	v_add_f32_e32 v252, 1.0, v252
	v_add_f32_e32 v253, 1.0, v253
; __device__ __forceinline__ unsigned cvtpk(float lo, float hi) { f32x2 v = {lo, hi}; bf16x2_t b = __builtin_convertvector(v, bf16x2_t); return __builtin_bit_cast(unsigned, b); }
;     __device__ __forceinline__ void operator()(const af4 (&acc)[2][2][4][2], const pg8::Unit& u, int wr, int wc, int fr_, int fq_) const {
;     ...
;             for (int b_ = 0; b_ < 4; ++b_) {
;                 const int ai = b_ >> 1, mp = b_ & 1;
;                 int RRb = row0 + ai * 128 + mp * 32; asm volatile("" : "+v"(RRb));
;                 const size_t ob = (size_t)RRb * 1024 + col0; v4u of_[2][2], ob_[2][2];
; #pragma unroll
;                 for (int mi = 0; mi < 2; ++mi)
; #pragma unroll
;                     for (int bj = 0; bj < 2; ++bj) { of_[mi][bj] = *(const v4u*)(ON + ob + mi * 16 * 1024 + bj * 128); ob_[mi][bj] = *(const v4u*)(OBp + ob + mi * 16 * 1024 + bj * 128); }
; #pragma unroll
;                 for (int mi = 0; mi < 2; ++mi) { float q = 0.f;
; #pragma unroll
;                     for (int bj = 0; bj < 2; ++bj) { const v4u a = of_[mi][bj], c = ob_[mi][bj];
;                         const float o0 = bflo(a.x) + bflo(c.x), o1 = bfhi(a.x) + bfhi(c.x), o2 = bflo(a.y) + bflo(c.y), o3 = bfhi(a.y) + bfhi(c.y), o4 = bflo(a.z) + bflo(c.z), o5 = bfhi(a.z) + bfhi(c.z), o6 = bflo(a.w) + bflo(c.w), o7 = bfhi(a.w) + bfhi(c.w);
;                         q += (o0 * o0 + o1 * o1) + (o2 * o2 + o3 * o3) + (o4 * o4 + o5 * o5) + (o6 * o6 + o7 * o7); }
;                     ssq[ai * 4 + mp * 2 + mi] = q; }
;     ...
;                 for (int mi = 0; mi < 2; ++mi) { const float rstd = rs[ai * 4 + mp * 2 + mi];
; #pragma unroll
;                     for (int bj = 0; bj < 2; ++bj) { af4 v0 = acc[ai][bj][mp * 2 + mi][0], v1 = acc[ai][bj][mp * 2 + mi][1]; asm volatile("" : "+v"(v0), "+v"(v1)); const v4u a = of_[mi][bj], c = ob_[mi][bj];
; #pragma unroll
;                         for (int e = 0; e < 4; ++e) { v0[e] = v0[e] * sigmoidf_(v0[e]) * (rstd * nwv[bj][0][e]); v1[e] = v1[e] * sigmoidf_(v1[e]) * (rstd * nwv[bj][1][e]); }
;                         v4u w; w.x = cvtpk(v0[0] * (bflo(a.x) + bflo(c.x)), v0[1] * (bfhi(a.x) + bfhi(c.x))); w.y = cvtpk(v0[2] * (bflo(a.y) + bflo(c.y)), v0[3] * (bfhi(a.y) + bfhi(c.y)));
;                         w.z = cvtpk(v1[0] * (bflo(a.z) + bflo(c.z)), v1[1] * (bfhi(a.z) + bfhi(c.z))); w.w = cvtpk(v1[2] * (bflo(a.w) + bflo(c.w)), v1[3] * (bfhi(a.w) + bfhi(c.w)));
	v_add_f32_e32 v219, 1.0, v219
	v_rcp_f32_e32 v200, v200
	v_rcp_f32_e32 v252, v252
	v_rcp_f32_e32 v253, v253
	v_rcp_f32_e32 v219, v219
	v_mul_f32_e32 v200, v100, v200
	v_mul_f32_e32 v252, v101, v252
	v_mul_f32_e32 v253, v102, v253
	v_mul_f32_e32 v219, v103, v219
	v_mul_f32_e32 v200, v200, v228
	v_mul_f32_e32 v252, v252, v229
	v_mul_f32_e32 v253, v253, v230
	v_mul_f32_e32 v219, v219, v231
	v_mul_f32_e32 v100, v200, v192
	v_mul_f32_e32 v101, v252, v193
	v_mul_f32_e32 v102, v253, v194
	v_mul_f32_e32 v103, v219, v195
	v_mul_f32_e32 v200, 0xbfb8aa3b, v92
	v_mul_f32_e32 v252, 0xbfb8aa3b, v93
	v_mul_f32_e32 v253, 0xbfb8aa3b, v94
	v_mul_f32_e32 v219, 0xbfb8aa3b, v95
	v_exp_f32_e32 v200, v200
	v_exp_f32_e32 v252, v252
	v_exp_f32_e32 v253, v253
	v_exp_f32_e32 v219, v219
	v_add_f32_e32 v200, 1.0, v200
	v_add_f32_e32 v252, 1.0, v252
	v_add_f32_e32 v253, 1.0, v253
	v_add_f32_e32 v219, 1.0, v219
	v_rcp_f32_e32 v200, v200
	v_rcp_f32_e32 v252, v252
	v_rcp_f32_e32 v253, v253
	v_rcp_f32_e32 v219, v219
	v_mul_f32_e32 v200, v92, v200
	v_mul_f32_e32 v252, v93, v252
	v_mul_f32_e32 v253, v94, v253
	v_mul_f32_e32 v219, v95, v219
	v_mul_f32_e32 v200, v200, v232
	v_mul_f32_e32 v252, v252, v233
	v_mul_f32_e32 v253, v253, v234
	v_mul_f32_e32 v219, v219, v235
	v_mul_f32_e32 v92, v200, v196
	v_mul_f32_e32 v93, v252, v197
	v_mul_f32_e32 v94, v253, v198
	v_mul_f32_e32 v95, v219, v199
	v_lshlrev_b32_e32 v192, 16, v164
	v_and_b32_e32 v193, 0xffff0000, v164
	v_lshlrev_b32_e32 v200, 16, v172
	v_and_b32_e32 v252, 0xffff0000, v172
	v_add_f32_e32 v192, v192, v200
	v_add_f32_e32 v193, v193, v252
	v_lshlrev_b32_e32 v194, 16, v165
	v_and_b32_e32 v195, 0xffff0000, v165
	v_lshlrev_b32_e32 v200, 16, v173
	v_and_b32_e32 v252, 0xffff0000, v173
	v_add_f32_e32 v194, v194, v200
	v_add_f32_e32 v195, v195, v252
	v_lshlrev_b32_e32 v196, 16, v166
	v_and_b32_e32 v197, 0xffff0000, v166
	v_lshlrev_b32_e32 v200, 16, v174
	v_and_b32_e32 v252, 0xffff0000, v174
	v_add_f32_e32 v196, v196, v200
	v_add_f32_e32 v197, v197, v252
	v_lshlrev_b32_e32 v198, 16, v167
	v_and_b32_e32 v199, 0xffff0000, v167
	v_lshlrev_b32_e32 v200, 16, v175
	v_and_b32_e32 v252, 0xffff0000, v175
	v_add_f32_e32 v198, v198, v200
	v_add_f32_e32 v199, v199, v252
	v_mul_f32_e32 v200, v192, v192
	v_mul_f32_e32 v252, v194, v194
	v_mul_f32_e32 v253, v196, v196
	v_mul_f32_e32 v219, v198, v198
	v_fmac_f32_e32 v200, v193, v193
	v_fmac_f32_e32 v252, v195, v195
	v_fmac_f32_e32 v253, v197, v197
	v_fmac_f32_e32 v219, v199, v199
	v_add_f32_e32 v200, v200, v252
	v_add_f32_e32 v253, v253, v219
	v_add_f32_e32 v200, v200, v253
	v_add_f32_e32 v246, v246, v200
	v_mul_f32_e32 v200, 0xbfb8aa3b, v80
	v_mul_f32_e32 v252, 0xbfb8aa3b, v81
	v_mul_f32_e32 v253, 0xbfb8aa3b, v82
	v_mul_f32_e32 v219, 0xbfb8aa3b, v83
	v_exp_f32_e32 v200, v200
	v_exp_f32_e32 v252, v252
	v_exp_f32_e32 v253, v253
	v_exp_f32_e32 v219, v219
	v_add_f32_e32 v200, 1.0, v200
	v_add_f32_e32 v252, 1.0, v252
	v_add_f32_e32 v253, 1.0, v253
	v_add_f32_e32 v219, 1.0, v219
	v_rcp_f32_e32 v200, v200
	v_rcp_f32_e32 v252, v252
	v_rcp_f32_e32 v253, v253
	v_rcp_f32_e32 v219, v219
	v_mul_f32_e32 v200, v80, v200
	v_mul_f32_e32 v252, v81, v252
	v_mul_f32_e32 v253, v82, v253
	v_mul_f32_e32 v219, v83, v219
	v_mul_f32_e32 v200, v200, v236
	v_mul_f32_e32 v252, v252, v237
	v_mul_f32_e32 v253, v253, v238
	v_mul_f32_e32 v219, v219, v239
	v_mul_f32_e32 v80, v200, v192
	v_mul_f32_e32 v81, v252, v193
	v_mul_f32_e32 v82, v253, v194
	v_mul_f32_e32 v83, v219, v195
	v_mul_f32_e32 v200, 0xbfb8aa3b, v72
	v_mul_f32_e32 v252, 0xbfb8aa3b, v73
	v_mul_f32_e32 v253, 0xbfb8aa3b, v74
	v_mul_f32_e32 v219, 0xbfb8aa3b, v75
	v_exp_f32_e32 v200, v200
	v_exp_f32_e32 v252, v252
	v_exp_f32_e32 v253, v253
	v_exp_f32_e32 v219, v219
	v_add_f32_e32 v200, 1.0, v200
	v_add_f32_e32 v252, 1.0, v252
	v_add_f32_e32 v253, 1.0, v253
	v_add_f32_e32 v219, 1.0, v219
	v_rcp_f32_e32 v200, v200
	v_rcp_f32_e32 v252, v252
	v_rcp_f32_e32 v253, v253
	v_rcp_f32_e32 v219, v219
	v_mul_f32_e32 v200, v72, v200
	v_mul_f32_e32 v252, v73, v252
	v_mul_f32_e32 v253, v74, v253
	v_mul_f32_e32 v219, v75, v219
	v_mul_f32_e32 v200, v200, v240
	v_mul_f32_e32 v252, v252, v241
	v_mul_f32_e32 v253, v253, v242
	v_mul_f32_e32 v219, v219, v243
	v_mul_f32_e32 v72, v200, v196
	v_mul_f32_e32 v73, v252, v197
	v_mul_f32_e32 v74, v253, v198
	v_mul_f32_e32 v75, v219, v199
	global_load_dwordx4 v[160:163], v[220:221], off
	global_load_dwordx4 v[164:167], v[220:221], off offset:256
	global_load_dwordx4 v[168:171], v[222:223], off
	global_load_dwordx4 v[172:175], v[222:223], off offset:256
	v_add_co_u32_e32 v220, vcc, 0x8000, v220
	s_nop 1
	v_addc_co_u32_e32 v221, vcc, 0, v221, vcc
	v_add_co_u32_e32 v222, vcc, 0x8000, v222
	s_nop 1
	v_addc_co_u32_e32 v223, vcc, 0, v223, vcc
	s_waitcnt vmcnt(8)
; __device__ __forceinline__ unsigned cvtpk(float lo, float hi) { f32x2 v = {lo, hi}; bf16x2_t b = __builtin_convertvector(v, bf16x2_t); return __builtin_bit_cast(unsigned, b); }
;     __device__ __forceinline__ void operator()(const af4 (&acc)[2][2][4][2], const pg8::Unit& u, int wr, int wc, int fr_, int fq_) const {
;     ...
;             for (int b_ = 0; b_ < 4; ++b_) {
;                 const int ai = b_ >> 1, mp = b_ & 1;
;                 int RRb = row0 + ai * 128 + mp * 32; asm volatile("" : "+v"(RRb));
;                 const size_t ob = (size_t)RRb * 1024 + col0; v4u of_[2][2], ob_[2][2];
; #pragma unroll
;                 for (int mi = 0; mi < 2; ++mi)
; #pragma unroll
;                     for (int bj = 0; bj < 2; ++bj) { of_[mi][bj] = *(const v4u*)(ON + ob + mi * 16 * 1024 + bj * 128); ob_[mi][bj] = *(const v4u*)(OBp + ob + mi * 16 * 1024 + bj * 128); }
; #pragma unroll
;                 for (int mi = 0; mi < 2; ++mi) { float q = 0.f;
; #pragma unroll
;                     for (int bj = 0; bj < 2; ++bj) { const v4u a = of_[mi][bj], c = ob_[mi][bj];
;                         const float o0 = bflo(a.x) + bflo(c.x), o1 = bfhi(a.x) + bfhi(c.x), o2 = bflo(a.y) + bflo(c.y), o3 = bfhi(a.y) + bfhi(c.y), o4 = bflo(a.z) + bflo(c.z), o5 = bfhi(a.z) + bfhi(c.z), o6 = bflo(a.w) + bflo(c.w), o7 = bfhi(a.w) + bfhi(c.w);
;                         q += (o0 * o0 + o1 * o1) + (o2 * o2 + o3 * o3) + (o4 * o4 + o5 * o5) + (o6 * o6 + o7 * o7); }
;                     ssq[ai * 4 + mp * 2 + mi] = q; }
;     ...
;                 for (int mi = 0; mi < 2; ++mi) { const float rstd = rs[ai * 4 + mp * 2 + mi];
; #pragma unroll
;                     for (int bj = 0; bj < 2; ++bj) { af4 v0 = acc[ai][bj][mp * 2 + mi][0], v1 = acc[ai][bj][mp * 2 + mi][1]; asm volatile("" : "+v"(v0), "+v"(v1)); const v4u a = of_[mi][bj], c = ob_[mi][bj];
; #pragma unroll
;                         for (int e = 0; e < 4; ++e) { v0[e] = v0[e] * sigmoidf_(v0[e]) * (rstd * nwv[bj][0][e]); v1[e] = v1[e] * sigmoidf_(v1[e]) * (rstd * nwv[bj][1][e]); }
;                         v4u w; w.x = cvtpk(v0[0] * (bflo(a.x) + bflo(c.x)), v0[1] * (bfhi(a.x) + bfhi(c.x))); w.y = cvtpk(v0[2] * (bflo(a.y) + bflo(c.y)), v0[3] * (bfhi(a.y) + bfhi(c.y)));
;                         w.z = cvtpk(v1[0] * (bflo(a.z) + bflo(c.z)), v1[1] * (bfhi(a.z) + bfhi(c.z))); w.w = cvtpk(v1[2] * (bflo(a.w) + bflo(c.w)), v1[3] * (bfhi(a.w) + bfhi(c.w)));
	v_lshlrev_b32_e32 v192, 16, v128
	v_and_b32_e32 v193, 0xffff0000, v128
	v_lshlrev_b32_e32 v200, 16, v136
	v_and_b32_e32 v252, 0xffff0000, v136
	v_add_f32_e32 v192, v192, v200
	v_add_f32_e32 v193, v193, v252
	v_lshlrev_b32_e32 v194, 16, v129
	v_and_b32_e32 v195, 0xffff0000, v129
	v_lshlrev_b32_e32 v200, 16, v137
	v_and_b32_e32 v252, 0xffff0000, v137
	v_add_f32_e32 v194, v194, v200
	v_add_f32_e32 v195, v195, v252
	v_lshlrev_b32_e32 v196, 16, v130
	v_and_b32_e32 v197, 0xffff0000, v130
	v_lshlrev_b32_e32 v200, 16, v138
	v_and_b32_e32 v252, 0xffff0000, v138
	v_add_f32_e32 v196, v196, v200
	v_add_f32_e32 v197, v197, v252
	v_lshlrev_b32_e32 v198, 16, v131
	v_and_b32_e32 v199, 0xffff0000, v131
	v_lshlrev_b32_e32 v200, 16, v139
	v_and_b32_e32 v252, 0xffff0000, v139
	v_add_f32_e32 v198, v198, v200
	v_add_f32_e32 v199, v199, v252
	v_mul_f32_e32 v200, v192, v192
	v_mul_f32_e32 v252, v194, v194
	v_mul_f32_e32 v253, v196, v196
	v_mul_f32_e32 v219, v198, v198
	v_fmac_f32_e32 v200, v193, v193
	v_fmac_f32_e32 v252, v195, v195
	v_fmac_f32_e32 v253, v197, v197
	v_fmac_f32_e32 v219, v199, v199
	v_add_f32_e32 v200, v200, v252
	v_add_f32_e32 v253, v253, v219
	v_add_f32_e32 v200, v200, v253
	v_add_f32_e32 v247, v247, v200
	v_mul_f32_e32 v200, 0xbfb8aa3b, v84
	v_mul_f32_e32 v252, 0xbfb8aa3b, v85
	v_mul_f32_e32 v253, 0xbfb8aa3b, v86
	v_mul_f32_e32 v219, 0xbfb8aa3b, v87
	v_exp_f32_e32 v200, v200
	v_exp_f32_e32 v252, v252
	v_exp_f32_e32 v253, v253
	v_exp_f32_e32 v219, v219
	v_add_f32_e32 v200, 1.0, v200
	v_add_f32_e32 v252, 1.0, v252
	v_add_f32_e32 v253, 1.0, v253
	v_add_f32_e32 v219, 1.0, v219
	v_rcp_f32_e32 v200, v200
	v_rcp_f32_e32 v252, v252
	v_rcp_f32_e32 v253, v253
	v_rcp_f32_e32 v219, v219
	v_mul_f32_e32 v200, v84, v200
	v_mul_f32_e32 v252, v85, v252
	v_mul_f32_e32 v253, v86, v253
	v_mul_f32_e32 v219, v87, v219
	v_mul_f32_e32 v200, v200, v228
	v_mul_f32_e32 v252, v252, v229
	v_mul_f32_e32 v253, v253, v230
	v_mul_f32_e32 v219, v219, v231
	v_mul_f32_e32 v84, v200, v192
	v_mul_f32_e32 v85, v252, v193
	v_mul_f32_e32 v86, v253, v194
	v_mul_f32_e32 v87, v219, v195
	v_mul_f32_e32 v200, 0xbfb8aa3b, v76
	v_mul_f32_e32 v252, 0xbfb8aa3b, v77
	v_mul_f32_e32 v253, 0xbfb8aa3b, v78
	v_mul_f32_e32 v219, 0xbfb8aa3b, v79
	v_exp_f32_e32 v200, v200
	v_exp_f32_e32 v252, v252
	v_exp_f32_e32 v253, v253
	v_exp_f32_e32 v219, v219
	v_add_f32_e32 v200, 1.0, v200
	v_add_f32_e32 v252, 1.0, v252
	v_add_f32_e32 v253, 1.0, v253
	v_add_f32_e32 v219, 1.0, v219
	v_rcp_f32_e32 v200, v200
	v_rcp_f32_e32 v252, v252
	v_rcp_f32_e32 v253, v253
	v_rcp_f32_e32 v219, v219
	v_mul_f32_e32 v200, v76, v200
	v_mul_f32_e32 v252, v77, v252
	v_mul_f32_e32 v253, v78, v253
	v_mul_f32_e32 v219, v79, v219
	v_mul_f32_e32 v200, v200, v232
	v_mul_f32_e32 v252, v252, v233
	v_mul_f32_e32 v253, v253, v234
	v_mul_f32_e32 v219, v219, v235
	v_mul_f32_e32 v76, v200, v196
	v_mul_f32_e32 v77, v252, v197
	v_mul_f32_e32 v78, v253, v198
	v_mul_f32_e32 v79, v219, v199
	v_lshlrev_b32_e32 v192, 16, v132
	v_and_b32_e32 v193, 0xffff0000, v132
	v_lshlrev_b32_e32 v200, 16, v140
	v_and_b32_e32 v252, 0xffff0000, v140
	v_add_f32_e32 v192, v192, v200
	v_add_f32_e32 v193, v193, v252
	v_lshlrev_b32_e32 v194, 16, v133
	v_and_b32_e32 v195, 0xffff0000, v133
	v_lshlrev_b32_e32 v200, 16, v141
	v_and_b32_e32 v252, 0xffff0000, v141
	v_add_f32_e32 v194, v194, v200
	v_add_f32_e32 v195, v195, v252
	v_lshlrev_b32_e32 v196, 16, v134
	v_and_b32_e32 v197, 0xffff0000, v134
	v_lshlrev_b32_e32 v200, 16, v142
	v_and_b32_e32 v252, 0xffff0000, v142
	v_add_f32_e32 v196, v196, v200
	v_add_f32_e32 v197, v197, v252
	v_lshlrev_b32_e32 v198, 16, v135
	v_and_b32_e32 v199, 0xffff0000, v135
	v_lshlrev_b32_e32 v200, 16, v143
	v_and_b32_e32 v252, 0xffff0000, v143
	v_add_f32_e32 v198, v198, v200
	v_add_f32_e32 v199, v199, v252
	v_mul_f32_e32 v200, v192, v192
	v_mul_f32_e32 v252, v194, v194
	v_mul_f32_e32 v253, v196, v196
	v_mul_f32_e32 v219, v198, v198
	v_fmac_f32_e32 v200, v193, v193
	v_fmac_f32_e32 v252, v195, v195
	v_fmac_f32_e32 v253, v197, v197
	v_fmac_f32_e32 v219, v199, v199
	v_add_f32_e32 v200, v200, v252
	v_add_f32_e32 v253, v253, v219
	v_add_f32_e32 v200, v200, v253
	v_add_f32_e32 v247, v247, v200
	v_mul_f32_e32 v200, 0xbfb8aa3b, v68
	v_mul_f32_e32 v252, 0xbfb8aa3b, v69
	v_mul_f32_e32 v253, 0xbfb8aa3b, v70
	v_mul_f32_e32 v219, 0xbfb8aa3b, v71
	v_exp_f32_e32 v200, v200
	v_exp_f32_e32 v252, v252
	v_exp_f32_e32 v253, v253
	v_exp_f32_e32 v219, v219
	v_add_f32_e32 v200, 1.0, v200
	v_add_f32_e32 v252, 1.0, v252
	v_add_f32_e32 v253, 1.0, v253
	v_add_f32_e32 v219, 1.0, v219
	v_rcp_f32_e32 v200, v200
	v_rcp_f32_e32 v252, v252
	v_rcp_f32_e32 v253, v253
	v_rcp_f32_e32 v219, v219
	v_mul_f32_e32 v200, v68, v200
	v_mul_f32_e32 v252, v69, v252
	v_mul_f32_e32 v253, v70, v253
	v_mul_f32_e32 v219, v71, v219
	v_mul_f32_e32 v200, v200, v236
	v_mul_f32_e32 v252, v252, v237
	v_mul_f32_e32 v253, v253, v238
	v_mul_f32_e32 v219, v219, v239
	v_mul_f32_e32 v68, v200, v192
	v_mul_f32_e32 v69, v252, v193
	v_mul_f32_e32 v70, v253, v194
	v_mul_f32_e32 v71, v219, v195
	v_mul_f32_e32 v200, 0xbfb8aa3b, v64
	v_mul_f32_e32 v252, 0xbfb8aa3b, v65
	v_mul_f32_e32 v253, 0xbfb8aa3b, v66
	v_mul_f32_e32 v219, 0xbfb8aa3b, v67
	v_exp_f32_e32 v200, v200
	v_exp_f32_e32 v252, v252
	v_exp_f32_e32 v253, v253
	v_exp_f32_e32 v219, v219
	v_add_f32_e32 v200, 1.0, v200
	v_add_f32_e32 v252, 1.0, v252
	v_add_f32_e32 v253, 1.0, v253
	v_add_f32_e32 v219, 1.0, v219
	v_rcp_f32_e32 v200, v200
	v_rcp_f32_e32 v252, v252
	v_rcp_f32_e32 v253, v253
	v_rcp_f32_e32 v219, v219
	v_mul_f32_e32 v200, v64, v200
	v_mul_f32_e32 v252, v65, v252
	v_mul_f32_e32 v253, v66, v253
	v_mul_f32_e32 v219, v67, v219
	v_mul_f32_e32 v200, v200, v240
	v_mul_f32_e32 v252, v252, v241
	v_mul_f32_e32 v253, v253, v242
	v_mul_f32_e32 v219, v219, v243
	v_mul_f32_e32 v64, v200, v196
	v_mul_f32_e32 v65, v252, v197
	v_mul_f32_e32 v66, v253, v198
	v_mul_f32_e32 v67, v219, v199
	global_load_dwordx4 v[128:131], v[220:221], off
	global_load_dwordx4 v[132:135], v[220:221], off offset:256
	global_load_dwordx4 v[136:139], v[222:223], off
	global_load_dwordx4 v[140:143], v[222:223], off offset:256
	v_add_co_u32_e32 v220, vcc, 0x8000, v220
	s_nop 1
	v_addc_co_u32_e32 v221, vcc, 0, v221, vcc
	v_add_co_u32_e32 v222, vcc, 0x8000, v222
	s_nop 1
	v_addc_co_u32_e32 v223, vcc, 0, v223, vcc
	s_waitcnt vmcnt(8)
; __device__ __forceinline__ unsigned cvtpk(float lo, float hi) { f32x2 v = {lo, hi}; bf16x2_t b = __builtin_convertvector(v, bf16x2_t); return __builtin_bit_cast(unsigned, b); }
;     __device__ __forceinline__ void operator()(const af4 (&acc)[2][2][4][2], const pg8::Unit& u, int wr, int wc, int fr_, int fq_) const {
;     ...
;             for (int b_ = 0; b_ < 4; ++b_) {
;                 const int ai = b_ >> 1, mp = b_ & 1;
;                 int RRb = row0 + ai * 128 + mp * 32; asm volatile("" : "+v"(RRb));
;                 const size_t ob = (size_t)RRb * 1024 + col0; v4u of_[2][2], ob_[2][2];
; #pragma unroll
;                 for (int mi = 0; mi < 2; ++mi)
; #pragma unroll
;                     for (int bj = 0; bj < 2; ++bj) { of_[mi][bj] = *(const v4u*)(ON + ob + mi * 16 * 1024 + bj * 128); ob_[mi][bj] = *(const v4u*)(OBp + ob + mi * 16 * 1024 + bj * 128); }
; #pragma unroll
;                 for (int mi = 0; mi < 2; ++mi) { float q = 0.f;
; #pragma unroll
;                     for (int bj = 0; bj < 2; ++bj) { const v4u a = of_[mi][bj], c = ob_[mi][bj];
;                         const float o0 = bflo(a.x) + bflo(c.x), o1 = bfhi(a.x) + bfhi(c.x), o2 = bflo(a.y) + bflo(c.y), o3 = bfhi(a.y) + bfhi(c.y), o4 = bflo(a.z) + bflo(c.z), o5 = bfhi(a.z) + bfhi(c.z), o6 = bflo(a.w) + bflo(c.w), o7 = bfhi(a.w) + bfhi(c.w);
;                         q += (o0 * o0 + o1 * o1) + (o2 * o2 + o3 * o3) + (o4 * o4 + o5 * o5) + (o6 * o6 + o7 * o7); }
;                     ssq[ai * 4 + mp * 2 + mi] = q; }
;     ...
;                 for (int mi = 0; mi < 2; ++mi) { const float rstd = rs[ai * 4 + mp * 2 + mi];
; #pragma unroll
;                     for (int bj = 0; bj < 2; ++bj) { af4 v0 = acc[ai][bj][mp * 2 + mi][0], v1 = acc[ai][bj][mp * 2 + mi][1]; asm volatile("" : "+v"(v0), "+v"(v1)); const v4u a = of_[mi][bj], c = ob_[mi][bj];
; #pragma unroll
;                         for (int e = 0; e < 4; ++e) { v0[e] = v0[e] * sigmoidf_(v0[e]) * (rstd * nwv[bj][0][e]); v1[e] = v1[e] * sigmoidf_(v1[e]) * (rstd * nwv[bj][1][e]); }
;                         v4u w; w.x = cvtpk(v0[0] * (bflo(a.x) + bflo(c.x)), v0[1] * (bfhi(a.x) + bfhi(c.x))); w.y = cvtpk(v0[2] * (bflo(a.y) + bflo(c.y)), v0[3] * (bfhi(a.y) + bfhi(c.y)));
;                         w.z = cvtpk(v1[0] * (bflo(a.z) + bflo(c.z)), v1[1] * (bfhi(a.z) + bfhi(c.z))); w.w = cvtpk(v1[2] * (bflo(a.w) + bflo(c.w)), v1[3] * (bfhi(a.w) + bfhi(c.w)));
	v_lshlrev_b32_e32 v192, 16, v144
	v_and_b32_e32 v193, 0xffff0000, v144
	v_lshlrev_b32_e32 v200, 16, v152
	v_and_b32_e32 v252, 0xffff0000, v152
	v_add_f32_e32 v192, v192, v200
	v_add_f32_e32 v193, v193, v252
	v_lshlrev_b32_e32 v194, 16, v145
	v_and_b32_e32 v195, 0xffff0000, v145
	v_lshlrev_b32_e32 v200, 16, v153
	v_and_b32_e32 v252, 0xffff0000, v153
	v_add_f32_e32 v194, v194, v200
	v_add_f32_e32 v195, v195, v252
	v_lshlrev_b32_e32 v196, 16, v146
	v_and_b32_e32 v197, 0xffff0000, v146
	v_lshlrev_b32_e32 v200, 16, v154
	v_and_b32_e32 v252, 0xffff0000, v154
	v_add_f32_e32 v196, v196, v200
	v_add_f32_e32 v197, v197, v252
	v_lshlrev_b32_e32 v198, 16, v147
	v_and_b32_e32 v199, 0xffff0000, v147
	v_lshlrev_b32_e32 v200, 16, v155
	v_and_b32_e32 v252, 0xffff0000, v155
	v_add_f32_e32 v198, v198, v200
	v_add_f32_e32 v199, v199, v252
	v_mul_f32_e32 v200, v192, v192
	v_mul_f32_e32 v252, v194, v194
	v_mul_f32_e32 v253, v196, v196
	v_mul_f32_e32 v219, v198, v198
	v_fmac_f32_e32 v200, v193, v193
	v_fmac_f32_e32 v252, v195, v195
	v_fmac_f32_e32 v253, v197, v197
	v_fmac_f32_e32 v219, v199, v199
	v_add_f32_e32 v200, v200, v252
	v_add_f32_e32 v253, v253, v219
	v_add_f32_e32 v200, v200, v253
	v_add_f32_e32 v248, v248, v200
	v_mul_f32_e32 v200, 0xbfb8aa3b, v60
	v_mul_f32_e32 v252, 0xbfb8aa3b, v61
	v_mul_f32_e32 v253, 0xbfb8aa3b, v62
	v_mul_f32_e32 v219, 0xbfb8aa3b, v63
	v_exp_f32_e32 v200, v200
	v_exp_f32_e32 v252, v252
	v_exp_f32_e32 v253, v253
	v_exp_f32_e32 v219, v219
	v_add_f32_e32 v200, 1.0, v200
	v_add_f32_e32 v252, 1.0, v252
	v_add_f32_e32 v253, 1.0, v253
	v_add_f32_e32 v219, 1.0, v219
	v_rcp_f32_e32 v200, v200
	v_rcp_f32_e32 v252, v252
	v_rcp_f32_e32 v253, v253
	v_rcp_f32_e32 v219, v219
	v_mul_f32_e32 v200, v60, v200
	v_mul_f32_e32 v252, v61, v252
	v_mul_f32_e32 v253, v62, v253
	v_mul_f32_e32 v219, v63, v219
	v_mul_f32_e32 v200, v200, v228
	v_mul_f32_e32 v252, v252, v229
	v_mul_f32_e32 v253, v253, v230
	v_mul_f32_e32 v219, v219, v231
	v_mul_f32_e32 v60, v200, v192
	v_mul_f32_e32 v61, v252, v193
	v_mul_f32_e32 v62, v253, v194
	v_mul_f32_e32 v63, v219, v195
	v_mul_f32_e32 v200, 0xbfb8aa3b, v56
	v_mul_f32_e32 v252, 0xbfb8aa3b, v57
	v_mul_f32_e32 v253, 0xbfb8aa3b, v58
	v_mul_f32_e32 v219, 0xbfb8aa3b, v59
	v_exp_f32_e32 v200, v200
	v_exp_f32_e32 v252, v252
	v_exp_f32_e32 v253, v253
	v_exp_f32_e32 v219, v219
	v_add_f32_e32 v200, 1.0, v200
	v_add_f32_e32 v252, 1.0, v252
	v_add_f32_e32 v253, 1.0, v253
	v_add_f32_e32 v219, 1.0, v219
	v_rcp_f32_e32 v200, v200
	v_rcp_f32_e32 v252, v252
	v_rcp_f32_e32 v253, v253
	v_rcp_f32_e32 v219, v219
	v_mul_f32_e32 v200, v56, v200
	v_mul_f32_e32 v252, v57, v252
	v_mul_f32_e32 v253, v58, v253
	v_mul_f32_e32 v219, v59, v219
	v_mul_f32_e32 v200, v200, v232
	v_mul_f32_e32 v252, v252, v233
	v_mul_f32_e32 v253, v253, v234
	v_mul_f32_e32 v219, v219, v235
	v_mul_f32_e32 v56, v200, v196
	v_mul_f32_e32 v57, v252, v197
	v_mul_f32_e32 v58, v253, v198
	v_mul_f32_e32 v59, v219, v199
	v_lshlrev_b32_e32 v192, 16, v148
	v_and_b32_e32 v193, 0xffff0000, v148
	v_lshlrev_b32_e32 v200, 16, v156
	v_and_b32_e32 v252, 0xffff0000, v156
	v_add_f32_e32 v192, v192, v200
	v_add_f32_e32 v193, v193, v252
	v_lshlrev_b32_e32 v194, 16, v149
	v_and_b32_e32 v195, 0xffff0000, v149
	v_lshlrev_b32_e32 v200, 16, v157
	v_and_b32_e32 v252, 0xffff0000, v157
	v_add_f32_e32 v194, v194, v200
	v_add_f32_e32 v195, v195, v252
	v_lshlrev_b32_e32 v196, 16, v150
	v_and_b32_e32 v197, 0xffff0000, v150
	v_lshlrev_b32_e32 v200, 16, v158
	v_and_b32_e32 v252, 0xffff0000, v158
	v_add_f32_e32 v196, v196, v200
	v_add_f32_e32 v197, v197, v252
	v_lshlrev_b32_e32 v198, 16, v151
	v_and_b32_e32 v199, 0xffff0000, v151
	v_lshlrev_b32_e32 v200, 16, v159
	v_and_b32_e32 v252, 0xffff0000, v159
	v_add_f32_e32 v198, v198, v200
	v_add_f32_e32 v199, v199, v252
	v_mul_f32_e32 v200, v192, v192
	v_mul_f32_e32 v252, v194, v194
	v_mul_f32_e32 v253, v196, v196
	v_mul_f32_e32 v219, v198, v198
	v_fmac_f32_e32 v200, v193, v193
	v_fmac_f32_e32 v252, v195, v195
	v_fmac_f32_e32 v253, v197, v197
	v_fmac_f32_e32 v219, v199, v199
	v_add_f32_e32 v200, v200, v252
	v_add_f32_e32 v253, v253, v219
	v_add_f32_e32 v200, v200, v253
	v_add_f32_e32 v248, v248, v200
	v_mul_f32_e32 v200, 0xbfb8aa3b, v48
	v_mul_f32_e32 v252, 0xbfb8aa3b, v49
	v_mul_f32_e32 v253, 0xbfb8aa3b, v50
	v_mul_f32_e32 v219, 0xbfb8aa3b, v51
	v_exp_f32_e32 v200, v200
	v_exp_f32_e32 v252, v252
	v_exp_f32_e32 v253, v253
	v_exp_f32_e32 v219, v219
	v_add_f32_e32 v200, 1.0, v200
	v_add_f32_e32 v252, 1.0, v252
	v_add_f32_e32 v253, 1.0, v253
	v_add_f32_e32 v219, 1.0, v219
	v_rcp_f32_e32 v200, v200
	v_rcp_f32_e32 v252, v252
	v_rcp_f32_e32 v253, v253
	v_rcp_f32_e32 v219, v219
	v_mul_f32_e32 v200, v48, v200
	v_mul_f32_e32 v252, v49, v252
	v_mul_f32_e32 v253, v50, v253
	v_mul_f32_e32 v219, v51, v219
	v_mul_f32_e32 v200, v200, v236
	v_mul_f32_e32 v252, v252, v237
	v_mul_f32_e32 v253, v253, v238
	v_mul_f32_e32 v219, v219, v239
	v_mul_f32_e32 v48, v200, v192
	v_mul_f32_e32 v49, v252, v193
	v_mul_f32_e32 v50, v253, v194
	v_mul_f32_e32 v51, v219, v195
	v_mul_f32_e32 v200, 0xbfb8aa3b, v40
	v_mul_f32_e32 v252, 0xbfb8aa3b, v41
	v_mul_f32_e32 v253, 0xbfb8aa3b, v42
	v_mul_f32_e32 v219, 0xbfb8aa3b, v43
	v_exp_f32_e32 v200, v200
	v_exp_f32_e32 v252, v252
	v_exp_f32_e32 v253, v253
	v_exp_f32_e32 v219, v219
	v_add_f32_e32 v200, 1.0, v200
	v_add_f32_e32 v252, 1.0, v252
	v_add_f32_e32 v253, 1.0, v253
	v_add_f32_e32 v219, 1.0, v219
	v_rcp_f32_e32 v200, v200
	v_rcp_f32_e32 v252, v252
	v_rcp_f32_e32 v253, v253
	v_rcp_f32_e32 v219, v219
	v_mul_f32_e32 v200, v40, v200
	v_mul_f32_e32 v252, v41, v252
	v_mul_f32_e32 v253, v42, v253
	v_mul_f32_e32 v219, v43, v219
	v_mul_f32_e32 v200, v200, v240
	v_mul_f32_e32 v252, v252, v241
	v_mul_f32_e32 v253, v253, v242
	v_mul_f32_e32 v219, v219, v243
	v_mul_f32_e32 v40, v200, v196
	v_mul_f32_e32 v41, v252, v197
	v_mul_f32_e32 v42, v253, v198
	v_mul_f32_e32 v43, v219, v199
	global_load_dwordx4 v[144:147], v[220:221], off
	global_load_dwordx4 v[148:151], v[220:221], off offset:256
	global_load_dwordx4 v[152:155], v[222:223], off
	global_load_dwordx4 v[156:159], v[222:223], off offset:256
	s_waitcnt vmcnt(8)
; __device__ __forceinline__ unsigned cvtpk(float lo, float hi) { f32x2 v = {lo, hi}; bf16x2_t b = __builtin_convertvector(v, bf16x2_t); return __builtin_bit_cast(unsigned, b); }
;     __device__ __forceinline__ void operator()(const af4 (&acc)[2][2][4][2], const pg8::Unit& u, int wr, int wc, int fr_, int fq_) const {
;     ...
;             for (int b_ = 0; b_ < 4; ++b_) {
;                 const int ai = b_ >> 1, mp = b_ & 1;
;                 int RRb = row0 + ai * 128 + mp * 32; asm volatile("" : "+v"(RRb));
;                 const size_t ob = (size_t)RRb * 1024 + col0; v4u of_[2][2], ob_[2][2];
; #pragma unroll
;                 for (int mi = 0; mi < 2; ++mi)
; #pragma unroll
;                     for (int bj = 0; bj < 2; ++bj) { of_[mi][bj] = *(const v4u*)(ON + ob + mi * 16 * 1024 + bj * 128); ob_[mi][bj] = *(const v4u*)(OBp + ob + mi * 16 * 1024 + bj * 128); }
; #pragma unroll
;                 for (int mi = 0; mi < 2; ++mi) { float q = 0.f;
; #pragma unroll
;                     for (int bj = 0; bj < 2; ++bj) { const v4u a = of_[mi][bj], c = ob_[mi][bj];
;                         const float o0 = bflo(a.x) + bflo(c.x), o1 = bfhi(a.x) + bfhi(c.x), o2 = bflo(a.y) + bflo(c.y), o3 = bfhi(a.y) + bfhi(c.y), o4 = bflo(a.z) + bflo(c.z), o5 = bfhi(a.z) + bfhi(c.z), o6 = bflo(a.w) + bflo(c.w), o7 = bfhi(a.w) + bfhi(c.w);
;                         q += (o0 * o0 + o1 * o1) + (o2 * o2 + o3 * o3) + (o4 * o4 + o5 * o5) + (o6 * o6 + o7 * o7); }
;                     ssq[ai * 4 + mp * 2 + mi] = q; }
;     ...
;                 for (int mi = 0; mi < 2; ++mi) { const float rstd = rs[ai * 4 + mp * 2 + mi];
; #pragma unroll
;                     for (int bj = 0; bj < 2; ++bj) { af4 v0 = acc[ai][bj][mp * 2 + mi][0], v1 = acc[ai][bj][mp * 2 + mi][1]; asm volatile("" : "+v"(v0), "+v"(v1)); const v4u a = of_[mi][bj], c = ob_[mi][bj];
; #pragma unroll
;                         for (int e = 0; e < 4; ++e) { v0[e] = v0[e] * sigmoidf_(v0[e]) * (rstd * nwv[bj][0][e]); v1[e] = v1[e] * sigmoidf_(v1[e]) * (rstd * nwv[bj][1][e]); }
;                         v4u w; w.x = cvtpk(v0[0] * (bflo(a.x) + bflo(c.x)), v0[1] * (bfhi(a.x) + bfhi(c.x))); w.y = cvtpk(v0[2] * (bflo(a.y) + bflo(c.y)), v0[3] * (bfhi(a.y) + bfhi(c.y)));
;                         w.z = cvtpk(v1[0] * (bflo(a.z) + bflo(c.z)), v1[1] * (bfhi(a.z) + bfhi(c.z))); w.w = cvtpk(v1[2] * (bflo(a.w) + bflo(c.w)), v1[3] * (bfhi(a.w) + bfhi(c.w)));
	v_lshlrev_b32_e32 v192, 16, v160
	v_and_b32_e32 v193, 0xffff0000, v160
	v_lshlrev_b32_e32 v200, 16, v168
	v_and_b32_e32 v252, 0xffff0000, v168
	v_add_f32_e32 v192, v192, v200
	v_add_f32_e32 v193, v193, v252
	v_lshlrev_b32_e32 v194, 16, v161
	v_and_b32_e32 v195, 0xffff0000, v161
	v_lshlrev_b32_e32 v200, 16, v169
	v_and_b32_e32 v252, 0xffff0000, v169
	v_add_f32_e32 v194, v194, v200
	v_add_f32_e32 v195, v195, v252
	v_lshlrev_b32_e32 v196, 16, v162
	v_and_b32_e32 v197, 0xffff0000, v162
	v_lshlrev_b32_e32 v200, 16, v170
	v_and_b32_e32 v252, 0xffff0000, v170
	v_add_f32_e32 v196, v196, v200
	v_add_f32_e32 v197, v197, v252
	v_lshlrev_b32_e32 v198, 16, v163
	v_and_b32_e32 v199, 0xffff0000, v163
	v_lshlrev_b32_e32 v200, 16, v171
	v_and_b32_e32 v252, 0xffff0000, v171
	v_add_f32_e32 v198, v198, v200
	v_add_f32_e32 v199, v199, v252
	v_mul_f32_e32 v200, v192, v192
	v_mul_f32_e32 v252, v194, v194
	v_mul_f32_e32 v253, v196, v196
	v_mul_f32_e32 v219, v198, v198
	v_fmac_f32_e32 v200, v193, v193
	v_fmac_f32_e32 v252, v195, v195
	v_fmac_f32_e32 v253, v197, v197
	v_fmac_f32_e32 v219, v199, v199
	v_add_f32_e32 v200, v200, v252
	v_add_f32_e32 v253, v253, v219
	v_add_f32_e32 v200, v200, v253
	v_add_f32_e32 v249, v249, v200
	v_mul_f32_e32 v200, 0xbfb8aa3b, v52
	v_mul_f32_e32 v252, 0xbfb8aa3b, v53
	v_mul_f32_e32 v253, 0xbfb8aa3b, v54
	v_mul_f32_e32 v219, 0xbfb8aa3b, v55
	v_exp_f32_e32 v200, v200
	v_exp_f32_e32 v252, v252
	v_exp_f32_e32 v253, v253
	v_exp_f32_e32 v219, v219
	v_add_f32_e32 v200, 1.0, v200
	v_add_f32_e32 v252, 1.0, v252
	v_add_f32_e32 v253, 1.0, v253
	v_add_f32_e32 v219, 1.0, v219
	v_rcp_f32_e32 v200, v200
	v_rcp_f32_e32 v252, v252
	v_rcp_f32_e32 v253, v253
	v_rcp_f32_e32 v219, v219
	v_mul_f32_e32 v200, v52, v200
	v_mul_f32_e32 v252, v53, v252
	v_mul_f32_e32 v253, v54, v253
	v_mul_f32_e32 v219, v55, v219
	v_mul_f32_e32 v200, v200, v228
	v_mul_f32_e32 v252, v252, v229
	v_mul_f32_e32 v253, v253, v230
	v_mul_f32_e32 v219, v219, v231
	v_mul_f32_e32 v52, v200, v192
	v_mul_f32_e32 v53, v252, v193
	v_mul_f32_e32 v54, v253, v194
	v_mul_f32_e32 v55, v219, v195
	v_mul_f32_e32 v200, 0xbfb8aa3b, v44
	v_mul_f32_e32 v252, 0xbfb8aa3b, v45
	v_mul_f32_e32 v253, 0xbfb8aa3b, v46
	v_mul_f32_e32 v219, 0xbfb8aa3b, v47
	v_exp_f32_e32 v200, v200
	v_exp_f32_e32 v252, v252
	v_exp_f32_e32 v253, v253
	v_exp_f32_e32 v219, v219
	v_add_f32_e32 v200, 1.0, v200
	v_add_f32_e32 v252, 1.0, v252
	v_add_f32_e32 v253, 1.0, v253
	v_add_f32_e32 v219, 1.0, v219
	v_rcp_f32_e32 v200, v200
	v_rcp_f32_e32 v252, v252
	v_rcp_f32_e32 v253, v253
	v_rcp_f32_e32 v219, v219
	v_mul_f32_e32 v200, v44, v200
	v_mul_f32_e32 v252, v45, v252
	v_mul_f32_e32 v253, v46, v253
	v_mul_f32_e32 v219, v47, v219
	v_mul_f32_e32 v200, v200, v232
	v_mul_f32_e32 v252, v252, v233
	v_mul_f32_e32 v253, v253, v234
	v_mul_f32_e32 v219, v219, v235
	v_mul_f32_e32 v44, v200, v196
	v_mul_f32_e32 v45, v252, v197
	v_mul_f32_e32 v46, v253, v198
	v_mul_f32_e32 v47, v219, v199
	v_lshlrev_b32_e32 v192, 16, v164
	v_and_b32_e32 v193, 0xffff0000, v164
	v_lshlrev_b32_e32 v200, 16, v172
	v_and_b32_e32 v252, 0xffff0000, v172
	v_add_f32_e32 v192, v192, v200
	v_add_f32_e32 v193, v193, v252
	v_lshlrev_b32_e32 v194, 16, v165
	v_and_b32_e32 v195, 0xffff0000, v165
	v_lshlrev_b32_e32 v200, 16, v173
	v_and_b32_e32 v252, 0xffff0000, v173
	v_add_f32_e32 v194, v194, v200
	v_add_f32_e32 v195, v195, v252
	v_lshlrev_b32_e32 v196, 16, v166
	v_and_b32_e32 v197, 0xffff0000, v166
	v_lshlrev_b32_e32 v200, 16, v174
	v_and_b32_e32 v252, 0xffff0000, v174
	v_add_f32_e32 v196, v196, v200
	v_add_f32_e32 v197, v197, v252
	v_lshlrev_b32_e32 v198, 16, v167
	v_and_b32_e32 v199, 0xffff0000, v167
	v_lshlrev_b32_e32 v200, 16, v175
	v_and_b32_e32 v252, 0xffff0000, v175
	v_add_f32_e32 v198, v198, v200
	v_add_f32_e32 v199, v199, v252
	v_mul_f32_e32 v200, v192, v192
	v_mul_f32_e32 v252, v194, v194
	v_mul_f32_e32 v253, v196, v196
	v_mul_f32_e32 v219, v198, v198
	v_fmac_f32_e32 v200, v193, v193
	v_fmac_f32_e32 v252, v195, v195
	v_fmac_f32_e32 v253, v197, v197
	v_fmac_f32_e32 v219, v199, v199
	v_add_f32_e32 v200, v200, v252
	v_add_f32_e32 v253, v253, v219
	v_add_f32_e32 v200, v200, v253
	v_add_f32_e32 v249, v249, v200
	v_mul_f32_e32 v200, 0xbfb8aa3b, v32
	v_mul_f32_e32 v252, 0xbfb8aa3b, v33
	v_mul_f32_e32 v253, 0xbfb8aa3b, v34
	v_mul_f32_e32 v219, 0xbfb8aa3b, v35
	v_exp_f32_e32 v200, v200
	v_exp_f32_e32 v252, v252
	v_exp_f32_e32 v253, v253
	v_exp_f32_e32 v219, v219
	v_add_f32_e32 v200, 1.0, v200
	v_add_f32_e32 v252, 1.0, v252
	v_add_f32_e32 v253, 1.0, v253
	v_add_f32_e32 v219, 1.0, v219
	v_rcp_f32_e32 v200, v200
	v_rcp_f32_e32 v252, v252
	v_rcp_f32_e32 v253, v253
	v_rcp_f32_e32 v219, v219
	v_mul_f32_e32 v200, v32, v200
	v_mul_f32_e32 v252, v33, v252
	v_mul_f32_e32 v253, v34, v253
	v_mul_f32_e32 v219, v35, v219
	v_mul_f32_e32 v200, v200, v236
	v_mul_f32_e32 v252, v252, v237
	v_mul_f32_e32 v253, v253, v238
	v_mul_f32_e32 v219, v219, v239
	v_mul_f32_e32 v32, v200, v192
	v_mul_f32_e32 v33, v252, v193
	v_mul_f32_e32 v34, v253, v194
	v_mul_f32_e32 v35, v219, v195
	v_mul_f32_e32 v200, 0xbfb8aa3b, v24
	v_mul_f32_e32 v252, 0xbfb8aa3b, v25
	v_mul_f32_e32 v253, 0xbfb8aa3b, v26
	v_mul_f32_e32 v219, 0xbfb8aa3b, v27
	v_exp_f32_e32 v200, v200
	v_exp_f32_e32 v252, v252
	v_exp_f32_e32 v253, v253
	v_exp_f32_e32 v219, v219
	v_add_f32_e32 v200, 1.0, v200
	v_add_f32_e32 v252, 1.0, v252
	v_add_f32_e32 v253, 1.0, v253
	v_add_f32_e32 v219, 1.0, v219
	v_rcp_f32_e32 v200, v200
	v_rcp_f32_e32 v252, v252
	v_rcp_f32_e32 v253, v253
	v_rcp_f32_e32 v219, v219
	v_mul_f32_e32 v200, v24, v200
	v_mul_f32_e32 v252, v25, v252
	v_mul_f32_e32 v253, v26, v253
	v_mul_f32_e32 v219, v27, v219
	v_mul_f32_e32 v200, v200, v240
	v_mul_f32_e32 v252, v252, v241
	v_mul_f32_e32 v253, v253, v242
	v_mul_f32_e32 v219, v219, v243
	v_mul_f32_e32 v24, v200, v196
	v_mul_f32_e32 v25, v252, v197
	v_mul_f32_e32 v26, v253, v198
	v_mul_f32_e32 v27, v219, v199
	s_waitcnt vmcnt(4)
; __device__ __forceinline__ unsigned cvtpk(float lo, float hi) { f32x2 v = {lo, hi}; bf16x2_t b = __builtin_convertvector(v, bf16x2_t); return __builtin_bit_cast(unsigned, b); }
;     __device__ __forceinline__ void operator()(const af4 (&acc)[2][2][4][2], const pg8::Unit& u, int wr, int wc, int fr_, int fq_) const {
;     ...
;             for (int b_ = 0; b_ < 4; ++b_) {
;                 const int ai = b_ >> 1, mp = b_ & 1;
;                 int RRb = row0 + ai * 128 + mp * 32; asm volatile("" : "+v"(RRb));
;                 const size_t ob = (size_t)RRb * 1024 + col0; v4u of_[2][2], ob_[2][2];
; #pragma unroll
;                 for (int mi = 0; mi < 2; ++mi)
; #pragma unroll
;                     for (int bj = 0; bj < 2; ++bj) { of_[mi][bj] = *(const v4u*)(ON + ob + mi * 16 * 1024 + bj * 128); ob_[mi][bj] = *(const v4u*)(OBp + ob + mi * 16 * 1024 + bj * 128); }
; #pragma unroll
;                 for (int mi = 0; mi < 2; ++mi) { float q = 0.f;
; #pragma unroll
;                     for (int bj = 0; bj < 2; ++bj) { const v4u a = of_[mi][bj], c = ob_[mi][bj];
;                         const float o0 = bflo(a.x) + bflo(c.x), o1 = bfhi(a.x) + bfhi(c.x), o2 = bflo(a.y) + bflo(c.y), o3 = bfhi(a.y) + bfhi(c.y), o4 = bflo(a.z) + bflo(c.z), o5 = bfhi(a.z) + bfhi(c.z), o6 = bflo(a.w) + bflo(c.w), o7 = bfhi(a.w) + bfhi(c.w);
;                         q += (o0 * o0 + o1 * o1) + (o2 * o2 + o3 * o3) + (o4 * o4 + o5 * o5) + (o6 * o6 + o7 * o7); }
;                     ssq[ai * 4 + mp * 2 + mi] = q; }
;     ...
;                 for (int mi = 0; mi < 2; ++mi) { const float rstd = rs[ai * 4 + mp * 2 + mi];
; #pragma unroll
;                     for (int bj = 0; bj < 2; ++bj) { af4 v0 = acc[ai][bj][mp * 2 + mi][0], v1 = acc[ai][bj][mp * 2 + mi][1]; asm volatile("" : "+v"(v0), "+v"(v1)); const v4u a = of_[mi][bj], c = ob_[mi][bj];
; #pragma unroll
;                         for (int e = 0; e < 4; ++e) { v0[e] = v0[e] * sigmoidf_(v0[e]) * (rstd * nwv[bj][0][e]); v1[e] = v1[e] * sigmoidf_(v1[e]) * (rstd * nwv[bj][1][e]); }
;                         v4u w; w.x = cvtpk(v0[0] * (bflo(a.x) + bflo(c.x)), v0[1] * (bfhi(a.x) + bfhi(c.x))); w.y = cvtpk(v0[2] * (bflo(a.y) + bflo(c.y)), v0[3] * (bfhi(a.y) + bfhi(c.y)));
;                         w.z = cvtpk(v1[0] * (bflo(a.z) + bflo(c.z)), v1[1] * (bfhi(a.z) + bfhi(c.z))); w.w = cvtpk(v1[2] * (bflo(a.w) + bflo(c.w)), v1[3] * (bfhi(a.w) + bfhi(c.w)));
	v_lshlrev_b32_e32 v192, 16, v128
	v_and_b32_e32 v193, 0xffff0000, v128
	v_lshlrev_b32_e32 v200, 16, v136
	v_and_b32_e32 v252, 0xffff0000, v136
	v_add_f32_e32 v192, v192, v200
	v_add_f32_e32 v193, v193, v252
	v_lshlrev_b32_e32 v194, 16, v129
	v_and_b32_e32 v195, 0xffff0000, v129
	v_lshlrev_b32_e32 v200, 16, v137
	v_and_b32_e32 v252, 0xffff0000, v137
	v_add_f32_e32 v194, v194, v200
	v_add_f32_e32 v195, v195, v252
	v_lshlrev_b32_e32 v196, 16, v130
	v_and_b32_e32 v197, 0xffff0000, v130
	v_lshlrev_b32_e32 v200, 16, v138
	v_and_b32_e32 v252, 0xffff0000, v138
	v_add_f32_e32 v196, v196, v200
	v_add_f32_e32 v197, v197, v252
	v_lshlrev_b32_e32 v198, 16, v131
	v_and_b32_e32 v199, 0xffff0000, v131
	v_lshlrev_b32_e32 v200, 16, v139
	v_and_b32_e32 v252, 0xffff0000, v139
	v_add_f32_e32 v198, v198, v200
	v_add_f32_e32 v199, v199, v252
	v_mul_f32_e32 v200, v192, v192
	v_mul_f32_e32 v252, v194, v194
	v_mul_f32_e32 v253, v196, v196
	v_mul_f32_e32 v219, v198, v198
	v_fmac_f32_e32 v200, v193, v193
	v_fmac_f32_e32 v252, v195, v195
	v_fmac_f32_e32 v253, v197, v197
	v_fmac_f32_e32 v219, v199, v199
	v_add_f32_e32 v200, v200, v252
	v_add_f32_e32 v253, v253, v219
	v_add_f32_e32 v200, v200, v253
	v_add_f32_e32 v250, v250, v200
	v_mul_f32_e32 v200, 0xbfb8aa3b, v36
	v_mul_f32_e32 v252, 0xbfb8aa3b, v37
	v_mul_f32_e32 v253, 0xbfb8aa3b, v38
	v_mul_f32_e32 v219, 0xbfb8aa3b, v39
	v_exp_f32_e32 v200, v200
	v_exp_f32_e32 v252, v252
	v_exp_f32_e32 v253, v253
	v_exp_f32_e32 v219, v219
	v_add_f32_e32 v200, 1.0, v200
	v_add_f32_e32 v252, 1.0, v252
	v_add_f32_e32 v253, 1.0, v253
	v_add_f32_e32 v219, 1.0, v219
	v_rcp_f32_e32 v200, v200
	v_rcp_f32_e32 v252, v252
	v_rcp_f32_e32 v253, v253
	v_rcp_f32_e32 v219, v219
	v_mul_f32_e32 v200, v36, v200
	v_mul_f32_e32 v252, v37, v252
	v_mul_f32_e32 v253, v38, v253
	v_mul_f32_e32 v219, v39, v219
	v_mul_f32_e32 v200, v200, v228
	v_mul_f32_e32 v252, v252, v229
	v_mul_f32_e32 v253, v253, v230
	v_mul_f32_e32 v219, v219, v231
	v_mul_f32_e32 v36, v200, v192
	v_mul_f32_e32 v37, v252, v193
	v_mul_f32_e32 v38, v253, v194
	v_mul_f32_e32 v39, v219, v195
	v_mul_f32_e32 v200, 0xbfb8aa3b, v28
	v_mul_f32_e32 v252, 0xbfb8aa3b, v29
	v_mul_f32_e32 v253, 0xbfb8aa3b, v30
	v_mul_f32_e32 v219, 0xbfb8aa3b, v31
	v_exp_f32_e32 v200, v200
	v_exp_f32_e32 v252, v252
	v_exp_f32_e32 v253, v253
	v_exp_f32_e32 v219, v219
	v_add_f32_e32 v200, 1.0, v200
	v_add_f32_e32 v252, 1.0, v252
	v_add_f32_e32 v253, 1.0, v253
	v_add_f32_e32 v219, 1.0, v219
	v_rcp_f32_e32 v200, v200
	v_rcp_f32_e32 v252, v252
	v_rcp_f32_e32 v253, v253
	v_rcp_f32_e32 v219, v219
	v_mul_f32_e32 v200, v28, v200
	v_mul_f32_e32 v252, v29, v252
	v_mul_f32_e32 v253, v30, v253
	v_mul_f32_e32 v219, v31, v219
	v_mul_f32_e32 v200, v200, v232
	v_mul_f32_e32 v252, v252, v233
	v_mul_f32_e32 v253, v253, v234
	v_mul_f32_e32 v219, v219, v235
	v_mul_f32_e32 v28, v200, v196
	v_mul_f32_e32 v29, v252, v197
	v_mul_f32_e32 v30, v253, v198
	v_mul_f32_e32 v31, v219, v199
	v_lshlrev_b32_e32 v192, 16, v132
	v_and_b32_e32 v193, 0xffff0000, v132
	v_lshlrev_b32_e32 v200, 16, v140
	v_and_b32_e32 v252, 0xffff0000, v140
	v_add_f32_e32 v192, v192, v200
	v_add_f32_e32 v193, v193, v252
	v_lshlrev_b32_e32 v194, 16, v133
	v_and_b32_e32 v195, 0xffff0000, v133
	v_lshlrev_b32_e32 v200, 16, v141
	v_and_b32_e32 v252, 0xffff0000, v141
	v_add_f32_e32 v194, v194, v200
	v_add_f32_e32 v195, v195, v252
	v_lshlrev_b32_e32 v196, 16, v134
	v_and_b32_e32 v197, 0xffff0000, v134
	v_lshlrev_b32_e32 v200, 16, v142
	v_and_b32_e32 v252, 0xffff0000, v142
	v_add_f32_e32 v196, v196, v200
	v_add_f32_e32 v197, v197, v252
	v_lshlrev_b32_e32 v198, 16, v135
	v_and_b32_e32 v199, 0xffff0000, v135
	v_lshlrev_b32_e32 v200, 16, v143
	v_and_b32_e32 v252, 0xffff0000, v143
	v_add_f32_e32 v198, v198, v200
	v_add_f32_e32 v199, v199, v252
	v_mul_f32_e32 v200, v192, v192
	v_mul_f32_e32 v252, v194, v194
	v_mul_f32_e32 v253, v196, v196
	v_mul_f32_e32 v219, v198, v198
	v_fmac_f32_e32 v200, v193, v193
	v_fmac_f32_e32 v252, v195, v195
	v_fmac_f32_e32 v253, v197, v197
	v_fmac_f32_e32 v219, v199, v199
	v_add_f32_e32 v200, v200, v252
	v_add_f32_e32 v253, v253, v219
	v_add_f32_e32 v200, v200, v253
	v_add_f32_e32 v250, v250, v200
	v_mul_f32_e32 v200, 0xbfb8aa3b, v16
	v_mul_f32_e32 v252, 0xbfb8aa3b, v17
	v_mul_f32_e32 v253, 0xbfb8aa3b, v18
	v_mul_f32_e32 v219, 0xbfb8aa3b, v19
	v_exp_f32_e32 v200, v200
	v_exp_f32_e32 v252, v252
	v_exp_f32_e32 v253, v253
	v_exp_f32_e32 v219, v219
	v_add_f32_e32 v200, 1.0, v200
	v_add_f32_e32 v252, 1.0, v252
	v_add_f32_e32 v253, 1.0, v253
	v_add_f32_e32 v219, 1.0, v219
	v_rcp_f32_e32 v200, v200
	v_rcp_f32_e32 v252, v252
	v_rcp_f32_e32 v253, v253
	v_rcp_f32_e32 v219, v219
	v_mul_f32_e32 v200, v16, v200
	v_mul_f32_e32 v252, v17, v252
	v_mul_f32_e32 v253, v18, v253
	v_mul_f32_e32 v219, v19, v219
	v_mul_f32_e32 v200, v200, v236
	v_mul_f32_e32 v252, v252, v237
	v_mul_f32_e32 v253, v253, v238
	v_mul_f32_e32 v219, v219, v239
	v_mul_f32_e32 v16, v200, v192
	v_mul_f32_e32 v17, v252, v193
	v_mul_f32_e32 v18, v253, v194
	v_mul_f32_e32 v19, v219, v195
	v_mul_f32_e32 v200, 0xbfb8aa3b, v8
	v_mul_f32_e32 v252, 0xbfb8aa3b, v9
	v_mul_f32_e32 v253, 0xbfb8aa3b, v10
	v_mul_f32_e32 v219, 0xbfb8aa3b, v11
	v_exp_f32_e32 v200, v200
	v_exp_f32_e32 v252, v252
	v_exp_f32_e32 v253, v253
	v_exp_f32_e32 v219, v219
	v_add_f32_e32 v200, 1.0, v200
	v_add_f32_e32 v252, 1.0, v252
	v_add_f32_e32 v253, 1.0, v253
	v_add_f32_e32 v219, 1.0, v219
	v_rcp_f32_e32 v200, v200
	v_rcp_f32_e32 v252, v252
	v_rcp_f32_e32 v253, v253
	v_rcp_f32_e32 v219, v219
	v_mul_f32_e32 v200, v8, v200
	v_mul_f32_e32 v252, v9, v252
	v_mul_f32_e32 v253, v10, v253
	v_mul_f32_e32 v219, v11, v219
	v_mul_f32_e32 v200, v200, v240
	v_mul_f32_e32 v252, v252, v241
	v_mul_f32_e32 v253, v253, v242
	v_mul_f32_e32 v219, v219, v243
	v_mul_f32_e32 v8, v200, v196
	v_mul_f32_e32 v9, v252, v197
	v_mul_f32_e32 v10, v253, v198
	v_mul_f32_e32 v11, v219, v199
	s_waitcnt vmcnt(0)
; __device__ __forceinline__ float bflo(unsigned u) { return __uint_as_float(u << 16); }
; __device__ __forceinline__ float bfhi(unsigned u) { return __uint_as_float(u & 0xffff0000u); }
;     __device__ __forceinline__ void operator()(const af4 (&acc)[2][2][4][2], const pg8::Unit& u, int wr, int wc, int fr_, int fq_) const {
;     ...
;             for (int b_ = 0; b_ < 4; ++b_) {
;                 const int ai = b_ >> 1, mp = b_ & 1;
;                 int RRb = row0 + ai * 128 + mp * 32; asm volatile("" : "+v"(RRb));
;                 const size_t ob = (size_t)RRb * 1024 + col0; v4u of_[2][2], ob_[2][2];
; #pragma unroll
;                 for (int mi = 0; mi < 2; ++mi)
; #pragma unroll
;                     for (int bj = 0; bj < 2; ++bj) { of_[mi][bj] = *(const v4u*)(ON + ob + mi * 16 * 1024 + bj * 128); ob_[mi][bj] = *(const v4u*)(OBp + ob + mi * 16 * 1024 + bj * 128); }
; #pragma unroll
;                 for (int mi = 0; mi < 2; ++mi) { float q = 0.f;
; #pragma unroll
;                     for (int bj = 0; bj < 2; ++bj) { const v4u a = of_[mi][bj], c = ob_[mi][bj];
;                         const float o0 = bflo(a.x) + bflo(c.x), o1 = bfhi(a.x) + bfhi(c.x), o2 = bflo(a.y) + bflo(c.y), o3 = bfhi(a.y) + bfhi(c.y), o4 = bflo(a.z) + bflo(c.z), o5 = bfhi(a.z) + bfhi(c.z), o6 = bflo(a.w) + bflo(c.w), o7 = bfhi(a.w) + bfhi(c.w);
;                         q += (o0 * o0 + o1 * o1) + (o2 * o2 + o3 * o3) + (o4 * o4 + o5 * o5) + (o6 * o6 + o7 * o7); }
;                     ssq[ai * 4 + mp * 2 + mi] = q; }
;                 asm volatile("" ::: "memory");
;             }
; #pragma unroll
;             for (int k = 0; k < 8; ++k) { float v = ssq[k];
;                 v += __int_as_float(__builtin_amdgcn_ds_bpermute((ln_ ^ 16) << 2, __float_as_int(v)));
;                 v += __int_as_float(__builtin_amdgcn_ds_bpermute((ln_ ^ 32) << 2, __float_as_int(v))); ssq[k] = v; }
;     ...
;                 for (int mi = 0; mi < 2; ++mi) { const float rstd = rs[ai * 4 + mp * 2 + mi];
; #pragma unroll
;                     for (int bj = 0; bj < 2; ++bj) { af4 v0 = acc[ai][bj][mp * 2 + mi][0], v1 = acc[ai][bj][mp * 2 + mi][1]; asm volatile("" : "+v"(v0), "+v"(v1)); const v4u a = of_[mi][bj], c = ob_[mi][bj];
; #pragma unroll
;                         for (int e = 0; e < 4; ++e) { v0[e] = v0[e] * sigmoidf_(v0[e]) * (rstd * nwv[bj][0][e]); v1[e] = v1[e] * sigmoidf_(v1[e]) * (rstd * nwv[bj][1][e]); }
	v_lshlrev_b32_e32 v192, 16, v144
	v_and_b32_e32 v193, 0xffff0000, v144
	v_lshlrev_b32_e32 v200, 16, v152
	v_and_b32_e32 v252, 0xffff0000, v152
	v_add_f32_e32 v192, v192, v200
	v_add_f32_e32 v193, v193, v252
	v_lshlrev_b32_e32 v194, 16, v145
	v_and_b32_e32 v195, 0xffff0000, v145
	v_lshlrev_b32_e32 v200, 16, v153
	v_and_b32_e32 v252, 0xffff0000, v153
	v_add_f32_e32 v194, v194, v200
	v_add_f32_e32 v195, v195, v252
	v_lshlrev_b32_e32 v196, 16, v146
	v_and_b32_e32 v197, 0xffff0000, v146
	v_lshlrev_b32_e32 v200, 16, v154
	v_and_b32_e32 v252, 0xffff0000, v154
	v_add_f32_e32 v196, v196, v200
	v_add_f32_e32 v197, v197, v252
	v_lshlrev_b32_e32 v198, 16, v147
	v_and_b32_e32 v199, 0xffff0000, v147
	v_lshlrev_b32_e32 v200, 16, v155
	v_and_b32_e32 v252, 0xffff0000, v155
	v_add_f32_e32 v198, v198, v200
	v_add_f32_e32 v199, v199, v252
	v_mul_f32_e32 v200, v192, v192
	v_mul_f32_e32 v252, v194, v194
	v_mul_f32_e32 v253, v196, v196
	v_mul_f32_e32 v219, v198, v198
	v_fmac_f32_e32 v200, v193, v193
	v_fmac_f32_e32 v252, v195, v195
	v_fmac_f32_e32 v253, v197, v197
	v_fmac_f32_e32 v219, v199, v199
	v_add_f32_e32 v200, v200, v252
	v_add_f32_e32 v253, v253, v219
	v_add_f32_e32 v200, v200, v253
	v_add_f32_e32 v251, v251, v200
	v_mul_f32_e32 v200, 0xbfb8aa3b, v20
	v_mul_f32_e32 v252, 0xbfb8aa3b, v21
	v_mul_f32_e32 v253, 0xbfb8aa3b, v22
	v_mul_f32_e32 v219, 0xbfb8aa3b, v23
	v_exp_f32_e32 v200, v200
	v_exp_f32_e32 v252, v252
	v_exp_f32_e32 v253, v253
	v_exp_f32_e32 v219, v219
	v_add_f32_e32 v200, 1.0, v200
	v_add_f32_e32 v252, 1.0, v252
	v_add_f32_e32 v253, 1.0, v253
	v_add_f32_e32 v219, 1.0, v219
	v_rcp_f32_e32 v200, v200
	v_rcp_f32_e32 v252, v252
	v_rcp_f32_e32 v253, v253
	v_rcp_f32_e32 v219, v219
	v_mul_f32_e32 v200, v20, v200
	v_mul_f32_e32 v252, v21, v252
	v_mul_f32_e32 v253, v22, v253
	v_mul_f32_e32 v219, v23, v219
	v_mul_f32_e32 v200, v200, v228
	v_mul_f32_e32 v252, v252, v229
	v_mul_f32_e32 v253, v253, v230
	v_mul_f32_e32 v219, v219, v231
	v_mul_f32_e32 v20, v200, v192
	v_mul_f32_e32 v21, v252, v193
	v_mul_f32_e32 v22, v253, v194
	v_mul_f32_e32 v23, v219, v195
	v_mul_f32_e32 v200, 0xbfb8aa3b, v12
	v_mul_f32_e32 v252, 0xbfb8aa3b, v13
	v_mul_f32_e32 v253, 0xbfb8aa3b, v14
	v_mul_f32_e32 v219, 0xbfb8aa3b, v15
	v_exp_f32_e32 v200, v200
	v_exp_f32_e32 v252, v252
	v_exp_f32_e32 v253, v253
	v_exp_f32_e32 v219, v219
	v_add_f32_e32 v200, 1.0, v200
	v_add_f32_e32 v252, 1.0, v252
	v_add_f32_e32 v253, 1.0, v253
	v_add_f32_e32 v219, 1.0, v219
	v_rcp_f32_e32 v200, v200
	v_rcp_f32_e32 v252, v252
	v_rcp_f32_e32 v253, v253
	v_rcp_f32_e32 v219, v219
	v_mul_f32_e32 v200, v12, v200
	v_mul_f32_e32 v252, v13, v252
	v_mul_f32_e32 v253, v14, v253
	v_mul_f32_e32 v219, v15, v219
	v_mul_f32_e32 v200, v200, v232
	v_mul_f32_e32 v252, v252, v233
	v_mul_f32_e32 v253, v253, v234
	v_mul_f32_e32 v219, v219, v235
	v_mul_f32_e32 v12, v200, v196
	v_mul_f32_e32 v13, v252, v197
	v_mul_f32_e32 v14, v253, v198
	v_mul_f32_e32 v15, v219, v199
	v_lshlrev_b32_e32 v192, 16, v148
	v_and_b32_e32 v193, 0xffff0000, v148
	v_lshlrev_b32_e32 v200, 16, v156
	v_and_b32_e32 v252, 0xffff0000, v156
	v_add_f32_e32 v192, v192, v200
	v_add_f32_e32 v193, v193, v252
	v_lshlrev_b32_e32 v194, 16, v149
	v_and_b32_e32 v195, 0xffff0000, v149
	v_lshlrev_b32_e32 v200, 16, v157
	v_and_b32_e32 v252, 0xffff0000, v157
	v_add_f32_e32 v194, v194, v200
	v_add_f32_e32 v195, v195, v252
	v_lshlrev_b32_e32 v196, 16, v150
	v_and_b32_e32 v197, 0xffff0000, v150
	v_lshlrev_b32_e32 v200, 16, v158
	v_and_b32_e32 v252, 0xffff0000, v158
	v_add_f32_e32 v196, v196, v200
	v_add_f32_e32 v197, v197, v252
	v_lshlrev_b32_e32 v198, 16, v151
	v_and_b32_e32 v199, 0xffff0000, v151
	v_lshlrev_b32_e32 v200, 16, v159
	v_and_b32_e32 v252, 0xffff0000, v159
	v_add_f32_e32 v198, v198, v200
	v_add_f32_e32 v199, v199, v252
	v_mul_f32_e32 v200, v192, v192
	v_mul_f32_e32 v252, v194, v194
	v_mul_f32_e32 v253, v196, v196
	v_mul_f32_e32 v219, v198, v198
	v_fmac_f32_e32 v200, v193, v193
	v_fmac_f32_e32 v252, v195, v195
	v_fmac_f32_e32 v253, v197, v197
	v_fmac_f32_e32 v219, v199, v199
	v_add_f32_e32 v200, v200, v252
	v_add_f32_e32 v253, v253, v219
	v_add_f32_e32 v200, v200, v253
	v_add_f32_e32 v251, v251, v200
	v_mul_f32_e32 v200, 0xbfb8aa3b, v4
	v_mul_f32_e32 v252, 0xbfb8aa3b, v5
	v_mul_f32_e32 v253, 0xbfb8aa3b, v6
	v_mul_f32_e32 v219, 0xbfb8aa3b, v7
	v_exp_f32_e32 v200, v200
	v_exp_f32_e32 v252, v252
	v_exp_f32_e32 v253, v253
	v_exp_f32_e32 v219, v219
	v_add_f32_e32 v200, 1.0, v200
	v_add_f32_e32 v252, 1.0, v252
	v_add_f32_e32 v253, 1.0, v253
	v_add_f32_e32 v219, 1.0, v219
	v_rcp_f32_e32 v200, v200
	v_rcp_f32_e32 v252, v252
	v_rcp_f32_e32 v253, v253
	v_rcp_f32_e32 v219, v219
	v_mul_f32_e32 v200, v4, v200
	v_mul_f32_e32 v252, v5, v252
	v_mul_f32_e32 v253, v6, v253
	v_mul_f32_e32 v219, v7, v219
	v_mul_f32_e32 v200, v200, v236
	v_mul_f32_e32 v252, v252, v237
	v_mul_f32_e32 v253, v253, v238
	v_mul_f32_e32 v219, v219, v239
	v_mul_f32_e32 v4, v200, v192
	v_mul_f32_e32 v5, v252, v193
	v_mul_f32_e32 v6, v253, v194
	v_mul_f32_e32 v7, v219, v195
	v_mul_f32_e32 v200, 0xbfb8aa3b, v0
	v_mul_f32_e32 v252, 0xbfb8aa3b, v1
	v_mul_f32_e32 v253, 0xbfb8aa3b, v2
	v_mul_f32_e32 v219, 0xbfb8aa3b, v3
	v_exp_f32_e32 v200, v200
	v_exp_f32_e32 v252, v252
	v_exp_f32_e32 v253, v253
	v_exp_f32_e32 v219, v219
	v_add_f32_e32 v200, 1.0, v200
	v_add_f32_e32 v252, 1.0, v252
	v_add_f32_e32 v253, 1.0, v253
	v_add_f32_e32 v219, 1.0, v219
	v_rcp_f32_e32 v200, v200
	v_rcp_f32_e32 v252, v252
	v_rcp_f32_e32 v253, v253
	v_rcp_f32_e32 v219, v219
	v_mul_f32_e32 v200, v0, v200
	v_mul_f32_e32 v252, v1, v252
	v_mul_f32_e32 v253, v2, v253
	v_mul_f32_e32 v219, v3, v219
	v_mul_f32_e32 v200, v200, v240
	v_mul_f32_e32 v252, v252, v241
	v_mul_f32_e32 v253, v253, v242
	v_mul_f32_e32 v219, v219, v243
	v_mul_f32_e32 v0, v200, v196
	v_mul_f32_e32 v1, v252, v197
	v_mul_f32_e32 v2, v253, v198
	v_mul_f32_e32 v3, v219, v199
	ds_bpermute_b32 v200, v226, v244
	ds_bpermute_b32 v252, v226, v245
	ds_bpermute_b32 v253, v226, v246
	ds_bpermute_b32 v219, v226, v247
	s_waitcnt lgkmcnt(0)
; #define LAS __attribute__((address_space(3)))
; __device__ __forceinline__ unsigned cvtpk(float lo, float hi) { f32x2 v = {lo, hi}; bf16x2_t b = __builtin_convertvector(v, bf16x2_t); return __builtin_bit_cast(unsigned, b); }
; __device__ __forceinline__ float bflo(unsigned u) { return __uint_as_float(u << 16); }
; __device__ __forceinline__ float bfhi(unsigned u) { return __uint_as_float(u & 0xffff0000u); }
;     __device__ __forceinline__ void operator()(const af4 (&acc)[2][2][4][2], const pg8::Unit& u, int wr, int wc, int fr_, int fq_) const {
;     ...
;             for (int k = 0; k < 8; ++k) { float v = ssq[k];
;                 v += __int_as_float(__builtin_amdgcn_ds_bpermute((ln_ ^ 16) << 2, __float_as_int(v)));
;                 v += __int_as_float(__builtin_amdgcn_ds_bpermute((ln_ ^ 32) << 2, __float_as_int(v))); ssq[k] = v; }
;             if (fq == 0) {
; #pragma unroll
;                 for (int k = 0; k < 8; ++k) xch[((k >> 2) * 128 + wr * 64 + (k & 3) * 16 + fr) * 4 + wc] = ssq[k];
;             }
;             asm volatile("s_waitcnt lgkmcnt(0)" ::: "memory"); __builtin_amdgcn_s_barrier(); asm volatile("" ::: "memory");
;             float rs[8];
; #pragma unroll
;             for (int k = 0; k < 8; ++k) { const f32x4 p4 = *(const LAS f32x4*)(xch + ((k >> 2) * 128 + wr * 64 + (k & 3) * 16 + fr) * 4);
;                 rs[k] = 1.0f / sqrtf(((p4[0] + p4[1]) + (p4[2] + p4[3])) * (1.f / 256.f) + LN_EPS); }
;     ...
;                         v4u w; w.x = cvtpk(v0[0] * (bflo(a.x) + bflo(c.x)), v0[1] * (bfhi(a.x) + bfhi(c.x))); w.y = cvtpk(v0[2] * (bflo(a.y) + bflo(c.y)), v0[3] * (bfhi(a.y) + bfhi(c.y)));
;                         w.z = cvtpk(v1[0] * (bflo(a.z) + bflo(c.z)), v1[1] * (bfhi(a.z) + bfhi(c.z))); w.w = cvtpk(v1[2] * (bflo(a.w) + bflo(c.w)), v1[3] * (bfhi(a.w) + bfhi(c.w)));
;                         *(v4u*)(ON + ob + mi * 16 * 1024 + bj * 128) = w; } }
	v_add_f32_e32 v244, v244, v200
	v_add_f32_e32 v245, v245, v252
	v_add_f32_e32 v246, v246, v253
	v_add_f32_e32 v247, v247, v219
	ds_bpermute_b32 v200, v226, v248
	ds_bpermute_b32 v252, v226, v249
	ds_bpermute_b32 v253, v226, v250
	ds_bpermute_b32 v219, v226, v251
	s_waitcnt lgkmcnt(0)
	v_add_f32_e32 v248, v248, v200
	v_add_f32_e32 v249, v249, v252
	v_add_f32_e32 v250, v250, v253
	v_add_f32_e32 v251, v251, v219
	ds_bpermute_b32 v200, v227, v244
	ds_bpermute_b32 v252, v227, v245
	ds_bpermute_b32 v253, v227, v246
	ds_bpermute_b32 v219, v227, v247
	s_waitcnt lgkmcnt(0)
	v_add_f32_e32 v244, v244, v200
	v_add_f32_e32 v245, v245, v252
	v_add_f32_e32 v246, v246, v253
	v_add_f32_e32 v247, v247, v219
	ds_bpermute_b32 v200, v227, v248
	ds_bpermute_b32 v252, v227, v249
	ds_bpermute_b32 v253, v227, v250
	ds_bpermute_b32 v219, v227, v251
	s_waitcnt lgkmcnt(0)
	v_add_f32_e32 v248, v248, v200
	v_add_f32_e32 v249, v249, v252
	v_add_f32_e32 v250, v250, v253
	v_add_f32_e32 v251, v251, v219
	ds_write_b32 v224, v244 offset:0
	ds_write_b32 v224, v245 offset:256
	ds_write_b32 v224, v246 offset:512
	ds_write_b32 v224, v247 offset:768
	ds_write_b32 v224, v248 offset:2048
	ds_write_b32 v224, v249 offset:2304
	ds_write_b32 v224, v250 offset:2560
	ds_write_b32 v224, v251 offset:2816
	s_waitcnt lgkmcnt(0)
	s_barrier
	ds_read_b128 v[128:131], v225 offset:0
	ds_read_b128 v[132:135], v225 offset:256
	ds_read_b128 v[136:139], v225 offset:512
	ds_read_b128 v[140:143], v225 offset:768
	ds_read_b128 v[144:147], v225 offset:2048
	ds_read_b128 v[148:151], v225 offset:2304
	ds_read_b128 v[152:155], v225 offset:2560
	ds_read_b128 v[156:159], v225 offset:2816
	s_waitcnt lgkmcnt(0)
	v_add_f32_e32 v128, v128, v129
	v_add_f32_e32 v130, v130, v131
	v_add_f32_e32 v128, v128, v130
	v_mul_f32_e32 v128, 0x3b800000, v128
	v_add_f32_e32 v128, 0x358637bd, v128
	v_add_f32_e32 v132, v132, v133
	v_add_f32_e32 v134, v134, v135
	v_add_f32_e32 v132, v132, v134
	v_mul_f32_e32 v132, 0x3b800000, v132
	v_add_f32_e32 v132, 0x358637bd, v132
	v_add_f32_e32 v136, v136, v137
	v_add_f32_e32 v138, v138, v139
	v_add_f32_e32 v136, v136, v138
	v_mul_f32_e32 v136, 0x3b800000, v136
	v_add_f32_e32 v136, 0x358637bd, v136
	v_add_f32_e32 v140, v140, v141
	v_add_f32_e32 v142, v142, v143
	v_add_f32_e32 v140, v140, v142
	v_mul_f32_e32 v140, 0x3b800000, v140
	v_add_f32_e32 v140, 0x358637bd, v140
	v_add_f32_e32 v144, v144, v145
	v_add_f32_e32 v146, v146, v147
	v_add_f32_e32 v144, v144, v146
	v_mul_f32_e32 v144, 0x3b800000, v144
	v_add_f32_e32 v144, 0x358637bd, v144
	v_add_f32_e32 v148, v148, v149
	v_add_f32_e32 v150, v150, v151
	v_add_f32_e32 v148, v148, v150
	v_mul_f32_e32 v148, 0x3b800000, v148
	v_add_f32_e32 v148, 0x358637bd, v148
	v_add_f32_e32 v152, v152, v153
	v_add_f32_e32 v154, v154, v155
	v_add_f32_e32 v152, v152, v154
	v_mul_f32_e32 v152, 0x3b800000, v152
	v_add_f32_e32 v152, 0x358637bd, v152
	v_add_f32_e32 v156, v156, v157
	v_add_f32_e32 v158, v158, v159
	v_add_f32_e32 v156, v156, v158
	v_mul_f32_e32 v156, 0x3b800000, v156
	v_add_f32_e32 v156, 0x358637bd, v156
	v_rsq_f32_e32 v244, v128
	v_rsq_f32_e32 v245, v132
	v_rsq_f32_e32 v246, v136
	v_rsq_f32_e32 v247, v140
	v_rsq_f32_e32 v248, v144
	v_rsq_f32_e32 v249, v148
	v_rsq_f32_e32 v250, v152
	v_rsq_f32_e32 v251, v156
	v_subrev_co_u32_e32 v220, vcc, 0x58000, v220
	s_nop 1
	v_subbrev_co_u32_e32 v221, vcc, 0, v221, vcc
	v_mul_f32_e32 v124, v124, v244
	v_mul_f32_e32 v125, v125, v244
	v_mul_f32_e32 v126, v126, v244
	v_mul_f32_e32 v127, v127, v244
	v_mul_f32_e32 v120, v120, v244
	v_mul_f32_e32 v121, v121, v244
	v_mul_f32_e32 v122, v122, v244
	v_mul_f32_e32 v123, v123, v244
	v_cvt_pk_bf16_f32 v160, v124, v125
	v_cvt_pk_bf16_f32 v161, v126, v127
	v_cvt_pk_bf16_f32 v162, v120, v121
	v_cvt_pk_bf16_f32 v163, v122, v123
	global_store_dwordx4 v[220:221], v[160:163], off
	v_mul_f32_e32 v112, v112, v244
	v_mul_f32_e32 v113, v113, v244
	v_mul_f32_e32 v114, v114, v244
	v_mul_f32_e32 v115, v115, v244
	v_mul_f32_e32 v104, v104, v244
	v_mul_f32_e32 v105, v105, v244
	v_mul_f32_e32 v106, v106, v244
	v_mul_f32_e32 v107, v107, v244
	v_cvt_pk_bf16_f32 v164, v112, v113
	v_cvt_pk_bf16_f32 v165, v114, v115
	v_cvt_pk_bf16_f32 v166, v104, v105
	v_cvt_pk_bf16_f32 v167, v106, v107
	global_store_dwordx4 v[220:221], v[164:167], off offset:256
	s_nop 0
	v_add_co_u32_e32 v220, vcc, 0x8000, v220
	s_nop 1
	v_addc_co_u32_e32 v221, vcc, 0, v221, vcc
	v_mul_f32_e32 v116, v116, v245
	v_mul_f32_e32 v117, v117, v245
	v_mul_f32_e32 v118, v118, v245
	v_mul_f32_e32 v119, v119, v245
	v_mul_f32_e32 v108, v108, v245
	v_mul_f32_e32 v109, v109, v245
	v_mul_f32_e32 v110, v110, v245
	v_mul_f32_e32 v111, v111, v245
	v_cvt_pk_bf16_f32 v160, v116, v117
	v_cvt_pk_bf16_f32 v161, v118, v119
	v_cvt_pk_bf16_f32 v162, v108, v109
	v_cvt_pk_bf16_f32 v163, v110, v111
	global_store_dwordx4 v[220:221], v[160:163], off
	v_mul_f32_e32 v96, v96, v245
	v_mul_f32_e32 v97, v97, v245
	v_mul_f32_e32 v98, v98, v245
	v_mul_f32_e32 v99, v99, v245
	v_mul_f32_e32 v88, v88, v245
	v_mul_f32_e32 v89, v89, v245
	v_mul_f32_e32 v90, v90, v245
	v_mul_f32_e32 v91, v91, v245
	v_cvt_pk_bf16_f32 v164, v96, v97
	v_cvt_pk_bf16_f32 v165, v98, v99
	v_cvt_pk_bf16_f32 v166, v88, v89
	v_cvt_pk_bf16_f32 v167, v90, v91
	global_store_dwordx4 v[220:221], v[164:167], off offset:256
	s_nop 0
	v_add_co_u32_e32 v220, vcc, 0x8000, v220
	s_nop 1
	v_addc_co_u32_e32 v221, vcc, 0, v221, vcc
	v_mul_f32_e32 v100, v100, v246
	v_mul_f32_e32 v101, v101, v246
	v_mul_f32_e32 v102, v102, v246
	v_mul_f32_e32 v103, v103, v246
	v_mul_f32_e32 v92, v92, v246
; __device__ __forceinline__ unsigned cvtpk(float lo, float hi) { f32x2 v = {lo, hi}; bf16x2_t b = __builtin_convertvector(v, bf16x2_t); return __builtin_bit_cast(unsigned, b); }
; __device__ __forceinline__ float bflo(unsigned u) { return __uint_as_float(u << 16); }
; __device__ __forceinline__ float bfhi(unsigned u) { return __uint_as_float(u & 0xffff0000u); }
; __device__ __forceinline__ float sigmoidf_(float x) { return __builtin_amdgcn_rcpf(1.0f + __expf(-x)); }
;     __device__ __forceinline__ void operator()(const af4 (&acc)[2][2][4][2], const pg8::Unit& u, int wr, int wc, int fr_, int fq_) const {
;     ...
;                 for (int mi = 0; mi < 2; ++mi) { const float rstd = rs[ai * 4 + mp * 2 + mi];
; #pragma unroll
;                     for (int bj = 0; bj < 2; ++bj) { af4 v0 = acc[ai][bj][mp * 2 + mi][0], v1 = acc[ai][bj][mp * 2 + mi][1]; asm volatile("" : "+v"(v0), "+v"(v1)); const v4u a = of_[mi][bj], c = ob_[mi][bj];
; #pragma unroll
;                         for (int e = 0; e < 4; ++e) { v0[e] = v0[e] * sigmoidf_(v0[e]) * (rstd * nwv[bj][0][e]); v1[e] = v1[e] * sigmoidf_(v1[e]) * (rstd * nwv[bj][1][e]); }
;                         v4u w; w.x = cvtpk(v0[0] * (bflo(a.x) + bflo(c.x)), v0[1] * (bfhi(a.x) + bfhi(c.x))); w.y = cvtpk(v0[2] * (bflo(a.y) + bflo(c.y)), v0[3] * (bfhi(a.y) + bfhi(c.y)));
;                         w.z = cvtpk(v1[0] * (bflo(a.z) + bflo(c.z)), v1[1] * (bfhi(a.z) + bfhi(c.z))); w.w = cvtpk(v1[2] * (bflo(a.w) + bflo(c.w)), v1[3] * (bfhi(a.w) + bfhi(c.w)));
;                         *(v4u*)(ON + ob + mi * 16 * 1024 + bj * 128) = w; } }
	v_mul_f32_e32 v93, v93, v246
	v_mul_f32_e32 v94, v94, v246
	v_mul_f32_e32 v95, v95, v246
	v_cvt_pk_bf16_f32 v160, v100, v101
	v_cvt_pk_bf16_f32 v161, v102, v103
	v_cvt_pk_bf16_f32 v162, v92, v93
	v_cvt_pk_bf16_f32 v163, v94, v95
	global_store_dwordx4 v[220:221], v[160:163], off
	v_mul_f32_e32 v80, v80, v246
	v_mul_f32_e32 v81, v81, v246
	v_mul_f32_e32 v82, v82, v246
	v_mul_f32_e32 v83, v83, v246
	v_mul_f32_e32 v72, v72, v246
	v_mul_f32_e32 v73, v73, v246
	v_mul_f32_e32 v74, v74, v246
	v_mul_f32_e32 v75, v75, v246
	v_cvt_pk_bf16_f32 v164, v80, v81
	v_cvt_pk_bf16_f32 v165, v82, v83
	v_cvt_pk_bf16_f32 v166, v72, v73
	v_cvt_pk_bf16_f32 v167, v74, v75
	global_store_dwordx4 v[220:221], v[164:167], off offset:256
	s_nop 0
	v_add_co_u32_e32 v220, vcc, 0x8000, v220
	s_nop 1
	v_addc_co_u32_e32 v221, vcc, 0, v221, vcc
	v_mul_f32_e32 v84, v84, v247
	v_mul_f32_e32 v85, v85, v247
	v_mul_f32_e32 v86, v86, v247
	v_mul_f32_e32 v87, v87, v247
	v_mul_f32_e32 v76, v76, v247
	v_mul_f32_e32 v77, v77, v247
	v_mul_f32_e32 v78, v78, v247
	v_mul_f32_e32 v79, v79, v247
	v_cvt_pk_bf16_f32 v160, v84, v85
	v_cvt_pk_bf16_f32 v161, v86, v87
	v_cvt_pk_bf16_f32 v162, v76, v77
	v_cvt_pk_bf16_f32 v163, v78, v79
	global_store_dwordx4 v[220:221], v[160:163], off
	v_mul_f32_e32 v68, v68, v247
	v_mul_f32_e32 v69, v69, v247
	v_mul_f32_e32 v70, v70, v247
	v_mul_f32_e32 v71, v71, v247
	v_mul_f32_e32 v64, v64, v247
	v_mul_f32_e32 v65, v65, v247
	v_mul_f32_e32 v66, v66, v247
	v_mul_f32_e32 v67, v67, v247
	v_cvt_pk_bf16_f32 v164, v68, v69
	v_cvt_pk_bf16_f32 v165, v70, v71
	v_cvt_pk_bf16_f32 v166, v64, v65
	v_cvt_pk_bf16_f32 v167, v66, v67
	global_store_dwordx4 v[220:221], v[164:167], off offset:256
	s_nop 0
	v_add_co_u32_e32 v220, vcc, 0x28000, v220
	s_nop 1
	v_addc_co_u32_e32 v221, vcc, 0, v221, vcc
	v_mul_f32_e32 v60, v60, v248
	v_mul_f32_e32 v61, v61, v248
	v_mul_f32_e32 v62, v62, v248
	v_mul_f32_e32 v63, v63, v248
	v_mul_f32_e32 v56, v56, v248
	v_mul_f32_e32 v57, v57, v248
	v_mul_f32_e32 v58, v58, v248
	v_mul_f32_e32 v59, v59, v248
	v_cvt_pk_bf16_f32 v160, v60, v61
	v_cvt_pk_bf16_f32 v161, v62, v63
	v_cvt_pk_bf16_f32 v162, v56, v57
	v_cvt_pk_bf16_f32 v163, v58, v59
	global_store_dwordx4 v[220:221], v[160:163], off
	v_mul_f32_e32 v48, v48, v248
	v_mul_f32_e32 v49, v49, v248
	v_mul_f32_e32 v50, v50, v248
	v_mul_f32_e32 v51, v51, v248
	v_mul_f32_e32 v40, v40, v248
	v_mul_f32_e32 v41, v41, v248
	v_mul_f32_e32 v42, v42, v248
	v_mul_f32_e32 v43, v43, v248
	v_cvt_pk_bf16_f32 v164, v48, v49
	v_cvt_pk_bf16_f32 v165, v50, v51
	v_cvt_pk_bf16_f32 v166, v40, v41
	v_cvt_pk_bf16_f32 v167, v42, v43
	global_store_dwordx4 v[220:221], v[164:167], off offset:256
	s_nop 0
	v_add_co_u32_e32 v220, vcc, 0x8000, v220
	s_nop 1
	v_addc_co_u32_e32 v221, vcc, 0, v221, vcc
	v_mul_f32_e32 v52, v52, v249
	v_mul_f32_e32 v53, v53, v249
	v_mul_f32_e32 v54, v54, v249
	v_mul_f32_e32 v55, v55, v249
	v_mul_f32_e32 v44, v44, v249
	v_mul_f32_e32 v45, v45, v249
	v_mul_f32_e32 v46, v46, v249
	v_mul_f32_e32 v47, v47, v249
	v_cvt_pk_bf16_f32 v160, v52, v53
	v_cvt_pk_bf16_f32 v161, v54, v55
	v_cvt_pk_bf16_f32 v162, v44, v45
	v_cvt_pk_bf16_f32 v163, v46, v47
	global_store_dwordx4 v[220:221], v[160:163], off
	v_mul_f32_e32 v32, v32, v249
	v_mul_f32_e32 v33, v33, v249
	v_mul_f32_e32 v34, v34, v249
	v_mul_f32_e32 v35, v35, v249
	v_mul_f32_e32 v24, v24, v249
	v_mul_f32_e32 v25, v25, v249
	v_mul_f32_e32 v26, v26, v249
	v_mul_f32_e32 v27, v27, v249
	v_cvt_pk_bf16_f32 v164, v32, v33
	v_cvt_pk_bf16_f32 v165, v34, v35
	v_cvt_pk_bf16_f32 v166, v24, v25
	v_cvt_pk_bf16_f32 v167, v26, v27
	global_store_dwordx4 v[220:221], v[164:167], off offset:256
	s_nop 0
	v_add_co_u32_e32 v220, vcc, 0x8000, v220
	s_nop 1
	v_addc_co_u32_e32 v221, vcc, 0, v221, vcc
	v_mul_f32_e32 v36, v36, v250
	v_mul_f32_e32 v37, v37, v250
	v_mul_f32_e32 v38, v38, v250
	v_mul_f32_e32 v39, v39, v250
	v_mul_f32_e32 v28, v28, v250
	v_mul_f32_e32 v29, v29, v250
	v_mul_f32_e32 v30, v30, v250
	v_mul_f32_e32 v31, v31, v250
	v_cvt_pk_bf16_f32 v160, v36, v37
	v_cvt_pk_bf16_f32 v161, v38, v39
	v_cvt_pk_bf16_f32 v162, v28, v29
	v_cvt_pk_bf16_f32 v163, v30, v31
	global_store_dwordx4 v[220:221], v[160:163], off
	v_mul_f32_e32 v16, v16, v250
	v_mul_f32_e32 v17, v17, v250
	v_mul_f32_e32 v18, v18, v250
	v_mul_f32_e32 v19, v19, v250
	v_mul_f32_e32 v8, v8, v250
	v_mul_f32_e32 v9, v9, v250
	v_mul_f32_e32 v10, v10, v250
	v_mul_f32_e32 v11, v11, v250
	v_cvt_pk_bf16_f32 v164, v16, v17
	v_cvt_pk_bf16_f32 v165, v18, v19
	v_cvt_pk_bf16_f32 v166, v8, v9
	v_cvt_pk_bf16_f32 v167, v10, v11
	global_store_dwordx4 v[220:221], v[164:167], off offset:256
	s_nop 0
	v_add_co_u32_e32 v220, vcc, 0x8000, v220
	s_nop 1
	v_addc_co_u32_e32 v221, vcc, 0, v221, vcc
	v_mul_f32_e32 v20, v20, v251
	v_mul_f32_e32 v21, v21, v251
	v_mul_f32_e32 v22, v22, v251
	v_mul_f32_e32 v23, v23, v251
	v_mul_f32_e32 v12, v12, v251
	v_mul_f32_e32 v13, v13, v251
	v_mul_f32_e32 v14, v14, v251
	v_mul_f32_e32 v15, v15, v251
	v_cvt_pk_bf16_f32 v160, v20, v21
	v_cvt_pk_bf16_f32 v161, v22, v23
	v_cvt_pk_bf16_f32 v162, v12, v13
	v_cvt_pk_bf16_f32 v163, v14, v15
	global_store_dwordx4 v[220:221], v[160:163], off
	v_mul_f32_e32 v4, v4, v251
	v_mul_f32_e32 v5, v5, v251
	v_mul_f32_e32 v6, v6, v251
	v_mul_f32_e32 v7, v7, v251
	v_mul_f32_e32 v0, v0, v251
	v_mul_f32_e32 v1, v1, v251
	v_mul_f32_e32 v2, v2, v251
	v_mul_f32_e32 v3, v3, v251
	v_cvt_pk_bf16_f32 v164, v4, v5
	v_cvt_pk_bf16_f32 v165, v6, v7
	v_cvt_pk_bf16_f32 v166, v0, v1
	v_cvt_pk_bf16_f32 v167, v2, v3
	global_store_dwordx4 v[220:221], v[164:167], off offset:256

; __device__ __forceinline__ float bflo(unsigned u) { return __uint_as_float(u << 16); }
; __device__ __forceinline__ float bfhi(unsigned u) { return __uint_as_float(u & 0xffff0000u); }
;     __device__ __forceinline__ void operator()(const af4 (&acc)[2][2][4][2], const pg8::Unit& u, int wr, int wc, int fr_, int fq_) const {
;     ...
;         } else if (pn < 6) {
;             const int col0 = (pn - 2) * 256 + wc * 32 + 8 * fq;
;             float ssq[8];
; #pragma unroll
;             for (int b_ = 0; b_ < 4; ++b_) {
;                 const int ai = b_ >> 1, mp = b_ & 1;
;                 int RRb = row0 + ai * 128 + mp * 32; asm volatile("" : "+v"(RRb));
;                 const size_t ob = (size_t)RRb * 1024 + col0; v4u of_[2][2], ob_[2][2];
; #pragma unroll
;                 for (int mi = 0; mi < 2; ++mi)
; #pragma unroll
;                     for (int bj = 0; bj < 2; ++bj) { of_[mi][bj] = *(const v4u*)(ON + ob + mi * 16 * 1024 + bj * 128); ob_[mi][bj] = *(const v4u*)(OBp + ob + mi * 16 * 1024 + bj * 128); }
; #pragma unroll
;                 for (int mi = 0; mi < 2; ++mi) { float q = 0.f;
; #pragma unroll
;                     for (int bj = 0; bj < 2; ++bj) { const v4u a = of_[mi][bj], c = ob_[mi][bj];
;                         const float o0 = bflo(a.x) + bflo(c.x), o1 = bfhi(a.x) + bfhi(c.x), o2 = bflo(a.y) + bflo(c.y), o3 = bfhi(a.y) + bfhi(c.y), o4 = bflo(a.z) + bflo(c.z), o5 = bfhi(a.z) + bfhi(c.z), o6 = bflo(a.w) + bflo(c.w), o7 = bfhi(a.w) + bfhi(c.w);
;                         q += (o0 * o0 + o1 * o1) + (o2 * o2 + o3 * o3) + (o4 * o4 + o5 * o5) + (o6 * o6 + o7 * o7); }
;                     ssq[ai * 4 + mp * 2 + mi] = q; }
;     ...
;             f32x4 nwv[2][2];
; #pragma unroll
;             for (int bj = 0; bj < 2; ++bj) { nwv[bj][0] = *(const f32x4*)(nw + col0 + bj * 128); nwv[bj][1] = *(const f32x4*)(nw + col0 + bj * 128 + 4); }
.LBB0_2644:
	s_andn2_b64 vcc, exec, s[6:7]
	s_cbranch_vccnz .LBB0_2648
	s_lshl_b32 s6, s65, 8
	s_add_i32 s6, s50, s6
	v_mov_b32_e32 v128, v214
	v_lshl_add_u32 v192, v215, 3, s6
	v_ashrrev_i32_e32 v193, 31, v192
	v_ashrrev_i32_e32 v129, 31, v128
	v_lshlrev_b64 v[128:129], 10, v[128:129]
	v_lshl_add_u64 v[128:129], v[128:129], 0, v[192:193]
	v_lshlrev_b64 v[128:129], 1, v[128:129]
	v_lshl_add_u64 v[130:131], s[12:13], 0, v[128:129]
	v_lshl_add_u64 v[128:129], s[14:15], 0, v[128:129]
	v_mov_b32_e32 v216, v136
	v_mov_b32_e32 v217, v137
	v_lshlrev_b32_e32 v218, 2, v192
	v_mov_b32_e32 v220, v130
	v_mov_b32_e32 v221, v131
	v_mov_b32_e32 v222, v128
	v_mov_b32_e32 v223, v129
	s_load_dwordx2 s[8:9], s[84:85], 0x58
	v_add_u32_e32 v225, s87, v216
	v_lshlrev_b32_e32 v225, 4, v225
	v_add_u32_e32 v225, 0x20400, v225
	s_lshr_b32 vcc_lo, s73, 3
	v_add_u32_e32 v224, vcc_lo, v225
	v_xor_b32_e32 v226, 16, v217
	v_lshlrev_b32_e32 v226, 2, v226
	v_xor_b32_e32 v227, 32, v217
	v_lshlrev_b32_e32 v227, 2, v227
	s_waitcnt lgkmcnt(0)
	s_add_u32 s8, s8, 0x3000
	s_addc_u32 s9, s9, 0
	global_load_dwordx4 v[228:231], v218, s[8:9]
	global_load_dwordx4 v[232:235], v218, s[8:9] offset:16
	global_load_dwordx4 v[236:239], v218, s[8:9] offset:512
	global_load_dwordx4 v[240:243], v218, s[8:9] offset:528
	v_mov_b32_e32 v244, 0
	v_mov_b32_e32 v245, 0
	v_mov_b32_e32 v246, 0
	v_mov_b32_e32 v247, 0
	v_mov_b32_e32 v248, 0
	v_mov_b32_e32 v249, 0
	v_mov_b32_e32 v250, 0
	v_mov_b32_e32 v251, 0
	global_load_dwordx4 v[128:131], v[220:221], off
	global_load_dwordx4 v[132:135], v[220:221], off offset:256
	global_load_dwordx4 v[136:139], v[222:223], off
	global_load_dwordx4 v[140:143], v[222:223], off offset:256
	v_add_co_u32_e32 v220, vcc, 0x8000, v220
	s_nop 1
	v_addc_co_u32_e32 v221, vcc, 0, v221, vcc
	v_add_co_u32_e32 v222, vcc, 0x8000, v222
	s_nop 1
	v_addc_co_u32_e32 v223, vcc, 0, v223, vcc
	global_load_dwordx4 v[144:147], v[220:221], off
	global_load_dwordx4 v[148:151], v[220:221], off offset:256
	global_load_dwordx4 v[152:155], v[222:223], off
	global_load_dwordx4 v[156:159], v[222:223], off offset:256
	v_add_co_u32_e32 v220, vcc, 0x8000, v220
	s_nop 1
	v_addc_co_u32_e32 v221, vcc, 0, v221, vcc
	v_add_co_u32_e32 v222, vcc, 0x8000, v222
	s_nop 1
	v_addc_co_u32_e32 v223, vcc, 0, v223, vcc
	global_load_dwordx4 v[160:163], v[220:221], off
	global_load_dwordx4 v[164:167], v[220:221], off offset:256
	global_load_dwordx4 v[168:171], v[222:223], off
	global_load_dwordx4 v[172:175], v[222:223], off offset:256
	v_add_co_u32_e32 v220, vcc, 0x8000, v220
	s_nop 1
	v_addc_co_u32_e32 v221, vcc, 0, v221, vcc
	v_add_co_u32_e32 v222, vcc, 0x8000, v222
	s_nop 1
	v_addc_co_u32_e32 v223, vcc, 0, v223, vcc
	s_waitcnt vmcnt(8)
	v_lshlrev_b32_e32 v192, 16, v128
	v_and_b32_e32 v193, 0xffff0000, v128
	v_lshlrev_b32_e32 v200, 16, v136
	v_and_b32_e32 v252, 0xffff0000, v136
	v_add_f32_e32 v192, v192, v200
	v_add_f32_e32 v193, v193, v252
	v_lshlrev_b32_e32 v194, 16, v129
	v_and_b32_e32 v195, 0xffff0000, v129
	v_lshlrev_b32_e32 v200, 16, v137
	v_and_b32_e32 v252, 0xffff0000, v137
	v_add_f32_e32 v194, v194, v200
	v_add_f32_e32 v195, v195, v252
	v_lshlrev_b32_e32 v196, 16, v130
	v_and_b32_e32 v197, 0xffff0000, v130
	v_lshlrev_b32_e32 v200, 16, v138
	v_and_b32_e32 v252, 0xffff0000, v138
	v_add_f32_e32 v196, v196, v200
	v_add_f32_e32 v197, v197, v252
	v_lshlrev_b32_e32 v198, 16, v131
	v_and_b32_e32 v199, 0xffff0000, v131
	v_lshlrev_b32_e32 v200, 16, v139
	v_and_b32_e32 v252, 0xffff0000, v139
	v_add_f32_e32 v198, v198, v200
	v_add_f32_e32 v199, v199, v252
	v_mul_f32_e32 v200, v192, v192
	v_mul_f32_e32 v252, v194, v194
	v_mul_f32_e32 v253, v196, v196
	v_mul_f32_e32 v219, v198, v198
	v_fmac_f32_e32 v200, v193, v193
	v_fmac_f32_e32 v252, v195, v195
	v_fmac_f32_e32 v253, v197, v197
	v_fmac_f32_e32 v219, v199, v199
	v_add_f32_e32 v200, v200, v252
	v_add_f32_e32 v253, v253, v219
	v_add_f32_e32 v200, v200, v253
	v_add_f32_e32 v244, v244, v200
	v_mul_f32_e32 v200, 0xbfb8aa3b, v124
	v_mul_f32_e32 v252, 0xbfb8aa3b, v125
	v_mul_f32_e32 v253, 0xbfb8aa3b, v126
	v_mul_f32_e32 v219, 0xbfb8aa3b, v127
	v_exp_f32_e32 v200, v200
	v_exp_f32_e32 v252, v252
	v_exp_f32_e32 v253, v253
	v_exp_f32_e32 v219, v219
	v_add_f32_e32 v200, 1.0, v200
	v_add_f32_e32 v252, 1.0, v252
	v_add_f32_e32 v253, 1.0, v253
	v_add_f32_e32 v219, 1.0, v219
	v_rcp_f32_e32 v200, v200
	v_rcp_f32_e32 v252, v252
	v_rcp_f32_e32 v253, v253
	v_rcp_f32_e32 v219, v219
	v_mul_f32_e32 v200, v124, v200
	v_mul_f32_e32 v252, v125, v252
	v_mul_f32_e32 v253, v126, v253
	v_mul_f32_e32 v219, v127, v219
	v_mul_f32_e32 v200, v200, v228
	v_mul_f32_e32 v252, v252, v229
	v_mul_f32_e32 v253, v253, v230
	v_mul_f32_e32 v219, v219, v231
	v_mul_f32_e32 v124, v200, v192
	v_mul_f32_e32 v125, v252, v193
	v_mul_f32_e32 v126, v253, v194
	v_mul_f32_e32 v127, v219, v195
	v_mul_f32_e32 v200, 0xbfb8aa3b, v120
	v_mul_f32_e32 v252, 0xbfb8aa3b, v121
	v_mul_f32_e32 v253, 0xbfb8aa3b, v122
	v_mul_f32_e32 v219, 0xbfb8aa3b, v123
	v_exp_f32_e32 v200, v200
	v_exp_f32_e32 v252, v252
	v_exp_f32_e32 v253, v253
	v_exp_f32_e32 v219, v219
	v_add_f32_e32 v200, 1.0, v200
	v_add_f32_e32 v252, 1.0, v252
	v_add_f32_e32 v253, 1.0, v253
	v_add_f32_e32 v219, 1.0, v219
	v_rcp_f32_e32 v200, v200
	v_rcp_f32_e32 v252, v252
	v_rcp_f32_e32 v253, v253
	v_rcp_f32_e32 v219, v219
	v_mul_f32_e32 v200, v120, v200
	v_mul_f32_e32 v252, v121, v252
	v_mul_f32_e32 v253, v122, v253
	v_mul_f32_e32 v219, v123, v219
	v_mul_f32_e32 v200, v200, v232
	v_mul_f32_e32 v252, v252, v233
	v_mul_f32_e32 v253, v253, v234
	v_mul_f32_e32 v219, v219, v235
	v_mul_f32_e32 v120, v200, v196
	v_mul_f32_e32 v121, v252, v197
	v_mul_f32_e32 v122, v253, v198
; __device__ __forceinline__ unsigned cvtpk(float lo, float hi) { f32x2 v = {lo, hi}; bf16x2_t b = __builtin_convertvector(v, bf16x2_t); return __builtin_bit_cast(unsigned, b); }
; __device__ __forceinline__ float bflo(unsigned u) { return __uint_as_float(u << 16); }
; __device__ __forceinline__ float bfhi(unsigned u) { return __uint_as_float(u & 0xffff0000u); }
;     __device__ __forceinline__ void operator()(const af4 (&acc)[2][2][4][2], const pg8::Unit& u, int wr, int wc, int fr_, int fq_) const {
;     ...
;                 const size_t ob = (size_t)RRb * 1024 + col0; v4u of_[2][2], ob_[2][2];
; #pragma unroll
;                 for (int mi = 0; mi < 2; ++mi)
; #pragma unroll
;                     for (int bj = 0; bj < 2; ++bj) { of_[mi][bj] = *(const v4u*)(ON + ob + mi * 16 * 1024 + bj * 128); ob_[mi][bj] = *(const v4u*)(OBp + ob + mi * 16 * 1024 + bj * 128); }
; #pragma unroll
;                 for (int mi = 0; mi < 2; ++mi) { float q = 0.f;
; #pragma unroll
;                     for (int bj = 0; bj < 2; ++bj) { const v4u a = of_[mi][bj], c = ob_[mi][bj];
;                         const float o0 = bflo(a.x) + bflo(c.x), o1 = bfhi(a.x) + bfhi(c.x), o2 = bflo(a.y) + bflo(c.y), o3 = bfhi(a.y) + bfhi(c.y), o4 = bflo(a.z) + bflo(c.z), o5 = bfhi(a.z) + bfhi(c.z), o6 = bflo(a.w) + bflo(c.w), o7 = bfhi(a.w) + bfhi(c.w);
;                         q += (o0 * o0 + o1 * o1) + (o2 * o2 + o3 * o3) + (o4 * o4 + o5 * o5) + (o6 * o6 + o7 * o7); }
;                     ssq[ai * 4 + mp * 2 + mi] = q; }
;     ...
;                 for (int mi = 0; mi < 2; ++mi) { const float rstd = rs[ai * 4 + mp * 2 + mi];
; #pragma unroll
;                     for (int bj = 0; bj < 2; ++bj) { af4 v0 = acc[ai][bj][mp * 2 + mi][0], v1 = acc[ai][bj][mp * 2 + mi][1]; asm volatile("" : "+v"(v0), "+v"(v1)); const v4u a = of_[mi][bj], c = ob_[mi][bj];
; #pragma unroll
;                         for (int e = 0; e < 4; ++e) { v0[e] = v0[e] * sigmoidf_(v0[e]) * (rstd * nwv[bj][0][e]); v1[e] = v1[e] * sigmoidf_(v1[e]) * (rstd * nwv[bj][1][e]); }
;                         v4u w; w.x = cvtpk(v0[0] * (bflo(a.x) + bflo(c.x)), v0[1] * (bfhi(a.x) + bfhi(c.x))); w.y = cvtpk(v0[2] * (bflo(a.y) + bflo(c.y)), v0[3] * (bfhi(a.y) + bfhi(c.y)));
;                         w.z = cvtpk(v1[0] * (bflo(a.z) + bflo(c.z)), v1[1] * (bfhi(a.z) + bfhi(c.z))); w.w = cvtpk(v1[2] * (bflo(a.w) + bflo(c.w)), v1[3] * (bfhi(a.w) + bfhi(c.w)));
	v_mul_f32_e32 v123, v219, v199
	v_lshlrev_b32_e32 v192, 16, v132
	v_and_b32_e32 v193, 0xffff0000, v132
	v_lshlrev_b32_e32 v200, 16, v140
	v_and_b32_e32 v252, 0xffff0000, v140
	v_add_f32_e32 v192, v192, v200
	v_add_f32_e32 v193, v193, v252
	v_lshlrev_b32_e32 v194, 16, v133
	v_and_b32_e32 v195, 0xffff0000, v133
	v_lshlrev_b32_e32 v200, 16, v141
	v_and_b32_e32 v252, 0xffff0000, v141
	v_add_f32_e32 v194, v194, v200
	v_add_f32_e32 v195, v195, v252
	v_lshlrev_b32_e32 v196, 16, v134
	v_and_b32_e32 v197, 0xffff0000, v134
	v_lshlrev_b32_e32 v200, 16, v142
	v_and_b32_e32 v252, 0xffff0000, v142
	v_add_f32_e32 v196, v196, v200
	v_add_f32_e32 v197, v197, v252
	v_lshlrev_b32_e32 v198, 16, v135
	v_and_b32_e32 v199, 0xffff0000, v135
	v_lshlrev_b32_e32 v200, 16, v143
	v_and_b32_e32 v252, 0xffff0000, v143
	v_add_f32_e32 v198, v198, v200
	v_add_f32_e32 v199, v199, v252
	v_mul_f32_e32 v200, v192, v192
	v_mul_f32_e32 v252, v194, v194
	v_mul_f32_e32 v253, v196, v196
	v_mul_f32_e32 v219, v198, v198
	v_fmac_f32_e32 v200, v193, v193
	v_fmac_f32_e32 v252, v195, v195
	v_fmac_f32_e32 v253, v197, v197
	v_fmac_f32_e32 v219, v199, v199
	v_add_f32_e32 v200, v200, v252
	v_add_f32_e32 v253, v253, v219
	v_add_f32_e32 v200, v200, v253
	v_add_f32_e32 v244, v244, v200
	v_mul_f32_e32 v200, 0xbfb8aa3b, v112
	v_mul_f32_e32 v252, 0xbfb8aa3b, v113
	v_mul_f32_e32 v253, 0xbfb8aa3b, v114
	v_mul_f32_e32 v219, 0xbfb8aa3b, v115
	v_exp_f32_e32 v200, v200
	v_exp_f32_e32 v252, v252
	v_exp_f32_e32 v253, v253
	v_exp_f32_e32 v219, v219
	v_add_f32_e32 v200, 1.0, v200
	v_add_f32_e32 v252, 1.0, v252
	v_add_f32_e32 v253, 1.0, v253
	v_add_f32_e32 v219, 1.0, v219
	v_rcp_f32_e32 v200, v200
	v_rcp_f32_e32 v252, v252
	v_rcp_f32_e32 v253, v253
	v_rcp_f32_e32 v219, v219
	v_mul_f32_e32 v200, v112, v200
	v_mul_f32_e32 v252, v113, v252
	v_mul_f32_e32 v253, v114, v253
	v_mul_f32_e32 v219, v115, v219
	v_mul_f32_e32 v200, v200, v236
	v_mul_f32_e32 v252, v252, v237
	v_mul_f32_e32 v253, v253, v238
	v_mul_f32_e32 v219, v219, v239
	v_mul_f32_e32 v112, v200, v192
	v_mul_f32_e32 v113, v252, v193
	v_mul_f32_e32 v114, v253, v194
	v_mul_f32_e32 v115, v219, v195
	v_mul_f32_e32 v200, 0xbfb8aa3b, v104
	v_mul_f32_e32 v252, 0xbfb8aa3b, v105
	v_mul_f32_e32 v253, 0xbfb8aa3b, v106
	v_mul_f32_e32 v219, 0xbfb8aa3b, v107
	v_exp_f32_e32 v200, v200
	v_exp_f32_e32 v252, v252
	v_exp_f32_e32 v253, v253
	v_exp_f32_e32 v219, v219
	v_add_f32_e32 v200, 1.0, v200
	v_add_f32_e32 v252, 1.0, v252
	v_add_f32_e32 v253, 1.0, v253
	v_add_f32_e32 v219, 1.0, v219
	v_rcp_f32_e32 v200, v200
	v_rcp_f32_e32 v252, v252
	v_rcp_f32_e32 v253, v253
	v_rcp_f32_e32 v219, v219
	v_mul_f32_e32 v200, v104, v200
	v_mul_f32_e32 v252, v105, v252
	v_mul_f32_e32 v253, v106, v253
	v_mul_f32_e32 v219, v107, v219
	v_mul_f32_e32 v200, v200, v240
	v_mul_f32_e32 v252, v252, v241
	v_mul_f32_e32 v253, v253, v242
	v_mul_f32_e32 v219, v219, v243
	v_mul_f32_e32 v104, v200, v196
	v_mul_f32_e32 v105, v252, v197
	v_mul_f32_e32 v106, v253, v198
	v_mul_f32_e32 v107, v219, v199
	global_load_dwordx4 v[128:131], v[220:221], off
	global_load_dwordx4 v[132:135], v[220:221], off offset:256
	global_load_dwordx4 v[136:139], v[222:223], off
	global_load_dwordx4 v[140:143], v[222:223], off offset:256
	v_add_co_u32_e32 v220, vcc, 0x28000, v220
	s_nop 1
	v_addc_co_u32_e32 v221, vcc, 0, v221, vcc
	v_add_co_u32_e32 v222, vcc, 0x28000, v222
	s_nop 1
	v_addc_co_u32_e32 v223, vcc, 0, v223, vcc
	s_waitcnt vmcnt(8)
	v_lshlrev_b32_e32 v192, 16, v144
	v_and_b32_e32 v193, 0xffff0000, v144
	v_lshlrev_b32_e32 v200, 16, v152
	v_and_b32_e32 v252, 0xffff0000, v152
	v_add_f32_e32 v192, v192, v200
	v_add_f32_e32 v193, v193, v252
	v_lshlrev_b32_e32 v194, 16, v145
	v_and_b32_e32 v195, 0xffff0000, v145
	v_lshlrev_b32_e32 v200, 16, v153
	v_and_b32_e32 v252, 0xffff0000, v153
	v_add_f32_e32 v194, v194, v200
	v_add_f32_e32 v195, v195, v252
	v_lshlrev_b32_e32 v196, 16, v146
	v_and_b32_e32 v197, 0xffff0000, v146
	v_lshlrev_b32_e32 v200, 16, v154
	v_and_b32_e32 v252, 0xffff0000, v154
	v_add_f32_e32 v196, v196, v200
	v_add_f32_e32 v197, v197, v252
	v_lshlrev_b32_e32 v198, 16, v147
	v_and_b32_e32 v199, 0xffff0000, v147
	v_lshlrev_b32_e32 v200, 16, v155
	v_and_b32_e32 v252, 0xffff0000, v155
	v_add_f32_e32 v198, v198, v200
	v_add_f32_e32 v199, v199, v252
	v_mul_f32_e32 v200, v192, v192
	v_mul_f32_e32 v252, v194, v194
	v_mul_f32_e32 v253, v196, v196
	v_mul_f32_e32 v219, v198, v198
	v_fmac_f32_e32 v200, v193, v193
	v_fmac_f32_e32 v252, v195, v195
	v_fmac_f32_e32 v253, v197, v197
	v_fmac_f32_e32 v219, v199, v199
	v_add_f32_e32 v200, v200, v252
	v_add_f32_e32 v253, v253, v219
	v_add_f32_e32 v200, v200, v253
	v_add_f32_e32 v245, v245, v200
	v_mul_f32_e32 v200, 0xbfb8aa3b, v116
	v_mul_f32_e32 v252, 0xbfb8aa3b, v117
	v_mul_f32_e32 v253, 0xbfb8aa3b, v118
	v_mul_f32_e32 v219, 0xbfb8aa3b, v119
	v_exp_f32_e32 v200, v200
	v_exp_f32_e32 v252, v252
	v_exp_f32_e32 v253, v253
	v_exp_f32_e32 v219, v219
	v_add_f32_e32 v200, 1.0, v200
	v_add_f32_e32 v252, 1.0, v252
	v_add_f32_e32 v253, 1.0, v253
	v_add_f32_e32 v219, 1.0, v219
	v_rcp_f32_e32 v200, v200
	v_rcp_f32_e32 v252, v252
	v_rcp_f32_e32 v253, v253
	v_rcp_f32_e32 v219, v219
	v_mul_f32_e32 v200, v116, v200
	v_mul_f32_e32 v252, v117, v252
	v_mul_f32_e32 v253, v118, v253
	v_mul_f32_e32 v219, v119, v219
	v_mul_f32_e32 v200, v200, v228
	v_mul_f32_e32 v252, v252, v229
	v_mul_f32_e32 v253, v253, v230
	v_mul_f32_e32 v219, v219, v231
	v_mul_f32_e32 v116, v200, v192
	v_mul_f32_e32 v117, v252, v193
	v_mul_f32_e32 v118, v253, v194
	v_mul_f32_e32 v119, v219, v195
	v_mul_f32_e32 v200, 0xbfb8aa3b, v108
	v_mul_f32_e32 v252, 0xbfb8aa3b, v109
	v_mul_f32_e32 v253, 0xbfb8aa3b, v110
	v_mul_f32_e32 v219, 0xbfb8aa3b, v111
; __device__ __forceinline__ unsigned cvtpk(float lo, float hi) { f32x2 v = {lo, hi}; bf16x2_t b = __builtin_convertvector(v, bf16x2_t); return __builtin_bit_cast(unsigned, b); }
; __device__ __forceinline__ float bflo(unsigned u) { return __uint_as_float(u << 16); }
; __device__ __forceinline__ float bfhi(unsigned u) { return __uint_as_float(u & 0xffff0000u); }
;     __device__ __forceinline__ void operator()(const af4 (&acc)[2][2][4][2], const pg8::Unit& u, int wr, int wc, int fr_, int fq_) const {
;     ...
;                 const size_t ob = (size_t)RRb * 1024 + col0; v4u of_[2][2], ob_[2][2];
; #pragma unroll
;                 for (int mi = 0; mi < 2; ++mi)
; #pragma unroll
;                     for (int bj = 0; bj < 2; ++bj) { of_[mi][bj] = *(const v4u*)(ON + ob + mi * 16 * 1024 + bj * 128); ob_[mi][bj] = *(const v4u*)(OBp + ob + mi * 16 * 1024 + bj * 128); }
; #pragma unroll
;                 for (int mi = 0; mi < 2; ++mi) { float q = 0.f;
; #pragma unroll
;                     for (int bj = 0; bj < 2; ++bj) { const v4u a = of_[mi][bj], c = ob_[mi][bj];
;                         const float o0 = bflo(a.x) + bflo(c.x), o1 = bfhi(a.x) + bfhi(c.x), o2 = bflo(a.y) + bflo(c.y), o3 = bfhi(a.y) + bfhi(c.y), o4 = bflo(a.z) + bflo(c.z), o5 = bfhi(a.z) + bfhi(c.z), o6 = bflo(a.w) + bflo(c.w), o7 = bfhi(a.w) + bfhi(c.w);
;                         q += (o0 * o0 + o1 * o1) + (o2 * o2 + o3 * o3) + (o4 * o4 + o5 * o5) + (o6 * o6 + o7 * o7); }
;                     ssq[ai * 4 + mp * 2 + mi] = q; }
;     ...
;                 for (int mi = 0; mi < 2; ++mi) { const float rstd = rs[ai * 4 + mp * 2 + mi];
; #pragma unroll
;                     for (int bj = 0; bj < 2; ++bj) { af4 v0 = acc[ai][bj][mp * 2 + mi][0], v1 = acc[ai][bj][mp * 2 + mi][1]; asm volatile("" : "+v"(v0), "+v"(v1)); const v4u a = of_[mi][bj], c = ob_[mi][bj];
; #pragma unroll
;                         for (int e = 0; e < 4; ++e) { v0[e] = v0[e] * sigmoidf_(v0[e]) * (rstd * nwv[bj][0][e]); v1[e] = v1[e] * sigmoidf_(v1[e]) * (rstd * nwv[bj][1][e]); }
;                         v4u w; w.x = cvtpk(v0[0] * (bflo(a.x) + bflo(c.x)), v0[1] * (bfhi(a.x) + bfhi(c.x))); w.y = cvtpk(v0[2] * (bflo(a.y) + bflo(c.y)), v0[3] * (bfhi(a.y) + bfhi(c.y)));
;                         w.z = cvtpk(v1[0] * (bflo(a.z) + bflo(c.z)), v1[1] * (bfhi(a.z) + bfhi(c.z))); w.w = cvtpk(v1[2] * (bflo(a.w) + bflo(c.w)), v1[3] * (bfhi(a.w) + bfhi(c.w)));
	v_exp_f32_e32 v200, v200
	v_exp_f32_e32 v252, v252
	v_exp_f32_e32 v253, v253
	v_exp_f32_e32 v219, v219
	v_add_f32_e32 v200, 1.0, v200
	v_add_f32_e32 v252, 1.0, v252
	v_add_f32_e32 v253, 1.0, v253
	v_add_f32_e32 v219, 1.0, v219
	v_rcp_f32_e32 v200, v200
	v_rcp_f32_e32 v252, v252
	v_rcp_f32_e32 v253, v253
	v_rcp_f32_e32 v219, v219
	v_mul_f32_e32 v200, v108, v200
	v_mul_f32_e32 v252, v109, v252
	v_mul_f32_e32 v253, v110, v253
	v_mul_f32_e32 v219, v111, v219
	v_mul_f32_e32 v200, v200, v232
	v_mul_f32_e32 v252, v252, v233
	v_mul_f32_e32 v253, v253, v234
	v_mul_f32_e32 v219, v219, v235
	v_mul_f32_e32 v108, v200, v196
	v_mul_f32_e32 v109, v252, v197
	v_mul_f32_e32 v110, v253, v198
	v_mul_f32_e32 v111, v219, v199
	v_lshlrev_b32_e32 v192, 16, v148
	v_and_b32_e32 v193, 0xffff0000, v148
	v_lshlrev_b32_e32 v200, 16, v156
	v_and_b32_e32 v252, 0xffff0000, v156
	v_add_f32_e32 v192, v192, v200
	v_add_f32_e32 v193, v193, v252
	v_lshlrev_b32_e32 v194, 16, v149
	v_and_b32_e32 v195, 0xffff0000, v149
	v_lshlrev_b32_e32 v200, 16, v157
	v_and_b32_e32 v252, 0xffff0000, v157
	v_add_f32_e32 v194, v194, v200
	v_add_f32_e32 v195, v195, v252
	v_lshlrev_b32_e32 v196, 16, v150
	v_and_b32_e32 v197, 0xffff0000, v150
	v_lshlrev_b32_e32 v200, 16, v158
	v_and_b32_e32 v252, 0xffff0000, v158
	v_add_f32_e32 v196, v196, v200
	v_add_f32_e32 v197, v197, v252
	v_lshlrev_b32_e32 v198, 16, v151
	v_and_b32_e32 v199, 0xffff0000, v151
	v_lshlrev_b32_e32 v200, 16, v159
	v_and_b32_e32 v252, 0xffff0000, v159
	v_add_f32_e32 v198, v198, v200
	v_add_f32_e32 v199, v199, v252
	v_mul_f32_e32 v200, v192, v192
	v_mul_f32_e32 v252, v194, v194
	v_mul_f32_e32 v253, v196, v196
	v_mul_f32_e32 v219, v198, v198
	v_fmac_f32_e32 v200, v193, v193
	v_fmac_f32_e32 v252, v195, v195
	v_fmac_f32_e32 v253, v197, v197
	v_fmac_f32_e32 v219, v199, v199
	v_add_f32_e32 v200, v200, v252
	v_add_f32_e32 v253, v253, v219
	v_add_f32_e32 v200, v200, v253
	v_add_f32_e32 v245, v245, v200
	v_mul_f32_e32 v200, 0xbfb8aa3b, v96
	v_mul_f32_e32 v252, 0xbfb8aa3b, v97
	v_mul_f32_e32 v253, 0xbfb8aa3b, v98
	v_mul_f32_e32 v219, 0xbfb8aa3b, v99
	v_exp_f32_e32 v200, v200
	v_exp_f32_e32 v252, v252
	v_exp_f32_e32 v253, v253
	v_exp_f32_e32 v219, v219
	v_add_f32_e32 v200, 1.0, v200
	v_add_f32_e32 v252, 1.0, v252
	v_add_f32_e32 v253, 1.0, v253
	v_add_f32_e32 v219, 1.0, v219
	v_rcp_f32_e32 v200, v200
	v_rcp_f32_e32 v252, v252
	v_rcp_f32_e32 v253, v253
	v_rcp_f32_e32 v219, v219
	v_mul_f32_e32 v200, v96, v200
	v_mul_f32_e32 v252, v97, v252
	v_mul_f32_e32 v253, v98, v253
	v_mul_f32_e32 v219, v99, v219
	v_mul_f32_e32 v200, v200, v236
	v_mul_f32_e32 v252, v252, v237
	v_mul_f32_e32 v253, v253, v238
	v_mul_f32_e32 v219, v219, v239
	v_mul_f32_e32 v96, v200, v192
	v_mul_f32_e32 v97, v252, v193
	v_mul_f32_e32 v98, v253, v194
	v_mul_f32_e32 v99, v219, v195
	v_mul_f32_e32 v200, 0xbfb8aa3b, v88
	v_mul_f32_e32 v252, 0xbfb8aa3b, v89
	v_mul_f32_e32 v253, 0xbfb8aa3b, v90
	v_mul_f32_e32 v219, 0xbfb8aa3b, v91
	v_exp_f32_e32 v200, v200
	v_exp_f32_e32 v252, v252
	v_exp_f32_e32 v253, v253
	v_exp_f32_e32 v219, v219
	v_add_f32_e32 v200, 1.0, v200
	v_add_f32_e32 v252, 1.0, v252
	v_add_f32_e32 v253, 1.0, v253
	v_add_f32_e32 v219, 1.0, v219
	v_rcp_f32_e32 v200, v200
	v_rcp_f32_e32 v252, v252
	v_rcp_f32_e32 v253, v253
	v_rcp_f32_e32 v219, v219
	v_mul_f32_e32 v200, v88, v200
	v_mul_f32_e32 v252, v89, v252
	v_mul_f32_e32 v253, v90, v253
	v_mul_f32_e32 v219, v91, v219
	v_mul_f32_e32 v200, v200, v240
	v_mul_f32_e32 v252, v252, v241
	v_mul_f32_e32 v253, v253, v242
	v_mul_f32_e32 v219, v219, v243
	v_mul_f32_e32 v88, v200, v196
	v_mul_f32_e32 v89, v252, v197
	v_mul_f32_e32 v90, v253, v198
	v_mul_f32_e32 v91, v219, v199
	global_load_dwordx4 v[144:147], v[220:221], off
	global_load_dwordx4 v[148:151], v[220:221], off offset:256
	global_load_dwordx4 v[152:155], v[222:223], off
	global_load_dwordx4 v[156:159], v[222:223], off offset:256
	v_add_co_u32_e32 v220, vcc, 0x8000, v220
	s_nop 1
	v_addc_co_u32_e32 v221, vcc, 0, v221, vcc
	v_add_co_u32_e32 v222, vcc, 0x8000, v222
	s_nop 1
	v_addc_co_u32_e32 v223, vcc, 0, v223, vcc
	s_waitcnt vmcnt(8)
	v_lshlrev_b32_e32 v192, 16, v160
	v_and_b32_e32 v193, 0xffff0000, v160
	v_lshlrev_b32_e32 v200, 16, v168
	v_and_b32_e32 v252, 0xffff0000, v168
	v_add_f32_e32 v192, v192, v200
	v_add_f32_e32 v193, v193, v252
	v_lshlrev_b32_e32 v194, 16, v161
	v_and_b32_e32 v195, 0xffff0000, v161
	v_lshlrev_b32_e32 v200, 16, v169
	v_and_b32_e32 v252, 0xffff0000, v169
	v_add_f32_e32 v194, v194, v200
	v_add_f32_e32 v195, v195, v252
	v_lshlrev_b32_e32 v196, 16, v162
	v_and_b32_e32 v197, 0xffff0000, v162
	v_lshlrev_b32_e32 v200, 16, v170
	v_and_b32_e32 v252, 0xffff0000, v170
	v_add_f32_e32 v196, v196, v200
	v_add_f32_e32 v197, v197, v252
	v_lshlrev_b32_e32 v198, 16, v163
	v_and_b32_e32 v199, 0xffff0000, v163
	v_lshlrev_b32_e32 v200, 16, v171
	v_and_b32_e32 v252, 0xffff0000, v171
	v_add_f32_e32 v198, v198, v200
	v_add_f32_e32 v199, v199, v252
	v_mul_f32_e32 v200, v192, v192
	v_mul_f32_e32 v252, v194, v194
	v_mul_f32_e32 v253, v196, v196
	v_mul_f32_e32 v219, v198, v198
	v_fmac_f32_e32 v200, v193, v193
	v_fmac_f32_e32 v252, v195, v195
	v_fmac_f32_e32 v253, v197, v197
	v_fmac_f32_e32 v219, v199, v199
	v_add_f32_e32 v200, v200, v252
	v_add_f32_e32 v253, v253, v219
	v_add_f32_e32 v200, v200, v253
	v_add_f32_e32 v246, v246, v200
	v_mul_f32_e32 v200, 0xbfb8aa3b, v100
	v_mul_f32_e32 v252, 0xbfb8aa3b, v101
	v_mul_f32_e32 v253, 0xbfb8aa3b, v102
	v_mul_f32_e32 v219, 0xbfb8aa3b, v103
	v_exp_f32_e32 v200, v200
	v_exp_f32_e32 v252, v252
	v_exp_f32_e32 v253, v253
	v_exp_f32_e32 v219, v219
	v_add_f32_e32 v200, 1.0, v200
	v_add_f32_e32 v252, 1.0, v252
	v_add_f32_e32 v253, 1.0, v253
; __device__ __forceinline__ unsigned cvtpk(float lo, float hi) { f32x2 v = {lo, hi}; bf16x2_t b = __builtin_convertvector(v, bf16x2_t); return __builtin_bit_cast(unsigned, b); }
; __device__ __forceinline__ float bflo(unsigned u) { return __uint_as_float(u << 16); }
; __device__ __forceinline__ float bfhi(unsigned u) { return __uint_as_float(u & 0xffff0000u); }
;     __device__ __forceinline__ void operator()(const af4 (&acc)[2][2][4][2], const pg8::Unit& u, int wr, int wc, int fr_, int fq_) const {
;     ...
;                 const size_t ob = (size_t)RRb * 1024 + col0; v4u of_[2][2], ob_[2][2];
; #pragma unroll
;                 for (int mi = 0; mi < 2; ++mi)
; #pragma unroll
;                     for (int bj = 0; bj < 2; ++bj) { of_[mi][bj] = *(const v4u*)(ON + ob + mi * 16 * 1024 + bj * 128); ob_[mi][bj] = *(const v4u*)(OBp + ob + mi * 16 * 1024 + bj * 128); }
; #pragma unroll
;                 for (int mi = 0; mi < 2; ++mi) { float q = 0.f;
; #pragma unroll
;                     for (int bj = 0; bj < 2; ++bj) { const v4u a = of_[mi][bj], c = ob_[mi][bj];
;                         const float o0 = bflo(a.x) + bflo(c.x), o1 = bfhi(a.x) + bfhi(c.x), o2 = bflo(a.y) + bflo(c.y), o3 = bfhi(a.y) + bfhi(c.y), o4 = bflo(a.z) + bflo(c.z), o5 = bfhi(a.z) + bfhi(c.z), o6 = bflo(a.w) + bflo(c.w), o7 = bfhi(a.w) + bfhi(c.w);
;                         q += (o0 * o0 + o1 * o1) + (o2 * o2 + o3 * o3) + (o4 * o4 + o5 * o5) + (o6 * o6 + o7 * o7); }
;                     ssq[ai * 4 + mp * 2 + mi] = q; }
;     ...
;                 for (int mi = 0; mi < 2; ++mi) { const float rstd = rs[ai * 4 + mp * 2 + mi];
; #pragma unroll
;                     for (int bj = 0; bj < 2; ++bj) { af4 v0 = acc[ai][bj][mp * 2 + mi][0], v1 = acc[ai][bj][mp * 2 + mi][1]; asm volatile("" : "+v"(v0), "+v"(v1)); const v4u a = of_[mi][bj], c = ob_[mi][bj];
; #pragma unroll
;                         for (int e = 0; e < 4; ++e) { v0[e] = v0[e] * sigmoidf_(v0[e]) * (rstd * nwv[bj][0][e]); v1[e] = v1[e] * sigmoidf_(v1[e]) * (rstd * nwv[bj][1][e]); }
;                         v4u w; w.x = cvtpk(v0[0] * (bflo(a.x) + bflo(c.x)), v0[1] * (bfhi(a.x) + bfhi(c.x))); w.y = cvtpk(v0[2] * (bflo(a.y) + bflo(c.y)), v0[3] * (bfhi(a.y) + bfhi(c.y)));
;                         w.z = cvtpk(v1[0] * (bflo(a.z) + bflo(c.z)), v1[1] * (bfhi(a.z) + bfhi(c.z))); w.w = cvtpk(v1[2] * (bflo(a.w) + bflo(c.w)), v1[3] * (bfhi(a.w) + bfhi(c.w)));
	v_add_f32_e32 v219, 1.0, v219
	v_rcp_f32_e32 v200, v200
	v_rcp_f32_e32 v252, v252
	v_rcp_f32_e32 v253, v253
	v_rcp_f32_e32 v219, v219
	v_mul_f32_e32 v200, v100, v200
	v_mul_f32_e32 v252, v101, v252
	v_mul_f32_e32 v253, v102, v253
	v_mul_f32_e32 v219, v103, v219
	v_mul_f32_e32 v200, v200, v228
	v_mul_f32_e32 v252, v252, v229
	v_mul_f32_e32 v253, v253, v230
	v_mul_f32_e32 v219, v219, v231
	v_mul_f32_e32 v100, v200, v192
	v_mul_f32_e32 v101, v252, v193
	v_mul_f32_e32 v102, v253, v194
	v_mul_f32_e32 v103, v219, v195
	v_mul_f32_e32 v200, 0xbfb8aa3b, v92
	v_mul_f32_e32 v252, 0xbfb8aa3b, v93
	v_mul_f32_e32 v253, 0xbfb8aa3b, v94
	v_mul_f32_e32 v219, 0xbfb8aa3b, v95
	v_exp_f32_e32 v200, v200
	v_exp_f32_e32 v252, v252
	v_exp_f32_e32 v253, v253
	v_exp_f32_e32 v219, v219
	v_add_f32_e32 v200, 1.0, v200
	v_add_f32_e32 v252, 1.0, v252
	v_add_f32_e32 v253, 1.0, v253
	v_add_f32_e32 v219, 1.0, v219
	v_rcp_f32_e32 v200, v200
	v_rcp_f32_e32 v252, v252
	v_rcp_f32_e32 v253, v253
	v_rcp_f32_e32 v219, v219
	v_mul_f32_e32 v200, v92, v200
	v_mul_f32_e32 v252, v93, v252
	v_mul_f32_e32 v253, v94, v253
	v_mul_f32_e32 v219, v95, v219
	v_mul_f32_e32 v200, v200, v232
	v_mul_f32_e32 v252, v252, v233
	v_mul_f32_e32 v253, v253, v234
	v_mul_f32_e32 v219, v219, v235
	v_mul_f32_e32 v92, v200, v196
	v_mul_f32_e32 v93, v252, v197
	v_mul_f32_e32 v94, v253, v198
	v_mul_f32_e32 v95, v219, v199
	v_lshlrev_b32_e32 v192, 16, v164
	v_and_b32_e32 v193, 0xffff0000, v164
	v_lshlrev_b32_e32 v200, 16, v172
	v_and_b32_e32 v252, 0xffff0000, v172
	v_add_f32_e32 v192, v192, v200
	v_add_f32_e32 v193, v193, v252
	v_lshlrev_b32_e32 v194, 16, v165
	v_and_b32_e32 v195, 0xffff0000, v165
	v_lshlrev_b32_e32 v200, 16, v173
	v_and_b32_e32 v252, 0xffff0000, v173
	v_add_f32_e32 v194, v194, v200
	v_add_f32_e32 v195, v195, v252
	v_lshlrev_b32_e32 v196, 16, v166
	v_and_b32_e32 v197, 0xffff0000, v166
	v_lshlrev_b32_e32 v200, 16, v174
	v_and_b32_e32 v252, 0xffff0000, v174
	v_add_f32_e32 v196, v196, v200
	v_add_f32_e32 v197, v197, v252
	v_lshlrev_b32_e32 v198, 16, v167
	v_and_b32_e32 v199, 0xffff0000, v167
	v_lshlrev_b32_e32 v200, 16, v175
	v_and_b32_e32 v252, 0xffff0000, v175
	v_add_f32_e32 v198, v198, v200
	v_add_f32_e32 v199, v199, v252
	v_mul_f32_e32 v200, v192, v192
	v_mul_f32_e32 v252, v194, v194
	v_mul_f32_e32 v253, v196, v196
	v_mul_f32_e32 v219, v198, v198
	v_fmac_f32_e32 v200, v193, v193
	v_fmac_f32_e32 v252, v195, v195
	v_fmac_f32_e32 v253, v197, v197
	v_fmac_f32_e32 v219, v199, v199
	v_add_f32_e32 v200, v200, v252
	v_add_f32_e32 v253, v253, v219
	v_add_f32_e32 v200, v200, v253
	v_add_f32_e32 v246, v246, v200
	v_mul_f32_e32 v200, 0xbfb8aa3b, v80
	v_mul_f32_e32 v252, 0xbfb8aa3b, v81
	v_mul_f32_e32 v253, 0xbfb8aa3b, v82
	v_mul_f32_e32 v219, 0xbfb8aa3b, v83
	v_exp_f32_e32 v200, v200
	v_exp_f32_e32 v252, v252
	v_exp_f32_e32 v253, v253
	v_exp_f32_e32 v219, v219
	v_add_f32_e32 v200, 1.0, v200
	v_add_f32_e32 v252, 1.0, v252
	v_add_f32_e32 v253, 1.0, v253
	v_add_f32_e32 v219, 1.0, v219
	v_rcp_f32_e32 v200, v200
	v_rcp_f32_e32 v252, v252
	v_rcp_f32_e32 v253, v253
	v_rcp_f32_e32 v219, v219
	v_mul_f32_e32 v200, v80, v200
	v_mul_f32_e32 v252, v81, v252
	v_mul_f32_e32 v253, v82, v253
	v_mul_f32_e32 v219, v83, v219
	v_mul_f32_e32 v200, v200, v236
	v_mul_f32_e32 v252, v252, v237
	v_mul_f32_e32 v253, v253, v238
	v_mul_f32_e32 v219, v219, v239
	v_mul_f32_e32 v80, v200, v192
	v_mul_f32_e32 v81, v252, v193
	v_mul_f32_e32 v82, v253, v194
	v_mul_f32_e32 v83, v219, v195
	v_mul_f32_e32 v200, 0xbfb8aa3b, v72
	v_mul_f32_e32 v252, 0xbfb8aa3b, v73
	v_mul_f32_e32 v253, 0xbfb8aa3b, v74
	v_mul_f32_e32 v219, 0xbfb8aa3b, v75
	v_exp_f32_e32 v200, v200
	v_exp_f32_e32 v252, v252
	v_exp_f32_e32 v253, v253
	v_exp_f32_e32 v219, v219
	v_add_f32_e32 v200, 1.0, v200
	v_add_f32_e32 v252, 1.0, v252
	v_add_f32_e32 v253, 1.0, v253
	v_add_f32_e32 v219, 1.0, v219
	v_rcp_f32_e32 v200, v200
	v_rcp_f32_e32 v252, v252
	v_rcp_f32_e32 v253, v253
	v_rcp_f32_e32 v219, v219
	v_mul_f32_e32 v200, v72, v200
	v_mul_f32_e32 v252, v73, v252
	v_mul_f32_e32 v253, v74, v253
	v_mul_f32_e32 v219, v75, v219
	v_mul_f32_e32 v200, v200, v240
	v_mul_f32_e32 v252, v252, v241
	v_mul_f32_e32 v253, v253, v242
	v_mul_f32_e32 v219, v219, v243
	v_mul_f32_e32 v72, v200, v196
	v_mul_f32_e32 v73, v252, v197
	v_mul_f32_e32 v74, v253, v198
	v_mul_f32_e32 v75, v219, v199
	global_load_dwordx4 v[160:163], v[220:221], off
	global_load_dwordx4 v[164:167], v[220:221], off offset:256
	global_load_dwordx4 v[168:171], v[222:223], off
	global_load_dwordx4 v[172:175], v[222:223], off offset:256
	v_add_co_u32_e32 v220, vcc, 0x8000, v220
	s_nop 1
	v_addc_co_u32_e32 v221, vcc, 0, v221, vcc
	v_add_co_u32_e32 v222, vcc, 0x8000, v222
	s_nop 1
	v_addc_co_u32_e32 v223, vcc, 0, v223, vcc
	s_waitcnt vmcnt(8)
; __device__ __forceinline__ unsigned cvtpk(float lo, float hi) { f32x2 v = {lo, hi}; bf16x2_t b = __builtin_convertvector(v, bf16x2_t); return __builtin_bit_cast(unsigned, b); }
; __device__ __forceinline__ float bflo(unsigned u) { return __uint_as_float(u << 16); }
; __device__ __forceinline__ float bfhi(unsigned u) { return __uint_as_float(u & 0xffff0000u); }
;     __device__ __forceinline__ void operator()(const af4 (&acc)[2][2][4][2], const pg8::Unit& u, int wr, int wc, int fr_, int fq_) const {
;     ...
;                 const size_t ob = (size_t)RRb * 1024 + col0; v4u of_[2][2], ob_[2][2];
; #pragma unroll
;                 for (int mi = 0; mi < 2; ++mi)
; #pragma unroll
;                     for (int bj = 0; bj < 2; ++bj) { of_[mi][bj] = *(const v4u*)(ON + ob + mi * 16 * 1024 + bj * 128); ob_[mi][bj] = *(const v4u*)(OBp + ob + mi * 16 * 1024 + bj * 128); }
; #pragma unroll
;                 for (int mi = 0; mi < 2; ++mi) { float q = 0.f;
; #pragma unroll
;                     for (int bj = 0; bj < 2; ++bj) { const v4u a = of_[mi][bj], c = ob_[mi][bj];
;                         const float o0 = bflo(a.x) + bflo(c.x), o1 = bfhi(a.x) + bfhi(c.x), o2 = bflo(a.y) + bflo(c.y), o3 = bfhi(a.y) + bfhi(c.y), o4 = bflo(a.z) + bflo(c.z), o5 = bfhi(a.z) + bfhi(c.z), o6 = bflo(a.w) + bflo(c.w), o7 = bfhi(a.w) + bfhi(c.w);
;                         q += (o0 * o0 + o1 * o1) + (o2 * o2 + o3 * o3) + (o4 * o4 + o5 * o5) + (o6 * o6 + o7 * o7); }
;                     ssq[ai * 4 + mp * 2 + mi] = q; }
;     ...
;                 for (int mi = 0; mi < 2; ++mi) { const float rstd = rs[ai * 4 + mp * 2 + mi];
; #pragma unroll
;                     for (int bj = 0; bj < 2; ++bj) { af4 v0 = acc[ai][bj][mp * 2 + mi][0], v1 = acc[ai][bj][mp * 2 + mi][1]; asm volatile("" : "+v"(v0), "+v"(v1)); const v4u a = of_[mi][bj], c = ob_[mi][bj];
; #pragma unroll
;                         for (int e = 0; e < 4; ++e) { v0[e] = v0[e] * sigmoidf_(v0[e]) * (rstd * nwv[bj][0][e]); v1[e] = v1[e] * sigmoidf_(v1[e]) * (rstd * nwv[bj][1][e]); }
;                         v4u w; w.x = cvtpk(v0[0] * (bflo(a.x) + bflo(c.x)), v0[1] * (bfhi(a.x) + bfhi(c.x))); w.y = cvtpk(v0[2] * (bflo(a.y) + bflo(c.y)), v0[3] * (bfhi(a.y) + bfhi(c.y)));
;                         w.z = cvtpk(v1[0] * (bflo(a.z) + bflo(c.z)), v1[1] * (bfhi(a.z) + bfhi(c.z))); w.w = cvtpk(v1[2] * (bflo(a.w) + bflo(c.w)), v1[3] * (bfhi(a.w) + bfhi(c.w)));
	v_lshlrev_b32_e32 v192, 16, v128
	v_and_b32_e32 v193, 0xffff0000, v128
	v_lshlrev_b32_e32 v200, 16, v136
	v_and_b32_e32 v252, 0xffff0000, v136
	v_add_f32_e32 v192, v192, v200
	v_add_f32_e32 v193, v193, v252
	v_lshlrev_b32_e32 v194, 16, v129
	v_and_b32_e32 v195, 0xffff0000, v129
	v_lshlrev_b32_e32 v200, 16, v137
	v_and_b32_e32 v252, 0xffff0000, v137
	v_add_f32_e32 v194, v194, v200
	v_add_f32_e32 v195, v195, v252
	v_lshlrev_b32_e32 v196, 16, v130
	v_and_b32_e32 v197, 0xffff0000, v130
	v_lshlrev_b32_e32 v200, 16, v138
	v_and_b32_e32 v252, 0xffff0000, v138
	v_add_f32_e32 v196, v196, v200
	v_add_f32_e32 v197, v197, v252
	v_lshlrev_b32_e32 v198, 16, v131
	v_and_b32_e32 v199, 0xffff0000, v131
	v_lshlrev_b32_e32 v200, 16, v139
	v_and_b32_e32 v252, 0xffff0000, v139
	v_add_f32_e32 v198, v198, v200
	v_add_f32_e32 v199, v199, v252
	v_mul_f32_e32 v200, v192, v192
	v_mul_f32_e32 v252, v194, v194
	v_mul_f32_e32 v253, v196, v196
	v_mul_f32_e32 v219, v198, v198
	v_fmac_f32_e32 v200, v193, v193
	v_fmac_f32_e32 v252, v195, v195
	v_fmac_f32_e32 v253, v197, v197
	v_fmac_f32_e32 v219, v199, v199
	v_add_f32_e32 v200, v200, v252
	v_add_f32_e32 v253, v253, v219
	v_add_f32_e32 v200, v200, v253
	v_add_f32_e32 v247, v247, v200
	v_mul_f32_e32 v200, 0xbfb8aa3b, v84
	v_mul_f32_e32 v252, 0xbfb8aa3b, v85
	v_mul_f32_e32 v253, 0xbfb8aa3b, v86
	v_mul_f32_e32 v219, 0xbfb8aa3b, v87
	v_exp_f32_e32 v200, v200
	v_exp_f32_e32 v252, v252
	v_exp_f32_e32 v253, v253
	v_exp_f32_e32 v219, v219
	v_add_f32_e32 v200, 1.0, v200
	v_add_f32_e32 v252, 1.0, v252
	v_add_f32_e32 v253, 1.0, v253
	v_add_f32_e32 v219, 1.0, v219
	v_rcp_f32_e32 v200, v200
	v_rcp_f32_e32 v252, v252
	v_rcp_f32_e32 v253, v253
	v_rcp_f32_e32 v219, v219
	v_mul_f32_e32 v200, v84, v200
	v_mul_f32_e32 v252, v85, v252
	v_mul_f32_e32 v253, v86, v253
	v_mul_f32_e32 v219, v87, v219
	v_mul_f32_e32 v200, v200, v228
	v_mul_f32_e32 v252, v252, v229
	v_mul_f32_e32 v253, v253, v230
	v_mul_f32_e32 v219, v219, v231
	v_mul_f32_e32 v84, v200, v192
	v_mul_f32_e32 v85, v252, v193
	v_mul_f32_e32 v86, v253, v194
	v_mul_f32_e32 v87, v219, v195
	v_mul_f32_e32 v200, 0xbfb8aa3b, v76
	v_mul_f32_e32 v252, 0xbfb8aa3b, v77
	v_mul_f32_e32 v253, 0xbfb8aa3b, v78
	v_mul_f32_e32 v219, 0xbfb8aa3b, v79
	v_exp_f32_e32 v200, v200
	v_exp_f32_e32 v252, v252
	v_exp_f32_e32 v253, v253
	v_exp_f32_e32 v219, v219
	v_add_f32_e32 v200, 1.0, v200
	v_add_f32_e32 v252, 1.0, v252
	v_add_f32_e32 v253, 1.0, v253
	v_add_f32_e32 v219, 1.0, v219
	v_rcp_f32_e32 v200, v200
	v_rcp_f32_e32 v252, v252
	v_rcp_f32_e32 v253, v253
	v_rcp_f32_e32 v219, v219
	v_mul_f32_e32 v200, v76, v200
	v_mul_f32_e32 v252, v77, v252
	v_mul_f32_e32 v253, v78, v253
	v_mul_f32_e32 v219, v79, v219
	v_mul_f32_e32 v200, v200, v232
	v_mul_f32_e32 v252, v252, v233
	v_mul_f32_e32 v253, v253, v234
	v_mul_f32_e32 v219, v219, v235
	v_mul_f32_e32 v76, v200, v196
	v_mul_f32_e32 v77, v252, v197
	v_mul_f32_e32 v78, v253, v198
	v_mul_f32_e32 v79, v219, v199
	v_lshlrev_b32_e32 v192, 16, v132
	v_and_b32_e32 v193, 0xffff0000, v132
	v_lshlrev_b32_e32 v200, 16, v140
	v_and_b32_e32 v252, 0xffff0000, v140
	v_add_f32_e32 v192, v192, v200
	v_add_f32_e32 v193, v193, v252
	v_lshlrev_b32_e32 v194, 16, v133
	v_and_b32_e32 v195, 0xffff0000, v133
	v_lshlrev_b32_e32 v200, 16, v141
	v_and_b32_e32 v252, 0xffff0000, v141
	v_add_f32_e32 v194, v194, v200
	v_add_f32_e32 v195, v195, v252
	v_lshlrev_b32_e32 v196, 16, v134
	v_and_b32_e32 v197, 0xffff0000, v134
	v_lshlrev_b32_e32 v200, 16, v142
	v_and_b32_e32 v252, 0xffff0000, v142
	v_add_f32_e32 v196, v196, v200
	v_add_f32_e32 v197, v197, v252
	v_lshlrev_b32_e32 v198, 16, v135
	v_and_b32_e32 v199, 0xffff0000, v135
	v_lshlrev_b32_e32 v200, 16, v143
	v_and_b32_e32 v252, 0xffff0000, v143
	v_add_f32_e32 v198, v198, v200
	v_add_f32_e32 v199, v199, v252
	v_mul_f32_e32 v200, v192, v192
	v_mul_f32_e32 v252, v194, v194
	v_mul_f32_e32 v253, v196, v196
	v_mul_f32_e32 v219, v198, v198
	v_fmac_f32_e32 v200, v193, v193
	v_fmac_f32_e32 v252, v195, v195
	v_fmac_f32_e32 v253, v197, v197
	v_fmac_f32_e32 v219, v199, v199
	v_add_f32_e32 v200, v200, v252
	v_add_f32_e32 v253, v253, v219
	v_add_f32_e32 v200, v200, v253
	v_add_f32_e32 v247, v247, v200
	v_mul_f32_e32 v200, 0xbfb8aa3b, v68
	v_mul_f32_e32 v252, 0xbfb8aa3b, v69
	v_mul_f32_e32 v253, 0xbfb8aa3b, v70
	v_mul_f32_e32 v219, 0xbfb8aa3b, v71
	v_exp_f32_e32 v200, v200
	v_exp_f32_e32 v252, v252
	v_exp_f32_e32 v253, v253
	v_exp_f32_e32 v219, v219
	v_add_f32_e32 v200, 1.0, v200
	v_add_f32_e32 v252, 1.0, v252
	v_add_f32_e32 v253, 1.0, v253
	v_add_f32_e32 v219, 1.0, v219
	v_rcp_f32_e32 v200, v200
	v_rcp_f32_e32 v252, v252
	v_rcp_f32_e32 v253, v253
	v_rcp_f32_e32 v219, v219
	v_mul_f32_e32 v200, v68, v200
	v_mul_f32_e32 v252, v69, v252
	v_mul_f32_e32 v253, v70, v253
	v_mul_f32_e32 v219, v71, v219
	v_mul_f32_e32 v200, v200, v236
	v_mul_f32_e32 v252, v252, v237
	v_mul_f32_e32 v253, v253, v238
	v_mul_f32_e32 v219, v219, v239
	v_mul_f32_e32 v68, v200, v192
	v_mul_f32_e32 v69, v252, v193
	v_mul_f32_e32 v70, v253, v194
	v_mul_f32_e32 v71, v219, v195
	v_mul_f32_e32 v200, 0xbfb8aa3b, v64
	v_mul_f32_e32 v252, 0xbfb8aa3b, v65
	v_mul_f32_e32 v253, 0xbfb8aa3b, v66
	v_mul_f32_e32 v219, 0xbfb8aa3b, v67
	v_exp_f32_e32 v200, v200
	v_exp_f32_e32 v252, v252
	v_exp_f32_e32 v253, v253
	v_exp_f32_e32 v219, v219
	v_add_f32_e32 v200, 1.0, v200
	v_add_f32_e32 v252, 1.0, v252
	v_add_f32_e32 v253, 1.0, v253
	v_add_f32_e32 v219, 1.0, v219
	v_rcp_f32_e32 v200, v200
	v_rcp_f32_e32 v252, v252
	v_rcp_f32_e32 v253, v253
	v_rcp_f32_e32 v219, v219
	v_mul_f32_e32 v200, v64, v200
	v_mul_f32_e32 v252, v65, v252
	v_mul_f32_e32 v253, v66, v253
	v_mul_f32_e32 v219, v67, v219
	v_mul_f32_e32 v200, v200, v240
	v_mul_f32_e32 v252, v252, v241
	v_mul_f32_e32 v253, v253, v242
	v_mul_f32_e32 v219, v219, v243
	v_mul_f32_e32 v64, v200, v196
	v_mul_f32_e32 v65, v252, v197
	v_mul_f32_e32 v66, v253, v198
	v_mul_f32_e32 v67, v219, v199
	global_load_dwordx4 v[128:131], v[220:221], off
	global_load_dwordx4 v[132:135], v[220:221], off offset:256
	global_load_dwordx4 v[136:139], v[222:223], off
	global_load_dwordx4 v[140:143], v[222:223], off offset:256
	v_add_co_u32_e32 v220, vcc, 0x8000, v220
	s_nop 1
	v_addc_co_u32_e32 v221, vcc, 0, v221, vcc
	v_add_co_u32_e32 v222, vcc, 0x8000, v222
	s_nop 1
	v_addc_co_u32_e32 v223, vcc, 0, v223, vcc
	s_waitcnt vmcnt(8)
; __device__ __forceinline__ unsigned cvtpk(float lo, float hi) { f32x2 v = {lo, hi}; bf16x2_t b = __builtin_convertvector(v, bf16x2_t); return __builtin_bit_cast(unsigned, b); }
; __device__ __forceinline__ float bflo(unsigned u) { return __uint_as_float(u << 16); }
; __device__ __forceinline__ float bfhi(unsigned u) { return __uint_as_float(u & 0xffff0000u); }
;     __device__ __forceinline__ void operator()(const af4 (&acc)[2][2][4][2], const pg8::Unit& u, int wr, int wc, int fr_, int fq_) const {
;     ...
;                 const size_t ob = (size_t)RRb * 1024 + col0; v4u of_[2][2], ob_[2][2];
; #pragma unroll
;                 for (int mi = 0; mi < 2; ++mi)
; #pragma unroll
;                     for (int bj = 0; bj < 2; ++bj) { of_[mi][bj] = *(const v4u*)(ON + ob + mi * 16 * 1024 + bj * 128); ob_[mi][bj] = *(const v4u*)(OBp + ob + mi * 16 * 1024 + bj * 128); }
; #pragma unroll
;                 for (int mi = 0; mi < 2; ++mi) { float q = 0.f;
; #pragma unroll
;                     for (int bj = 0; bj < 2; ++bj) { const v4u a = of_[mi][bj], c = ob_[mi][bj];
;                         const float o0 = bflo(a.x) + bflo(c.x), o1 = bfhi(a.x) + bfhi(c.x), o2 = bflo(a.y) + bflo(c.y), o3 = bfhi(a.y) + bfhi(c.y), o4 = bflo(a.z) + bflo(c.z), o5 = bfhi(a.z) + bfhi(c.z), o6 = bflo(a.w) + bflo(c.w), o7 = bfhi(a.w) + bfhi(c.w);
;                         q += (o0 * o0 + o1 * o1) + (o2 * o2 + o3 * o3) + (o4 * o4 + o5 * o5) + (o6 * o6 + o7 * o7); }
;                     ssq[ai * 4 + mp * 2 + mi] = q; }
;     ...
;                 for (int mi = 0; mi < 2; ++mi) { const float rstd = rs[ai * 4 + mp * 2 + mi];
; #pragma unroll
;                     for (int bj = 0; bj < 2; ++bj) { af4 v0 = acc[ai][bj][mp * 2 + mi][0], v1 = acc[ai][bj][mp * 2 + mi][1]; asm volatile("" : "+v"(v0), "+v"(v1)); const v4u a = of_[mi][bj], c = ob_[mi][bj];
; #pragma unroll
;                         for (int e = 0; e < 4; ++e) { v0[e] = v0[e] * sigmoidf_(v0[e]) * (rstd * nwv[bj][0][e]); v1[e] = v1[e] * sigmoidf_(v1[e]) * (rstd * nwv[bj][1][e]); }
;                         v4u w; w.x = cvtpk(v0[0] * (bflo(a.x) + bflo(c.x)), v0[1] * (bfhi(a.x) + bfhi(c.x))); w.y = cvtpk(v0[2] * (bflo(a.y) + bflo(c.y)), v0[3] * (bfhi(a.y) + bfhi(c.y)));
;                         w.z = cvtpk(v1[0] * (bflo(a.z) + bflo(c.z)), v1[1] * (bfhi(a.z) + bfhi(c.z))); w.w = cvtpk(v1[2] * (bflo(a.w) + bflo(c.w)), v1[3] * (bfhi(a.w) + bfhi(c.w)));
	v_lshlrev_b32_e32 v192, 16, v144
	v_and_b32_e32 v193, 0xffff0000, v144
	v_lshlrev_b32_e32 v200, 16, v152
	v_and_b32_e32 v252, 0xffff0000, v152
	v_add_f32_e32 v192, v192, v200
	v_add_f32_e32 v193, v193, v252
	v_lshlrev_b32_e32 v194, 16, v145
	v_and_b32_e32 v195, 0xffff0000, v145
	v_lshlrev_b32_e32 v200, 16, v153
	v_and_b32_e32 v252, 0xffff0000, v153
	v_add_f32_e32 v194, v194, v200
	v_add_f32_e32 v195, v195, v252
	v_lshlrev_b32_e32 v196, 16, v146
	v_and_b32_e32 v197, 0xffff0000, v146
	v_lshlrev_b32_e32 v200, 16, v154
	v_and_b32_e32 v252, 0xffff0000, v154
	v_add_f32_e32 v196, v196, v200
	v_add_f32_e32 v197, v197, v252
	v_lshlrev_b32_e32 v198, 16, v147
	v_and_b32_e32 v199, 0xffff0000, v147
	v_lshlrev_b32_e32 v200, 16, v155
	v_and_b32_e32 v252, 0xffff0000, v155
	v_add_f32_e32 v198, v198, v200
	v_add_f32_e32 v199, v199, v252
	v_mul_f32_e32 v200, v192, v192
	v_mul_f32_e32 v252, v194, v194
	v_mul_f32_e32 v253, v196, v196
	v_mul_f32_e32 v219, v198, v198
	v_fmac_f32_e32 v200, v193, v193
	v_fmac_f32_e32 v252, v195, v195
	v_fmac_f32_e32 v253, v197, v197
	v_fmac_f32_e32 v219, v199, v199
	v_add_f32_e32 v200, v200, v252
	v_add_f32_e32 v253, v253, v219
	v_add_f32_e32 v200, v200, v253
	v_add_f32_e32 v248, v248, v200
	v_mul_f32_e32 v200, 0xbfb8aa3b, v60
	v_mul_f32_e32 v252, 0xbfb8aa3b, v61
	v_mul_f32_e32 v253, 0xbfb8aa3b, v62
	v_mul_f32_e32 v219, 0xbfb8aa3b, v63
	v_exp_f32_e32 v200, v200
	v_exp_f32_e32 v252, v252
	v_exp_f32_e32 v253, v253
	v_exp_f32_e32 v219, v219
	v_add_f32_e32 v200, 1.0, v200
	v_add_f32_e32 v252, 1.0, v252
	v_add_f32_e32 v253, 1.0, v253
	v_add_f32_e32 v219, 1.0, v219
	v_rcp_f32_e32 v200, v200
	v_rcp_f32_e32 v252, v252
	v_rcp_f32_e32 v253, v253
	v_rcp_f32_e32 v219, v219
	v_mul_f32_e32 v200, v60, v200
	v_mul_f32_e32 v252, v61, v252
	v_mul_f32_e32 v253, v62, v253
	v_mul_f32_e32 v219, v63, v219
	v_mul_f32_e32 v200, v200, v228
	v_mul_f32_e32 v252, v252, v229
	v_mul_f32_e32 v253, v253, v230
	v_mul_f32_e32 v219, v219, v231
	v_mul_f32_e32 v60, v200, v192
	v_mul_f32_e32 v61, v252, v193
	v_mul_f32_e32 v62, v253, v194
	v_mul_f32_e32 v63, v219, v195
	v_mul_f32_e32 v200, 0xbfb8aa3b, v56
	v_mul_f32_e32 v252, 0xbfb8aa3b, v57
	v_mul_f32_e32 v253, 0xbfb8aa3b, v58
	v_mul_f32_e32 v219, 0xbfb8aa3b, v59
	v_exp_f32_e32 v200, v200
	v_exp_f32_e32 v252, v252
	v_exp_f32_e32 v253, v253
	v_exp_f32_e32 v219, v219
	v_add_f32_e32 v200, 1.0, v200
	v_add_f32_e32 v252, 1.0, v252
	v_add_f32_e32 v253, 1.0, v253
	v_add_f32_e32 v219, 1.0, v219
	v_rcp_f32_e32 v200, v200
	v_rcp_f32_e32 v252, v252
	v_rcp_f32_e32 v253, v253
	v_rcp_f32_e32 v219, v219
	v_mul_f32_e32 v200, v56, v200
	v_mul_f32_e32 v252, v57, v252
	v_mul_f32_e32 v253, v58, v253
	v_mul_f32_e32 v219, v59, v219
	v_mul_f32_e32 v200, v200, v232
	v_mul_f32_e32 v252, v252, v233
	v_mul_f32_e32 v253, v253, v234
	v_mul_f32_e32 v219, v219, v235
	v_mul_f32_e32 v56, v200, v196
	v_mul_f32_e32 v57, v252, v197
	v_mul_f32_e32 v58, v253, v198
	v_mul_f32_e32 v59, v219, v199
	v_lshlrev_b32_e32 v192, 16, v148
	v_and_b32_e32 v193, 0xffff0000, v148
	v_lshlrev_b32_e32 v200, 16, v156
	v_and_b32_e32 v252, 0xffff0000, v156
	v_add_f32_e32 v192, v192, v200
	v_add_f32_e32 v193, v193, v252
	v_lshlrev_b32_e32 v194, 16, v149
	v_and_b32_e32 v195, 0xffff0000, v149
	v_lshlrev_b32_e32 v200, 16, v157
	v_and_b32_e32 v252, 0xffff0000, v157
	v_add_f32_e32 v194, v194, v200
	v_add_f32_e32 v195, v195, v252
	v_lshlrev_b32_e32 v196, 16, v150
	v_and_b32_e32 v197, 0xffff0000, v150
	v_lshlrev_b32_e32 v200, 16, v158
	v_and_b32_e32 v252, 0xffff0000, v158
	v_add_f32_e32 v196, v196, v200
	v_add_f32_e32 v197, v197, v252
	v_lshlrev_b32_e32 v198, 16, v151
	v_and_b32_e32 v199, 0xffff0000, v151
	v_lshlrev_b32_e32 v200, 16, v159
	v_and_b32_e32 v252, 0xffff0000, v159
	v_add_f32_e32 v198, v198, v200
	v_add_f32_e32 v199, v199, v252
	v_mul_f32_e32 v200, v192, v192
	v_mul_f32_e32 v252, v194, v194
	v_mul_f32_e32 v253, v196, v196
	v_mul_f32_e32 v219, v198, v198
	v_fmac_f32_e32 v200, v193, v193
	v_fmac_f32_e32 v252, v195, v195
	v_fmac_f32_e32 v253, v197, v197
	v_fmac_f32_e32 v219, v199, v199
	v_add_f32_e32 v200, v200, v252
	v_add_f32_e32 v253, v253, v219
	v_add_f32_e32 v200, v200, v253
	v_add_f32_e32 v248, v248, v200
	v_mul_f32_e32 v200, 0xbfb8aa3b, v48
	v_mul_f32_e32 v252, 0xbfb8aa3b, v49
	v_mul_f32_e32 v253, 0xbfb8aa3b, v50
	v_mul_f32_e32 v219, 0xbfb8aa3b, v51
	v_exp_f32_e32 v200, v200
	v_exp_f32_e32 v252, v252
	v_exp_f32_e32 v253, v253
	v_exp_f32_e32 v219, v219
	v_add_f32_e32 v200, 1.0, v200
	v_add_f32_e32 v252, 1.0, v252
	v_add_f32_e32 v253, 1.0, v253
	v_add_f32_e32 v219, 1.0, v219
	v_rcp_f32_e32 v200, v200
	v_rcp_f32_e32 v252, v252
	v_rcp_f32_e32 v253, v253
	v_rcp_f32_e32 v219, v219
	v_mul_f32_e32 v200, v48, v200
	v_mul_f32_e32 v252, v49, v252
	v_mul_f32_e32 v253, v50, v253
	v_mul_f32_e32 v219, v51, v219
	v_mul_f32_e32 v200, v200, v236
	v_mul_f32_e32 v252, v252, v237
	v_mul_f32_e32 v253, v253, v238
	v_mul_f32_e32 v219, v219, v239
	v_mul_f32_e32 v48, v200, v192
	v_mul_f32_e32 v49, v252, v193
	v_mul_f32_e32 v50, v253, v194
	v_mul_f32_e32 v51, v219, v195
	v_mul_f32_e32 v200, 0xbfb8aa3b, v40
	v_mul_f32_e32 v252, 0xbfb8aa3b, v41
	v_mul_f32_e32 v253, 0xbfb8aa3b, v42
	v_mul_f32_e32 v219, 0xbfb8aa3b, v43
	v_exp_f32_e32 v200, v200
	v_exp_f32_e32 v252, v252
	v_exp_f32_e32 v253, v253
	v_exp_f32_e32 v219, v219
	v_add_f32_e32 v200, 1.0, v200
	v_add_f32_e32 v252, 1.0, v252
	v_add_f32_e32 v253, 1.0, v253
	v_add_f32_e32 v219, 1.0, v219
	v_rcp_f32_e32 v200, v200
	v_rcp_f32_e32 v252, v252
	v_rcp_f32_e32 v253, v253
	v_rcp_f32_e32 v219, v219
	v_mul_f32_e32 v200, v40, v200
	v_mul_f32_e32 v252, v41, v252
	v_mul_f32_e32 v253, v42, v253
	v_mul_f32_e32 v219, v43, v219
	v_mul_f32_e32 v200, v200, v240
	v_mul_f32_e32 v252, v252, v241
	v_mul_f32_e32 v253, v253, v242
	v_mul_f32_e32 v219, v219, v243
	v_mul_f32_e32 v40, v200, v196
	v_mul_f32_e32 v41, v252, v197
	v_mul_f32_e32 v42, v253, v198
	v_mul_f32_e32 v43, v219, v199
	global_load_dwordx4 v[144:147], v[220:221], off
	global_load_dwordx4 v[148:151], v[220:221], off offset:256
	global_load_dwordx4 v[152:155], v[222:223], off
	global_load_dwordx4 v[156:159], v[222:223], off offset:256
	s_waitcnt vmcnt(8)
; __device__ __forceinline__ unsigned cvtpk(float lo, float hi) { f32x2 v = {lo, hi}; bf16x2_t b = __builtin_convertvector(v, bf16x2_t); return __builtin_bit_cast(unsigned, b); }
; __device__ __forceinline__ float bflo(unsigned u) { return __uint_as_float(u << 16); }
; __device__ __forceinline__ float bfhi(unsigned u) { return __uint_as_float(u & 0xffff0000u); }
;     __device__ __forceinline__ void operator()(const af4 (&acc)[2][2][4][2], const pg8::Unit& u, int wr, int wc, int fr_, int fq_) const {
;     ...
;                 const size_t ob = (size_t)RRb * 1024 + col0; v4u of_[2][2], ob_[2][2];
; #pragma unroll
;                 for (int mi = 0; mi < 2; ++mi)
; #pragma unroll
;                     for (int bj = 0; bj < 2; ++bj) { of_[mi][bj] = *(const v4u*)(ON + ob + mi * 16 * 1024 + bj * 128); ob_[mi][bj] = *(const v4u*)(OBp + ob + mi * 16 * 1024 + bj * 128); }
; #pragma unroll
;                 for (int mi = 0; mi < 2; ++mi) { float q = 0.f;
; #pragma unroll
;                     for (int bj = 0; bj < 2; ++bj) { const v4u a = of_[mi][bj], c = ob_[mi][bj];
;                         const float o0 = bflo(a.x) + bflo(c.x), o1 = bfhi(a.x) + bfhi(c.x), o2 = bflo(a.y) + bflo(c.y), o3 = bfhi(a.y) + bfhi(c.y), o4 = bflo(a.z) + bflo(c.z), o5 = bfhi(a.z) + bfhi(c.z), o6 = bflo(a.w) + bflo(c.w), o7 = bfhi(a.w) + bfhi(c.w);
;                         q += (o0 * o0 + o1 * o1) + (o2 * o2 + o3 * o3) + (o4 * o4 + o5 * o5) + (o6 * o6 + o7 * o7); }
;                     ssq[ai * 4 + mp * 2 + mi] = q; }
;     ...
;                 for (int mi = 0; mi < 2; ++mi) { const float rstd = rs[ai * 4 + mp * 2 + mi];
; #pragma unroll
;                     for (int bj = 0; bj < 2; ++bj) { af4 v0 = acc[ai][bj][mp * 2 + mi][0], v1 = acc[ai][bj][mp * 2 + mi][1]; asm volatile("" : "+v"(v0), "+v"(v1)); const v4u a = of_[mi][bj], c = ob_[mi][bj];
; #pragma unroll
;                         for (int e = 0; e < 4; ++e) { v0[e] = v0[e] * sigmoidf_(v0[e]) * (rstd * nwv[bj][0][e]); v1[e] = v1[e] * sigmoidf_(v1[e]) * (rstd * nwv[bj][1][e]); }
;                         v4u w; w.x = cvtpk(v0[0] * (bflo(a.x) + bflo(c.x)), v0[1] * (bfhi(a.x) + bfhi(c.x))); w.y = cvtpk(v0[2] * (bflo(a.y) + bflo(c.y)), v0[3] * (bfhi(a.y) + bfhi(c.y)));
;                         w.z = cvtpk(v1[0] * (bflo(a.z) + bflo(c.z)), v1[1] * (bfhi(a.z) + bfhi(c.z))); w.w = cvtpk(v1[2] * (bflo(a.w) + bflo(c.w)), v1[3] * (bfhi(a.w) + bfhi(c.w)));
	v_lshlrev_b32_e32 v192, 16, v160
	v_and_b32_e32 v193, 0xffff0000, v160
	v_lshlrev_b32_e32 v200, 16, v168
	v_and_b32_e32 v252, 0xffff0000, v168
	v_add_f32_e32 v192, v192, v200
	v_add_f32_e32 v193, v193, v252
	v_lshlrev_b32_e32 v194, 16, v161
	v_and_b32_e32 v195, 0xffff0000, v161
	v_lshlrev_b32_e32 v200, 16, v169
	v_and_b32_e32 v252, 0xffff0000, v169
	v_add_f32_e32 v194, v194, v200
	v_add_f32_e32 v195, v195, v252
	v_lshlrev_b32_e32 v196, 16, v162
	v_and_b32_e32 v197, 0xffff0000, v162
	v_lshlrev_b32_e32 v200, 16, v170
	v_and_b32_e32 v252, 0xffff0000, v170
	v_add_f32_e32 v196, v196, v200
	v_add_f32_e32 v197, v197, v252
	v_lshlrev_b32_e32 v198, 16, v163
	v_and_b32_e32 v199, 0xffff0000, v163
	v_lshlrev_b32_e32 v200, 16, v171
	v_and_b32_e32 v252, 0xffff0000, v171
	v_add_f32_e32 v198, v198, v200
	v_add_f32_e32 v199, v199, v252
	v_mul_f32_e32 v200, v192, v192
	v_mul_f32_e32 v252, v194, v194
	v_mul_f32_e32 v253, v196, v196
	v_mul_f32_e32 v219, v198, v198
	v_fmac_f32_e32 v200, v193, v193
	v_fmac_f32_e32 v252, v195, v195
	v_fmac_f32_e32 v253, v197, v197
	v_fmac_f32_e32 v219, v199, v199
	v_add_f32_e32 v200, v200, v252
	v_add_f32_e32 v253, v253, v219
	v_add_f32_e32 v200, v200, v253
	v_add_f32_e32 v249, v249, v200
	v_mul_f32_e32 v200, 0xbfb8aa3b, v52
	v_mul_f32_e32 v252, 0xbfb8aa3b, v53
	v_mul_f32_e32 v253, 0xbfb8aa3b, v54
	v_mul_f32_e32 v219, 0xbfb8aa3b, v55
	v_exp_f32_e32 v200, v200
	v_exp_f32_e32 v252, v252
	v_exp_f32_e32 v253, v253
	v_exp_f32_e32 v219, v219
	v_add_f32_e32 v200, 1.0, v200
	v_add_f32_e32 v252, 1.0, v252
	v_add_f32_e32 v253, 1.0, v253
	v_add_f32_e32 v219, 1.0, v219
	v_rcp_f32_e32 v200, v200
	v_rcp_f32_e32 v252, v252
	v_rcp_f32_e32 v253, v253
	v_rcp_f32_e32 v219, v219
	v_mul_f32_e32 v200, v52, v200
	v_mul_f32_e32 v252, v53, v252
	v_mul_f32_e32 v253, v54, v253
	v_mul_f32_e32 v219, v55, v219
	v_mul_f32_e32 v200, v200, v228
	v_mul_f32_e32 v252, v252, v229
	v_mul_f32_e32 v253, v253, v230
	v_mul_f32_e32 v219, v219, v231
	v_mul_f32_e32 v52, v200, v192
	v_mul_f32_e32 v53, v252, v193
	v_mul_f32_e32 v54, v253, v194
	v_mul_f32_e32 v55, v219, v195
	v_mul_f32_e32 v200, 0xbfb8aa3b, v44
	v_mul_f32_e32 v252, 0xbfb8aa3b, v45
	v_mul_f32_e32 v253, 0xbfb8aa3b, v46
	v_mul_f32_e32 v219, 0xbfb8aa3b, v47
	v_exp_f32_e32 v200, v200
	v_exp_f32_e32 v252, v252
	v_exp_f32_e32 v253, v253
	v_exp_f32_e32 v219, v219
	v_add_f32_e32 v200, 1.0, v200
	v_add_f32_e32 v252, 1.0, v252
	v_add_f32_e32 v253, 1.0, v253
	v_add_f32_e32 v219, 1.0, v219
	v_rcp_f32_e32 v200, v200
	v_rcp_f32_e32 v252, v252
	v_rcp_f32_e32 v253, v253
	v_rcp_f32_e32 v219, v219
	v_mul_f32_e32 v200, v44, v200
	v_mul_f32_e32 v252, v45, v252
	v_mul_f32_e32 v253, v46, v253
	v_mul_f32_e32 v219, v47, v219
	v_mul_f32_e32 v200, v200, v232
	v_mul_f32_e32 v252, v252, v233
	v_mul_f32_e32 v253, v253, v234
	v_mul_f32_e32 v219, v219, v235
	v_mul_f32_e32 v44, v200, v196
	v_mul_f32_e32 v45, v252, v197
	v_mul_f32_e32 v46, v253, v198
	v_mul_f32_e32 v47, v219, v199
	v_lshlrev_b32_e32 v192, 16, v164
	v_and_b32_e32 v193, 0xffff0000, v164
	v_lshlrev_b32_e32 v200, 16, v172
	v_and_b32_e32 v252, 0xffff0000, v172
	v_add_f32_e32 v192, v192, v200
	v_add_f32_e32 v193, v193, v252
	v_lshlrev_b32_e32 v194, 16, v165
	v_and_b32_e32 v195, 0xffff0000, v165
	v_lshlrev_b32_e32 v200, 16, v173
	v_and_b32_e32 v252, 0xffff0000, v173
	v_add_f32_e32 v194, v194, v200
	v_add_f32_e32 v195, v195, v252
	v_lshlrev_b32_e32 v196, 16, v166
	v_and_b32_e32 v197, 0xffff0000, v166
	v_lshlrev_b32_e32 v200, 16, v174
	v_and_b32_e32 v252, 0xffff0000, v174
	v_add_f32_e32 v196, v196, v200
	v_add_f32_e32 v197, v197, v252
	v_lshlrev_b32_e32 v198, 16, v167
	v_and_b32_e32 v199, 0xffff0000, v167
	v_lshlrev_b32_e32 v200, 16, v175
	v_and_b32_e32 v252, 0xffff0000, v175
	v_add_f32_e32 v198, v198, v200
	v_add_f32_e32 v199, v199, v252
	v_mul_f32_e32 v200, v192, v192
	v_mul_f32_e32 v252, v194, v194
	v_mul_f32_e32 v253, v196, v196
	v_mul_f32_e32 v219, v198, v198
	v_fmac_f32_e32 v200, v193, v193
	v_fmac_f32_e32 v252, v195, v195
	v_fmac_f32_e32 v253, v197, v197
	v_fmac_f32_e32 v219, v199, v199
	v_add_f32_e32 v200, v200, v252
	v_add_f32_e32 v253, v253, v219
	v_add_f32_e32 v200, v200, v253
	v_add_f32_e32 v249, v249, v200
	v_mul_f32_e32 v200, 0xbfb8aa3b, v32
	v_mul_f32_e32 v252, 0xbfb8aa3b, v33
	v_mul_f32_e32 v253, 0xbfb8aa3b, v34
	v_mul_f32_e32 v219, 0xbfb8aa3b, v35
	v_exp_f32_e32 v200, v200
	v_exp_f32_e32 v252, v252
	v_exp_f32_e32 v253, v253
	v_exp_f32_e32 v219, v219
	v_add_f32_e32 v200, 1.0, v200
	v_add_f32_e32 v252, 1.0, v252
	v_add_f32_e32 v253, 1.0, v253
	v_add_f32_e32 v219, 1.0, v219
	v_rcp_f32_e32 v200, v200
	v_rcp_f32_e32 v252, v252
	v_rcp_f32_e32 v253, v253
	v_rcp_f32_e32 v219, v219
	v_mul_f32_e32 v200, v32, v200
	v_mul_f32_e32 v252, v33, v252
	v_mul_f32_e32 v253, v34, v253
	v_mul_f32_e32 v219, v35, v219
	v_mul_f32_e32 v200, v200, v236
	v_mul_f32_e32 v252, v252, v237
	v_mul_f32_e32 v253, v253, v238
	v_mul_f32_e32 v219, v219, v239
	v_mul_f32_e32 v32, v200, v192
	v_mul_f32_e32 v33, v252, v193
	v_mul_f32_e32 v34, v253, v194
	v_mul_f32_e32 v35, v219, v195
	v_mul_f32_e32 v200, 0xbfb8aa3b, v24
	v_mul_f32_e32 v252, 0xbfb8aa3b, v25
	v_mul_f32_e32 v253, 0xbfb8aa3b, v26
	v_mul_f32_e32 v219, 0xbfb8aa3b, v27
	v_exp_f32_e32 v200, v200
	v_exp_f32_e32 v252, v252
	v_exp_f32_e32 v253, v253
	v_exp_f32_e32 v219, v219
	v_add_f32_e32 v200, 1.0, v200
	v_add_f32_e32 v252, 1.0, v252
	v_add_f32_e32 v253, 1.0, v253
	v_add_f32_e32 v219, 1.0, v219
	v_rcp_f32_e32 v200, v200
	v_rcp_f32_e32 v252, v252
	v_rcp_f32_e32 v253, v253
	v_rcp_f32_e32 v219, v219
	v_mul_f32_e32 v200, v24, v200
	v_mul_f32_e32 v252, v25, v252
	v_mul_f32_e32 v253, v26, v253
	v_mul_f32_e32 v219, v27, v219
	v_mul_f32_e32 v200, v200, v240
	v_mul_f32_e32 v252, v252, v241
	v_mul_f32_e32 v253, v253, v242
	v_mul_f32_e32 v219, v219, v243
	v_mul_f32_e32 v24, v200, v196
	v_mul_f32_e32 v25, v252, v197
	v_mul_f32_e32 v26, v253, v198
	v_mul_f32_e32 v27, v219, v199
	s_waitcnt vmcnt(4)
; __device__ __forceinline__ unsigned cvtpk(float lo, float hi) { f32x2 v = {lo, hi}; bf16x2_t b = __builtin_convertvector(v, bf16x2_t); return __builtin_bit_cast(unsigned, b); }
; __device__ __forceinline__ float bflo(unsigned u) { return __uint_as_float(u << 16); }
; __device__ __forceinline__ float bfhi(unsigned u) { return __uint_as_float(u & 0xffff0000u); }
;     __device__ __forceinline__ void operator()(const af4 (&acc)[2][2][4][2], const pg8::Unit& u, int wr, int wc, int fr_, int fq_) const {
;     ...
;                 const size_t ob = (size_t)RRb * 1024 + col0; v4u of_[2][2], ob_[2][2];
; #pragma unroll
;                 for (int mi = 0; mi < 2; ++mi)
; #pragma unroll
;                     for (int bj = 0; bj < 2; ++bj) { of_[mi][bj] = *(const v4u*)(ON + ob + mi * 16 * 1024 + bj * 128); ob_[mi][bj] = *(const v4u*)(OBp + ob + mi * 16 * 1024 + bj * 128); }
; #pragma unroll
;                 for (int mi = 0; mi < 2; ++mi) { float q = 0.f;
; #pragma unroll
;                     for (int bj = 0; bj < 2; ++bj) { const v4u a = of_[mi][bj], c = ob_[mi][bj];
;                         const float o0 = bflo(a.x) + bflo(c.x), o1 = bfhi(a.x) + bfhi(c.x), o2 = bflo(a.y) + bflo(c.y), o3 = bfhi(a.y) + bfhi(c.y), o4 = bflo(a.z) + bflo(c.z), o5 = bfhi(a.z) + bfhi(c.z), o6 = bflo(a.w) + bflo(c.w), o7 = bfhi(a.w) + bfhi(c.w);
;                         q += (o0 * o0 + o1 * o1) + (o2 * o2 + o3 * o3) + (o4 * o4 + o5 * o5) + (o6 * o6 + o7 * o7); }
;                     ssq[ai * 4 + mp * 2 + mi] = q; }
;     ...
;                 for (int mi = 0; mi < 2; ++mi) { const float rstd = rs[ai * 4 + mp * 2 + mi];
; #pragma unroll
;                     for (int bj = 0; bj < 2; ++bj) { af4 v0 = acc[ai][bj][mp * 2 + mi][0], v1 = acc[ai][bj][mp * 2 + mi][1]; asm volatile("" : "+v"(v0), "+v"(v1)); const v4u a = of_[mi][bj], c = ob_[mi][bj];
; #pragma unroll
;                         for (int e = 0; e < 4; ++e) { v0[e] = v0[e] * sigmoidf_(v0[e]) * (rstd * nwv[bj][0][e]); v1[e] = v1[e] * sigmoidf_(v1[e]) * (rstd * nwv[bj][1][e]); }
;                         v4u w; w.x = cvtpk(v0[0] * (bflo(a.x) + bflo(c.x)), v0[1] * (bfhi(a.x) + bfhi(c.x))); w.y = cvtpk(v0[2] * (bflo(a.y) + bflo(c.y)), v0[3] * (bfhi(a.y) + bfhi(c.y)));
;                         w.z = cvtpk(v1[0] * (bflo(a.z) + bflo(c.z)), v1[1] * (bfhi(a.z) + bfhi(c.z))); w.w = cvtpk(v1[2] * (bflo(a.w) + bflo(c.w)), v1[3] * (bfhi(a.w) + bfhi(c.w)));
	v_lshlrev_b32_e32 v192, 16, v128
	v_and_b32_e32 v193, 0xffff0000, v128
	v_lshlrev_b32_e32 v200, 16, v136
	v_and_b32_e32 v252, 0xffff0000, v136
	v_add_f32_e32 v192, v192, v200
	v_add_f32_e32 v193, v193, v252
	v_lshlrev_b32_e32 v194, 16, v129
	v_and_b32_e32 v195, 0xffff0000, v129
	v_lshlrev_b32_e32 v200, 16, v137
	v_and_b32_e32 v252, 0xffff0000, v137
	v_add_f32_e32 v194, v194, v200
	v_add_f32_e32 v195, v195, v252
	v_lshlrev_b32_e32 v196, 16, v130
	v_and_b32_e32 v197, 0xffff0000, v130
	v_lshlrev_b32_e32 v200, 16, v138
	v_and_b32_e32 v252, 0xffff0000, v138
	v_add_f32_e32 v196, v196, v200
	v_add_f32_e32 v197, v197, v252
	v_lshlrev_b32_e32 v198, 16, v131
	v_and_b32_e32 v199, 0xffff0000, v131
	v_lshlrev_b32_e32 v200, 16, v139
	v_and_b32_e32 v252, 0xffff0000, v139
	v_add_f32_e32 v198, v198, v200
	v_add_f32_e32 v199, v199, v252
	v_mul_f32_e32 v200, v192, v192
	v_mul_f32_e32 v252, v194, v194
	v_mul_f32_e32 v253, v196, v196
	v_mul_f32_e32 v219, v198, v198
	v_fmac_f32_e32 v200, v193, v193
	v_fmac_f32_e32 v252, v195, v195
	v_fmac_f32_e32 v253, v197, v197
	v_fmac_f32_e32 v219, v199, v199
	v_add_f32_e32 v200, v200, v252
	v_add_f32_e32 v253, v253, v219
	v_add_f32_e32 v200, v200, v253
	v_add_f32_e32 v250, v250, v200
	v_mul_f32_e32 v200, 0xbfb8aa3b, v36
	v_mul_f32_e32 v252, 0xbfb8aa3b, v37
	v_mul_f32_e32 v253, 0xbfb8aa3b, v38
	v_mul_f32_e32 v219, 0xbfb8aa3b, v39
	v_exp_f32_e32 v200, v200
	v_exp_f32_e32 v252, v252
	v_exp_f32_e32 v253, v253
	v_exp_f32_e32 v219, v219
	v_add_f32_e32 v200, 1.0, v200
	v_add_f32_e32 v252, 1.0, v252
	v_add_f32_e32 v253, 1.0, v253
	v_add_f32_e32 v219, 1.0, v219
	v_rcp_f32_e32 v200, v200
	v_rcp_f32_e32 v252, v252
	v_rcp_f32_e32 v253, v253
	v_rcp_f32_e32 v219, v219
	v_mul_f32_e32 v200, v36, v200
	v_mul_f32_e32 v252, v37, v252
	v_mul_f32_e32 v253, v38, v253
	v_mul_f32_e32 v219, v39, v219
	v_mul_f32_e32 v200, v200, v228
	v_mul_f32_e32 v252, v252, v229
	v_mul_f32_e32 v253, v253, v230
	v_mul_f32_e32 v219, v219, v231
	v_mul_f32_e32 v36, v200, v192
	v_mul_f32_e32 v37, v252, v193
	v_mul_f32_e32 v38, v253, v194
	v_mul_f32_e32 v39, v219, v195
	v_mul_f32_e32 v200, 0xbfb8aa3b, v28
	v_mul_f32_e32 v252, 0xbfb8aa3b, v29
	v_mul_f32_e32 v253, 0xbfb8aa3b, v30
	v_mul_f32_e32 v219, 0xbfb8aa3b, v31
	v_exp_f32_e32 v200, v200
	v_exp_f32_e32 v252, v252
	v_exp_f32_e32 v253, v253
	v_exp_f32_e32 v219, v219
	v_add_f32_e32 v200, 1.0, v200
	v_add_f32_e32 v252, 1.0, v252
	v_add_f32_e32 v253, 1.0, v253
	v_add_f32_e32 v219, 1.0, v219
	v_rcp_f32_e32 v200, v200
	v_rcp_f32_e32 v252, v252
	v_rcp_f32_e32 v253, v253
	v_rcp_f32_e32 v219, v219
	v_mul_f32_e32 v200, v28, v200
	v_mul_f32_e32 v252, v29, v252
	v_mul_f32_e32 v253, v30, v253
	v_mul_f32_e32 v219, v31, v219
	v_mul_f32_e32 v200, v200, v232
	v_mul_f32_e32 v252, v252, v233
	v_mul_f32_e32 v253, v253, v234
	v_mul_f32_e32 v219, v219, v235
	v_mul_f32_e32 v28, v200, v196
	v_mul_f32_e32 v29, v252, v197
	v_mul_f32_e32 v30, v253, v198
	v_mul_f32_e32 v31, v219, v199
	v_lshlrev_b32_e32 v192, 16, v132
	v_and_b32_e32 v193, 0xffff0000, v132
	v_lshlrev_b32_e32 v200, 16, v140
	v_and_b32_e32 v252, 0xffff0000, v140
	v_add_f32_e32 v192, v192, v200
	v_add_f32_e32 v193, v193, v252
	v_lshlrev_b32_e32 v194, 16, v133
	v_and_b32_e32 v195, 0xffff0000, v133
	v_lshlrev_b32_e32 v200, 16, v141
	v_and_b32_e32 v252, 0xffff0000, v141
	v_add_f32_e32 v194, v194, v200
	v_add_f32_e32 v195, v195, v252
	v_lshlrev_b32_e32 v196, 16, v134
	v_and_b32_e32 v197, 0xffff0000, v134
	v_lshlrev_b32_e32 v200, 16, v142
	v_and_b32_e32 v252, 0xffff0000, v142
	v_add_f32_e32 v196, v196, v200
	v_add_f32_e32 v197, v197, v252
	v_lshlrev_b32_e32 v198, 16, v135
	v_and_b32_e32 v199, 0xffff0000, v135
	v_lshlrev_b32_e32 v200, 16, v143
	v_and_b32_e32 v252, 0xffff0000, v143
	v_add_f32_e32 v198, v198, v200
	v_add_f32_e32 v199, v199, v252
	v_mul_f32_e32 v200, v192, v192
	v_mul_f32_e32 v252, v194, v194
	v_mul_f32_e32 v253, v196, v196
	v_mul_f32_e32 v219, v198, v198
	v_fmac_f32_e32 v200, v193, v193
	v_fmac_f32_e32 v252, v195, v195
	v_fmac_f32_e32 v253, v197, v197
	v_fmac_f32_e32 v219, v199, v199
	v_add_f32_e32 v200, v200, v252
	v_add_f32_e32 v253, v253, v219
	v_add_f32_e32 v200, v200, v253
	v_add_f32_e32 v250, v250, v200
	v_mul_f32_e32 v200, 0xbfb8aa3b, v16
	v_mul_f32_e32 v252, 0xbfb8aa3b, v17
	v_mul_f32_e32 v253, 0xbfb8aa3b, v18
	v_mul_f32_e32 v219, 0xbfb8aa3b, v19
	v_exp_f32_e32 v200, v200
	v_exp_f32_e32 v252, v252
	v_exp_f32_e32 v253, v253
	v_exp_f32_e32 v219, v219
	v_add_f32_e32 v200, 1.0, v200
	v_add_f32_e32 v252, 1.0, v252
	v_add_f32_e32 v253, 1.0, v253
	v_add_f32_e32 v219, 1.0, v219
	v_rcp_f32_e32 v200, v200
	v_rcp_f32_e32 v252, v252
	v_rcp_f32_e32 v253, v253
	v_rcp_f32_e32 v219, v219
	v_mul_f32_e32 v200, v16, v200
	v_mul_f32_e32 v252, v17, v252
	v_mul_f32_e32 v253, v18, v253
	v_mul_f32_e32 v219, v19, v219
	v_mul_f32_e32 v200, v200, v236
	v_mul_f32_e32 v252, v252, v237
	v_mul_f32_e32 v253, v253, v238
	v_mul_f32_e32 v219, v219, v239
	v_mul_f32_e32 v16, v200, v192
	v_mul_f32_e32 v17, v252, v193
	v_mul_f32_e32 v18, v253, v194
	v_mul_f32_e32 v19, v219, v195
	v_mul_f32_e32 v200, 0xbfb8aa3b, v8
	v_mul_f32_e32 v252, 0xbfb8aa3b, v9
	v_mul_f32_e32 v253, 0xbfb8aa3b, v10
	v_mul_f32_e32 v219, 0xbfb8aa3b, v11
	v_exp_f32_e32 v200, v200
	v_exp_f32_e32 v252, v252
	v_exp_f32_e32 v253, v253
	v_exp_f32_e32 v219, v219
	v_add_f32_e32 v200, 1.0, v200
	v_add_f32_e32 v252, 1.0, v252
	v_add_f32_e32 v253, 1.0, v253
	v_add_f32_e32 v219, 1.0, v219
	v_rcp_f32_e32 v200, v200
	v_rcp_f32_e32 v252, v252
	v_rcp_f32_e32 v253, v253
	v_rcp_f32_e32 v219, v219
	v_mul_f32_e32 v200, v8, v200
	v_mul_f32_e32 v252, v9, v252
	v_mul_f32_e32 v253, v10, v253
	v_mul_f32_e32 v219, v11, v219
	v_mul_f32_e32 v200, v200, v240
	v_mul_f32_e32 v252, v252, v241
	v_mul_f32_e32 v253, v253, v242
	v_mul_f32_e32 v219, v219, v243
	v_mul_f32_e32 v8, v200, v196
	v_mul_f32_e32 v9, v252, v197
	v_mul_f32_e32 v10, v253, v198
	v_mul_f32_e32 v11, v219, v199
	s_waitcnt vmcnt(0)
; __device__ __forceinline__ float bflo(unsigned u) { return __uint_as_float(u << 16); }
; __device__ __forceinline__ float bfhi(unsigned u) { return __uint_as_float(u & 0xffff0000u); }
;     __device__ __forceinline__ void operator()(const af4 (&acc)[2][2][4][2], const pg8::Unit& u, int wr, int wc, int fr_, int fq_) const {
;     ...
;             for (int b_ = 0; b_ < 4; ++b_) {
;                 const int ai = b_ >> 1, mp = b_ & 1;
;                 int RRb = row0 + ai * 128 + mp * 32; asm volatile("" : "+v"(RRb));
;                 const size_t ob = (size_t)RRb * 1024 + col0; v4u of_[2][2], ob_[2][2];
; #pragma unroll
;                 for (int mi = 0; mi < 2; ++mi)
; #pragma unroll
;                     for (int bj = 0; bj < 2; ++bj) { of_[mi][bj] = *(const v4u*)(ON + ob + mi * 16 * 1024 + bj * 128); ob_[mi][bj] = *(const v4u*)(OBp + ob + mi * 16 * 1024 + bj * 128); }
; #pragma unroll
;                 for (int mi = 0; mi < 2; ++mi) { float q = 0.f;
; #pragma unroll
;                     for (int bj = 0; bj < 2; ++bj) { const v4u a = of_[mi][bj], c = ob_[mi][bj];
;                         const float o0 = bflo(a.x) + bflo(c.x), o1 = bfhi(a.x) + bfhi(c.x), o2 = bflo(a.y) + bflo(c.y), o3 = bfhi(a.y) + bfhi(c.y), o4 = bflo(a.z) + bflo(c.z), o5 = bfhi(a.z) + bfhi(c.z), o6 = bflo(a.w) + bflo(c.w), o7 = bfhi(a.w) + bfhi(c.w);
;                         q += (o0 * o0 + o1 * o1) + (o2 * o2 + o3 * o3) + (o4 * o4 + o5 * o5) + (o6 * o6 + o7 * o7); }
;                     ssq[ai * 4 + mp * 2 + mi] = q; }
;                 asm volatile("" ::: "memory");
;             }
; #pragma unroll
;             for (int k = 0; k < 8; ++k) { float v = ssq[k];
;                 v += __int_as_float(__builtin_amdgcn_ds_bpermute((ln_ ^ 16) << 2, __float_as_int(v)));
;                 v += __int_as_float(__builtin_amdgcn_ds_bpermute((ln_ ^ 32) << 2, __float_as_int(v))); ssq[k] = v; }
;     ...
;                 for (int mi = 0; mi < 2; ++mi) { const float rstd = rs[ai * 4 + mp * 2 + mi];
; #pragma unroll
;                     for (int bj = 0; bj < 2; ++bj) { af4 v0 = acc[ai][bj][mp * 2 + mi][0], v1 = acc[ai][bj][mp * 2 + mi][1]; asm volatile("" : "+v"(v0), "+v"(v1)); const v4u a = of_[mi][bj], c = ob_[mi][bj];
; #pragma unroll
;                         for (int e = 0; e < 4; ++e) { v0[e] = v0[e] * sigmoidf_(v0[e]) * (rstd * nwv[bj][0][e]); v1[e] = v1[e] * sigmoidf_(v1[e]) * (rstd * nwv[bj][1][e]); }
	v_lshlrev_b32_e32 v192, 16, v144
	v_and_b32_e32 v193, 0xffff0000, v144
	v_lshlrev_b32_e32 v200, 16, v152
	v_and_b32_e32 v252, 0xffff0000, v152
	v_add_f32_e32 v192, v192, v200
	v_add_f32_e32 v193, v193, v252
	v_lshlrev_b32_e32 v194, 16, v145
	v_and_b32_e32 v195, 0xffff0000, v145
	v_lshlrev_b32_e32 v200, 16, v153
	v_and_b32_e32 v252, 0xffff0000, v153
	v_add_f32_e32 v194, v194, v200
	v_add_f32_e32 v195, v195, v252
	v_lshlrev_b32_e32 v196, 16, v146
	v_and_b32_e32 v197, 0xffff0000, v146
	v_lshlrev_b32_e32 v200, 16, v154
	v_and_b32_e32 v252, 0xffff0000, v154
	v_add_f32_e32 v196, v196, v200
	v_add_f32_e32 v197, v197, v252
	v_lshlrev_b32_e32 v198, 16, v147
	v_and_b32_e32 v199, 0xffff0000, v147
	v_lshlrev_b32_e32 v200, 16, v155
	v_and_b32_e32 v252, 0xffff0000, v155
	v_add_f32_e32 v198, v198, v200
	v_add_f32_e32 v199, v199, v252
	v_mul_f32_e32 v200, v192, v192
	v_mul_f32_e32 v252, v194, v194
	v_mul_f32_e32 v253, v196, v196
	v_mul_f32_e32 v219, v198, v198
	v_fmac_f32_e32 v200, v193, v193
	v_fmac_f32_e32 v252, v195, v195
	v_fmac_f32_e32 v253, v197, v197
	v_fmac_f32_e32 v219, v199, v199
	v_add_f32_e32 v200, v200, v252
	v_add_f32_e32 v253, v253, v219
	v_add_f32_e32 v200, v200, v253
	v_add_f32_e32 v251, v251, v200
	v_mul_f32_e32 v200, 0xbfb8aa3b, v20
	v_mul_f32_e32 v252, 0xbfb8aa3b, v21
	v_mul_f32_e32 v253, 0xbfb8aa3b, v22
	v_mul_f32_e32 v219, 0xbfb8aa3b, v23
	v_exp_f32_e32 v200, v200
	v_exp_f32_e32 v252, v252
	v_exp_f32_e32 v253, v253
	v_exp_f32_e32 v219, v219
	v_add_f32_e32 v200, 1.0, v200
	v_add_f32_e32 v252, 1.0, v252
	v_add_f32_e32 v253, 1.0, v253
	v_add_f32_e32 v219, 1.0, v219
	v_rcp_f32_e32 v200, v200
	v_rcp_f32_e32 v252, v252
	v_rcp_f32_e32 v253, v253
	v_rcp_f32_e32 v219, v219
	v_mul_f32_e32 v200, v20, v200
	v_mul_f32_e32 v252, v21, v252
	v_mul_f32_e32 v253, v22, v253
	v_mul_f32_e32 v219, v23, v219
	v_mul_f32_e32 v200, v200, v228
	v_mul_f32_e32 v252, v252, v229
	v_mul_f32_e32 v253, v253, v230
	v_mul_f32_e32 v219, v219, v231
	v_mul_f32_e32 v20, v200, v192
	v_mul_f32_e32 v21, v252, v193
	v_mul_f32_e32 v22, v253, v194
	v_mul_f32_e32 v23, v219, v195
	v_mul_f32_e32 v200, 0xbfb8aa3b, v12
	v_mul_f32_e32 v252, 0xbfb8aa3b, v13
	v_mul_f32_e32 v253, 0xbfb8aa3b, v14
	v_mul_f32_e32 v219, 0xbfb8aa3b, v15
	v_exp_f32_e32 v200, v200
	v_exp_f32_e32 v252, v252
	v_exp_f32_e32 v253, v253
	v_exp_f32_e32 v219, v219
	v_add_f32_e32 v200, 1.0, v200
	v_add_f32_e32 v252, 1.0, v252
	v_add_f32_e32 v253, 1.0, v253
	v_add_f32_e32 v219, 1.0, v219
	v_rcp_f32_e32 v200, v200
	v_rcp_f32_e32 v252, v252
	v_rcp_f32_e32 v253, v253
	v_rcp_f32_e32 v219, v219
	v_mul_f32_e32 v200, v12, v200
	v_mul_f32_e32 v252, v13, v252
	v_mul_f32_e32 v253, v14, v253
	v_mul_f32_e32 v219, v15, v219
	v_mul_f32_e32 v200, v200, v232
	v_mul_f32_e32 v252, v252, v233
	v_mul_f32_e32 v253, v253, v234
	v_mul_f32_e32 v219, v219, v235
	v_mul_f32_e32 v12, v200, v196
	v_mul_f32_e32 v13, v252, v197
	v_mul_f32_e32 v14, v253, v198
	v_mul_f32_e32 v15, v219, v199
	v_lshlrev_b32_e32 v192, 16, v148
	v_and_b32_e32 v193, 0xffff0000, v148
	v_lshlrev_b32_e32 v200, 16, v156
	v_and_b32_e32 v252, 0xffff0000, v156
	v_add_f32_e32 v192, v192, v200
	v_add_f32_e32 v193, v193, v252
	v_lshlrev_b32_e32 v194, 16, v149
	v_and_b32_e32 v195, 0xffff0000, v149
	v_lshlrev_b32_e32 v200, 16, v157
	v_and_b32_e32 v252, 0xffff0000, v157
	v_add_f32_e32 v194, v194, v200
	v_add_f32_e32 v195, v195, v252
	v_lshlrev_b32_e32 v196, 16, v150
	v_and_b32_e32 v197, 0xffff0000, v150
	v_lshlrev_b32_e32 v200, 16, v158
	v_and_b32_e32 v252, 0xffff0000, v158
	v_add_f32_e32 v196, v196, v200
	v_add_f32_e32 v197, v197, v252
	v_lshlrev_b32_e32 v198, 16, v151
	v_and_b32_e32 v199, 0xffff0000, v151
	v_lshlrev_b32_e32 v200, 16, v159
	v_and_b32_e32 v252, 0xffff0000, v159
	v_add_f32_e32 v198, v198, v200
	v_add_f32_e32 v199, v199, v252
	v_mul_f32_e32 v200, v192, v192
	v_mul_f32_e32 v252, v194, v194
	v_mul_f32_e32 v253, v196, v196
	v_mul_f32_e32 v219, v198, v198
	v_fmac_f32_e32 v200, v193, v193
	v_fmac_f32_e32 v252, v195, v195
	v_fmac_f32_e32 v253, v197, v197
	v_fmac_f32_e32 v219, v199, v199
	v_add_f32_e32 v200, v200, v252
	v_add_f32_e32 v253, v253, v219
	v_add_f32_e32 v200, v200, v253
	v_add_f32_e32 v251, v251, v200
	v_mul_f32_e32 v200, 0xbfb8aa3b, v4
	v_mul_f32_e32 v252, 0xbfb8aa3b, v5
	v_mul_f32_e32 v253, 0xbfb8aa3b, v6
	v_mul_f32_e32 v219, 0xbfb8aa3b, v7
	v_exp_f32_e32 v200, v200
	v_exp_f32_e32 v252, v252
	v_exp_f32_e32 v253, v253
	v_exp_f32_e32 v219, v219
	v_add_f32_e32 v200, 1.0, v200
	v_add_f32_e32 v252, 1.0, v252
	v_add_f32_e32 v253, 1.0, v253
	v_add_f32_e32 v219, 1.0, v219
	v_rcp_f32_e32 v200, v200
	v_rcp_f32_e32 v252, v252
	v_rcp_f32_e32 v253, v253
	v_rcp_f32_e32 v219, v219
	v_mul_f32_e32 v200, v4, v200
	v_mul_f32_e32 v252, v5, v252
	v_mul_f32_e32 v253, v6, v253
	v_mul_f32_e32 v219, v7, v219
	v_mul_f32_e32 v200, v200, v236
	v_mul_f32_e32 v252, v252, v237
	v_mul_f32_e32 v253, v253, v238
	v_mul_f32_e32 v219, v219, v239
	v_mul_f32_e32 v4, v200, v192
	v_mul_f32_e32 v5, v252, v193
	v_mul_f32_e32 v6, v253, v194
	v_mul_f32_e32 v7, v219, v195
	v_mul_f32_e32 v200, 0xbfb8aa3b, v0
	v_mul_f32_e32 v252, 0xbfb8aa3b, v1
	v_mul_f32_e32 v253, 0xbfb8aa3b, v2
	v_mul_f32_e32 v219, 0xbfb8aa3b, v3
	v_exp_f32_e32 v200, v200
	v_exp_f32_e32 v252, v252
	v_exp_f32_e32 v253, v253
	v_exp_f32_e32 v219, v219
	v_add_f32_e32 v200, 1.0, v200
	v_add_f32_e32 v252, 1.0, v252
	v_add_f32_e32 v253, 1.0, v253
	v_add_f32_e32 v219, 1.0, v219
	v_rcp_f32_e32 v200, v200
	v_rcp_f32_e32 v252, v252
	v_rcp_f32_e32 v253, v253
	v_rcp_f32_e32 v219, v219
	v_mul_f32_e32 v200, v0, v200
	v_mul_f32_e32 v252, v1, v252
	v_mul_f32_e32 v253, v2, v253
	v_mul_f32_e32 v219, v3, v219
	v_mul_f32_e32 v200, v200, v240
	v_mul_f32_e32 v252, v252, v241
	v_mul_f32_e32 v253, v253, v242
	v_mul_f32_e32 v219, v219, v243
	v_mul_f32_e32 v0, v200, v196
	v_mul_f32_e32 v1, v252, v197
	v_mul_f32_e32 v2, v253, v198
	v_mul_f32_e32 v3, v219, v199
	ds_bpermute_b32 v200, v226, v244
	ds_bpermute_b32 v252, v226, v245
	ds_bpermute_b32 v253, v226, v246
	ds_bpermute_b32 v219, v226, v247
	s_waitcnt lgkmcnt(0)
; #define LAS __attribute__((address_space(3)))
; __device__ __forceinline__ unsigned cvtpk(float lo, float hi) { f32x2 v = {lo, hi}; bf16x2_t b = __builtin_convertvector(v, bf16x2_t); return __builtin_bit_cast(unsigned, b); }
; __device__ __forceinline__ float bflo(unsigned u) { return __uint_as_float(u << 16); }
; __device__ __forceinline__ float bfhi(unsigned u) { return __uint_as_float(u & 0xffff0000u); }
;     __device__ __forceinline__ void operator()(const af4 (&acc)[2][2][4][2], const pg8::Unit& u, int wr, int wc, int fr_, int fq_) const {
;     ...
;             for (int k = 0; k < 8; ++k) { float v = ssq[k];
;                 v += __int_as_float(__builtin_amdgcn_ds_bpermute((ln_ ^ 16) << 2, __float_as_int(v)));
;                 v += __int_as_float(__builtin_amdgcn_ds_bpermute((ln_ ^ 32) << 2, __float_as_int(v))); ssq[k] = v; }
;             if (fq == 0) {
; #pragma unroll
;                 for (int k = 0; k < 8; ++k) xch[((k >> 2) * 128 + wr * 64 + (k & 3) * 16 + fr) * 4 + wc] = ssq[k];
;             }
;             asm volatile("s_waitcnt lgkmcnt(0)" ::: "memory"); __builtin_amdgcn_s_barrier(); asm volatile("" ::: "memory");
;             float rs[8];
; #pragma unroll
;             for (int k = 0; k < 8; ++k) { const f32x4 p4 = *(const LAS f32x4*)(xch + ((k >> 2) * 128 + wr * 64 + (k & 3) * 16 + fr) * 4);
;                 rs[k] = 1.0f / sqrtf(((p4[0] + p4[1]) + (p4[2] + p4[3])) * (1.f / 256.f) + LN_EPS); }
;     ...
;                         v4u w; w.x = cvtpk(v0[0] * (bflo(a.x) + bflo(c.x)), v0[1] * (bfhi(a.x) + bfhi(c.x))); w.y = cvtpk(v0[2] * (bflo(a.y) + bflo(c.y)), v0[3] * (bfhi(a.y) + bfhi(c.y)));
;                         w.z = cvtpk(v1[0] * (bflo(a.z) + bflo(c.z)), v1[1] * (bfhi(a.z) + bfhi(c.z))); w.w = cvtpk(v1[2] * (bflo(a.w) + bflo(c.w)), v1[3] * (bfhi(a.w) + bfhi(c.w)));
;                         *(v4u*)(ON + ob + mi * 16 * 1024 + bj * 128) = w; } }
	v_add_f32_e32 v244, v244, v200
	v_add_f32_e32 v245, v245, v252
	v_add_f32_e32 v246, v246, v253
	v_add_f32_e32 v247, v247, v219
	ds_bpermute_b32 v200, v226, v248
	ds_bpermute_b32 v252, v226, v249
	ds_bpermute_b32 v253, v226, v250
	ds_bpermute_b32 v219, v226, v251
	s_waitcnt lgkmcnt(0)
	v_add_f32_e32 v248, v248, v200
	v_add_f32_e32 v249, v249, v252
	v_add_f32_e32 v250, v250, v253
	v_add_f32_e32 v251, v251, v219
	ds_bpermute_b32 v200, v227, v244
	ds_bpermute_b32 v252, v227, v245
	ds_bpermute_b32 v253, v227, v246
	ds_bpermute_b32 v219, v227, v247
	s_waitcnt lgkmcnt(0)
	v_add_f32_e32 v244, v244, v200
	v_add_f32_e32 v245, v245, v252
	v_add_f32_e32 v246, v246, v253
	v_add_f32_e32 v247, v247, v219
	ds_bpermute_b32 v200, v227, v248
	ds_bpermute_b32 v252, v227, v249
	ds_bpermute_b32 v253, v227, v250
	ds_bpermute_b32 v219, v227, v251
	s_waitcnt lgkmcnt(0)
	v_add_f32_e32 v248, v248, v200
	v_add_f32_e32 v249, v249, v252
	v_add_f32_e32 v250, v250, v253
	v_add_f32_e32 v251, v251, v219
	ds_write_b32 v224, v244 offset:0
	ds_write_b32 v224, v245 offset:256
	ds_write_b32 v224, v246 offset:512
	ds_write_b32 v224, v247 offset:768
	ds_write_b32 v224, v248 offset:2048
	ds_write_b32 v224, v249 offset:2304
	ds_write_b32 v224, v250 offset:2560
	ds_write_b32 v224, v251 offset:2816
	s_waitcnt lgkmcnt(0)
	s_barrier
	ds_read_b128 v[128:131], v225 offset:0
	ds_read_b128 v[132:135], v225 offset:256
	ds_read_b128 v[136:139], v225 offset:512
	ds_read_b128 v[140:143], v225 offset:768
	ds_read_b128 v[144:147], v225 offset:2048
	ds_read_b128 v[148:151], v225 offset:2304
	ds_read_b128 v[152:155], v225 offset:2560
	ds_read_b128 v[156:159], v225 offset:2816
	s_waitcnt lgkmcnt(0)
	v_add_f32_e32 v128, v128, v129
	v_add_f32_e32 v130, v130, v131
	v_add_f32_e32 v128, v128, v130
	v_mul_f32_e32 v128, 0x3b800000, v128
	v_add_f32_e32 v128, 0x358637bd, v128
	v_add_f32_e32 v132, v132, v133
	v_add_f32_e32 v134, v134, v135
	v_add_f32_e32 v132, v132, v134
	v_mul_f32_e32 v132, 0x3b800000, v132
	v_add_f32_e32 v132, 0x358637bd, v132
	v_add_f32_e32 v136, v136, v137
	v_add_f32_e32 v138, v138, v139
	v_add_f32_e32 v136, v136, v138
	v_mul_f32_e32 v136, 0x3b800000, v136
	v_add_f32_e32 v136, 0x358637bd, v136
	v_add_f32_e32 v140, v140, v141
	v_add_f32_e32 v142, v142, v143
	v_add_f32_e32 v140, v140, v142
	v_mul_f32_e32 v140, 0x3b800000, v140
	v_add_f32_e32 v140, 0x358637bd, v140
	v_add_f32_e32 v144, v144, v145
	v_add_f32_e32 v146, v146, v147
	v_add_f32_e32 v144, v144, v146
	v_mul_f32_e32 v144, 0x3b800000, v144
	v_add_f32_e32 v144, 0x358637bd, v144
	v_add_f32_e32 v148, v148, v149
	v_add_f32_e32 v150, v150, v151
	v_add_f32_e32 v148, v148, v150
	v_mul_f32_e32 v148, 0x3b800000, v148
	v_add_f32_e32 v148, 0x358637bd, v148
	v_add_f32_e32 v152, v152, v153
	v_add_f32_e32 v154, v154, v155
	v_add_f32_e32 v152, v152, v154
	v_mul_f32_e32 v152, 0x3b800000, v152
	v_add_f32_e32 v152, 0x358637bd, v152
	v_add_f32_e32 v156, v156, v157
	v_add_f32_e32 v158, v158, v159
	v_add_f32_e32 v156, v156, v158
	v_mul_f32_e32 v156, 0x3b800000, v156
	v_add_f32_e32 v156, 0x358637bd, v156
	v_rsq_f32_e32 v244, v128
	v_rsq_f32_e32 v245, v132
	v_rsq_f32_e32 v246, v136
	v_rsq_f32_e32 v247, v140
	v_rsq_f32_e32 v248, v144
	v_rsq_f32_e32 v249, v148
	v_rsq_f32_e32 v250, v152
	v_rsq_f32_e32 v251, v156
	v_subrev_co_u32_e32 v220, vcc, 0x58000, v220
	s_nop 1
	v_subbrev_co_u32_e32 v221, vcc, 0, v221, vcc
	v_mul_f32_e32 v124, v124, v244
	v_mul_f32_e32 v125, v125, v244
	v_mul_f32_e32 v126, v126, v244
	v_mul_f32_e32 v127, v127, v244
	v_mul_f32_e32 v120, v120, v244
	v_mul_f32_e32 v121, v121, v244
	v_mul_f32_e32 v122, v122, v244
	v_mul_f32_e32 v123, v123, v244
	v_cvt_pk_bf16_f32 v160, v124, v125
	v_cvt_pk_bf16_f32 v161, v126, v127
	v_cvt_pk_bf16_f32 v162, v120, v121
	v_cvt_pk_bf16_f32 v163, v122, v123
	global_store_dwordx4 v[220:221], v[160:163], off
	v_mul_f32_e32 v112, v112, v244
	v_mul_f32_e32 v113, v113, v244
	v_mul_f32_e32 v114, v114, v244
	v_mul_f32_e32 v115, v115, v244
	v_mul_f32_e32 v104, v104, v244
	v_mul_f32_e32 v105, v105, v244
	v_mul_f32_e32 v106, v106, v244
	v_mul_f32_e32 v107, v107, v244
	v_cvt_pk_bf16_f32 v164, v112, v113
	v_cvt_pk_bf16_f32 v165, v114, v115
	v_cvt_pk_bf16_f32 v166, v104, v105
	v_cvt_pk_bf16_f32 v167, v106, v107
	global_store_dwordx4 v[220:221], v[164:167], off offset:256
	s_nop 0
	v_add_co_u32_e32 v220, vcc, 0x8000, v220
	s_nop 1
	v_addc_co_u32_e32 v221, vcc, 0, v221, vcc
	v_mul_f32_e32 v116, v116, v245
	v_mul_f32_e32 v117, v117, v245
	v_mul_f32_e32 v118, v118, v245
	v_mul_f32_e32 v119, v119, v245
	v_mul_f32_e32 v108, v108, v245
	v_mul_f32_e32 v109, v109, v245
	v_mul_f32_e32 v110, v110, v245
	v_mul_f32_e32 v111, v111, v245
	v_cvt_pk_bf16_f32 v160, v116, v117
	v_cvt_pk_bf16_f32 v161, v118, v119
	v_cvt_pk_bf16_f32 v162, v108, v109
	v_cvt_pk_bf16_f32 v163, v110, v111
	global_store_dwordx4 v[220:221], v[160:163], off
	v_mul_f32_e32 v96, v96, v245
	v_mul_f32_e32 v97, v97, v245
	v_mul_f32_e32 v98, v98, v245
	v_mul_f32_e32 v99, v99, v245
	v_mul_f32_e32 v88, v88, v245
	v_mul_f32_e32 v89, v89, v245
	v_mul_f32_e32 v90, v90, v245
	v_mul_f32_e32 v91, v91, v245
	v_cvt_pk_bf16_f32 v164, v96, v97
	v_cvt_pk_bf16_f32 v165, v98, v99
	v_cvt_pk_bf16_f32 v166, v88, v89
	v_cvt_pk_bf16_f32 v167, v90, v91
	global_store_dwordx4 v[220:221], v[164:167], off offset:256
	s_nop 0
	v_add_co_u32_e32 v220, vcc, 0x8000, v220
	s_nop 1
	v_addc_co_u32_e32 v221, vcc, 0, v221, vcc
	v_mul_f32_e32 v100, v100, v246
	v_mul_f32_e32 v101, v101, v246
	v_mul_f32_e32 v102, v102, v246
	v_mul_f32_e32 v103, v103, v246
	v_mul_f32_e32 v92, v92, v246
; __device__ __forceinline__ unsigned cvtpk(float lo, float hi) { f32x2 v = {lo, hi}; bf16x2_t b = __builtin_convertvector(v, bf16x2_t); return __builtin_bit_cast(unsigned, b); }
; __device__ __forceinline__ float bflo(unsigned u) { return __uint_as_float(u << 16); }
; __device__ __forceinline__ float bfhi(unsigned u) { return __uint_as_float(u & 0xffff0000u); }
; __device__ __forceinline__ float sigmoidf_(float x) { return __builtin_amdgcn_rcpf(1.0f + __expf(-x)); }
;     __device__ __forceinline__ void operator()(const af4 (&acc)[2][2][4][2], const pg8::Unit& u, int wr, int wc, int fr_, int fq_) const {
;     ...
;                 for (int mi = 0; mi < 2; ++mi) { const float rstd = rs[ai * 4 + mp * 2 + mi];
; #pragma unroll
;                     for (int bj = 0; bj < 2; ++bj) { af4 v0 = acc[ai][bj][mp * 2 + mi][0], v1 = acc[ai][bj][mp * 2 + mi][1]; asm volatile("" : "+v"(v0), "+v"(v1)); const v4u a = of_[mi][bj], c = ob_[mi][bj];
; #pragma unroll
;                         for (int e = 0; e < 4; ++e) { v0[e] = v0[e] * sigmoidf_(v0[e]) * (rstd * nwv[bj][0][e]); v1[e] = v1[e] * sigmoidf_(v1[e]) * (rstd * nwv[bj][1][e]); }
;                         v4u w; w.x = cvtpk(v0[0] * (bflo(a.x) + bflo(c.x)), v0[1] * (bfhi(a.x) + bfhi(c.x))); w.y = cvtpk(v0[2] * (bflo(a.y) + bflo(c.y)), v0[3] * (bfhi(a.y) + bfhi(c.y)));
;                         w.z = cvtpk(v1[0] * (bflo(a.z) + bflo(c.z)), v1[1] * (bfhi(a.z) + bfhi(c.z))); w.w = cvtpk(v1[2] * (bflo(a.w) + bflo(c.w)), v1[3] * (bfhi(a.w) + bfhi(c.w)));
;                         *(v4u*)(ON + ob + mi * 16 * 1024 + bj * 128) = w; } }
	v_mul_f32_e32 v93, v93, v246
	v_mul_f32_e32 v94, v94, v246
	v_mul_f32_e32 v95, v95, v246
	v_cvt_pk_bf16_f32 v160, v100, v101
	v_cvt_pk_bf16_f32 v161, v102, v103
	v_cvt_pk_bf16_f32 v162, v92, v93
	v_cvt_pk_bf16_f32 v163, v94, v95
	global_store_dwordx4 v[220:221], v[160:163], off
	v_mul_f32_e32 v80, v80, v246
	v_mul_f32_e32 v81, v81, v246
	v_mul_f32_e32 v82, v82, v246
	v_mul_f32_e32 v83, v83, v246
	v_mul_f32_e32 v72, v72, v246
	v_mul_f32_e32 v73, v73, v246
	v_mul_f32_e32 v74, v74, v246
	v_mul_f32_e32 v75, v75, v246
	v_cvt_pk_bf16_f32 v164, v80, v81
	v_cvt_pk_bf16_f32 v165, v82, v83
	v_cvt_pk_bf16_f32 v166, v72, v73
	v_cvt_pk_bf16_f32 v167, v74, v75
	global_store_dwordx4 v[220:221], v[164:167], off offset:256
	s_nop 0
	v_add_co_u32_e32 v220, vcc, 0x8000, v220
	s_nop 1
	v_addc_co_u32_e32 v221, vcc, 0, v221, vcc
	v_mul_f32_e32 v84, v84, v247
	v_mul_f32_e32 v85, v85, v247
	v_mul_f32_e32 v86, v86, v247
	v_mul_f32_e32 v87, v87, v247
	v_mul_f32_e32 v76, v76, v247
	v_mul_f32_e32 v77, v77, v247
	v_mul_f32_e32 v78, v78, v247
	v_mul_f32_e32 v79, v79, v247
	v_cvt_pk_bf16_f32 v160, v84, v85
	v_cvt_pk_bf16_f32 v161, v86, v87
	v_cvt_pk_bf16_f32 v162, v76, v77
	v_cvt_pk_bf16_f32 v163, v78, v79
	global_store_dwordx4 v[220:221], v[160:163], off
	v_mul_f32_e32 v68, v68, v247
	v_mul_f32_e32 v69, v69, v247
	v_mul_f32_e32 v70, v70, v247
	v_mul_f32_e32 v71, v71, v247
	v_mul_f32_e32 v64, v64, v247
	v_mul_f32_e32 v65, v65, v247
	v_mul_f32_e32 v66, v66, v247
	v_mul_f32_e32 v67, v67, v247
	v_cvt_pk_bf16_f32 v164, v68, v69
	v_cvt_pk_bf16_f32 v165, v70, v71
	v_cvt_pk_bf16_f32 v166, v64, v65
	v_cvt_pk_bf16_f32 v167, v66, v67
	global_store_dwordx4 v[220:221], v[164:167], off offset:256
	s_nop 0
	v_add_co_u32_e32 v220, vcc, 0x28000, v220
	s_nop 1
	v_addc_co_u32_e32 v221, vcc, 0, v221, vcc
	v_mul_f32_e32 v60, v60, v248
	v_mul_f32_e32 v61, v61, v248
	v_mul_f32_e32 v62, v62, v248
	v_mul_f32_e32 v63, v63, v248
	v_mul_f32_e32 v56, v56, v248
	v_mul_f32_e32 v57, v57, v248
	v_mul_f32_e32 v58, v58, v248
	v_mul_f32_e32 v59, v59, v248
	v_cvt_pk_bf16_f32 v160, v60, v61
	v_cvt_pk_bf16_f32 v161, v62, v63
	v_cvt_pk_bf16_f32 v162, v56, v57
	v_cvt_pk_bf16_f32 v163, v58, v59
	global_store_dwordx4 v[220:221], v[160:163], off
	v_mul_f32_e32 v48, v48, v248
	v_mul_f32_e32 v49, v49, v248
	v_mul_f32_e32 v50, v50, v248
	v_mul_f32_e32 v51, v51, v248
	v_mul_f32_e32 v40, v40, v248
	v_mul_f32_e32 v41, v41, v248
	v_mul_f32_e32 v42, v42, v248
	v_mul_f32_e32 v43, v43, v248
	v_cvt_pk_bf16_f32 v164, v48, v49
	v_cvt_pk_bf16_f32 v165, v50, v51
	v_cvt_pk_bf16_f32 v166, v40, v41
	v_cvt_pk_bf16_f32 v167, v42, v43
	global_store_dwordx4 v[220:221], v[164:167], off offset:256
	s_nop 0
	v_add_co_u32_e32 v220, vcc, 0x8000, v220
	s_nop 1
	v_addc_co_u32_e32 v221, vcc, 0, v221, vcc
	v_mul_f32_e32 v52, v52, v249
	v_mul_f32_e32 v53, v53, v249
	v_mul_f32_e32 v54, v54, v249
	v_mul_f32_e32 v55, v55, v249
	v_mul_f32_e32 v44, v44, v249
	v_mul_f32_e32 v45, v45, v249
	v_mul_f32_e32 v46, v46, v249
	v_mul_f32_e32 v47, v47, v249
	v_cvt_pk_bf16_f32 v160, v52, v53
	v_cvt_pk_bf16_f32 v161, v54, v55
	v_cvt_pk_bf16_f32 v162, v44, v45
	v_cvt_pk_bf16_f32 v163, v46, v47
	global_store_dwordx4 v[220:221], v[160:163], off
	v_mul_f32_e32 v32, v32, v249
	v_mul_f32_e32 v33, v33, v249
	v_mul_f32_e32 v34, v34, v249
	v_mul_f32_e32 v35, v35, v249
	v_mul_f32_e32 v24, v24, v249
	v_mul_f32_e32 v25, v25, v249
	v_mul_f32_e32 v26, v26, v249
	v_mul_f32_e32 v27, v27, v249
	v_cvt_pk_bf16_f32 v164, v32, v33
	v_cvt_pk_bf16_f32 v165, v34, v35
	v_cvt_pk_bf16_f32 v166, v24, v25
	v_cvt_pk_bf16_f32 v167, v26, v27
	global_store_dwordx4 v[220:221], v[164:167], off offset:256
	s_nop 0
	v_add_co_u32_e32 v220, vcc, 0x8000, v220
	s_nop 1
	v_addc_co_u32_e32 v221, vcc, 0, v221, vcc
	v_mul_f32_e32 v36, v36, v250
	v_mul_f32_e32 v37, v37, v250
	v_mul_f32_e32 v38, v38, v250
	v_mul_f32_e32 v39, v39, v250
	v_mul_f32_e32 v28, v28, v250
	v_mul_f32_e32 v29, v29, v250
	v_mul_f32_e32 v30, v30, v250
	v_mul_f32_e32 v31, v31, v250
	v_cvt_pk_bf16_f32 v160, v36, v37
	v_cvt_pk_bf16_f32 v161, v38, v39
	v_cvt_pk_bf16_f32 v162, v28, v29
	v_cvt_pk_bf16_f32 v163, v30, v31
	global_store_dwordx4 v[220:221], v[160:163], off
	v_mul_f32_e32 v16, v16, v250
	v_mul_f32_e32 v17, v17, v250
	v_mul_f32_e32 v18, v18, v250
	v_mul_f32_e32 v19, v19, v250
	v_mul_f32_e32 v8, v8, v250
	v_mul_f32_e32 v9, v9, v250
	v_mul_f32_e32 v10, v10, v250
	v_mul_f32_e32 v11, v11, v250
	v_cvt_pk_bf16_f32 v164, v16, v17
	v_cvt_pk_bf16_f32 v165, v18, v19
	v_cvt_pk_bf16_f32 v166, v8, v9
	v_cvt_pk_bf16_f32 v167, v10, v11
	global_store_dwordx4 v[220:221], v[164:167], off offset:256
	s_nop 0
	v_add_co_u32_e32 v220, vcc, 0x8000, v220
	s_nop 1
	v_addc_co_u32_e32 v221, vcc, 0, v221, vcc
	v_mul_f32_e32 v20, v20, v251
	v_mul_f32_e32 v21, v21, v251
	v_mul_f32_e32 v22, v22, v251
	v_mul_f32_e32 v23, v23, v251
	v_mul_f32_e32 v12, v12, v251
	v_mul_f32_e32 v13, v13, v251
	v_mul_f32_e32 v14, v14, v251
	v_mul_f32_e32 v15, v15, v251
	v_cvt_pk_bf16_f32 v160, v20, v21
	v_cvt_pk_bf16_f32 v161, v22, v23
	v_cvt_pk_bf16_f32 v162, v12, v13
	v_cvt_pk_bf16_f32 v163, v14, v15
	global_store_dwordx4 v[220:221], v[160:163], off
	v_mul_f32_e32 v4, v4, v251
	v_mul_f32_e32 v5, v5, v251
	v_mul_f32_e32 v6, v6, v251
	v_mul_f32_e32 v7, v7, v251
	v_mul_f32_e32 v0, v0, v251
	v_mul_f32_e32 v1, v1, v251
	v_mul_f32_e32 v2, v2, v251
	v_mul_f32_e32 v3, v3, v251
	v_cvt_pk_bf16_f32 v164, v4, v5
	v_cvt_pk_bf16_f32 v165, v6, v7
	v_cvt_pk_bf16_f32 v166, v0, v1
	v_cvt_pk_bf16_f32 v167, v2, v3
	global_store_dwordx4 v[220:221], v[164:167], off offset:256
